# sc1 write-through on all global stores except final norm (cheaper release at grid barriers)
# speedup vs baseline: 1.0144x; 1.0144x over previous
; __device__ __forceinline__ u32x4 pack8(f32x4 a, f32x4 b) { u32x4 w; w.x = cvt_pk_bf16(a[0], a[1]); w.y = cvt_pk_bf16(a[2], a[3]); w.z = cvt_pk_bf16(b[0], b[1]); w.w = cvt_pk_bf16(b[2], b[3]); return w; }
; __device__ __forceinline__ bf16x8 pack8(f32x4 a, f32x4 b) { u32x4 w = {cvtpk(a[0], a[1]), cvtpk(a[2], a[3]), cvtpk(b[0], b[1]), cvtpk(b[2], b[3])}; return *reinterpret_cast<bf16x8*>(&w); }
;     PG8_RSTD_HOOKS
;     __device__ __forceinline__ void operator()(const f32x4 (&acc)[2][2][4][2], const Unit& u, int wr, int wc, int fr, int fq, int par) const {
;         const int row0 = u.pm * BM + wr * 64 + fr, col0 = u.pn * BM + wc * 32 + 8 * fq;
;         float rsv[2][4]; rstd_read(tab, par, wr, fr, rsv);
; #pragma unroll
;         for (int ai = 0; ai < 2; ++ai)
; #pragma unroll
;             for (int m = 0; m < 4; ++m) { const float rs = rsv[ai][m];
;                 bf16_t* rowp = H + ((size_t)(u.pm * 64 + u.pn * 4 + wc) * 256 + (ai * HALF + wr * 64 + m * 16 + fr)) * 64 + 8 * fq;
; #pragma unroll
;                 for (int bj = 0; bj < 2; ++bj) { f32x4 v0 = acc[ai][bj][m][0] * rs, v1 = acc[ai][bj][m][1] * rs;
; #pragma unroll
;                     for (int j = 0; j < 4; ++j) { const float a = fmaxf(v0[j], 0.f), b = fmaxf(v1[j], 0.f); v0[j] = a * a; v1[j] = b * b; }
;                     *(u32x4*)(rowp + bj * 32) = pack8(v0, v1); } }
.LBB0_51:
	s_lshl_b32 s0, s80, 10
	s_and_b32 s0, s0, 0x400
	v_add_u32_e32 v168, s0, v178
	s_lshl_b32 s0, s47, 6
	s_lshl_b32 s1, s46, 2
	s_add_i32 s0, s0, s1
	ds_read2_b32 v[172:173], v168 offset1:16
	ds_read2_b32 v[174:175], v168 offset0:32 offset1:48
	ds_read2_b32 v[170:171], v168 offset0:128 offset1:144
	ds_read2_b32 v[168:169], v168 offset0:160 offset1:176
	s_or_b32 s0, s0, s43
	s_ashr_i32 s1, s0, 31
	s_lshl_b64 s[0:1], s[0:1], 15
	s_waitcnt lgkmcnt(0)
	v_pk_mul_f32 v[132:133], v[132:133], v[172:173] op_sel_hi:[1,0]
	s_add_u32 s22, s88, s0
	v_pk_mul_f32 v[136:137], v[136:137], v[172:173] op_sel_hi:[1,0]
	v_pk_mul_f32 v[134:135], v[134:135], v[172:173] op_sel_hi:[1,0]
	v_max_f32_e32 v132, 0, v132
	s_addc_u32 s23, s89, s1
	v_pk_mul_f32 v[138:139], v[138:139], v[172:173] op_sel_hi:[1,0]
	v_mul_f32_e32 v182, v132, v132
	v_max_f32_e32 v132, 0, v137
	v_max_f32_e32 v133, 0, v133
	v_max_f32_e32 v134, 0, v134
	v_lshl_add_u64 v[180:181], s[22:23], 0, v[148:149]
	v_max_f32_e32 v136, 0, v136
	v_mul_f32_e32 v132, v132, v132
	v_mul_f32_e32 v137, v133, v133
	v_max_f32_e32 v133, 0, v138
	v_mul_f32_e32 v138, v134, v134
	v_max_f32_e32 v134, 0, v139
	v_max_f32_e32 v135, 0, v135
	v_pk_mul_f32 v[126:127], v[126:127], v[172:173] op_sel_hi:[1,0]
	v_pk_mul_f32 v[124:125], v[124:125], v[172:173] op_sel_hi:[1,0]
	v_lshl_add_u64 v[180:181], v[180:181], 0, v[98:99]
	v_mul_f32_e32 v136, v136, v136
	v_mul_f32_e32 v133, v133, v133
	v_mul_f32_e32 v134, v134, v134
	v_mul_f32_e32 v135, v135, v135
	v_cvt_pk_bf16_f32 v132, v136, v132
	v_pk_mul_f32 v[130:131], v[130:131], v[172:173] op_sel_hi:[1,0]
	v_pk_mul_f32 v[128:129], v[128:129], v[172:173] op_sel_hi:[1,0]
	v_max_f32_e32 v124, 0, v124
	v_max_f32_e32 v125, 0, v125
	v_max_f32_e32 v126, 0, v126
	v_cvt_pk_bf16_f32 v133, v133, v134
	v_cvt_pk_bf16_f32 v134, v182, v137
	v_cvt_pk_bf16_f32 v135, v138, v135
	global_store_dwordx4 v[180:181], v[132:135], off sc1
	v_max_f32_e32 v128, 0, v128
	v_max_f32_e32 v127, 0, v127
	v_mul_f32_e32 v132, v124, v124
	v_max_f32_e32 v124, 0, v129
	v_mul_f32_e32 v129, v125, v125
	v_max_f32_e32 v125, 0, v130
	v_mul_f32_e32 v130, v126, v126
	v_max_f32_e32 v126, 0, v131
	v_mul_f32_e32 v124, v124, v124
	v_mul_f32_e32 v125, v125, v125
	v_mul_f32_e32 v126, v126, v126
	v_mul_f32_e32 v128, v128, v128
	v_mul_f32_e32 v127, v127, v127
	v_cvt_pk_bf16_f32 v124, v128, v124
	v_cvt_pk_bf16_f32 v125, v125, v126
	v_cvt_pk_bf16_f32 v126, v132, v129
	v_cvt_pk_bf16_f32 v127, v130, v127
	global_store_dwordx4 v[180:181], v[124:127], off offset:64 sc1
	v_pk_mul_f32 v[100:101], v[100:101], v[174:175] op_sel_hi:[1,0]
	v_pk_mul_f32 v[104:105], v[104:105], v[174:175] op_sel_hi:[1,0]
	v_mov_b32_e32 v126, v173
	v_pk_mul_f32 v[116:117], v[116:117], v[126:127] op_sel_hi:[1,0]
	v_pk_mul_f32 v[120:121], v[120:121], v[126:127] op_sel_hi:[1,0]
	v_pk_mul_f32 v[118:119], v[118:119], v[126:127] op_sel_hi:[1,0]
	v_max_f32_e32 v116, 0, v116
	v_pk_mul_f32 v[122:123], v[122:123], v[126:127] op_sel_hi:[1,0]
	v_mul_f32_e32 v127, v116, v116
	v_max_f32_e32 v116, 0, v121
	v_max_f32_e32 v117, 0, v117
	v_max_f32_e32 v118, 0, v118
	v_lshl_add_u64 v[124:125], s[22:23], 0, v[150:151]
	v_max_f32_e32 v120, 0, v120
	v_mul_f32_e32 v116, v116, v116
	v_mul_f32_e32 v121, v117, v117
	v_max_f32_e32 v117, 0, v122
	v_mul_f32_e32 v122, v118, v118
	v_max_f32_e32 v118, 0, v123
	v_max_f32_e32 v119, 0, v119
	v_pk_mul_f32 v[110:111], v[110:111], v[126:127] op_sel_hi:[1,0]
	v_pk_mul_f32 v[108:109], v[108:109], v[126:127] op_sel_hi:[1,0]
	v_lshl_add_u64 v[124:125], v[124:125], 0, v[98:99]
	v_mul_f32_e32 v120, v120, v120
	v_mul_f32_e32 v117, v117, v117
	v_mul_f32_e32 v118, v118, v118
	v_mul_f32_e32 v119, v119, v119
	v_cvt_pk_bf16_f32 v116, v120, v116
	v_pk_mul_f32 v[114:115], v[114:115], v[126:127] op_sel_hi:[1,0]
	v_pk_mul_f32 v[112:113], v[112:113], v[126:127] op_sel_hi:[1,0]
	v_max_f32_e32 v108, 0, v108
	v_max_f32_e32 v109, 0, v109
	v_max_f32_e32 v110, 0, v110
	v_cvt_pk_bf16_f32 v117, v117, v118
	v_cvt_pk_bf16_f32 v118, v127, v121
	v_cvt_pk_bf16_f32 v119, v122, v119
	global_store_dwordx4 v[124:125], v[116:119], off sc1
	v_max_f32_e32 v112, 0, v112
	v_max_f32_e32 v111, 0, v111
	v_mul_f32_e32 v116, v108, v108
	v_max_f32_e32 v108, 0, v113
	v_mul_f32_e32 v113, v109, v109
	v_max_f32_e32 v109, 0, v114
	v_mul_f32_e32 v114, v110, v110
	v_max_f32_e32 v110, 0, v115
	v_mul_f32_e32 v108, v108, v108
	v_mul_f32_e32 v109, v109, v109
	v_mul_f32_e32 v110, v110, v110
	v_mul_f32_e32 v112, v112, v112
	v_mul_f32_e32 v111, v111, v111
	v_cvt_pk_bf16_f32 v108, v112, v108
	v_cvt_pk_bf16_f32 v109, v109, v110
	v_cvt_pk_bf16_f32 v110, v116, v113
	v_pk_mul_f32 v[102:103], v[102:103], v[174:175] op_sel_hi:[1,0]
	v_max_f32_e32 v100, 0, v100
	v_cvt_pk_bf16_f32 v111, v114, v111
	global_store_dwordx4 v[124:125], v[108:111], off offset:64 sc1
	v_pk_mul_f32 v[106:107], v[106:107], v[174:175] op_sel_hi:[1,0]
	v_max_f32_e32 v101, 0, v101
	v_mul_f32_e32 v110, v100, v100
	v_max_f32_e32 v100, 0, v105
	v_max_f32_e32 v102, 0, v102
	v_lshl_add_u64 v[108:109], s[22:23], 0, v[152:153]
	v_max_f32_e32 v104, 0, v104
	v_mul_f32_e32 v100, v100, v100
	v_mul_f32_e32 v105, v101, v101
	v_max_f32_e32 v101, 0, v106
	v_mul_f32_e32 v106, v102, v102
	v_max_f32_e32 v102, 0, v107
	v_max_f32_e32 v103, 0, v103
	v_pk_mul_f32 v[92:93], v[92:93], v[174:175] op_sel_hi:[1,0]
	v_pk_mul_f32 v[90:91], v[90:91], v[174:175] op_sel_hi:[1,0]
	v_lshl_add_u64 v[108:109], v[108:109], 0, v[98:99]
	v_mul_f32_e32 v104, v104, v104
	v_mul_f32_e32 v101, v101, v101
	v_mul_f32_e32 v102, v102, v102
	v_mul_f32_e32 v103, v103, v103
	v_cvt_pk_bf16_f32 v100, v104, v100
	v_pk_mul_f32 v[96:97], v[96:97], v[174:175] op_sel_hi:[1,0]
; __device__ __forceinline__ u32x4 pack8(f32x4 a, f32x4 b) { u32x4 w; w.x = cvt_pk_bf16(a[0], a[1]); w.y = cvt_pk_bf16(a[2], a[3]); w.z = cvt_pk_bf16(b[0], b[1]); w.w = cvt_pk_bf16(b[2], b[3]); return w; }
; __device__ __forceinline__ bf16x8 pack8(f32x4 a, f32x4 b) { u32x4 w = {cvtpk(a[0], a[1]), cvtpk(a[2], a[3]), cvtpk(b[0], b[1]), cvtpk(b[2], b[3])}; return *reinterpret_cast<bf16x8*>(&w); }
;     PG8_RSTD_HOOKS
;     __device__ __forceinline__ void operator()(const f32x4 (&acc)[2][2][4][2], const Unit& u, int wr, int wc, int fr, int fq, int par) const {
;     ...
;             for (int m = 0; m < 4; ++m) { const float rs = rsv[ai][m];
;                 bf16_t* rowp = H + ((size_t)(u.pm * 64 + u.pn * 4 + wc) * 256 + (ai * HALF + wr * 64 + m * 16 + fr)) * 64 + 8 * fq;
; #pragma unroll
;                 for (int bj = 0; bj < 2; ++bj) { f32x4 v0 = acc[ai][bj][m][0] * rs, v1 = acc[ai][bj][m][1] * rs;
; #pragma unroll
;                     for (int j = 0; j < 4; ++j) { const float a = fmaxf(v0[j], 0.f), b = fmaxf(v1[j], 0.f); v0[j] = a * a; v1[j] = b * b; }
;                     *(u32x4*)(rowp + bj * 32) = pack8(v0, v1); } }
	v_pk_mul_f32 v[94:95], v[94:95], v[174:175] op_sel_hi:[1,0]
	v_max_f32_e32 v90, 0, v90
	v_max_f32_e32 v91, 0, v91
	v_max_f32_e32 v92, 0, v92
	v_cvt_pk_bf16_f32 v101, v101, v102
	v_cvt_pk_bf16_f32 v102, v110, v105
	v_cvt_pk_bf16_f32 v103, v106, v103
	global_store_dwordx4 v[108:109], v[100:103], off sc1
	v_max_f32_e32 v94, 0, v94
	v_max_f32_e32 v93, 0, v93
	v_mul_f32_e32 v100, v90, v90
	v_max_f32_e32 v90, 0, v95
	v_mul_f32_e32 v95, v91, v91
	v_max_f32_e32 v91, 0, v96
	v_mul_f32_e32 v96, v92, v92
	v_max_f32_e32 v92, 0, v97
	v_mul_f32_e32 v90, v90, v90
	v_mul_f32_e32 v91, v91, v91
	v_mul_f32_e32 v92, v92, v92
	v_mul_f32_e32 v94, v94, v94
	v_mul_f32_e32 v93, v93, v93
	v_cvt_pk_bf16_f32 v90, v94, v90
	v_cvt_pk_bf16_f32 v91, v91, v92
	v_cvt_pk_bf16_f32 v92, v100, v95
	v_cvt_pk_bf16_f32 v93, v96, v93
	global_store_dwordx4 v[108:109], v[90:93], off offset:64 sc1
	v_pk_mul_f32 v[66:67], v[66:67], v[170:171] op_sel_hi:[1,0]
	v_pk_mul_f32 v[70:71], v[70:71], v[170:171] op_sel_hi:[1,0]
	v_mov_b32_e32 v92, v175
	v_pk_mul_f32 v[82:83], v[82:83], v[92:93] op_sel_hi:[1,0]
	v_pk_mul_f32 v[86:87], v[86:87], v[92:93] op_sel_hi:[1,0]
	v_pk_mul_f32 v[84:85], v[84:85], v[92:93] op_sel_hi:[1,0]
	v_max_f32_e32 v82, 0, v82
	v_pk_mul_f32 v[88:89], v[88:89], v[92:93] op_sel_hi:[1,0]
	v_mul_f32_e32 v93, v82, v82
	v_max_f32_e32 v82, 0, v87
	v_max_f32_e32 v83, 0, v83
	v_max_f32_e32 v84, 0, v84
	v_lshl_add_u64 v[90:91], s[22:23], 0, v[154:155]
	v_max_f32_e32 v86, 0, v86
	v_mul_f32_e32 v82, v82, v82
	v_mul_f32_e32 v87, v83, v83
	v_max_f32_e32 v83, 0, v88
	v_mul_f32_e32 v88, v84, v84
	v_max_f32_e32 v84, 0, v89
	v_max_f32_e32 v85, 0, v85
	v_pk_mul_f32 v[76:77], v[76:77], v[92:93] op_sel_hi:[1,0]
	v_pk_mul_f32 v[74:75], v[74:75], v[92:93] op_sel_hi:[1,0]
	v_lshl_add_u64 v[90:91], v[90:91], 0, v[98:99]
	v_mul_f32_e32 v86, v86, v86
	v_mul_f32_e32 v83, v83, v83
	v_mul_f32_e32 v84, v84, v84
	v_mul_f32_e32 v85, v85, v85
	v_cvt_pk_bf16_f32 v82, v86, v82
	v_pk_mul_f32 v[80:81], v[80:81], v[92:93] op_sel_hi:[1,0]
	v_pk_mul_f32 v[78:79], v[78:79], v[92:93] op_sel_hi:[1,0]
	v_max_f32_e32 v74, 0, v74
	v_max_f32_e32 v75, 0, v75
	v_max_f32_e32 v76, 0, v76
	v_cvt_pk_bf16_f32 v83, v83, v84
	v_cvt_pk_bf16_f32 v84, v93, v87
	v_cvt_pk_bf16_f32 v85, v88, v85
	global_store_dwordx4 v[90:91], v[82:85], off sc1
	v_max_f32_e32 v78, 0, v78
	v_max_f32_e32 v77, 0, v77
	v_mul_f32_e32 v82, v74, v74
	v_max_f32_e32 v74, 0, v79
	v_mul_f32_e32 v79, v75, v75
	v_max_f32_e32 v75, 0, v80
	v_mul_f32_e32 v80, v76, v76
	v_max_f32_e32 v76, 0, v81
	v_mul_f32_e32 v74, v74, v74
	v_mul_f32_e32 v75, v75, v75
	v_mul_f32_e32 v76, v76, v76
	v_mul_f32_e32 v78, v78, v78
	v_mul_f32_e32 v77, v77, v77
	v_cvt_pk_bf16_f32 v74, v78, v74
	v_cvt_pk_bf16_f32 v75, v75, v76
	v_cvt_pk_bf16_f32 v76, v82, v79
	v_pk_mul_f32 v[68:69], v[68:69], v[170:171] op_sel_hi:[1,0]
	v_max_f32_e32 v66, 0, v66
	v_cvt_pk_bf16_f32 v77, v80, v77
	global_store_dwordx4 v[90:91], v[74:77], off offset:64 sc1
	v_pk_mul_f32 v[72:73], v[72:73], v[170:171] op_sel_hi:[1,0]
	v_max_f32_e32 v67, 0, v67
	v_mul_f32_e32 v76, v66, v66
	v_max_f32_e32 v66, 0, v71
	v_max_f32_e32 v68, 0, v68
	v_lshl_add_u64 v[74:75], s[22:23], 0, v[156:157]
	v_max_f32_e32 v70, 0, v70
	v_mul_f32_e32 v66, v66, v66
	v_mul_f32_e32 v71, v67, v67
	v_max_f32_e32 v67, 0, v72
	v_mul_f32_e32 v72, v68, v68
	v_max_f32_e32 v68, 0, v73
	v_max_f32_e32 v69, 0, v69
	v_pk_mul_f32 v[60:61], v[60:61], v[170:171] op_sel_hi:[1,0]
	v_pk_mul_f32 v[58:59], v[58:59], v[170:171] op_sel_hi:[1,0]
	v_lshl_add_u64 v[74:75], v[74:75], 0, v[98:99]
	v_mul_f32_e32 v70, v70, v70
	v_mul_f32_e32 v67, v67, v67
	v_mul_f32_e32 v68, v68, v68
	v_mul_f32_e32 v69, v69, v69
	v_cvt_pk_bf16_f32 v66, v70, v66
	v_pk_mul_f32 v[64:65], v[64:65], v[170:171] op_sel_hi:[1,0]
	v_pk_mul_f32 v[62:63], v[62:63], v[170:171] op_sel_hi:[1,0]
	v_max_f32_e32 v58, 0, v58
	v_max_f32_e32 v59, 0, v59
	v_max_f32_e32 v60, 0, v60
	v_cvt_pk_bf16_f32 v67, v67, v68
	v_cvt_pk_bf16_f32 v68, v76, v71
	v_cvt_pk_bf16_f32 v69, v72, v69
	global_store_dwordx4 v[74:75], v[66:69], off sc1
	v_max_f32_e32 v62, 0, v62
	v_max_f32_e32 v61, 0, v61
	v_mul_f32_e32 v66, v58, v58
	v_max_f32_e32 v58, 0, v63
	v_mul_f32_e32 v63, v59, v59
	v_max_f32_e32 v59, 0, v64
	v_mul_f32_e32 v64, v60, v60
	v_max_f32_e32 v60, 0, v65
	v_mul_f32_e32 v58, v58, v58
	v_mul_f32_e32 v59, v59, v59
	v_mul_f32_e32 v60, v60, v60
	v_mul_f32_e32 v62, v62, v62
	v_mul_f32_e32 v61, v61, v61
	v_cvt_pk_bf16_f32 v58, v62, v58
	v_cvt_pk_bf16_f32 v59, v59, v60
	v_cvt_pk_bf16_f32 v60, v66, v63
	v_cvt_pk_bf16_f32 v61, v64, v61
	global_store_dwordx4 v[74:75], v[58:61], off offset:64 sc1
	v_pk_mul_f32 v[34:35], v[34:35], v[168:169] op_sel_hi:[1,0]
	v_pk_mul_f32 v[38:39], v[38:39], v[168:169] op_sel_hi:[1,0]
	v_mov_b32_e32 v60, v171
	v_pk_mul_f32 v[50:51], v[50:51], v[60:61] op_sel_hi:[1,0]
	v_pk_mul_f32 v[54:55], v[54:55], v[60:61] op_sel_hi:[1,0]
	v_pk_mul_f32 v[52:53], v[52:53], v[60:61] op_sel_hi:[1,0]
	v_max_f32_e32 v50, 0, v50
	v_pk_mul_f32 v[56:57], v[56:57], v[60:61] op_sel_hi:[1,0]
	v_mul_f32_e32 v61, v50, v50
	v_max_f32_e32 v50, 0, v55
	v_max_f32_e32 v51, 0, v51
	v_max_f32_e32 v52, 0, v52
	v_lshl_add_u64 v[58:59], s[22:23], 0, v[158:159]
	v_max_f32_e32 v54, 0, v54
	v_mul_f32_e32 v50, v50, v50
	v_mul_f32_e32 v55, v51, v51
	v_max_f32_e32 v51, 0, v56
	v_mul_f32_e32 v56, v52, v52
	v_max_f32_e32 v52, 0, v57
	v_max_f32_e32 v53, 0, v53
	v_pk_mul_f32 v[44:45], v[44:45], v[60:61] op_sel_hi:[1,0]
	v_pk_mul_f32 v[42:43], v[42:43], v[60:61] op_sel_hi:[1,0]
; __device__ __forceinline__ int opaque_tid() { int t = threadIdx.x; asm volatile("" : "+v"(t)); return t; }
; #define PG8_LAS __attribute__((address_space(3)))
; __device__ __forceinline__ u32x4 pack8(f32x4 a, f32x4 b) { u32x4 w; w.x = cvt_pk_bf16(a[0], a[1]); w.y = cvt_pk_bf16(a[2], a[3]); w.z = cvt_pk_bf16(b[0], b[1]); w.w = cvt_pk_bf16(b[2], b[3]); return w; }
; __device__ __forceinline__ bf16x8 pack8(f32x4 a, f32x4 b) { u32x4 w = {cvtpk(a[0], a[1]), cvtpk(a[2], a[3]), cvtpk(b[0], b[1]), cvtpk(b[2], b[3])}; return *reinterpret_cast<bf16x8*>(&w); }
; __device__ __forceinline__ void rstd_store(PG8_LAS float* tab, const RstdIni& ini, int par) {
;     const int tid = opaque_tid();
;     float s = ((ini.a[0] + ini.a[1]) + (ini.a[2] + ini.a[3])) + ((ini.b[0] + ini.b[1]) + (ini.b[2] + ini.b[3]));
;     s += __shfl_xor(s, 1);
;     if (!(tid & 1)) tab[par * BM + (tid >> 1)] = __builtin_amdgcn_rsqf(s * (1.0f / 1024.0f) + 1e-6f);
; }
;     PG8_RSTD_HOOKS
;     __device__ __forceinline__ void operator()(const f32x4 (&acc)[2][2][4][2], const Unit& u, int wr, int wc, int fr, int fq, int par) const {
;     ...
;             for (int m = 0; m < 4; ++m) { const float rs = rsv[ai][m];
;                 bf16_t* rowp = H + ((size_t)(u.pm * 64 + u.pn * 4 + wc) * 256 + (ai * HALF + wr * 64 + m * 16 + fr)) * 64 + 8 * fq;
; #pragma unroll
;                 for (int bj = 0; bj < 2; ++bj) { f32x4 v0 = acc[ai][bj][m][0] * rs, v1 = acc[ai][bj][m][1] * rs;
; #pragma unroll
;                     for (int j = 0; j < 4; ++j) { const float a = fmaxf(v0[j], 0.f), b = fmaxf(v1[j], 0.f); v0[j] = a * a; v1[j] = b * b; }
;                     *(u32x4*)(rowp + bj * 32) = pack8(v0, v1); } }
	v_lshl_add_u64 v[58:59], v[58:59], 0, v[98:99]
	v_mul_f32_e32 v54, v54, v54
	v_mul_f32_e32 v51, v51, v51
	v_mul_f32_e32 v52, v52, v52
	v_mul_f32_e32 v53, v53, v53
	v_cvt_pk_bf16_f32 v50, v54, v50
	v_pk_mul_f32 v[48:49], v[48:49], v[60:61] op_sel_hi:[1,0]
	v_pk_mul_f32 v[46:47], v[46:47], v[60:61] op_sel_hi:[1,0]
	v_max_f32_e32 v42, 0, v42
	v_max_f32_e32 v43, 0, v43
	v_max_f32_e32 v44, 0, v44
	v_cvt_pk_bf16_f32 v51, v51, v52
	v_cvt_pk_bf16_f32 v52, v61, v55
	v_cvt_pk_bf16_f32 v53, v56, v53
	global_store_dwordx4 v[58:59], v[50:53], off sc1
	v_max_f32_e32 v46, 0, v46
	v_max_f32_e32 v45, 0, v45
	v_mul_f32_e32 v50, v42, v42
	v_max_f32_e32 v42, 0, v47
	v_mul_f32_e32 v47, v43, v43
	v_max_f32_e32 v43, 0, v48
	v_mul_f32_e32 v48, v44, v44
	v_max_f32_e32 v44, 0, v49
	v_mul_f32_e32 v42, v42, v42
	v_mul_f32_e32 v43, v43, v43
	v_mul_f32_e32 v44, v44, v44
	v_mul_f32_e32 v46, v46, v46
	v_mul_f32_e32 v45, v45, v45
	v_cvt_pk_bf16_f32 v42, v46, v42
	v_cvt_pk_bf16_f32 v43, v43, v44
	v_cvt_pk_bf16_f32 v44, v50, v47
	v_pk_mul_f32 v[36:37], v[36:37], v[168:169] op_sel_hi:[1,0]
	v_max_f32_e32 v34, 0, v34
	v_cvt_pk_bf16_f32 v45, v48, v45
	global_store_dwordx4 v[58:59], v[42:45], off offset:64 sc1
	v_pk_mul_f32 v[40:41], v[40:41], v[168:169] op_sel_hi:[1,0]
	v_max_f32_e32 v35, 0, v35
	v_mul_f32_e32 v44, v34, v34
	v_max_f32_e32 v34, 0, v39
	v_max_f32_e32 v36, 0, v36
	v_lshl_add_u64 v[42:43], s[22:23], 0, v[160:161]
	v_max_f32_e32 v38, 0, v38
	v_mul_f32_e32 v34, v34, v34
	v_mul_f32_e32 v39, v35, v35
	v_max_f32_e32 v35, 0, v40
	v_mul_f32_e32 v40, v36, v36
	v_max_f32_e32 v36, 0, v41
	v_max_f32_e32 v37, 0, v37
	v_pk_mul_f32 v[28:29], v[28:29], v[168:169] op_sel_hi:[1,0]
	v_pk_mul_f32 v[26:27], v[26:27], v[168:169] op_sel_hi:[1,0]
	v_lshl_add_u64 v[42:43], v[42:43], 0, v[98:99]
	v_mul_f32_e32 v38, v38, v38
	v_mul_f32_e32 v35, v35, v35
	v_mul_f32_e32 v36, v36, v36
	v_mul_f32_e32 v37, v37, v37
	v_cvt_pk_bf16_f32 v34, v38, v34
	v_pk_mul_f32 v[32:33], v[32:33], v[168:169] op_sel_hi:[1,0]
	v_pk_mul_f32 v[30:31], v[30:31], v[168:169] op_sel_hi:[1,0]
	v_max_f32_e32 v26, 0, v26
	v_max_f32_e32 v27, 0, v27
	v_max_f32_e32 v28, 0, v28
	v_cvt_pk_bf16_f32 v35, v35, v36
	v_cvt_pk_bf16_f32 v36, v44, v39
	v_cvt_pk_bf16_f32 v37, v40, v37
	global_store_dwordx4 v[42:43], v[34:37], off sc1
	v_max_f32_e32 v30, 0, v30
	v_max_f32_e32 v29, 0, v29
	v_mul_f32_e32 v34, v26, v26
	v_max_f32_e32 v26, 0, v31
	v_mul_f32_e32 v31, v27, v27
	v_max_f32_e32 v27, 0, v32
	v_mul_f32_e32 v32, v28, v28
	v_max_f32_e32 v28, 0, v33
	v_mul_f32_e32 v26, v26, v26
	v_mul_f32_e32 v27, v27, v27
	v_mul_f32_e32 v28, v28, v28
	v_mul_f32_e32 v30, v30, v30
	v_mul_f32_e32 v29, v29, v29
	v_cvt_pk_bf16_f32 v26, v30, v26
	v_cvt_pk_bf16_f32 v27, v27, v28
	v_cvt_pk_bf16_f32 v28, v34, v31
	v_cvt_pk_bf16_f32 v29, v32, v29
	global_store_dwordx4 v[42:43], v[26:29], off offset:64 sc1
	s_and_b64 vcc, exec, s[38:39]
	s_mov_b64 s[0:1], -1
	v_mov_b32_e32 v28, v169
	v_pk_mul_f32 v[18:19], v[18:19], v[28:29] op_sel_hi:[1,0]
	v_pk_mul_f32 v[22:23], v[22:23], v[28:29] op_sel_hi:[1,0]
	v_pk_mul_f32 v[20:21], v[20:21], v[28:29] op_sel_hi:[1,0]
	v_max_f32_e32 v18, 0, v18
	v_pk_mul_f32 v[24:25], v[24:25], v[28:29] op_sel_hi:[1,0]
	v_mul_f32_e32 v29, v18, v18
	v_max_f32_e32 v18, 0, v23
	v_max_f32_e32 v19, 0, v19
	v_max_f32_e32 v20, 0, v20
	v_lshl_add_u64 v[26:27], s[22:23], 0, v[162:163]
	v_max_f32_e32 v22, 0, v22
	v_mul_f32_e32 v18, v18, v18
	v_mul_f32_e32 v23, v19, v19
	v_max_f32_e32 v19, 0, v24
	v_mul_f32_e32 v24, v20, v20
	v_max_f32_e32 v20, 0, v25
	v_max_f32_e32 v21, 0, v21
	v_pk_mul_f32 v[12:13], v[12:13], v[28:29] op_sel_hi:[1,0]
	v_pk_mul_f32 v[10:11], v[10:11], v[28:29] op_sel_hi:[1,0]
	v_lshl_add_u64 v[26:27], v[26:27], 0, v[98:99]
	v_mul_f32_e32 v22, v22, v22
	v_mul_f32_e32 v19, v19, v19
	v_mul_f32_e32 v20, v20, v20
	v_mul_f32_e32 v21, v21, v21
	v_cvt_pk_bf16_f32 v18, v22, v18
	v_pk_mul_f32 v[16:17], v[16:17], v[28:29] op_sel_hi:[1,0]
	v_pk_mul_f32 v[14:15], v[14:15], v[28:29] op_sel_hi:[1,0]
	v_max_f32_e32 v10, 0, v10
	v_max_f32_e32 v11, 0, v11
	v_max_f32_e32 v12, 0, v12
	v_cvt_pk_bf16_f32 v19, v19, v20
	v_cvt_pk_bf16_f32 v20, v29, v23
	v_cvt_pk_bf16_f32 v21, v24, v21
	global_store_dwordx4 v[26:27], v[18:21], off sc1
	v_max_f32_e32 v13, 0, v13
	v_max_f32_e32 v14, 0, v14
	v_mul_f32_e32 v18, v10, v10
	v_max_f32_e32 v10, 0, v15
	v_mul_f32_e32 v15, v11, v11
	v_max_f32_e32 v11, 0, v16
	v_mul_f32_e32 v16, v12, v12
	v_max_f32_e32 v12, 0, v17
	v_mul_f32_e32 v10, v10, v10
	v_mul_f32_e32 v11, v11, v11
	v_mul_f32_e32 v12, v12, v12
	v_mul_f32_e32 v13, v13, v13
	v_mul_f32_e32 v14, v14, v14
	v_cvt_pk_bf16_f32 v10, v14, v10
	v_cvt_pk_bf16_f32 v11, v11, v12
	v_cvt_pk_bf16_f32 v12, v18, v15
	v_cvt_pk_bf16_f32 v13, v16, v13
	global_store_dwordx4 v[26:27], v[10:13], off offset:64 sc1
	s_cbranch_vccnz .LBB0_38
	s_waitcnt vmcnt(0)
	v_add_f32_e32 v10, v6, v7
	v_add_f32_e32 v11, v8, v9
	v_add_f32_e32 v10, v10, v11
	v_add_f32_e32 v11, v2, v3
	v_add_f32_e32 v12, v4, v5
	v_add_f32_e32 v11, v11, v12
	v_add_f32_e32 v11, v11, v10
	ds_bpermute_b32 v12, v176, v11
	v_mov_b32_e32 v10, v0
	s_nop 0
	v_and_b32_e32 v13, 1, v10
	v_cmp_eq_u32_e32 vcc, 0, v13
	s_and_saveexec_b64 s[0:1], vcc
	s_cbranch_execz .LBB0_54
	s_waitcnt lgkmcnt(0)
	v_add_f32_e32 v11, v11, v12
	s_lshl_b32 s6, s45, 10
	v_fmamk_f32 v11, v11, 0x3a800000, v1
	s_and_b32 s6, s6, 0x400
	v_rsq_f32_e32 v11, v11
	s_add_i32 s6, s6, 0
	v_lshl_add_u32 v10, v10, 1, s6
	v_add_u32_e32 v10, 0x21000, v10
	ds_write_b32 v10, v11

; __device__ __forceinline__ unsigned pk2(float lo, float hi) { return pg8::cvt_pk_bf16(lo, hi); }
; __device__ __forceinline__ float bf_lo(unsigned w) { return __uint_as_float(w << 16); }
; __device__ __forceinline__ float bf_hi(unsigned w) { return __uint_as_float(w & 0xffff0000u); }
; __device__ __forceinline__ void conv_prep(const bf16* Z, const bf16* GB, const float* cw, bf16* A2, int vcu, int G, int tid) {
;     const int gt = vcu * 512 + tid, NT = G * 512;
;     for (int it = gt; it < (M / 16) * 128; it += NT) { const int c8 = (it & 127) * 8, rb = (it >> 7) * 16, t0 = rb & (SEQ - 1);
;         f32x4 w0[2], w1[2], w2[2];
; #pragma unroll
;         for (int k = 0; k < 2; ++k) { w0[k] = *(const f32x4*)(cw + c8 + 4 * k); w1[k] = *(const f32x4*)(cw + 1024 + c8 + 4 * k); w2[k] = *(const f32x4*)(cw + 2048 + c8 + 4 * k); }
;         const v4u zero = {0u, 0u, 0u, 0u};
;         v4u z0 = (t0 >= 2) ? *(const v4u*)(Z + (size_t)(rb - 2) * DM + c8) : zero;
;         v4u z1 = (t0 >= 1) ? *(const v4u*)(Z + (size_t)(rb - 1) * DM + c8) : zero;
;         v4u zz[16], gg[16];
; #pragma unroll
;         for (int i = 0; i < 16; ++i) { zz[i] = *(const v4u*)(Z + (size_t)(rb + i) * DM + c8); gg[i] = *(const v4u*)(GB + (size_t)(rb + i) * DM + c8); }
; #pragma unroll
;         for (int i = 0; i < 16; ++i) { const v4u z2 = zz[i], gb = gg[i]; v4u o;
; #pragma unroll
;             for (int k = 0; k < 4; ++k) { const int e = 2 * k;
;                 const float a = bf_lo(gb[k]) * (w0[e >> 2][e & 3] * bf_lo(z0[k]) + w1[e >> 2][e & 3] * bf_lo(z1[k]) + w2[e >> 2][e & 3] * bf_lo(z2[k]));
;                 const float b = bf_hi(gb[k]) * (w0[(e + 1) >> 2][(e + 1) & 3] * bf_hi(z0[k]) + w1[(e + 1) >> 2][(e + 1) & 3] * bf_hi(z1[k]) + w2[(e + 1) >> 2][(e + 1) & 3] * bf_hi(z2[k]));
;                 o[k] = pk2(a, b); }
;             *(v4u*)(A2 + (size_t)(rb + i) * DM + c8) = o; z0 = z1; z1 = z2; }
.LBB0_68:
	s_or_b64 exec, exec, s[0:1]
	v_readlane_b32 s0, v253, 51
	v_lshl_add_u64 v[32:33], s[88:89], 0, v[98:99]
	v_readlane_b32 s1, v253, 52
	v_lshlrev_b64 v[214:215], 11, v[26:27]
	v_lshl_add_u64 v[28:29], v[32:33], 0, v[214:215]
	v_lshl_add_u64 v[34:35], s[0:1], 0, v[98:99]
	v_lshl_add_u64 v[36:37], v[34:35], 0, v[214:215]
	global_load_dwordx4 v[164:167], v[28:29], off
	global_load_dwordx4 v[172:175], v[36:37], off
	v_or_b32_e32 v28, 1, v26
	v_ashrrev_i32_e32 v29, 31, v28
	v_lshlrev_b64 v[192:193], 11, v[28:29]
	v_lshl_add_u64 v[28:29], v[32:33], 0, v[192:193]
	v_lshl_add_u64 v[36:37], v[34:35], 0, v[192:193]
	global_load_dwordx4 v[144:147], v[28:29], off
	global_load_dwordx4 v[148:151], v[36:37], off
	v_or_b32_e32 v28, 2, v26
	v_ashrrev_i32_e32 v29, 31, v28
	v_lshlrev_b64 v[194:195], 11, v[28:29]
	v_lshl_add_u64 v[28:29], v[32:33], 0, v[194:195]
	v_lshl_add_u64 v[36:37], v[34:35], 0, v[194:195]
	global_load_dwordx4 v[124:127], v[28:29], off
	global_load_dwordx4 v[140:143], v[36:37], off
	v_or_b32_e32 v28, 3, v26
	v_ashrrev_i32_e32 v29, 31, v28
	v_lshlrev_b64 v[188:189], 11, v[28:29]
	v_lshl_add_u64 v[28:29], v[32:33], 0, v[188:189]
	v_lshl_add_u64 v[36:37], v[34:35], 0, v[188:189]
	global_load_dwordx4 v[128:131], v[28:29], off
	global_load_dwordx4 v[132:135], v[36:37], off
	v_or_b32_e32 v28, 4, v26
	v_ashrrev_i32_e32 v29, 31, v28
	v_lshlrev_b64 v[190:191], 11, v[28:29]
	v_lshl_add_u64 v[28:29], v[32:33], 0, v[190:191]
	v_lshl_add_u64 v[36:37], v[34:35], 0, v[190:191]
	global_load_dwordx4 v[108:111], v[28:29], off
	global_load_dwordx4 v[120:123], v[36:37], off
	v_or_b32_e32 v28, 5, v26
	v_ashrrev_i32_e32 v29, 31, v28
	v_lshlrev_b64 v[184:185], 11, v[28:29]
	v_lshl_add_u64 v[28:29], v[32:33], 0, v[184:185]
	v_lshl_add_u64 v[36:37], v[34:35], 0, v[184:185]
	global_load_dwordx4 v[112:115], v[28:29], off
	global_load_dwordx4 v[116:119], v[36:37], off
	v_or_b32_e32 v28, 6, v26
	v_ashrrev_i32_e32 v29, 31, v28
	v_lshlrev_b64 v[186:187], 11, v[28:29]
	v_lshl_add_u64 v[28:29], v[32:33], 0, v[186:187]
	v_lshl_add_u64 v[36:37], v[34:35], 0, v[186:187]
	global_load_dwordx4 v[90:93], v[28:29], off
	global_load_dwordx4 v[104:107], v[36:37], off
	v_or_b32_e32 v28, 7, v26
	v_ashrrev_i32_e32 v29, 31, v28
	v_lshlrev_b64 v[180:181], 11, v[28:29]
	v_lshl_add_u64 v[28:29], v[32:33], 0, v[180:181]
	v_lshl_add_u64 v[36:37], v[34:35], 0, v[180:181]
	global_load_dwordx4 v[94:97], v[28:29], off
	global_load_dwordx4 v[100:103], v[36:37], off
	v_or_b32_e32 v28, 8, v26
	v_ashrrev_i32_e32 v29, 31, v28
	v_lshlrev_b64 v[182:183], 11, v[28:29]
	v_lshl_add_u64 v[28:29], v[32:33], 0, v[182:183]
	v_lshl_add_u64 v[36:37], v[34:35], 0, v[182:183]
	global_load_dwordx4 v[74:77], v[28:29], off
	global_load_dwordx4 v[86:89], v[36:37], off
	v_or_b32_e32 v28, 9, v26
	v_ashrrev_i32_e32 v29, 31, v28
	v_lshlrev_b64 v[176:177], 11, v[28:29]
	v_lshl_add_u64 v[28:29], v[32:33], 0, v[176:177]
	v_lshl_add_u64 v[36:37], v[34:35], 0, v[176:177]
	global_load_dwordx4 v[78:81], v[28:29], off
	global_load_dwordx4 v[82:85], v[36:37], off
	v_or_b32_e32 v28, 10, v26
	v_ashrrev_i32_e32 v29, 31, v28
	v_lshlrev_b64 v[178:179], 11, v[28:29]
	v_lshl_add_u64 v[28:29], v[32:33], 0, v[178:179]
	v_lshl_add_u64 v[36:37], v[34:35], 0, v[178:179]
	global_load_dwordx4 v[58:61], v[28:29], off
	global_load_dwordx4 v[70:73], v[36:37], off
	v_or_b32_e32 v28, 11, v26
	v_ashrrev_i32_e32 v29, 31, v28
	v_lshlrev_b64 v[168:169], 11, v[28:29]
	s_waitcnt vmcnt(0)
	v_lshlrev_b32_e32 v217, 16, v152
	v_mov_b32_e32 v196, v22
	v_mov_b32_e32 v197, v14
	v_lshl_add_u64 v[28:29], v[32:33], 0, v[168:169]
	v_and_b32_e32 v209, 0xffff0000, v152
	v_lshl_add_u64 v[36:37], v[34:35], 0, v[168:169]
	global_load_dwordx4 v[62:65], v[28:29], off
	global_load_dwordx4 v[66:69], v[36:37], off
	v_or_b32_e32 v28, 12, v26
	v_lshlrev_b32_e32 v207, 16, v153
	v_ashrrev_i32_e32 v29, 31, v28
	v_readlane_b32 s0, v253, 55
	v_lshlrev_b32_e32 v203, 16, v154
	v_and_b32_e32 v201, 0xffff0000, v154
	v_lshlrev_b32_e32 v199, 16, v155
	v_mov_b32_e32 v154, v9
	v_lshlrev_b32_e32 v216, 16, v164
	v_pk_mul_f32 v[218:219], v[196:197], v[216:217]
	v_and_b32_e32 v208, 0xffff0000, v164
	v_mov_b32_e32 v196, v23
	v_mov_b32_e32 v197, v15
	v_pk_mul_f32 v[226:227], v[196:197], v[208:209]
	v_lshlrev_b32_e32 v206, 16, v165
	v_mov_b32_e32 v196, v24
	v_mov_b32_e32 v197, v16
	v_pk_mul_f32 v[228:229], v[196:197], v[206:207]
	v_and_b32_e32 v197, 0xffff0000, v155
	v_and_b32_e32 v196, 0xffff0000, v167
	v_mov_b32_e32 v155, v5
	v_lshlrev_b32_e32 v238, 16, v136
	v_lshlrev_b64 v[170:171], 11, v[28:29]
	v_readlane_b32 s1, v253, 56
	v_pk_mul_f32 v[236:237], v[154:155], v[196:197]
	v_fma_f32 v154, v18, v238, v219
	v_lshl_add_u64 v[28:29], v[32:33], 0, v[170:171]
	v_lshl_add_u64 v[158:159], s[0:1], 0, v[98:99]
	v_lshlrev_b32_e32 v98, 16, v172
	v_and_b32_e32 v204, 0xffff0000, v165
	v_lshlrev_b32_e32 v202, 16, v166
	v_mov_b32_e32 v164, v6
	v_mov_b32_e32 v165, v2
	v_and_b32_e32 v200, 0xffff0000, v166
	v_lshlrev_b32_e32 v198, 16, v167
	v_lshlrev_b32_e32 v239, 16, v144
	v_add_f32_e32 v154, v218, v154
	v_mov_b32_e32 v166, v14
	v_mov_b32_e32 v167, v22
	v_lshl_add_u64 v[36:37], v[34:35], 0, v[170:171]
	global_load_dwordx4 v[42:45], v[28:29], off
	global_load_dwordx4 v[54:57], v[36:37], off
	v_or_b32_e32 v28, 13, v26
	v_pk_mul_f32 v[230:231], v[164:165], v[202:203]
	v_mov_b32_e32 v164, v7
	v_mov_b32_e32 v165, v3
	v_mul_f32_e32 v98, v154, v98
	v_pk_mul_f32 v[154:155], v[166:167], v[238:239]
	v_ashrrev_i32_e32 v29, 31, v28
	v_or_b32_e32 v26, 14, v26
	v_or_b32_e32 v30, 15, v30
	v_pk_mul_f32 v[232:233], v[164:165], v[200:201]
	v_mov_b32_e32 v164, v8
	v_mov_b32_e32 v165, v4
	v_fma_f32 v154, v18, v216, v154
; __device__ __forceinline__ unsigned pk2(float lo, float hi) { return pg8::cvt_pk_bf16(lo, hi); }
; __device__ __forceinline__ float bf_lo(unsigned w) { return __uint_as_float(w << 16); }
; __device__ __forceinline__ float bf_hi(unsigned w) { return __uint_as_float(w & 0xffff0000u); }
; __device__ __forceinline__ void conv_prep(const bf16* Z, const bf16* GB, const float* cw, bf16* A2, int vcu, int G, int tid) {
;     ...
;         for (int i = 0; i < 16; ++i) { zz[i] = *(const v4u*)(Z + (size_t)(rb + i) * DM + c8); gg[i] = *(const v4u*)(GB + (size_t)(rb + i) * DM + c8); }
; #pragma unroll
;         for (int i = 0; i < 16; ++i) { const v4u z2 = zz[i], gb = gg[i]; v4u o;
; #pragma unroll
;             for (int k = 0; k < 4; ++k) { const int e = 2 * k;
;                 const float a = bf_lo(gb[k]) * (w0[e >> 2][e & 3] * bf_lo(z0[k]) + w1[e >> 2][e & 3] * bf_lo(z1[k]) + w2[e >> 2][e & 3] * bf_lo(z2[k]));
;                 const float b = bf_hi(gb[k]) * (w0[(e + 1) >> 2][(e + 1) & 3] * bf_hi(z0[k]) + w1[(e + 1) >> 2][(e + 1) & 3] * bf_hi(z1[k]) + w2[(e + 1) >> 2][(e + 1) & 3] * bf_hi(z2[k]));
;                 o[k] = pk2(a, b); }
;             *(v4u*)(A2 + (size_t)(rb + i) * DM + c8) = o; z0 = z1; z1 = z2; }
	v_lshlrev_b64 v[160:161], 11, v[28:29]
	v_ashrrev_i32_e32 v27, 31, v26
	v_ashrrev_i32_e32 v31, 31, v30
	v_pk_mul_f32 v[234:235], v[164:165], v[198:199]
	v_lshlrev_b32_e32 v164, 16, v148
	v_add_f32_e32 v154, v154, v155
	v_and_b32_e32 v218, 0xffff0000, v136
	v_lshl_add_u64 v[28:29], v[32:33], 0, v[160:161]
	v_lshl_add_u64 v[36:37], v[34:35], 0, v[160:161]
	v_lshlrev_b64 v[162:163], 11, v[26:27]
	v_lshlrev_b64 v[156:157], 11, v[30:31]
	v_mul_f32_e32 v197, v154, v164
	v_and_b32_e32 v219, 0xffff0000, v144
	v_fma_f32 v136, v19, v218, v227
	v_mov_b32_e32 v164, v15
	v_mov_b32_e32 v165, v23
	global_load_dwordx4 v[46:49], v[28:29], off
	global_load_dwordx4 v[50:53], v[36:37], off
	v_lshl_add_u64 v[26:27], v[32:33], 0, v[162:163]
	v_lshl_add_u64 v[36:37], v[34:35], 0, v[162:163]
	v_lshl_add_u64 v[30:31], v[32:33], 0, v[156:157]
	v_lshl_add_u64 v[34:35], v[34:35], 0, v[156:157]
	v_and_b32_e32 v172, 0xffff0000, v172
	v_add_f32_e32 v136, v226, v136
	v_pk_mul_f32 v[154:155], v[164:165], v[218:219]
	global_load_dwordx4 v[26:29], v[26:27], off
	s_nop 0
	global_load_dwordx4 v[38:41], v[36:37], off
	s_nop 0
	global_load_dwordx4 v[30:33], v[30:31], off
	s_nop 0
	global_load_dwordx4 v[34:37], v[34:35], off
	v_mul_f32_e32 v136, v136, v172
	v_cvt_pk_bf16_f32 v172, v98, v136
	v_fma_f32 v98, v19, v208, v154
	v_and_b32_e32 v205, 0xffff0000, v153
	v_mov_b32_e32 v152, v25
	v_mov_b32_e32 v153, v17
	v_add_f32_e32 v98, v98, v155
	v_lshlrev_b32_e32 v226, 16, v137
	v_lshlrev_b32_e32 v227, 16, v145
	v_mov_b32_e32 v154, v16
	v_mov_b32_e32 v155, v24
	v_pk_mul_f32 v[152:153], v[152:153], v[204:205]
	v_lshlrev_b32_e32 v205, 16, v174
	v_and_b32_e32 v203, 0xffff0000, v174
	v_lshlrev_b32_e32 v201, 16, v175
	v_and_b32_e32 v199, 0xffff0000, v175
	v_and_b32_e32 v148, 0xffff0000, v148
	v_pk_mul_f32 v[174:175], v[154:155], v[226:227]
	v_mul_f32_e32 v98, v98, v148
	v_fma_f32 v144, v20, v226, v229
	v_fma_f32 v148, v20, v206, v174
	v_lshlrev_b32_e32 v136, 16, v149
	v_add_f32_e32 v144, v228, v144
	v_add_f32_e32 v148, v148, v175
	v_and_b32_e32 v228, 0xffff0000, v137
	v_mul_f32_e32 v207, v148, v136
	v_fma_f32 v136, v21, v228, v153
	v_lshlrev_b32_e32 v209, 16, v173
	v_and_b32_e32 v173, 0xffff0000, v173
	v_add_f32_e32 v136, v152, v136
	v_and_b32_e32 v229, 0xffff0000, v145
	v_mul_f32_e32 v136, v136, v173
	v_mov_b32_e32 v152, v17
	v_mov_b32_e32 v153, v25
	v_mul_f32_e32 v144, v144, v209
	v_cvt_pk_bf16_f32 v173, v144, v136
	v_pk_mul_f32 v[136:137], v[152:153], v[228:229]
	v_and_b32_e32 v148, 0xffff0000, v149
	v_fma_f32 v136, v21, v204, v136
	v_add_f32_e32 v136, v136, v137
	v_lshlrev_b32_e32 v240, 16, v138
	v_mul_f32_e32 v209, v136, v148
	v_fma_f32 v136, v10, v240, v231
	v_lshlrev_b32_e32 v241, 16, v146
	v_add_f32_e32 v136, v230, v136
	v_mov_b32_e32 v144, v2
	v_mov_b32_e32 v145, v6
	v_mul_f32_e32 v149, v136, v205
	v_pk_mul_f32 v[136:137], v[144:145], v[240:241]
	v_lshlrev_b32_e32 v148, 16, v150
	v_fma_f32 v136, v10, v202, v136
	v_add_f32_e32 v136, v136, v137
	v_and_b32_e32 v230, 0xffff0000, v138
	v_mul_f32_e32 v205, v136, v148
	v_fma_f32 v136, v11, v230, v233
	v_add_f32_e32 v136, v232, v136
	v_mul_f32_e32 v136, v136, v203
	v_and_b32_e32 v231, 0xffff0000, v146
	v_cvt_pk_bf16_f32 v174, v149, v136
	v_mov_b32_e32 v136, v3
	v_mov_b32_e32 v137, v7
	v_pk_mul_f32 v[148:149], v[136:137], v[230:231]
	v_lshlrev_b32_e32 v232, 16, v139
	v_fma_f32 v138, v11, v200, v148
	v_fma_f32 v148, v12, v232, v235
	v_and_b32_e32 v150, 0xffff0000, v150
	v_add_f32_e32 v138, v138, v149
	v_add_f32_e32 v148, v234, v148
	v_mul_f32_e32 v138, v138, v150
	v_lshlrev_b32_e32 v233, 16, v147
	v_mul_f32_e32 v150, v148, v201
	v_mov_b32_e32 v148, v4
	v_mov_b32_e32 v149, v8
	v_pk_mul_f32 v[234:235], v[148:149], v[232:233]
	v_lshlrev_b32_e32 v146, 16, v151
	v_fma_f32 v175, v12, v198, v234
	v_add_f32_e32 v175, v175, v235
	v_mul_f32_e32 v201, v175, v146
	v_and_b32_e32 v146, 0xffff0000, v139
	v_fma_f32 v139, v13, v146, v237
	v_add_f32_e32 v139, v236, v139
	v_lshl_add_u64 v[214:215], v[158:159], 0, v[214:215]
	v_mul_f32_e32 v139, v139, v199
	v_and_b32_e32 v147, 0xffff0000, v147
	v_cvt_pk_bf16_f32 v175, v150, v139
	global_store_dwordx4 v[214:215], v[172:175], off sc1
	v_mov_b32_e32 v139, v9
	v_and_b32_e32 v203, 0xffff0000, v151
	v_cvt_pk_bf16_f32 v172, v197, v98
	v_cvt_pk_bf16_f32 v173, v207, v209
	v_cvt_pk_bf16_f32 v174, v205, v138
	v_mov_b32_e32 v138, v5
	v_pk_mul_f32 v[150:151], v[138:139], v[146:147]
	v_and_b32_e32 v146, 0xffff0000, v140
	v_fma_f32 v98, v13, v196, v150
	v_add_f32_e32 v98, v98, v151
	v_lshl_add_u64 v[150:151], v[158:159], 0, v[192:193]
	v_mul_f32_e32 v98, v98, v203
	v_cvt_pk_bf16_f32 v175, v201, v98
	global_store_dwordx4 v[150:151], v[172:175], off sc1
	v_lshlrev_b32_e32 v98, 16, v140
	v_lshlrev_b32_e32 v197, 16, v141
	v_lshlrev_b32_e32 v172, 16, v124
	v_mov_b32_e32 v217, v172
	v_and_b32_e32 v199, 0xffff0000, v141
	v_pk_mul_f32 v[140:141], v[166:167], v[216:217]
	v_lshlrev_b32_e32 v173, 16, v128
	v_fma_f32 v140, v18, v239, v140
	v_add_f32_e32 v140, v140, v141
	v_mul_f32_e32 v98, v140, v98
	v_mov_b32_e32 v140, v18
	v_mov_b32_e32 v141, v22
	v_lshlrev_b32_e32 v201, 16, v142
	v_and_b32_e32 v214, 0xffff0000, v142
	v_lshlrev_b32_e32 v215, 16, v143
	v_and_b32_e32 v218, 0xffff0000, v143
	v_pk_mul_f32 v[142:143], v[140:141], v[172:173]
	v_lshlrev_b32_e32 v174, 16, v132
	v_fma_f32 v22, v14, v239, v142
	v_add_f32_e32 v22, v22, v143
	v_mul_f32_e32 v216, v22, v174
	v_and_b32_e32 v174, 0xffff0000, v124
	v_mov_b32_e32 v209, v174
	v_pk_mul_f32 v[142:143], v[164:165], v[208:209]
	v_and_b32_e32 v192, 0xffff0000, v132
	v_fma_f32 v22, v19, v219, v142
	v_add_f32_e32 v22, v22, v143
	v_mul_f32_e32 v22, v22, v146
	v_and_b32_e32 v175, 0xffff0000, v128
; __device__ __forceinline__ unsigned pk2(float lo, float hi) { return pg8::cvt_pk_bf16(lo, hi); }
; __device__ __forceinline__ float bf_lo(unsigned w) { return __uint_as_float(w << 16); }
; __device__ __forceinline__ float bf_hi(unsigned w) { return __uint_as_float(w & 0xffff0000u); }
; __device__ __forceinline__ void conv_prep(const bf16* Z, const bf16* GB, const float* cw, bf16* A2, int vcu, int G, int tid) {
;     ...
;         for (int i = 0; i < 16; ++i) { zz[i] = *(const v4u*)(Z + (size_t)(rb + i) * DM + c8); gg[i] = *(const v4u*)(GB + (size_t)(rb + i) * DM + c8); }
; #pragma unroll
;         for (int i = 0; i < 16; ++i) { const v4u z2 = zz[i], gb = gg[i]; v4u o;
; #pragma unroll
;             for (int k = 0; k < 4; ++k) { const int e = 2 * k;
;                 const float a = bf_lo(gb[k]) * (w0[e >> 2][e & 3] * bf_lo(z0[k]) + w1[e >> 2][e & 3] * bf_lo(z1[k]) + w2[e >> 2][e & 3] * bf_lo(z2[k]));
;                 const float b = bf_hi(gb[k]) * (w0[(e + 1) >> 2][(e + 1) & 3] * bf_hi(z0[k]) + w1[(e + 1) >> 2][(e + 1) & 3] * bf_hi(z1[k]) + w2[(e + 1) >> 2][(e + 1) & 3] * bf_hi(z2[k]));
;                 o[k] = pk2(a, b); }
;             *(v4u*)(A2 + (size_t)(rb + i) * DM + c8) = o; z0 = z1; z1 = z2; }
	v_cvt_pk_bf16_f32 v132, v98, v22
	v_mov_b32_e32 v22, v19
	v_pk_mul_f32 v[142:143], v[22:23], v[174:175]
	v_lshlrev_b32_e32 v193, 16, v129
	v_fma_f32 v98, v15, v219, v142
	v_add_f32_e32 v98, v98, v143
	v_mul_f32_e32 v98, v98, v192
	v_lshlrev_b32_e32 v192, 16, v125
	v_mov_b32_e32 v207, v192
	v_pk_mul_f32 v[142:143], v[154:155], v[206:207]
	v_lshl_add_u64 v[150:151], v[158:159], 0, v[194:195]
	v_fma_f32 v128, v20, v227, v142
	v_add_f32_e32 v128, v128, v143
	v_mov_b32_e32 v142, v20
	v_mov_b32_e32 v143, v24
	v_pk_mul_f32 v[194:195], v[142:143], v[192:193]
	v_lshlrev_b32_e32 v124, 16, v133
	v_fma_f32 v24, v16, v227, v194
	v_and_b32_e32 v194, 0xffff0000, v125
	v_add_f32_e32 v24, v24, v195
	v_mov_b32_e32 v205, v194
	v_mul_f32_e32 v146, v24, v124
	v_pk_mul_f32 v[124:125], v[152:153], v[204:205]
	v_mul_f32_e32 v128, v128, v197
	v_fma_f32 v24, v21, v229, v124
	v_add_f32_e32 v24, v24, v125
	v_mul_f32_e32 v24, v24, v199
	v_and_b32_e32 v197, 0xffff0000, v133
	v_and_b32_e32 v195, 0xffff0000, v129
	v_cvt_pk_bf16_f32 v133, v128, v24
	v_mov_b32_e32 v24, v21
	v_pk_mul_f32 v[124:125], v[24:25], v[194:195]
	v_lshlrev_b32_e32 v204, 16, v126
	v_fma_f32 v124, v17, v229, v124
	v_add_f32_e32 v124, v124, v125
	v_mov_b32_e32 v203, v204
	v_mul_f32_e32 v206, v124, v197
	v_pk_mul_f32 v[124:125], v[144:145], v[202:203]
	v_lshlrev_b32_e32 v205, 16, v130
	v_fma_f32 v124, v10, v241, v124
	v_add_f32_e32 v124, v124, v125
	v_mul_f32_e32 v199, v124, v201
	v_mov_b32_e32 v124, v10
	v_mov_b32_e32 v125, v6
	v_pk_mul_f32 v[128:129], v[124:125], v[204:205]
	v_and_b32_e32 v202, 0xffff0000, v126
	v_fma_f32 v6, v2, v241, v128
	v_mov_b32_e32 v201, v202
	v_lshlrev_b32_e32 v197, 16, v134
	v_add_f32_e32 v6, v6, v129
	v_pk_mul_f32 v[128:129], v[136:137], v[200:201]
	v_mul_f32_e32 v207, v6, v197
	v_fma_f32 v6, v11, v231, v128
	v_add_f32_e32 v6, v6, v129
	v_mul_f32_e32 v6, v6, v214
	v_and_b32_e32 v197, 0xffff0000, v134
	v_and_b32_e32 v203, 0xffff0000, v130
	v_cvt_pk_bf16_f32 v134, v199, v6
	v_mov_b32_e32 v6, v11
	v_pk_mul_f32 v[128:129], v[6:7], v[202:203]
	v_lshlrev_b32_e32 v200, 16, v127
	v_fma_f32 v126, v3, v231, v128
	v_mov_b32_e32 v199, v200
	v_add_f32_e32 v126, v126, v129
	v_pk_mul_f32 v[128:129], v[148:149], v[198:199]
	v_lshlrev_b32_e32 v201, 16, v131
	v_fma_f32 v128, v12, v233, v128
	v_add_f32_e32 v128, v128, v129
	v_mul_f32_e32 v130, v128, v215
	v_mov_b32_e32 v128, v12
	v_mov_b32_e32 v129, v8
	v_pk_mul_f32 v[198:199], v[128:129], v[200:201]
	v_mul_f32_e32 v208, v126, v197
	v_fma_f32 v8, v4, v233, v198
	v_and_b32_e32 v198, 0xffff0000, v127
	v_lshlrev_b32_e32 v126, 16, v135
	v_add_f32_e32 v8, v8, v199
	v_mov_b32_e32 v197, v198
	v_mul_f32_e32 v209, v8, v126
	v_pk_mul_f32 v[126:127], v[138:139], v[196:197]
	v_and_b32_e32 v214, 0xffff0000, v135
	v_fma_f32 v8, v13, v147, v126
	v_add_f32_e32 v8, v8, v127
	v_mul_f32_e32 v8, v8, v218
	v_and_b32_e32 v199, 0xffff0000, v131
	v_cvt_pk_bf16_f32 v135, v130, v8
	v_mov_b32_e32 v8, v13
	v_pk_mul_f32 v[126:127], v[8:9], v[198:199]
	global_store_dwordx4 v[150:151], v[132:135], off sc1
	v_cvt_pk_bf16_f32 v130, v216, v98
	v_fma_f32 v98, v5, v147, v126
	v_cvt_pk_bf16_f32 v131, v146, v206
	v_add_f32_e32 v98, v98, v127
	v_lshl_add_u64 v[126:127], v[158:159], 0, v[188:189]
	v_lshlrev_b32_e32 v146, 16, v122
	v_and_b32_e32 v147, 0xffff0000, v122
	v_lshlrev_b32_e32 v122, 16, v108
	v_cvt_pk_bf16_f32 v132, v207, v208
	v_mul_f32_e32 v98, v98, v214
	v_cvt_pk_bf16_f32 v133, v209, v98
	global_store_dwordx4 v[126:127], v[130:133], off sc1
	v_mov_b32_e32 v126, v172
	v_mov_b32_e32 v127, v122
	v_pk_mul_f32 v[126:127], v[166:167], v[126:127]
	v_lshlrev_b32_e32 v98, 16, v120
	v_fma_f32 v126, v18, v173, v126
	v_lshlrev_b32_e32 v150, 16, v123
	v_and_b32_e32 v151, 0xffff0000, v123
	v_lshlrev_b32_e32 v123, 16, v112
	v_add_f32_e32 v126, v126, v127
	v_mul_f32_e32 v98, v126, v98
	v_pk_mul_f32 v[126:127], v[140:141], v[122:123]
	v_lshlrev_b32_e32 v130, 16, v116
	v_fma_f32 v126, v14, v173, v126
	v_add_f32_e32 v126, v126, v127
	v_mul_f32_e32 v172, v126, v130
	v_and_b32_e32 v126, 0xffff0000, v108
	v_mov_b32_e32 v130, v174
	v_mov_b32_e32 v131, v126
	v_pk_mul_f32 v[130:131], v[164:165], v[130:131]
	v_and_b32_e32 v132, 0xffff0000, v120
	v_fma_f32 v108, v19, v175, v130
	v_and_b32_e32 v127, 0xffff0000, v112
	v_add_f32_e32 v108, v108, v131
	v_mul_f32_e32 v108, v108, v132
	v_pk_mul_f32 v[130:131], v[22:23], v[126:127]
	v_cvt_pk_bf16_f32 v108, v98, v108
	v_mov_b32_e32 v132, v192
	v_fma_f32 v98, v15, v175, v130
	v_lshlrev_b32_e32 v130, 16, v109
	v_mov_b32_e32 v133, v130
	v_and_b32_e32 v116, 0xffff0000, v116
	v_add_f32_e32 v98, v98, v131
	v_pk_mul_f32 v[132:133], v[154:155], v[132:133]
	v_mul_f32_e32 v98, v98, v116
	v_lshlrev_b32_e32 v131, 16, v113
	v_fma_f32 v116, v20, v193, v132
	v_lshlrev_b32_e32 v134, 16, v121
	v_add_f32_e32 v116, v116, v133
	v_pk_mul_f32 v[132:133], v[142:143], v[130:131]
	v_mul_f32_e32 v134, v116, v134
	v_fma_f32 v116, v16, v193, v132
	v_lshlrev_b32_e32 v112, 16, v117
	v_add_f32_e32 v116, v116, v133
	v_mul_f32_e32 v173, v116, v112
	v_and_b32_e32 v112, 0xffff0000, v109
	v_and_b32_e32 v132, 0xffff0000, v117
	v_mov_b32_e32 v116, v194
	v_mov_b32_e32 v117, v112
	v_pk_mul_f32 v[116:117], v[152:153], v[116:117]
	v_and_b32_e32 v113, 0xffff0000, v113
	v_fma_f32 v109, v21, v195, v116
	v_add_f32_e32 v109, v109, v117
	v_pk_mul_f32 v[116:117], v[24:25], v[112:113]
	v_and_b32_e32 v135, 0xffff0000, v121
	v_fma_f32 v116, v17, v195, v116
	v_add_f32_e32 v116, v116, v117
	v_mul_f32_e32 v174, v116, v132
	v_lshlrev_b32_e32 v116, 16, v110
	v_mov_b32_e32 v132, v204
	v_mov_b32_e32 v133, v116
	v_pk_mul_f32 v[132:133], v[144:145], v[132:133]
	v_lshlrev_b32_e32 v117, 16, v114
; __device__ __forceinline__ unsigned pk2(float lo, float hi) { return pg8::cvt_pk_bf16(lo, hi); }
; __device__ __forceinline__ float bf_lo(unsigned w) { return __uint_as_float(w << 16); }
; __device__ __forceinline__ float bf_hi(unsigned w) { return __uint_as_float(w & 0xffff0000u); }
; __device__ __forceinline__ void conv_prep(const bf16* Z, const bf16* GB, const float* cw, bf16* A2, int vcu, int G, int tid) {
;     ...
;         for (int i = 0; i < 16; ++i) { zz[i] = *(const v4u*)(Z + (size_t)(rb + i) * DM + c8); gg[i] = *(const v4u*)(GB + (size_t)(rb + i) * DM + c8); }
; #pragma unroll
;         for (int i = 0; i < 16; ++i) { const v4u z2 = zz[i], gb = gg[i]; v4u o;
; #pragma unroll
;             for (int k = 0; k < 4; ++k) { const int e = 2 * k;
;                 const float a = bf_lo(gb[k]) * (w0[e >> 2][e & 3] * bf_lo(z0[k]) + w1[e >> 2][e & 3] * bf_lo(z1[k]) + w2[e >> 2][e & 3] * bf_lo(z2[k]));
;                 const float b = bf_hi(gb[k]) * (w0[(e + 1) >> 2][(e + 1) & 3] * bf_hi(z0[k]) + w1[(e + 1) >> 2][(e + 1) & 3] * bf_hi(z1[k]) + w2[(e + 1) >> 2][(e + 1) & 3] * bf_hi(z2[k]));
;                 o[k] = pk2(a, b); }
;             *(v4u*)(A2 + (size_t)(rb + i) * DM + c8) = o; z0 = z1; z1 = z2; }
	v_fma_f32 v132, v10, v205, v132
	v_add_f32_e32 v132, v132, v133
	v_mul_f32_e32 v146, v132, v146
	v_pk_mul_f32 v[132:133], v[124:125], v[116:117]
	v_mul_f32_e32 v109, v109, v135
	v_fma_f32 v132, v2, v205, v132
	v_cvt_pk_bf16_f32 v109, v134, v109
	v_lshlrev_b32_e32 v134, 16, v118
	v_add_f32_e32 v132, v132, v133
	v_mul_f32_e32 v175, v132, v134
	v_and_b32_e32 v132, 0xffff0000, v110
	v_mov_b32_e32 v134, v202
	v_mov_b32_e32 v135, v132
	v_pk_mul_f32 v[134:135], v[136:137], v[134:135]
	v_and_b32_e32 v133, 0xffff0000, v114
	v_fma_f32 v110, v11, v203, v134
	v_add_f32_e32 v110, v110, v135
	v_pk_mul_f32 v[134:135], v[6:7], v[132:133]
	v_mul_f32_e32 v110, v110, v147
	v_fma_f32 v114, v3, v203, v134
	v_lshlrev_b32_e32 v134, 16, v111
	v_cvt_pk_bf16_f32 v110, v146, v110
	v_mov_b32_e32 v146, v200
	v_mov_b32_e32 v147, v134
	v_and_b32_e32 v118, 0xffff0000, v118
	v_add_f32_e32 v114, v114, v135
	v_pk_mul_f32 v[146:147], v[148:149], v[146:147]
	v_mul_f32_e32 v188, v114, v118
	v_lshlrev_b32_e32 v135, 16, v115
	v_fma_f32 v118, v12, v201, v146
	v_add_f32_e32 v118, v118, v147
	v_pk_mul_f32 v[146:147], v[128:129], v[134:135]
	v_mul_f32_e32 v150, v118, v150
	v_fma_f32 v118, v4, v201, v146
	v_lshlrev_b32_e32 v114, 16, v119
	v_add_f32_e32 v118, v118, v147
	v_mul_f32_e32 v146, v118, v114
	v_and_b32_e32 v114, 0xffff0000, v111
	v_and_b32_e32 v147, 0xffff0000, v119
	v_mov_b32_e32 v118, v198
	v_mov_b32_e32 v119, v114
	v_pk_mul_f32 v[118:119], v[138:139], v[118:119]
	v_and_b32_e32 v115, 0xffff0000, v115
	v_fma_f32 v111, v13, v199, v118
	v_add_f32_e32 v111, v111, v119
	v_lshl_add_u64 v[120:121], v[158:159], 0, v[190:191]
	v_mul_f32_e32 v111, v111, v151
	v_pk_mul_f32 v[118:119], v[8:9], v[114:115]
	v_cvt_pk_bf16_f32 v111, v150, v111
	global_store_dwordx4 v[120:121], v[108:111], off sc1
	v_lshlrev_b32_e32 v150, 16, v107
	v_and_b32_e32 v151, 0xffff0000, v107
	v_cvt_pk_bf16_f32 v108, v172, v98
	v_fma_f32 v98, v5, v199, v118
	v_add_f32_e32 v98, v98, v119
	v_cvt_pk_bf16_f32 v109, v173, v174
	v_cvt_pk_bf16_f32 v110, v175, v188
	v_mul_f32_e32 v98, v98, v147
	v_cvt_pk_bf16_f32 v111, v146, v98
	v_lshl_add_u64 v[118:119], v[158:159], 0, v[184:185]
	v_lshlrev_b32_e32 v146, 16, v106
	v_and_b32_e32 v147, 0xffff0000, v106
	v_lshlrev_b32_e32 v106, 16, v90
	global_store_dwordx4 v[118:119], v[108:111], off sc1
	v_lshlrev_b32_e32 v98, 16, v104
	v_lshlrev_b32_e32 v107, 16, v94
	v_mov_b32_e32 v108, v122
	v_mov_b32_e32 v109, v106
	v_pk_mul_f32 v[108:109], v[166:167], v[108:109]
	v_lshlrev_b32_e32 v110, 16, v100
	v_fma_f32 v108, v18, v123, v108
	v_add_f32_e32 v108, v108, v109
	v_mul_f32_e32 v98, v108, v98
	v_pk_mul_f32 v[108:109], v[140:141], v[106:107]
	v_and_b32_e32 v118, 0xffff0000, v104
	v_fma_f32 v108, v14, v123, v108
	v_add_f32_e32 v108, v108, v109
	v_mul_f32_e32 v122, v108, v110
	v_and_b32_e32 v108, 0xffff0000, v90
	v_mov_b32_e32 v110, v126
	v_mov_b32_e32 v111, v108
	v_pk_mul_f32 v[110:111], v[164:165], v[110:111]
	v_and_b32_e32 v109, 0xffff0000, v94
	v_fma_f32 v90, v19, v127, v110
	v_add_f32_e32 v90, v90, v111
	v_pk_mul_f32 v[110:111], v[22:23], v[108:109]
	v_mul_f32_e32 v90, v90, v118
	v_fma_f32 v94, v15, v127, v110
	v_lshlrev_b32_e32 v110, 16, v91
	v_mov_b32_e32 v118, v130
	v_mov_b32_e32 v119, v110
	v_and_b32_e32 v100, 0xffff0000, v100
	v_add_f32_e32 v94, v94, v111
	v_pk_mul_f32 v[118:119], v[154:155], v[118:119]
	v_cvt_pk_bf16_f32 v90, v98, v90
	v_mul_f32_e32 v98, v94, v100
	v_lshlrev_b32_e32 v111, 16, v95
	v_fma_f32 v100, v20, v131, v118
	v_lshlrev_b32_e32 v120, 16, v105
	v_add_f32_e32 v100, v100, v119
	v_pk_mul_f32 v[118:119], v[142:143], v[110:111]
	v_mul_f32_e32 v120, v100, v120
	v_fma_f32 v100, v16, v131, v118
	v_lshlrev_b32_e32 v94, 16, v101
	v_add_f32_e32 v100, v100, v119
	v_mul_f32_e32 v123, v100, v94
	v_and_b32_e32 v94, 0xffff0000, v91
	v_and_b32_e32 v118, 0xffff0000, v101
	v_mov_b32_e32 v100, v112
	v_mov_b32_e32 v101, v94
	v_pk_mul_f32 v[100:101], v[152:153], v[100:101]
	v_and_b32_e32 v95, 0xffff0000, v95
	v_fma_f32 v91, v21, v113, v100
	v_add_f32_e32 v91, v91, v101
	v_pk_mul_f32 v[100:101], v[24:25], v[94:95]
	v_and_b32_e32 v121, 0xffff0000, v105
	v_fma_f32 v100, v17, v113, v100
	v_mul_f32_e32 v91, v91, v121
	v_add_f32_e32 v100, v100, v101
	v_cvt_pk_bf16_f32 v91, v120, v91
	v_mul_f32_e32 v120, v100, v118
	v_lshlrev_b32_e32 v100, 16, v92
	v_mov_b32_e32 v112, v116
	v_mov_b32_e32 v113, v100
	v_pk_mul_f32 v[112:113], v[144:145], v[112:113]
	v_lshlrev_b32_e32 v101, 16, v96
	v_fma_f32 v112, v10, v117, v112
	v_add_f32_e32 v112, v112, v113
	v_mul_f32_e32 v119, v112, v146
	v_pk_mul_f32 v[112:113], v[124:125], v[100:101]
	v_lshlrev_b32_e32 v118, 16, v102
	v_fma_f32 v112, v2, v117, v112
	v_add_f32_e32 v112, v112, v113
	v_mul_f32_e32 v121, v112, v118
	v_and_b32_e32 v112, 0xffff0000, v92
	v_mov_b32_e32 v116, v132
	v_mov_b32_e32 v117, v112
	v_pk_mul_f32 v[116:117], v[136:137], v[116:117]
	v_and_b32_e32 v113, 0xffff0000, v96
	v_fma_f32 v92, v11, v133, v116
	v_add_f32_e32 v92, v92, v117
	v_pk_mul_f32 v[116:117], v[6:7], v[112:113]
	v_mul_f32_e32 v92, v92, v147
	v_fma_f32 v96, v3, v133, v116
	v_lshlrev_b32_e32 v116, 16, v93
	v_cvt_pk_bf16_f32 v92, v119, v92
	v_mov_b32_e32 v118, v134
	v_mov_b32_e32 v119, v116
	v_and_b32_e32 v102, 0xffff0000, v102
	v_add_f32_e32 v96, v96, v117
	v_pk_mul_f32 v[118:119], v[148:149], v[118:119]
	v_mul_f32_e32 v126, v96, v102
	v_lshlrev_b32_e32 v117, 16, v97
	v_fma_f32 v102, v12, v135, v118
	v_add_f32_e32 v102, v102, v119
	v_pk_mul_f32 v[118:119], v[128:129], v[116:117]
	v_mul_f32_e32 v127, v102, v150
	v_fma_f32 v102, v4, v135, v118
	v_lshlrev_b32_e32 v96, 16, v103
	v_add_f32_e32 v102, v102, v119
	v_mul_f32_e32 v118, v102, v96
	v_and_b32_e32 v96, 0xffff0000, v93
; __device__ __forceinline__ unsigned pk2(float lo, float hi) { return pg8::cvt_pk_bf16(lo, hi); }
; __device__ __forceinline__ float bf_lo(unsigned w) { return __uint_as_float(w << 16); }
; __device__ __forceinline__ float bf_hi(unsigned w) { return __uint_as_float(w & 0xffff0000u); }
; __device__ __forceinline__ void conv_prep(const bf16* Z, const bf16* GB, const float* cw, bf16* A2, int vcu, int G, int tid) {
;     ...
;         for (int i = 0; i < 16; ++i) { zz[i] = *(const v4u*)(Z + (size_t)(rb + i) * DM + c8); gg[i] = *(const v4u*)(GB + (size_t)(rb + i) * DM + c8); }
; #pragma unroll
;         for (int i = 0; i < 16; ++i) { const v4u z2 = zz[i], gb = gg[i]; v4u o;
; #pragma unroll
;             for (int k = 0; k < 4; ++k) { const int e = 2 * k;
;                 const float a = bf_lo(gb[k]) * (w0[e >> 2][e & 3] * bf_lo(z0[k]) + w1[e >> 2][e & 3] * bf_lo(z1[k]) + w2[e >> 2][e & 3] * bf_lo(z2[k]));
;                 const float b = bf_hi(gb[k]) * (w0[(e + 1) >> 2][(e + 1) & 3] * bf_hi(z0[k]) + w1[(e + 1) >> 2][(e + 1) & 3] * bf_hi(z1[k]) + w2[(e + 1) >> 2][(e + 1) & 3] * bf_hi(z2[k]));
;                 o[k] = pk2(a, b); }
;             *(v4u*)(A2 + (size_t)(rb + i) * DM + c8) = o; z0 = z1; z1 = z2; }
	v_and_b32_e32 v119, 0xffff0000, v103
	v_mov_b32_e32 v102, v114
	v_mov_b32_e32 v103, v96
	v_pk_mul_f32 v[102:103], v[138:139], v[102:103]
	v_and_b32_e32 v97, 0xffff0000, v97
	v_fma_f32 v93, v13, v115, v102
	v_add_f32_e32 v93, v93, v103
	v_mul_f32_e32 v93, v93, v151
	v_lshl_add_u64 v[104:105], v[158:159], 0, v[186:187]
	v_cvt_pk_bf16_f32 v93, v127, v93
	v_pk_mul_f32 v[102:103], v[8:9], v[96:97]
	global_store_dwordx4 v[104:105], v[90:93], off sc1
	v_lshlrev_b32_e32 v114, 16, v88
	v_lshlrev_b32_e32 v104, 16, v87
	v_fma_f32 v93, v5, v115, v102
	v_add_f32_e32 v93, v93, v103
	v_cvt_pk_bf16_f32 v90, v122, v98
	v_cvt_pk_bf16_f32 v91, v123, v120
	v_mul_f32_e32 v93, v93, v119
	v_lshl_add_u64 v[102:103], v[158:159], 0, v[180:181]
	v_and_b32_e32 v115, 0xffff0000, v88
	v_lshlrev_b32_e32 v88, 16, v74
	v_cvt_pk_bf16_f32 v92, v121, v126
	v_cvt_pk_bf16_f32 v93, v118, v93
	global_store_dwordx4 v[102:103], v[90:93], off sc1
	v_lshlrev_b32_e32 v118, 16, v89
	v_and_b32_e32 v119, 0xffff0000, v89
	v_mov_b32_e32 v90, v106
	v_mov_b32_e32 v91, v88
	v_pk_mul_f32 v[90:91], v[166:167], v[90:91]
	v_lshlrev_b32_e32 v92, 16, v86
	v_fma_f32 v90, v18, v107, v90
	v_lshlrev_b32_e32 v89, 16, v78
	v_add_f32_e32 v90, v90, v91
	v_mul_f32_e32 v102, v90, v92
	v_pk_mul_f32 v[90:91], v[140:141], v[88:89]
	v_lshlrev_b32_e32 v93, 16, v82
	v_fma_f32 v90, v14, v107, v90
	v_add_f32_e32 v90, v90, v91
	v_mul_f32_e32 v106, v90, v93
	v_and_b32_e32 v90, 0xffff0000, v74
	v_mov_b32_e32 v92, v108
	v_mov_b32_e32 v93, v90
	v_pk_mul_f32 v[92:93], v[164:165], v[92:93]
	v_and_b32_e32 v91, 0xffff0000, v78
	v_fma_f32 v74, v19, v109, v92
	v_and_b32_e32 v98, 0xffff0000, v86
	v_add_f32_e32 v74, v74, v93
	v_pk_mul_f32 v[92:93], v[22:23], v[90:91]
	v_mul_f32_e32 v74, v74, v98
	v_fma_f32 v78, v15, v109, v92
	v_lshlrev_b32_e32 v92, 16, v75
	v_cvt_pk_bf16_f32 v74, v102, v74
	v_mov_b32_e32 v102, v110
	v_mov_b32_e32 v103, v92
	v_and_b32_e32 v82, 0xffff0000, v82
	v_add_f32_e32 v78, v78, v93
	v_pk_mul_f32 v[102:103], v[154:155], v[102:103]
	v_mul_f32_e32 v98, v78, v82
	v_lshlrev_b32_e32 v93, 16, v79
	v_fma_f32 v82, v20, v111, v102
	v_add_f32_e32 v82, v82, v103
	v_pk_mul_f32 v[102:103], v[142:143], v[92:93]
	v_mul_f32_e32 v104, v82, v104
	v_fma_f32 v82, v16, v111, v102
	v_lshlrev_b32_e32 v78, 16, v83
	v_add_f32_e32 v82, v82, v103
	v_mul_f32_e32 v107, v82, v78
	v_and_b32_e32 v78, 0xffff0000, v75
	v_and_b32_e32 v102, 0xffff0000, v83
	v_mov_b32_e32 v82, v94
	v_mov_b32_e32 v83, v78
	v_pk_mul_f32 v[82:83], v[152:153], v[82:83]
	v_and_b32_e32 v79, 0xffff0000, v79
	v_fma_f32 v75, v21, v95, v82
	v_add_f32_e32 v75, v75, v83
	v_pk_mul_f32 v[82:83], v[24:25], v[78:79]
	v_and_b32_e32 v105, 0xffff0000, v87
	v_fma_f32 v82, v17, v95, v82
	v_mul_f32_e32 v75, v75, v105
	v_add_f32_e32 v82, v82, v83
	v_cvt_pk_bf16_f32 v75, v104, v75
	v_mul_f32_e32 v104, v82, v102
	v_lshlrev_b32_e32 v82, 16, v76
	v_mov_b32_e32 v94, v100
	v_mov_b32_e32 v95, v82
	v_pk_mul_f32 v[94:95], v[144:145], v[94:95]
	v_lshlrev_b32_e32 v83, 16, v80
	v_fma_f32 v94, v10, v101, v94
	v_add_f32_e32 v94, v94, v95
	v_mul_f32_e32 v103, v94, v114
	v_pk_mul_f32 v[94:95], v[124:125], v[82:83]
	v_lshlrev_b32_e32 v102, 16, v84
	v_fma_f32 v94, v2, v101, v94
	v_add_f32_e32 v94, v94, v95
	v_mul_f32_e32 v105, v94, v102
	v_and_b32_e32 v94, 0xffff0000, v76
	v_mov_b32_e32 v100, v112
	v_mov_b32_e32 v101, v94
	v_pk_mul_f32 v[100:101], v[136:137], v[100:101]
	v_and_b32_e32 v95, 0xffff0000, v80
	v_fma_f32 v76, v11, v113, v100
	v_add_f32_e32 v76, v76, v101
	v_pk_mul_f32 v[100:101], v[6:7], v[94:95]
	v_mul_f32_e32 v76, v76, v115
	v_fma_f32 v80, v3, v113, v100
	v_lshlrev_b32_e32 v100, 16, v77
	v_cvt_pk_bf16_f32 v76, v103, v76
	v_mov_b32_e32 v102, v116
	v_mov_b32_e32 v103, v100
	v_and_b32_e32 v84, 0xffff0000, v84
	v_add_f32_e32 v80, v80, v101
	v_pk_mul_f32 v[102:103], v[148:149], v[102:103]
	v_mul_f32_e32 v108, v80, v84
	v_lshlrev_b32_e32 v101, 16, v81
	v_fma_f32 v84, v12, v117, v102
	v_add_f32_e32 v84, v84, v103
	v_pk_mul_f32 v[102:103], v[128:129], v[100:101]
	v_mul_f32_e32 v109, v84, v118
	v_fma_f32 v84, v4, v117, v102
	v_lshlrev_b32_e32 v80, 16, v85
	v_add_f32_e32 v84, v84, v103
	v_mul_f32_e32 v102, v84, v80
	v_and_b32_e32 v80, 0xffff0000, v77
	v_and_b32_e32 v103, 0xffff0000, v85
	v_mov_b32_e32 v84, v96
	v_mov_b32_e32 v85, v80
	v_pk_mul_f32 v[84:85], v[138:139], v[84:85]
	v_and_b32_e32 v81, 0xffff0000, v81
	v_fma_f32 v77, v13, v97, v84
	v_add_f32_e32 v77, v77, v85
	v_mul_f32_e32 v77, v77, v119
	v_lshl_add_u64 v[86:87], v[158:159], 0, v[182:183]
	v_cvt_pk_bf16_f32 v77, v109, v77
	v_pk_mul_f32 v[84:85], v[8:9], v[80:81]
	global_store_dwordx4 v[86:87], v[74:77], off sc1
	v_lshlrev_b32_e32 v96, 16, v72
	v_lshlrev_b32_e32 v86, 16, v71
	v_fma_f32 v77, v5, v97, v84
	v_add_f32_e32 v77, v77, v85
	v_cvt_pk_bf16_f32 v74, v106, v98
	v_cvt_pk_bf16_f32 v75, v107, v104
	v_mul_f32_e32 v77, v77, v103
	v_lshl_add_u64 v[84:85], v[158:159], 0, v[176:177]
	v_and_b32_e32 v97, 0xffff0000, v72
	v_lshlrev_b32_e32 v72, 16, v58
	v_cvt_pk_bf16_f32 v76, v105, v108
	v_cvt_pk_bf16_f32 v77, v102, v77
	global_store_dwordx4 v[84:85], v[74:77], off sc1
	v_lshlrev_b32_e32 v98, 16, v73
	v_and_b32_e32 v102, 0xffff0000, v73
	v_mov_b32_e32 v74, v88
	v_mov_b32_e32 v75, v72
	v_pk_mul_f32 v[74:75], v[166:167], v[74:75]
	v_lshlrev_b32_e32 v76, 16, v70
	v_fma_f32 v74, v18, v89, v74
	s_waitcnt vmcnt(19)
	v_lshlrev_b32_e32 v73, 16, v62
	v_add_f32_e32 v74, v74, v75
	v_mul_f32_e32 v85, v74, v76
	v_pk_mul_f32 v[74:75], v[140:141], v[72:73]
	s_waitcnt vmcnt(18)
; __device__ __forceinline__ unsigned pk2(float lo, float hi) { return pg8::cvt_pk_bf16(lo, hi); }
; __device__ __forceinline__ float bf_lo(unsigned w) { return __uint_as_float(w << 16); }
; __device__ __forceinline__ float bf_hi(unsigned w) { return __uint_as_float(w & 0xffff0000u); }
; __device__ __forceinline__ void conv_prep(const bf16* Z, const bf16* GB, const float* cw, bf16* A2, int vcu, int G, int tid) {
;     ...
;         for (int i = 0; i < 16; ++i) { zz[i] = *(const v4u*)(Z + (size_t)(rb + i) * DM + c8); gg[i] = *(const v4u*)(GB + (size_t)(rb + i) * DM + c8); }
; #pragma unroll
;         for (int i = 0; i < 16; ++i) { const v4u z2 = zz[i], gb = gg[i]; v4u o;
; #pragma unroll
;             for (int k = 0; k < 4; ++k) { const int e = 2 * k;
;                 const float a = bf_lo(gb[k]) * (w0[e >> 2][e & 3] * bf_lo(z0[k]) + w1[e >> 2][e & 3] * bf_lo(z1[k]) + w2[e >> 2][e & 3] * bf_lo(z2[k]));
;                 const float b = bf_hi(gb[k]) * (w0[(e + 1) >> 2][(e + 1) & 3] * bf_hi(z0[k]) + w1[(e + 1) >> 2][(e + 1) & 3] * bf_hi(z1[k]) + w2[(e + 1) >> 2][(e + 1) & 3] * bf_hi(z2[k]));
;                 o[k] = pk2(a, b); }
;             *(v4u*)(A2 + (size_t)(rb + i) * DM + c8) = o; z0 = z1; z1 = z2; }
	v_lshlrev_b32_e32 v77, 16, v66
	v_fma_f32 v74, v14, v89, v74
	v_add_f32_e32 v74, v74, v75
	v_mul_f32_e32 v88, v74, v77
	v_and_b32_e32 v74, 0xffff0000, v58
	v_mov_b32_e32 v76, v90
	v_mov_b32_e32 v77, v74
	v_pk_mul_f32 v[76:77], v[164:165], v[76:77]
	v_and_b32_e32 v75, 0xffff0000, v62
	v_fma_f32 v58, v19, v91, v76
	v_and_b32_e32 v84, 0xffff0000, v70
	v_add_f32_e32 v58, v58, v77
	v_pk_mul_f32 v[76:77], v[22:23], v[74:75]
	v_mul_f32_e32 v58, v58, v84
	v_fma_f32 v62, v15, v91, v76
	v_lshlrev_b32_e32 v76, 16, v59
	v_cvt_pk_bf16_f32 v58, v85, v58
	v_mov_b32_e32 v84, v92
	v_mov_b32_e32 v85, v76
	v_and_b32_e32 v66, 0xffff0000, v66
	v_add_f32_e32 v62, v62, v77
	v_pk_mul_f32 v[84:85], v[154:155], v[84:85]
	v_mul_f32_e32 v89, v62, v66
	v_lshlrev_b32_e32 v77, 16, v63
	v_fma_f32 v66, v20, v93, v84
	v_add_f32_e32 v66, v66, v85
	v_pk_mul_f32 v[84:85], v[142:143], v[76:77]
	v_mul_f32_e32 v86, v66, v86
	v_fma_f32 v66, v16, v93, v84
	v_lshlrev_b32_e32 v62, 16, v67
	v_add_f32_e32 v66, v66, v85
	v_mul_f32_e32 v90, v66, v62
	v_and_b32_e32 v62, 0xffff0000, v59
	v_and_b32_e32 v84, 0xffff0000, v67
	v_mov_b32_e32 v66, v78
	v_mov_b32_e32 v67, v62
	v_pk_mul_f32 v[66:67], v[152:153], v[66:67]
	v_and_b32_e32 v63, 0xffff0000, v63
	v_fma_f32 v59, v21, v79, v66
	v_add_f32_e32 v59, v59, v67
	v_pk_mul_f32 v[66:67], v[24:25], v[62:63]
	v_and_b32_e32 v87, 0xffff0000, v71
	v_fma_f32 v66, v17, v79, v66
	v_mul_f32_e32 v59, v59, v87
	v_add_f32_e32 v66, v66, v67
	v_cvt_pk_bf16_f32 v59, v86, v59
	v_mul_f32_e32 v86, v66, v84
	v_lshlrev_b32_e32 v66, 16, v60
	v_mov_b32_e32 v78, v82
	v_mov_b32_e32 v79, v66
	v_pk_mul_f32 v[78:79], v[144:145], v[78:79]
	v_lshlrev_b32_e32 v67, 16, v64
	v_fma_f32 v78, v10, v83, v78
	v_add_f32_e32 v78, v78, v79
	v_mul_f32_e32 v85, v78, v96
	v_pk_mul_f32 v[78:79], v[124:125], v[66:67]
	v_lshlrev_b32_e32 v84, 16, v68
	v_fma_f32 v78, v2, v83, v78
	v_add_f32_e32 v78, v78, v79
	v_mul_f32_e32 v87, v78, v84
	v_and_b32_e32 v78, 0xffff0000, v60
	v_mov_b32_e32 v82, v94
	v_mov_b32_e32 v83, v78
	v_pk_mul_f32 v[82:83], v[136:137], v[82:83]
	v_and_b32_e32 v79, 0xffff0000, v64
	v_fma_f32 v60, v11, v95, v82
	v_add_f32_e32 v60, v60, v83
	v_pk_mul_f32 v[82:83], v[6:7], v[78:79]
	v_mul_f32_e32 v60, v60, v97
	v_fma_f32 v64, v3, v95, v82
	v_lshlrev_b32_e32 v82, 16, v61
	v_cvt_pk_bf16_f32 v60, v85, v60
	v_mov_b32_e32 v84, v100
	v_mov_b32_e32 v85, v82
	v_and_b32_e32 v68, 0xffff0000, v68
	v_add_f32_e32 v64, v64, v83
	v_pk_mul_f32 v[84:85], v[148:149], v[84:85]
	v_mul_f32_e32 v91, v64, v68
	v_lshlrev_b32_e32 v83, 16, v65
	v_fma_f32 v68, v12, v101, v84
	v_add_f32_e32 v68, v68, v85
	v_pk_mul_f32 v[84:85], v[128:129], v[82:83]
	v_mul_f32_e32 v92, v68, v98
	v_fma_f32 v68, v4, v101, v84
	v_lshlrev_b32_e32 v64, 16, v69
	v_add_f32_e32 v68, v68, v85
	v_mul_f32_e32 v84, v68, v64
	v_and_b32_e32 v64, 0xffff0000, v61
	v_and_b32_e32 v85, 0xffff0000, v69
	v_mov_b32_e32 v68, v80
	v_mov_b32_e32 v69, v64
	v_pk_mul_f32 v[68:69], v[138:139], v[68:69]
	v_and_b32_e32 v65, 0xffff0000, v65
	v_fma_f32 v61, v13, v81, v68
	v_add_f32_e32 v61, v61, v69
	v_mul_f32_e32 v61, v61, v102
	v_lshl_add_u64 v[70:71], v[158:159], 0, v[178:179]
	v_cvt_pk_bf16_f32 v61, v92, v61
	v_pk_mul_f32 v[68:69], v[8:9], v[64:65]
	global_store_dwordx4 v[70:71], v[58:61], off sc1
	s_waitcnt vmcnt(17)
	v_lshlrev_b32_e32 v80, 16, v56
	v_lshlrev_b32_e32 v70, 16, v55
	v_fma_f32 v61, v5, v81, v68
	v_add_f32_e32 v61, v61, v69
	v_cvt_pk_bf16_f32 v58, v88, v89
	v_cvt_pk_bf16_f32 v59, v90, v86
	v_mul_f32_e32 v61, v61, v85
	v_lshl_add_u64 v[68:69], v[158:159], 0, v[168:169]
	v_and_b32_e32 v81, 0xffff0000, v56
	v_lshlrev_b32_e32 v56, 16, v42
	v_cvt_pk_bf16_f32 v60, v87, v91
	v_cvt_pk_bf16_f32 v61, v84, v61
	global_store_dwordx4 v[68:69], v[58:61], off sc1
	v_lshlrev_b32_e32 v84, 16, v57
	v_and_b32_e32 v85, 0xffff0000, v57
	v_mov_b32_e32 v58, v72
	v_mov_b32_e32 v59, v56
	v_pk_mul_f32 v[58:59], v[166:167], v[58:59]
	v_lshlrev_b32_e32 v60, 16, v54
	v_fma_f32 v58, v18, v73, v58
	s_waitcnt vmcnt(17)
	v_lshlrev_b32_e32 v57, 16, v46
	v_add_f32_e32 v58, v58, v59
	v_mul_f32_e32 v69, v58, v60
	v_pk_mul_f32 v[58:59], v[140:141], v[56:57]
	s_waitcnt vmcnt(16)
	v_lshlrev_b32_e32 v61, 16, v50
	v_fma_f32 v58, v14, v73, v58
	v_add_f32_e32 v58, v58, v59
	v_mul_f32_e32 v72, v58, v61
	v_and_b32_e32 v58, 0xffff0000, v42
	v_mov_b32_e32 v60, v74
	v_mov_b32_e32 v61, v58
	v_pk_mul_f32 v[60:61], v[164:165], v[60:61]
	v_and_b32_e32 v59, 0xffff0000, v46
	v_fma_f32 v42, v19, v75, v60
	v_and_b32_e32 v68, 0xffff0000, v54
	v_add_f32_e32 v42, v42, v61
	v_pk_mul_f32 v[60:61], v[22:23], v[58:59]
	v_mul_f32_e32 v42, v42, v68
	v_fma_f32 v46, v15, v75, v60
	v_lshlrev_b32_e32 v60, 16, v43
	v_cvt_pk_bf16_f32 v42, v69, v42
	v_mov_b32_e32 v68, v76
	v_mov_b32_e32 v69, v60
	v_and_b32_e32 v50, 0xffff0000, v50
	v_add_f32_e32 v46, v46, v61
	v_pk_mul_f32 v[68:69], v[154:155], v[68:69]
	v_mul_f32_e32 v73, v46, v50
	v_lshlrev_b32_e32 v61, 16, v47
	v_fma_f32 v50, v20, v77, v68
	v_add_f32_e32 v50, v50, v69
	v_pk_mul_f32 v[68:69], v[142:143], v[60:61]
	v_mul_f32_e32 v70, v50, v70
	v_fma_f32 v50, v16, v77, v68
	v_lshlrev_b32_e32 v46, 16, v51
	v_add_f32_e32 v50, v50, v69
	v_mul_f32_e32 v74, v50, v46
	v_and_b32_e32 v46, 0xffff0000, v43
	v_and_b32_e32 v68, 0xffff0000, v51
	v_mov_b32_e32 v50, v62
	v_mov_b32_e32 v51, v46
	v_pk_mul_f32 v[50:51], v[152:153], v[50:51]
	v_and_b32_e32 v47, 0xffff0000, v47
	v_fma_f32 v43, v21, v63, v50
	v_add_f32_e32 v43, v43, v51
	v_pk_mul_f32 v[50:51], v[24:25], v[46:47]
	v_and_b32_e32 v71, 0xffff0000, v55
	v_fma_f32 v50, v17, v63, v50
	v_mul_f32_e32 v43, v43, v71
	v_add_f32_e32 v50, v50, v51
	v_cvt_pk_bf16_f32 v43, v70, v43
	v_mul_f32_e32 v70, v50, v68
; __device__ __forceinline__ unsigned pk2(float lo, float hi) { return pg8::cvt_pk_bf16(lo, hi); }
; __device__ __forceinline__ float bf_lo(unsigned w) { return __uint_as_float(w << 16); }
; __device__ __forceinline__ float bf_hi(unsigned w) { return __uint_as_float(w & 0xffff0000u); }
; __device__ __forceinline__ void conv_prep(const bf16* Z, const bf16* GB, const float* cw, bf16* A2, int vcu, int G, int tid) {
;     ...
;         for (int i = 0; i < 16; ++i) { zz[i] = *(const v4u*)(Z + (size_t)(rb + i) * DM + c8); gg[i] = *(const v4u*)(GB + (size_t)(rb + i) * DM + c8); }
; #pragma unroll
;         for (int i = 0; i < 16; ++i) { const v4u z2 = zz[i], gb = gg[i]; v4u o;
; #pragma unroll
;             for (int k = 0; k < 4; ++k) { const int e = 2 * k;
;                 const float a = bf_lo(gb[k]) * (w0[e >> 2][e & 3] * bf_lo(z0[k]) + w1[e >> 2][e & 3] * bf_lo(z1[k]) + w2[e >> 2][e & 3] * bf_lo(z2[k]));
;                 const float b = bf_hi(gb[k]) * (w0[(e + 1) >> 2][(e + 1) & 3] * bf_hi(z0[k]) + w1[(e + 1) >> 2][(e + 1) & 3] * bf_hi(z1[k]) + w2[(e + 1) >> 2][(e + 1) & 3] * bf_hi(z2[k]));
;                 o[k] = pk2(a, b); }
;             *(v4u*)(A2 + (size_t)(rb + i) * DM + c8) = o; z0 = z1; z1 = z2; }
	v_lshlrev_b32_e32 v50, 16, v44
	v_mov_b32_e32 v62, v66
	v_mov_b32_e32 v63, v50
	v_pk_mul_f32 v[62:63], v[144:145], v[62:63]
	v_lshlrev_b32_e32 v51, 16, v48
	v_fma_f32 v62, v10, v67, v62
	v_add_f32_e32 v62, v62, v63
	v_mul_f32_e32 v69, v62, v80
	v_pk_mul_f32 v[62:63], v[124:125], v[50:51]
	v_lshlrev_b32_e32 v68, 16, v52
	v_fma_f32 v62, v2, v67, v62
	v_add_f32_e32 v62, v62, v63
	v_mul_f32_e32 v71, v62, v68
	v_and_b32_e32 v62, 0xffff0000, v44
	v_mov_b32_e32 v66, v78
	v_mov_b32_e32 v67, v62
	v_pk_mul_f32 v[66:67], v[136:137], v[66:67]
	v_and_b32_e32 v63, 0xffff0000, v48
	v_fma_f32 v44, v11, v79, v66
	v_add_f32_e32 v44, v44, v67
	v_pk_mul_f32 v[66:67], v[6:7], v[62:63]
	v_mul_f32_e32 v44, v44, v81
	v_fma_f32 v48, v3, v79, v66
	v_lshlrev_b32_e32 v66, 16, v45
	v_cvt_pk_bf16_f32 v44, v69, v44
	v_mov_b32_e32 v68, v82
	v_mov_b32_e32 v69, v66
	v_and_b32_e32 v52, 0xffff0000, v52
	v_add_f32_e32 v48, v48, v67
	v_pk_mul_f32 v[68:69], v[148:149], v[68:69]
	v_mul_f32_e32 v75, v48, v52
	v_lshlrev_b32_e32 v67, 16, v49
	v_fma_f32 v52, v12, v83, v68
	v_add_f32_e32 v52, v52, v69
	v_pk_mul_f32 v[68:69], v[128:129], v[66:67]
	v_mul_f32_e32 v76, v52, v84
	v_fma_f32 v52, v4, v83, v68
	v_lshlrev_b32_e32 v48, 16, v53
	v_add_f32_e32 v52, v52, v69
	v_mul_f32_e32 v68, v52, v48
	v_and_b32_e32 v48, 0xffff0000, v45
	v_and_b32_e32 v69, 0xffff0000, v53
	v_mov_b32_e32 v52, v64
	v_mov_b32_e32 v53, v48
	v_pk_mul_f32 v[52:53], v[138:139], v[52:53]
	v_and_b32_e32 v49, 0xffff0000, v49
	v_fma_f32 v45, v13, v65, v52
	v_add_f32_e32 v45, v45, v53
	v_mul_f32_e32 v45, v45, v85
	v_lshl_add_u64 v[54:55], v[158:159], 0, v[170:171]
	v_cvt_pk_bf16_f32 v45, v76, v45
	v_pk_mul_f32 v[52:53], v[8:9], v[48:49]
	global_store_dwordx4 v[54:55], v[42:45], off sc1
	s_waitcnt vmcnt(15)
	v_lshlrev_b32_e32 v54, 16, v40
	v_and_b32_e32 v55, 0xffff0000, v40
	v_fma_f32 v45, v5, v65, v52
	v_add_f32_e32 v45, v45, v53
	v_cvt_pk_bf16_f32 v42, v72, v73
	v_cvt_pk_bf16_f32 v43, v74, v70
	v_mul_f32_e32 v45, v45, v69
	v_lshl_add_u64 v[52:53], v[158:159], 0, v[160:161]
	v_lshlrev_b32_e32 v40, 16, v26
	v_cvt_pk_bf16_f32 v44, v71, v75
	v_cvt_pk_bf16_f32 v45, v68, v45
	global_store_dwordx4 v[52:53], v[42:45], off sc1
	v_lshlrev_b32_e32 v64, 16, v41
	v_and_b32_e32 v65, 0xffff0000, v41
	s_waitcnt vmcnt(15)
	v_lshlrev_b32_e32 v41, 16, v30
	v_mov_b32_e32 v42, v56
	v_mov_b32_e32 v43, v40
	v_pk_mul_f32 v[42:43], v[166:167], v[42:43]
	v_pk_mul_f32 v[40:41], v[140:141], v[40:41]
	v_fma_f32 v18, v18, v57, v42
	v_fma_f32 v14, v14, v57, v40
	v_and_b32_e32 v40, 0xffff0000, v26
	v_add_f32_e32 v18, v18, v43
	v_mov_b32_e32 v42, v58
	v_mov_b32_e32 v43, v40
	v_lshlrev_b32_e32 v44, 16, v38
	s_waitcnt vmcnt(14)
	v_lshlrev_b32_e32 v68, 16, v34
	v_add_f32_e32 v14, v14, v41
	v_pk_mul_f32 v[42:43], v[164:165], v[42:43]
	v_mul_f32_e32 v18, v18, v44
	v_mul_f32_e32 v44, v14, v68
	v_fma_f32 v14, v19, v59, v42
	v_and_b32_e32 v45, 0xffff0000, v38
	v_add_f32_e32 v14, v14, v43
	v_and_b32_e32 v41, 0xffff0000, v30
	v_mul_f32_e32 v14, v14, v45
	v_cvt_pk_bf16_f32 v14, v18, v14
	v_pk_mul_f32 v[18:19], v[22:23], v[40:41]
	v_mov_b32_e32 v22, v60
	v_fma_f32 v15, v15, v59, v18
	v_lshlrev_b32_e32 v18, 16, v27
	v_add_f32_e32 v15, v15, v19
	v_lshlrev_b32_e32 v19, 16, v31
	v_mov_b32_e32 v23, v18
	v_pk_mul_f32 v[22:23], v[154:155], v[22:23]
	v_pk_mul_f32 v[18:19], v[142:143], v[18:19]
	v_fma_f32 v20, v20, v61, v22
	v_fma_f32 v16, v16, v61, v18
	v_and_b32_e32 v18, 0xffff0000, v27
	v_and_b32_e32 v34, 0xffff0000, v34
	v_add_f32_e32 v20, v20, v23
	v_mov_b32_e32 v22, v46
	v_mov_b32_e32 v23, v18
	v_mul_f32_e32 v26, v15, v34
	v_lshlrev_b32_e32 v15, 16, v35
	v_add_f32_e32 v16, v16, v19
	v_and_b32_e32 v19, 0xffff0000, v31
	v_pk_mul_f32 v[22:23], v[152:153], v[22:23]
	v_mul_f32_e32 v30, v16, v15
	v_fma_f32 v15, v21, v47, v22
	v_pk_mul_f32 v[18:19], v[24:25], v[18:19]
	v_lshlrev_b32_e32 v52, 16, v39
	v_and_b32_e32 v53, 0xffff0000, v39
	v_add_f32_e32 v15, v15, v23
	v_fma_f32 v17, v17, v47, v18
	v_mul_f32_e32 v20, v20, v52
	v_and_b32_e32 v16, 0xffff0000, v35
	v_mul_f32_e32 v15, v15, v53
	v_add_f32_e32 v17, v17, v19
	v_cvt_pk_bf16_f32 v15, v20, v15
	v_mul_f32_e32 v20, v17, v16
	v_lshlrev_b32_e32 v16, 16, v28
	v_lshlrev_b32_e32 v17, 16, v32
	v_mov_b32_e32 v18, v50
	v_mov_b32_e32 v19, v16
	v_pk_mul_f32 v[18:19], v[144:145], v[18:19]
	v_pk_mul_f32 v[16:17], v[124:125], v[16:17]
	v_fma_f32 v10, v10, v51, v18
	v_fma_f32 v2, v2, v51, v16
	v_and_b32_e32 v18, 0xffff0000, v28
	v_add_f32_e32 v10, v10, v19
	v_add_f32_e32 v2, v2, v17
	v_and_b32_e32 v19, 0xffff0000, v32
	v_mov_b32_e32 v16, v62
	v_mov_b32_e32 v17, v18
	v_pk_mul_f32 v[16:17], v[136:137], v[16:17]
	v_pk_mul_f32 v[6:7], v[6:7], v[18:19]
	v_lshlrev_b32_e32 v21, 16, v36
	v_fma_f32 v11, v11, v63, v16
	v_fma_f32 v3, v3, v63, v6
	v_mul_f32_e32 v10, v10, v54
	v_mul_f32_e32 v21, v2, v21
	v_and_b32_e32 v2, 0xffff0000, v36
	v_add_f32_e32 v11, v11, v17
	v_add_f32_e32 v3, v3, v7
	v_mul_f32_e32 v11, v11, v55
	v_cvt_pk_bf16_f32 v16, v10, v11
	v_mul_f32_e32 v10, v3, v2
	v_lshlrev_b32_e32 v2, 16, v29
	v_mov_b32_e32 v6, v66
	v_mov_b32_e32 v7, v2
	v_lshlrev_b32_e32 v3, 16, v33
	v_pk_mul_f32 v[6:7], v[148:149], v[6:7]
	v_pk_mul_f32 v[2:3], v[128:129], v[2:3]
	v_fma_f32 v6, v12, v67, v6
	v_add_f32_e32 v6, v6, v7
	v_fma_f32 v2, v4, v67, v2
	v_lshlrev_b32_e32 v11, 16, v37
	v_mul_f32_e32 v12, v6, v64
	v_add_f32_e32 v2, v2, v3
	v_and_b32_e32 v6, 0xffff0000, v29
	v_mul_f32_e32 v11, v2, v11
	v_and_b32_e32 v7, 0xffff0000, v33
	v_mov_b32_e32 v2, v48
	v_mov_b32_e32 v3, v6
	v_pk_mul_f32 v[2:3], v[138:139], v[2:3]
	v_pk_mul_f32 v[6:7], v[8:9], v[6:7]
	v_fma_f32 v2, v13, v49, v2
	v_fma_f32 v5, v5, v49, v6
	v_add_u32_e32 v223, s2, v223
	v_and_b32_e32 v18, 0xffff0000, v37
	v_add_f32_e32 v2, v2, v3
	v_add_f32_e32 v5, v5, v7
	v_cmp_lt_i32_e32 vcc, s29, v223
	v_lshl_add_u64 v[38:39], v[158:159], 0, v[162:163]
	v_mul_f32_e32 v2, v2, v65
	v_mul_f32_e32 v5, v5, v18
	v_lshl_add_u64 v[6:7], v[158:159], 0, v[156:157]
	s_or_b64 s[10:11], vcc, s[10:11]
	v_add_u32_e32 v224, s3, v224
	v_cvt_pk_bf16_f32 v17, v12, v2
	global_store_dwordx4 v[38:39], v[14:17], off sc1
	v_cvt_pk_bf16_f32 v2, v44, v26
	v_cvt_pk_bf16_f32 v3, v30, v20
	v_cvt_pk_bf16_f32 v4, v21, v10
	v_cvt_pk_bf16_f32 v5, v11, v5
	global_store_dwordx4 v[6:7], v[2:5], off sc1
	s_andn2_b64 exec, exec, s[10:11]
	s_cbranch_execz .LBB0_73

; __device__ __forceinline__ void finishSM(f32x16& p0, f32x16& p1, float alpha, float& l_reg, bf16x8& pa0, bf16x8& pa1, bf16x8& pa2, bf16x8& pa3) {
;     for (int r = 0; r < 16; ++r) p1[r] = __builtin_amdgcn_exp2f(p1[r]);
;     float ps = 0; for (int r = 0; r < 16; ++r) ps += p0[r]; for (int r = 0; r < 16; ++r) ps += p1[r];
;     { auto rr = __builtin_amdgcn_permlane32_swap(__float_as_uint(ps), __float_as_uint(ps), false, false);
;       ps = __uint_as_float(rr[0]) + __uint_as_float(rr[1]); }
;     l_reg = l_reg * alpha + ps;
;     ...
;     PK4(p0, 0, pa0); PK4(p0, 8, pa1); PK4(p1, 0, pa2); PK4(p1, 8, pa3);
;     ...
; }
; template <int KB>
; __device__ __forceinline__ void qkt(f32x16& p0, f32x16& p1, const char* K_lds, int r32, int hi, const bf16x8* qr) {
;     p0 = f32x16{}; p1 = f32x16{};
;     const char* kb[4];
; #pragma unroll
;     for (int dd = 0; dd < 4; ++dd) kb[dd] = K_lds + KB * SHM_K + KSWZ(r32, (dd * 16 + hi * 8) * 2);
; #pragma unroll
;     for (int d0 = 0; d0 < 8; ++d0) { const char* a = kb[d0 & 3] + (d0 >> 2) * 128;
;         bf16x8 b0 = *reinterpret_cast<const bf16x8*>(a);
;         bf16x8 b1 = *reinterpret_cast<const bf16x8*>(a + 32 * 256);
;         p0 = __builtin_amdgcn_mfma_f32_32x32x16_bf16(b0, qr[d0], p0, 0, 0, 0);
;         p1 = __builtin_amdgcn_mfma_f32_32x32x16_bf16(b1, qr[d0], p1, 0, 0, 0); }
; }
; template <int VB>
; __device__ __forceinline__ void pv_tile(f32x16* o, int vb0, bf16x8 pa0, bf16x8 pa1, bf16x8 pa2, bf16x8 pa3) {
;     ...
;     PV_D0(0); PV_D0(1); PV_D0(2); PV_D0(3);
.LBB0_113:
	v_cndmask_b32_e64 v106, v106, v198, s[40:41]
	v_mul_f32_e32 v106, 0xbe0293ee, v106
	v_fmamk_f32 v107, v66, 0x3e0293ee, v106
	v_fmamk_f32 v152, v67, 0x3e0293ee, v106
	v_fmamk_f32 v158, v81, 0x3e0293ee, v106
	v_exp_f32_e32 v81, v107
	v_fmamk_f32 v68, v68, 0x3e0293ee, v106
	v_fmamk_f32 v67, v83, 0x3e0293ee, v106
	v_exp_f32_e32 v83, v152
	v_fmamk_f32 v69, v69, 0x3e0293ee, v106
	v_fmamk_f32 v156, v79, 0x3e0293ee, v106
	v_exp_f32_e32 v79, v68
	v_fmamk_f32 v70, v70, 0x3e0293ee, v106
	v_fmamk_f32 v66, v82, 0x3e0293ee, v106
	v_exp_f32_e32 v82, v69
	v_fmamk_f32 v71, v71, 0x3e0293ee, v106
	v_fmamk_f32 v72, v72, 0x3e0293ee, v106
	v_fmamk_f32 v73, v73, 0x3e0293ee, v106
	v_fmamk_f32 v74, v74, 0x3e0293ee, v106
	v_fmamk_f32 v75, v75, 0x3e0293ee, v106
	v_fmamk_f32 v153, v76, 0x3e0293ee, v106
	v_fmamk_f32 v154, v77, 0x3e0293ee, v106
	v_fmamk_f32 v155, v78, 0x3e0293ee, v106
	v_fmamk_f32 v157, v80, 0x3e0293ee, v106
	v_fmamk_f32 v84, v84, 0x3e0293ee, v106
	v_fmamk_f32 v85, v85, 0x3e0293ee, v106
	v_fmamk_f32 v86, v86, 0x3e0293ee, v106
	v_fmamk_f32 v87, v87, 0x3e0293ee, v106
	v_fmamk_f32 v88, v88, 0x3e0293ee, v106
	v_fmamk_f32 v89, v89, 0x3e0293ee, v106
	v_fmamk_f32 v90, v90, 0x3e0293ee, v106
	v_fmamk_f32 v91, v91, 0x3e0293ee, v106
	v_fmamk_f32 v92, v92, 0x3e0293ee, v106
	v_fmamk_f32 v93, v93, 0x3e0293ee, v106
	v_fmamk_f32 v94, v94, 0x3e0293ee, v106
	v_exp_f32_e32 v77, v70
	v_fmamk_f32 v95, v95, 0x3e0293ee, v106
	v_fmamk_f32 v96, v96, 0x3e0293ee, v106
	v_fmac_f32_e32 v106, 0x3e0293ee, v97
	v_exp_f32_e32 v97, v66
	v_add_f32_e32 v66, 0, v81
	v_exp_f32_e32 v80, v71
	v_add_f32_e32 v66, v83, v66
	v_exp_f32_e32 v76, v72
	v_add_f32_e32 v66, v79, v66
	v_exp_f32_e32 v78, v73
	v_add_f32_e32 v66, v82, v66
	v_exp_f32_e32 v73, v74
	v_add_f32_e32 v66, v77, v66
	v_exp_f32_e32 v75, v75
	v_add_f32_e32 v66, v80, v66
	v_exp_f32_e32 v71, v153
	v_add_f32_e32 v66, v76, v66
	v_exp_f32_e32 v74, v154
	v_add_f32_e32 v66, v78, v66
	v_exp_f32_e32 v69, v155
	v_add_f32_e32 v66, v73, v66
	v_exp_f32_e32 v72, v156
	v_add_f32_e32 v66, v75, v66
	v_exp_f32_e32 v68, v157
	v_add_f32_e32 v66, v71, v66
	v_exp_f32_e32 v70, v158
	v_add_f32_e32 v66, v74, v66
	v_add_f32_e32 v66, v69, v66
	v_exp_f32_e32 v107, v67
	v_add_f32_e32 v66, v72, v66
	v_exp_f32_e32 v152, v84
	v_add_f32_e32 v66, v68, v66
	v_exp_f32_e32 v153, v85
	v_add_f32_e32 v66, v70, v66
	v_exp_f32_e32 v154, v86
	v_add_f32_e32 v66, v97, v66
	v_exp_f32_e32 v155, v87
	v_add_f32_e32 v66, v107, v66
	v_exp_f32_e32 v88, v88
	v_add_f32_e32 v66, v152, v66
	v_exp_f32_e32 v89, v89
	v_add_f32_e32 v66, v153, v66
	v_exp_f32_e32 v90, v90
	v_add_f32_e32 v66, v154, v66
	v_exp_f32_e32 v91, v91
	v_add_f32_e32 v66, v155, v66
	v_exp_f32_e32 v92, v92
	v_add_f32_e32 v66, v88, v66
	v_exp_f32_e32 v93, v93
	v_add_f32_e32 v66, v89, v66
	v_exp_f32_e32 v94, v94
	v_add_f32_e32 v66, v90, v66
	v_exp_f32_e32 v95, v95
	v_add_f32_e32 v66, v91, v66
	v_exp_f32_e32 v96, v96
	v_add_f32_e32 v66, v92, v66
	v_exp_f32_e32 v106, v106
	v_add_f32_e32 v66, v93, v66
	v_add_f32_e32 v66, v94, v66
	v_add_f32_e32 v66, v95, v66
	v_add_f32_e32 v66, v96, v66
	v_add_f32_e32 v66, v106, v66
	v_mov_b32_e32 v67, v66
	s_nop 1
	v_permlane32_swap_b32_e32 v66, v67
	v_cvt_pk_bf16_f32 v84, v81, v83
	v_cvt_pk_bf16_f32 v85, v79, v82
	v_cvt_pk_bf16_f32 v86, v77, v80
	v_cvt_pk_bf16_f32 v87, v76, v78
	v_cvt_pk_bf16_f32 v76, v73, v75
	v_cvt_pk_bf16_f32 v77, v71, v74
	v_cvt_pk_bf16_f32 v78, v69, v72
	v_cvt_pk_bf16_f32 v79, v68, v70
	v_cvt_pk_bf16_f32 v68, v97, v107
	v_cvt_pk_bf16_f32 v69, v152, v153
	v_cvt_pk_bf16_f32 v70, v154, v155
	v_cvt_pk_bf16_f32 v71, v88, v89
	v_cvt_pk_bf16_f32 v72, v90, v91
	v_cvt_pk_bf16_f32 v73, v92, v93
	v_cvt_pk_bf16_f32 v74, v94, v95
	v_cvt_pk_bf16_f32 v75, v96, v106
	s_nop 0
	v_permlane32_swap_b32_e32 v84, v86
	v_permlane32_swap_b32_e32 v85, v87
	v_permlane32_swap_b32_e32 v76, v78
	v_permlane32_swap_b32_e32 v77, v79
	v_permlane32_swap_b32_e32 v68, v70
	v_permlane32_swap_b32_e32 v69, v71
	v_permlane32_swap_b32_e32 v72, v74
	v_permlane32_swap_b32_e32 v73, v75
	ds_read_b64_tr_b16 v[80:81], v185 offset:0x4000
	ds_read_b64_tr_b16 v[82:83], v185 offset:0x4800
	ds_read_b64_tr_b16 v[88:89], v185 offset:0x5000
	ds_read_b64_tr_b16 v[90:91], v185 offset:0x5800
	ds_read_b64_tr_b16 v[92:93], v185 offset:0x6000
	ds_read_b64_tr_b16 v[94:95], v185 offset:0x6800
	ds_read_b64_tr_b16 v[152:153], v185 offset:0x7000
	ds_read_b64_tr_b16 v[154:155], v185 offset:0x7800
	s_waitcnt lgkmcnt(0)
	s_nop 0
	v_mfma_f32_32x32x16_bf16 v[50:65], v[84:87], v[80:83], v[50:65]
	ds_read_b64_tr_b16 v[80:81], v185 offset:0x4200
	ds_read_b64_tr_b16 v[82:83], v185 offset:0x4a00
	v_mfma_f32_32x32x16_bf16 v[50:65], v[76:79], v[88:91], v[50:65]
	ds_read_b64_tr_b16 v[88:89], v185 offset:0x5200
	ds_read_b64_tr_b16 v[90:91], v185 offset:0x5a00
	v_mfma_f32_32x32x16_bf16 v[50:65], v[68:71], v[92:95], v[50:65]
	ds_read_b64_tr_b16 v[92:93], v185 offset:0x6200
	ds_read_b64_tr_b16 v[94:95], v185 offset:0x6a00
	v_mfma_f32_32x32x16_bf16 v[50:65], v[72:75], v[152:155], v[50:65]
	ds_read_b64_tr_b16 v[152:153], v185 offset:0x7200
	ds_read_b64_tr_b16 v[154:155], v185 offset:0x7a00
	s_waitcnt lgkmcnt(0)
	v_mfma_f32_32x32x16_bf16 v[34:49], v[84:87], v[80:83], v[34:49]
	ds_read_b64_tr_b16 v[80:81], v185 offset:0x4400
	ds_read_b64_tr_b16 v[82:83], v185 offset:0x4c00
	v_mfma_f32_32x32x16_bf16 v[34:49], v[76:79], v[88:91], v[34:49]
	ds_read_b64_tr_b16 v[88:89], v185 offset:0x5400
	ds_read_b64_tr_b16 v[90:91], v185 offset:0x5c00
	v_mfma_f32_32x32x16_bf16 v[34:49], v[68:71], v[92:95], v[34:49]
	ds_read_b64_tr_b16 v[92:93], v185 offset:0x6400
	ds_read_b64_tr_b16 v[94:95], v185 offset:0x6c00
	v_mfma_f32_32x32x16_bf16 v[34:49], v[72:75], v[152:155], v[34:49]
	ds_read_b64_tr_b16 v[152:153], v185 offset:0x7400
	ds_read_b64_tr_b16 v[154:155], v185 offset:0x7c00
	s_waitcnt lgkmcnt(0)
; #define SBAR() __builtin_amdgcn_sched_barrier(0)
; __device__ __forceinline__ int crow(int r, int hi) { return (r & 3) + 8 * (r >> 2) + 4 * hi; }
; __device__ __forceinline__ unsigned cvtpk(float lo, float hi) { unsigned r; asm volatile("v_cvt_pk_bf16_f32 %0, %1, %2" : "=v"(r) : "v"(lo), "v"(hi)); return r; }
; #define SEAM_K0() do { VMWN(NQL); SWRITE_HK(0); SBAR(); } while (0)
; template <int VB>
; __device__ __forceinline__ void pv_tile(f32x16* o, int vb0, bf16x8 pa0, bf16x8 pa1, bf16x8 pa2, bf16x8 pa3) {
;     ...
;     PV_D0(0); PV_D0(1); PV_D0(2); PV_D0(3);
; __device__ __forceinline__ void moba_block(const BlockRef& cur, const BlockRef& nxt, char* lds, Seam& S) {
;     ...
;     SBAR(); SEAM_K0();
;     if (hi == 0) li_l[r32] = l_reg; asm volatile("s_waitcnt lgkmcnt(0)" ::: "memory");
;     float rli[16];
; #pragma unroll
;     for (int r = 0; r < 16; ++r) rli[r] = __builtin_amdgcn_rcpf(li_l[crow(r, hi)]);
;     bf16* Ow = cur.O + (size_t)(wid * QBLK) * OSTR;
; #pragma unroll
;     for (int r = 0; r < 16; ++r) { const int orow = crow(r, hi);
; #pragma unroll
;         for (int d0 = 0; d0 < 4; ++d0) { const float v = o[d0][r] * rli[r];
;             const float vn = __shfl_xor(v, 1);
;             if ((r32 & 1) == 0) *(unsigned*)(Ow + (size_t)orow * OSTR + d0 * 32 + r32) = cvtpk(v, vn); } }
	v_mfma_f32_32x32x16_bf16 v[18:33], v[84:87], v[80:83], v[18:33]
	ds_read_b64_tr_b16 v[80:81], v185 offset:0x4600
	ds_read_b64_tr_b16 v[82:83], v185 offset:0x4e00
	v_mfma_f32_32x32x16_bf16 v[18:33], v[76:79], v[88:91], v[18:33]
	ds_read_b64_tr_b16 v[88:89], v185 offset:0x5600
	ds_read_b64_tr_b16 v[90:91], v185 offset:0x5e00
	v_mfma_f32_32x32x16_bf16 v[18:33], v[68:71], v[92:95], v[18:33]
	ds_read_b64_tr_b16 v[92:93], v185 offset:0x6600
	ds_read_b64_tr_b16 v[94:95], v185 offset:0x6e00
	v_mfma_f32_32x32x16_bf16 v[18:33], v[72:75], v[152:155], v[18:33]
	ds_read_b64_tr_b16 v[152:153], v185 offset:0x7600
	ds_read_b64_tr_b16 v[154:155], v185 offset:0x7e00
	s_waitcnt lgkmcnt(0)
	v_mfma_f32_32x32x16_bf16 v[2:17], v[84:87], v[80:83], v[2:17]
	v_mfma_f32_32x32x16_bf16 v[2:17], v[76:79], v[88:91], v[2:17]
	v_mfma_f32_32x32x16_bf16 v[2:17], v[68:71], v[92:95], v[2:17]
	v_mfma_f32_32x32x16_bf16 v[2:17], v[72:75], v[152:155], v[2:17]
	s_waitcnt vmcnt(8)
	s_waitcnt vmcnt(9)
	ds_write_b128 v188, v[144:147] offset:32768
	s_waitcnt vmcnt(8)
	ds_write_b128 v188, v[148:151] offset:40960
	s_and_saveexec_b64 s[0:1], s[38:39]
	v_add_f32_e32 v68, v98, v104
	v_fmac_f32_e32 v68, v189, v201
	v_add_f32_e32 v66, v66, v67
	v_fmac_f32_e32 v66, v68, v105
	ds_write_b32 v187, v66
	s_or_b64 exec, exec, s[0:1]
	s_waitcnt lgkmcnt(0)
	ds_read_b128 v[78:81], v186
	ds_read_b128 v[74:77], v186 offset:32
	s_ashr_i32 s95, s94, 31
	ds_read_b128 v[70:73], v186 offset:64
	ds_read_b128 v[66:69], v186 offset:96
	s_lshl_b64 s[0:1], s[94:95], 11
	s_waitcnt lgkmcnt(3)
	v_rcp_f32_e32 v84, v78
	v_xor_b32_e32 v78, 1, v212
	v_cmp_lt_i32_e32 vcc, v78, v213
	s_add_u32 s0, s92, s0
	v_mul_f32_e32 v50, v50, v84
	v_cndmask_b32_e32 v78, v212, v78, vcc
	v_lshlrev_b32_e32 v78, 2, v78
	ds_bpermute_b32 v85, v78, v50
	s_addc_u32 s1, s93, s1
	v_and_b32_e32 v82, 1, v183
	v_lshlrev_b32_e32 v98, 1, v184
	v_cmp_eq_u32_e64 s[38:39], 0, v82
	v_lshl_add_u64 v[82:83], s[0:1], 0, v[98:99]
	v_lshlrev_b32_e32 v98, 13, v182
	v_lshl_add_u64 v[82:83], v[82:83], 0, v[98:99]
	s_and_saveexec_b64 s[0:1], s[38:39]
	s_cbranch_execz .LBB0_117
	s_waitcnt lgkmcnt(0)
	v_cvt_pk_bf16_f32 v50, v50, v85
	global_store_dword v[82:83], v50, off sc1
.LBB0_117:
	s_or_b64 exec, exec, s[0:1]
	v_mul_f32_e32 v34, v34, v84
	ds_bpermute_b32 v50, v78, v34
	s_and_saveexec_b64 s[0:1], s[38:39]
	s_cbranch_execz .LBB0_119
	s_waitcnt lgkmcnt(0)
	v_cvt_pk_bf16_f32 v34, v34, v50
	global_store_dword v[82:83], v34, off offset:64 sc1
.LBB0_119:
	s_or_b64 exec, exec, s[0:1]
	v_mul_f32_e32 v18, v18, v84
	ds_bpermute_b32 v34, v78, v18
	s_and_saveexec_b64 s[0:1], s[38:39]
	s_cbranch_execz .LBB0_121
	s_waitcnt lgkmcnt(0)
	v_cvt_pk_bf16_f32 v18, v18, v34
	global_store_dword v[82:83], v18, off offset:128 sc1
.LBB0_121:
	s_or_b64 exec, exec, s[0:1]
	v_mul_f32_e32 v2, v2, v84
	ds_bpermute_b32 v18, v78, v2
	s_and_saveexec_b64 s[0:1], s[38:39]
	s_cbranch_execz .LBB0_123
	s_waitcnt lgkmcnt(0)
	v_cvt_pk_bf16_f32 v2, v2, v18
	global_store_dword v[82:83], v2, off offset:192 sc1
.LBB0_123:
	s_or_b64 exec, exec, s[0:1]
	v_rcp_f32_e32 v2, v79
	s_waitcnt lgkmcnt(0)
	v_mul_f32_e32 v18, v51, v2
	ds_bpermute_b32 v34, v78, v18
	s_and_saveexec_b64 s[0:1], s[38:39]
	s_cbranch_execz .LBB0_125
	s_waitcnt lgkmcnt(0)
	v_cvt_pk_bf16_f32 v18, v18, v34
	global_store_dword v[82:83], v18, off offset:2048 sc1
.LBB0_125:
	s_or_b64 exec, exec, s[0:1]
	v_mul_f32_e32 v18, v35, v2
	s_waitcnt lgkmcnt(0)
	ds_bpermute_b32 v34, v78, v18
	s_and_saveexec_b64 s[0:1], s[38:39]
	s_cbranch_execz .LBB0_127
	s_waitcnt lgkmcnt(0)
	v_cvt_pk_bf16_f32 v18, v18, v34
	global_store_dword v[82:83], v18, off offset:2112 sc1
.LBB0_127:
	s_or_b64 exec, exec, s[0:1]
	v_mul_f32_e32 v18, v19, v2
	ds_bpermute_b32 v19, v78, v18
	s_and_saveexec_b64 s[0:1], s[38:39]
	s_cbranch_execz .LBB0_129
	s_waitcnt lgkmcnt(0)
	v_cvt_pk_bf16_f32 v18, v18, v19
	global_store_dword v[82:83], v18, off offset:2176 sc1
.LBB0_129:
	s_or_b64 exec, exec, s[0:1]
	v_mul_f32_e32 v2, v3, v2
	ds_bpermute_b32 v3, v78, v2
	s_and_saveexec_b64 s[0:1], s[38:39]
	s_cbranch_execz .LBB0_131
	s_waitcnt lgkmcnt(0)
	v_cvt_pk_bf16_f32 v2, v2, v3
	global_store_dword v[82:83], v2, off offset:2240 sc1
.LBB0_131:
	s_or_b64 exec, exec, s[0:1]
	v_rcp_f32_e32 v2, v80
	s_waitcnt lgkmcnt(0)
	v_mul_f32_e32 v3, v52, v2
	ds_bpermute_b32 v18, v78, v3
	s_and_saveexec_b64 s[0:1], s[38:39]
	s_cbranch_execz .LBB0_133
	s_waitcnt lgkmcnt(0)
	v_cvt_pk_bf16_f32 v3, v3, v18
	v_add_co_u32_e32 v18, vcc, 0x1000, v82
	s_nop 1
	v_addc_co_u32_e32 v19, vcc, 0, v83, vcc
	global_store_dword v[18:19], v3, off sc1
.LBB0_133:
	s_or_b64 exec, exec, s[0:1]
	v_mul_f32_e32 v3, v36, v2
	s_waitcnt lgkmcnt(0)
	ds_bpermute_b32 v18, v78, v3
	s_and_saveexec_b64 s[0:1], s[38:39]
	s_cbranch_execz .LBB0_135
	s_waitcnt lgkmcnt(0)
	v_cvt_pk_bf16_f32 v3, v3, v18
	v_add_co_u32_e32 v18, vcc, 0x1000, v82
	s_nop 1
	v_addc_co_u32_e32 v19, vcc, 0, v83, vcc
	global_store_dword v[18:19], v3, off offset:64 sc1
.LBB0_135:
	s_or_b64 exec, exec, s[0:1]
	v_mul_f32_e32 v3, v20, v2
	s_waitcnt lgkmcnt(0)
	ds_bpermute_b32 v18, v78, v3
	s_and_saveexec_b64 s[0:1], s[38:39]
	s_cbranch_execz .LBB0_137
	s_waitcnt lgkmcnt(0)
	v_cvt_pk_bf16_f32 v3, v3, v18
	v_add_co_u32_e32 v18, vcc, 0x1000, v82
	s_nop 1
	v_addc_co_u32_e32 v19, vcc, 0, v83, vcc
	global_store_dword v[18:19], v3, off offset:128 sc1
.LBB0_137:
	s_or_b64 exec, exec, s[0:1]
	v_mul_f32_e32 v2, v4, v2
	ds_bpermute_b32 v3, v78, v2
	s_and_saveexec_b64 s[0:1], s[38:39]
	s_cbranch_execz .LBB0_139
	s_waitcnt lgkmcnt(0)
	v_cvt_pk_bf16_f32 v4, v2, v3
	v_add_co_u32_e32 v2, vcc, 0x1000, v82
	s_nop 1
	v_addc_co_u32_e32 v3, vcc, 0, v83, vcc
	global_store_dword v[2:3], v4, off offset:192 sc1
; __device__ __forceinline__ int crow(int r, int hi) { return (r & 3) + 8 * (r >> 2) + 4 * hi; }
; __device__ __forceinline__ unsigned cvtpk(float lo, float hi) { unsigned r; asm volatile("v_cvt_pk_bf16_f32 %0, %1, %2" : "=v"(r) : "v"(lo), "v"(hi)); return r; }
; __device__ __forceinline__ void moba_block(const BlockRef& cur, const BlockRef& nxt, char* lds, Seam& S) {
;     ...
;     for (int r = 0; r < 16; ++r) rli[r] = __builtin_amdgcn_rcpf(li_l[crow(r, hi)]);
;     bf16* Ow = cur.O + (size_t)(wid * QBLK) * OSTR;
; #pragma unroll
;     for (int r = 0; r < 16; ++r) { const int orow = crow(r, hi);
; #pragma unroll
;         for (int d0 = 0; d0 < 4; ++d0) { const float v = o[d0][r] * rli[r];
;             const float vn = __shfl_xor(v, 1);
;             if ((r32 & 1) == 0) *(unsigned*)(Ow + (size_t)orow * OSTR + d0 * 32 + r32) = cvtpk(v, vn); } }
.LBB0_139:
	s_or_b64 exec, exec, s[0:1]
	v_rcp_f32_e32 v2, v81
	s_waitcnt lgkmcnt(0)
	v_mul_f32_e32 v3, v53, v2
	ds_bpermute_b32 v4, v78, v3
	s_and_saveexec_b64 s[0:1], s[38:39]
	s_cbranch_execz .LBB0_141
	v_add_co_u32_e32 v18, vcc, 0x1000, v82
	s_waitcnt lgkmcnt(0)
	v_cvt_pk_bf16_f32 v3, v3, v4
	s_nop 0
	v_addc_co_u32_e32 v19, vcc, 0, v83, vcc
	global_store_dword v[18:19], v3, off offset:2048 sc1
.LBB0_141:
	s_or_b64 exec, exec, s[0:1]
	v_mul_f32_e32 v3, v37, v2
	s_waitcnt lgkmcnt(0)
	ds_bpermute_b32 v4, v78, v3
	s_and_saveexec_b64 s[0:1], s[38:39]
	s_cbranch_execz .LBB0_143
	v_add_co_u32_e32 v18, vcc, 0x1000, v82
	s_waitcnt lgkmcnt(0)
	v_cvt_pk_bf16_f32 v3, v3, v4
	s_nop 0
	v_addc_co_u32_e32 v19, vcc, 0, v83, vcc
	global_store_dword v[18:19], v3, off offset:2112 sc1
.LBB0_143:
	s_or_b64 exec, exec, s[0:1]
	v_mul_f32_e32 v3, v21, v2
	s_waitcnt lgkmcnt(0)
	ds_bpermute_b32 v4, v78, v3
	s_and_saveexec_b64 s[0:1], s[38:39]
	s_cbranch_execz .LBB0_145
	v_add_co_u32_e32 v18, vcc, 0x1000, v82
	s_waitcnt lgkmcnt(0)
	v_cvt_pk_bf16_f32 v3, v3, v4
	s_nop 0
	v_addc_co_u32_e32 v19, vcc, 0, v83, vcc
	global_store_dword v[18:19], v3, off offset:2176 sc1
.LBB0_145:
	s_or_b64 exec, exec, s[0:1]
	v_mul_f32_e32 v2, v5, v2
	ds_bpermute_b32 v3, v78, v2
	s_and_saveexec_b64 s[0:1], s[38:39]
	s_cbranch_execz .LBB0_147
	s_waitcnt lgkmcnt(0)
	v_cvt_pk_bf16_f32 v4, v2, v3
	v_add_co_u32_e32 v2, vcc, 0x1000, v82
	s_nop 1
	v_addc_co_u32_e32 v3, vcc, 0, v83, vcc
	global_store_dword v[2:3], v4, off offset:2240 sc1
.LBB0_147:
	s_or_b64 exec, exec, s[0:1]
	v_rcp_f32_e32 v2, v74
	s_waitcnt lgkmcnt(0)
	v_mul_f32_e32 v3, v54, v2
	ds_bpermute_b32 v4, v78, v3
	s_and_saveexec_b64 s[0:1], s[38:39]
	s_cbranch_execz .LBB0_149
	s_waitcnt lgkmcnt(0)
	v_cvt_pk_bf16_f32 v3, v3, v4
	v_add_co_u32_e32 v4, vcc, 0x4000, v82
	s_nop 1
	v_addc_co_u32_e32 v5, vcc, 0, v83, vcc
	global_store_dword v[4:5], v3, off sc1
.LBB0_149:
	s_or_b64 exec, exec, s[0:1]
	v_mul_f32_e32 v3, v38, v2
	s_waitcnt lgkmcnt(0)
	ds_bpermute_b32 v4, v78, v3
	s_and_saveexec_b64 s[0:1], s[38:39]
	s_cbranch_execz .LBB0_151
	s_waitcnt lgkmcnt(0)
	v_cvt_pk_bf16_f32 v3, v3, v4
	v_add_co_u32_e32 v4, vcc, 0x4000, v82
	s_nop 1
	v_addc_co_u32_e32 v5, vcc, 0, v83, vcc
	global_store_dword v[4:5], v3, off offset:64 sc1
.LBB0_151:
	s_or_b64 exec, exec, s[0:1]
	v_mul_f32_e32 v3, v22, v2
	s_waitcnt lgkmcnt(0)
	ds_bpermute_b32 v4, v78, v3
	s_and_saveexec_b64 s[0:1], s[38:39]
	s_cbranch_execz .LBB0_153
	s_waitcnt lgkmcnt(0)
	v_cvt_pk_bf16_f32 v3, v3, v4
	v_add_co_u32_e32 v4, vcc, 0x4000, v82
	s_nop 1
	v_addc_co_u32_e32 v5, vcc, 0, v83, vcc
	global_store_dword v[4:5], v3, off offset:128 sc1
.LBB0_153:
	s_or_b64 exec, exec, s[0:1]
	v_mul_f32_e32 v2, v6, v2
	ds_bpermute_b32 v3, v78, v2
	s_and_saveexec_b64 s[0:1], s[38:39]
	s_cbranch_execz .LBB0_155
	s_waitcnt lgkmcnt(0)
	v_cvt_pk_bf16_f32 v4, v2, v3
	v_add_co_u32_e32 v2, vcc, 0x4000, v82
	s_nop 1
	v_addc_co_u32_e32 v3, vcc, 0, v83, vcc
	global_store_dword v[2:3], v4, off offset:192 sc1
.LBB0_155:
	s_or_b64 exec, exec, s[0:1]
	v_rcp_f32_e32 v2, v75
	s_waitcnt lgkmcnt(0)
	v_mul_f32_e32 v3, v55, v2
	ds_bpermute_b32 v4, v78, v3
	s_and_saveexec_b64 s[0:1], s[38:39]
	s_cbranch_execz .LBB0_157
	s_waitcnt lgkmcnt(0)
	v_cvt_pk_bf16_f32 v3, v3, v4
	v_add_co_u32_e32 v4, vcc, 0x4000, v82
	s_nop 1
	v_addc_co_u32_e32 v5, vcc, 0, v83, vcc
	global_store_dword v[4:5], v3, off offset:2048 sc1
.LBB0_157:
	s_or_b64 exec, exec, s[0:1]
	v_mul_f32_e32 v3, v39, v2
	s_waitcnt lgkmcnt(0)
	ds_bpermute_b32 v4, v78, v3
	s_and_saveexec_b64 s[0:1], s[38:39]
	s_cbranch_execz .LBB0_159
	s_waitcnt lgkmcnt(0)
	v_cvt_pk_bf16_f32 v3, v3, v4
	v_add_co_u32_e32 v4, vcc, 0x4000, v82
	s_nop 1
	v_addc_co_u32_e32 v5, vcc, 0, v83, vcc
	global_store_dword v[4:5], v3, off offset:2112 sc1
.LBB0_159:
	s_or_b64 exec, exec, s[0:1]
	v_mul_f32_e32 v3, v23, v2
	s_waitcnt lgkmcnt(0)
	ds_bpermute_b32 v4, v78, v3
	s_and_saveexec_b64 s[0:1], s[38:39]
	s_cbranch_execz .LBB0_161
	s_waitcnt lgkmcnt(0)
	v_cvt_pk_bf16_f32 v3, v3, v4
	v_add_co_u32_e32 v4, vcc, 0x4000, v82
	s_nop 1
	v_addc_co_u32_e32 v5, vcc, 0, v83, vcc
	global_store_dword v[4:5], v3, off offset:2176 sc1
.LBB0_161:
	s_or_b64 exec, exec, s[0:1]
	v_mul_f32_e32 v2, v7, v2
	ds_bpermute_b32 v3, v78, v2
	s_and_saveexec_b64 s[0:1], s[38:39]
	s_cbranch_execz .LBB0_163
	s_waitcnt lgkmcnt(0)
	v_cvt_pk_bf16_f32 v4, v2, v3
	v_add_co_u32_e32 v2, vcc, 0x4000, v82
	s_nop 1
	v_addc_co_u32_e32 v3, vcc, 0, v83, vcc
	global_store_dword v[2:3], v4, off offset:2240 sc1
.LBB0_163:
	s_or_b64 exec, exec, s[0:1]
	v_rcp_f32_e32 v2, v76
	s_waitcnt lgkmcnt(0)
	v_mul_f32_e32 v3, v56, v2
	ds_bpermute_b32 v4, v78, v3
	s_and_saveexec_b64 s[0:1], s[38:39]
	s_cbranch_execz .LBB0_165
	s_waitcnt lgkmcnt(0)
	v_cvt_pk_bf16_f32 v3, v3, v4
	v_add_co_u32_e32 v4, vcc, 0x5000, v82
	s_nop 1
	v_addc_co_u32_e32 v5, vcc, 0, v83, vcc
	global_store_dword v[4:5], v3, off sc1
.LBB0_165:
	s_or_b64 exec, exec, s[0:1]
	v_mul_f32_e32 v3, v40, v2
	s_waitcnt lgkmcnt(0)
	ds_bpermute_b32 v4, v78, v3
	s_and_saveexec_b64 s[0:1], s[38:39]
	s_cbranch_execz .LBB0_167
	s_waitcnt lgkmcnt(0)
	v_cvt_pk_bf16_f32 v3, v3, v4
	v_add_co_u32_e32 v4, vcc, 0x5000, v82
	s_nop 1
	v_addc_co_u32_e32 v5, vcc, 0, v83, vcc
	global_store_dword v[4:5], v3, off offset:64 sc1
.LBB0_167:
	s_or_b64 exec, exec, s[0:1]
	v_mul_f32_e32 v3, v24, v2
	s_waitcnt lgkmcnt(0)
	ds_bpermute_b32 v4, v78, v3
	s_and_saveexec_b64 s[0:1], s[38:39]
	s_cbranch_execz .LBB0_169
	s_waitcnt lgkmcnt(0)
	v_cvt_pk_bf16_f32 v3, v3, v4
	v_add_co_u32_e32 v4, vcc, 0x5000, v82
	s_nop 1
	v_addc_co_u32_e32 v5, vcc, 0, v83, vcc
	global_store_dword v[4:5], v3, off offset:128 sc1
; __device__ __forceinline__ int crow(int r, int hi) { return (r & 3) + 8 * (r >> 2) + 4 * hi; }
; __device__ __forceinline__ unsigned cvtpk(float lo, float hi) { unsigned r; asm volatile("v_cvt_pk_bf16_f32 %0, %1, %2" : "=v"(r) : "v"(lo), "v"(hi)); return r; }
; __device__ __forceinline__ void moba_block(const BlockRef& cur, const BlockRef& nxt, char* lds, Seam& S) {
;     ...
;     for (int r = 0; r < 16; ++r) rli[r] = __builtin_amdgcn_rcpf(li_l[crow(r, hi)]);
;     bf16* Ow = cur.O + (size_t)(wid * QBLK) * OSTR;
; #pragma unroll
;     for (int r = 0; r < 16; ++r) { const int orow = crow(r, hi);
; #pragma unroll
;         for (int d0 = 0; d0 < 4; ++d0) { const float v = o[d0][r] * rli[r];
;             const float vn = __shfl_xor(v, 1);
;             if ((r32 & 1) == 0) *(unsigned*)(Ow + (size_t)orow * OSTR + d0 * 32 + r32) = cvtpk(v, vn); } }
.LBB0_169:
	s_or_b64 exec, exec, s[0:1]
	v_mul_f32_e32 v2, v8, v2
	ds_bpermute_b32 v3, v78, v2
	s_and_saveexec_b64 s[0:1], s[38:39]
	s_cbranch_execz .LBB0_171
	s_waitcnt lgkmcnt(0)
	v_cvt_pk_bf16_f32 v4, v2, v3
	v_add_co_u32_e32 v2, vcc, 0x5000, v82
	s_nop 1
	v_addc_co_u32_e32 v3, vcc, 0, v83, vcc
	global_store_dword v[2:3], v4, off offset:192 sc1
.LBB0_171:
	s_or_b64 exec, exec, s[0:1]
	v_rcp_f32_e32 v2, v77
	s_waitcnt lgkmcnt(0)
	v_mul_f32_e32 v3, v57, v2
	ds_bpermute_b32 v4, v78, v3
	s_and_saveexec_b64 s[0:1], s[38:39]
	s_cbranch_execz .LBB0_173
	s_waitcnt lgkmcnt(0)
	v_cvt_pk_bf16_f32 v3, v3, v4
	v_add_co_u32_e32 v4, vcc, 0x5000, v82
	s_nop 1
	v_addc_co_u32_e32 v5, vcc, 0, v83, vcc
	global_store_dword v[4:5], v3, off offset:2048 sc1
.LBB0_173:
	s_or_b64 exec, exec, s[0:1]
	v_mul_f32_e32 v3, v41, v2
	s_waitcnt lgkmcnt(0)
	ds_bpermute_b32 v4, v78, v3
	s_and_saveexec_b64 s[0:1], s[38:39]
	s_cbranch_execz .LBB0_175
	s_waitcnt lgkmcnt(0)
	v_cvt_pk_bf16_f32 v3, v3, v4
	v_add_co_u32_e32 v4, vcc, 0x5000, v82
	s_nop 1
	v_addc_co_u32_e32 v5, vcc, 0, v83, vcc
	global_store_dword v[4:5], v3, off offset:2112 sc1
.LBB0_175:
	s_or_b64 exec, exec, s[0:1]
	v_mul_f32_e32 v3, v25, v2
	s_waitcnt lgkmcnt(0)
	ds_bpermute_b32 v4, v78, v3
	s_and_saveexec_b64 s[0:1], s[38:39]
	s_cbranch_execz .LBB0_177
	s_waitcnt lgkmcnt(0)
	v_cvt_pk_bf16_f32 v3, v3, v4
	v_add_co_u32_e32 v4, vcc, 0x5000, v82
	s_nop 1
	v_addc_co_u32_e32 v5, vcc, 0, v83, vcc
	global_store_dword v[4:5], v3, off offset:2176 sc1
.LBB0_177:
	s_or_b64 exec, exec, s[0:1]
	v_mul_f32_e32 v2, v9, v2
	ds_bpermute_b32 v3, v78, v2
	s_and_saveexec_b64 s[0:1], s[38:39]
	s_cbranch_execz .LBB0_179
	s_waitcnt lgkmcnt(0)
	v_cvt_pk_bf16_f32 v4, v2, v3
	v_add_co_u32_e32 v2, vcc, 0x5000, v82
	s_nop 1
	v_addc_co_u32_e32 v3, vcc, 0, v83, vcc
	global_store_dword v[2:3], v4, off offset:2240 sc1
.LBB0_179:
	s_or_b64 exec, exec, s[0:1]
	v_rcp_f32_e32 v2, v70
	s_waitcnt lgkmcnt(0)
	v_mul_f32_e32 v3, v58, v2
	ds_bpermute_b32 v4, v78, v3
	s_and_saveexec_b64 s[0:1], s[38:39]
	s_cbranch_execz .LBB0_181
	s_waitcnt lgkmcnt(0)
	v_cvt_pk_bf16_f32 v3, v3, v4
	v_add_co_u32_e32 v4, vcc, 0x8000, v82
	s_nop 1
	v_addc_co_u32_e32 v5, vcc, 0, v83, vcc
	global_store_dword v[4:5], v3, off sc1
.LBB0_181:
	s_or_b64 exec, exec, s[0:1]
	v_mul_f32_e32 v3, v42, v2
	s_waitcnt lgkmcnt(0)
	ds_bpermute_b32 v4, v78, v3
	s_and_saveexec_b64 s[0:1], s[38:39]
	s_cbranch_execz .LBB0_183
	s_waitcnt lgkmcnt(0)
	v_cvt_pk_bf16_f32 v3, v3, v4
	v_add_co_u32_e32 v4, vcc, 0x8000, v82
	s_nop 1
	v_addc_co_u32_e32 v5, vcc, 0, v83, vcc
	global_store_dword v[4:5], v3, off offset:64 sc1
.LBB0_183:
	s_or_b64 exec, exec, s[0:1]
	v_mul_f32_e32 v3, v26, v2
	s_waitcnt lgkmcnt(0)
	ds_bpermute_b32 v4, v78, v3
	s_and_saveexec_b64 s[0:1], s[38:39]
	s_cbranch_execz .LBB0_185
	s_waitcnt lgkmcnt(0)
	v_cvt_pk_bf16_f32 v3, v3, v4
	v_add_co_u32_e32 v4, vcc, 0x8000, v82
	s_nop 1
	v_addc_co_u32_e32 v5, vcc, 0, v83, vcc
	global_store_dword v[4:5], v3, off offset:128 sc1
.LBB0_185:
	s_or_b64 exec, exec, s[0:1]
	v_mul_f32_e32 v2, v10, v2
	ds_bpermute_b32 v3, v78, v2
	s_and_saveexec_b64 s[0:1], s[38:39]
	s_cbranch_execz .LBB0_187
	s_waitcnt lgkmcnt(0)
	v_cvt_pk_bf16_f32 v4, v2, v3
	v_add_co_u32_e32 v2, vcc, 0x8000, v82
	s_nop 1
	v_addc_co_u32_e32 v3, vcc, 0, v83, vcc
	global_store_dword v[2:3], v4, off offset:192 sc1
.LBB0_187:
	s_or_b64 exec, exec, s[0:1]
	v_rcp_f32_e32 v2, v71
	s_waitcnt lgkmcnt(0)
	v_mul_f32_e32 v3, v59, v2
	ds_bpermute_b32 v4, v78, v3
	s_and_saveexec_b64 s[0:1], s[38:39]
	s_cbranch_execz .LBB0_189
	s_waitcnt lgkmcnt(0)
	v_cvt_pk_bf16_f32 v3, v3, v4
	v_add_co_u32_e32 v4, vcc, 0x8000, v82
	s_nop 1
	v_addc_co_u32_e32 v5, vcc, 0, v83, vcc
	global_store_dword v[4:5], v3, off offset:2048 sc1
.LBB0_189:
	s_or_b64 exec, exec, s[0:1]
	v_mul_f32_e32 v3, v43, v2
	s_waitcnt lgkmcnt(0)
	ds_bpermute_b32 v4, v78, v3
	s_and_saveexec_b64 s[0:1], s[38:39]
	s_cbranch_execz .LBB0_191
	s_waitcnt lgkmcnt(0)
	v_cvt_pk_bf16_f32 v3, v3, v4
	v_add_co_u32_e32 v4, vcc, 0x8000, v82
	s_nop 1
	v_addc_co_u32_e32 v5, vcc, 0, v83, vcc
	global_store_dword v[4:5], v3, off offset:2112 sc1
.LBB0_191:
	s_or_b64 exec, exec, s[0:1]
	v_mul_f32_e32 v3, v27, v2
	s_waitcnt lgkmcnt(0)
	ds_bpermute_b32 v4, v78, v3
	s_and_saveexec_b64 s[0:1], s[38:39]
	s_cbranch_execz .LBB0_193
	s_waitcnt lgkmcnt(0)
	v_cvt_pk_bf16_f32 v3, v3, v4
	v_add_co_u32_e32 v4, vcc, 0x8000, v82
	s_nop 1
	v_addc_co_u32_e32 v5, vcc, 0, v83, vcc
	global_store_dword v[4:5], v3, off offset:2176 sc1
.LBB0_193:
	s_or_b64 exec, exec, s[0:1]
	v_mul_f32_e32 v2, v11, v2
	ds_bpermute_b32 v3, v78, v2
	s_and_saveexec_b64 s[0:1], s[38:39]
	s_cbranch_execz .LBB0_195
	s_waitcnt lgkmcnt(0)
	v_cvt_pk_bf16_f32 v4, v2, v3
	v_add_co_u32_e32 v2, vcc, 0x8000, v82
	s_nop 1
	v_addc_co_u32_e32 v3, vcc, 0, v83, vcc
	global_store_dword v[2:3], v4, off offset:2240 sc1
.LBB0_195:
	s_or_b64 exec, exec, s[0:1]
	v_rcp_f32_e32 v2, v72
	s_waitcnt lgkmcnt(0)
	v_mul_f32_e32 v3, v60, v2
	ds_bpermute_b32 v4, v78, v3
	s_and_saveexec_b64 s[0:1], s[38:39]
	s_cbranch_execz .LBB0_197
	s_waitcnt lgkmcnt(0)
	v_cvt_pk_bf16_f32 v3, v3, v4
	v_add_co_u32_e32 v4, vcc, 0x9000, v82
	s_nop 1
	v_addc_co_u32_e32 v5, vcc, 0, v83, vcc
	global_store_dword v[4:5], v3, off sc1
.LBB0_197:
	s_or_b64 exec, exec, s[0:1]
	v_mul_f32_e32 v3, v44, v2
	s_waitcnt lgkmcnt(0)
	ds_bpermute_b32 v4, v78, v3
	s_and_saveexec_b64 s[0:1], s[38:39]
	s_cbranch_execz .LBB0_199
	s_waitcnt lgkmcnt(0)
	v_cvt_pk_bf16_f32 v3, v3, v4
	v_add_co_u32_e32 v4, vcc, 0x9000, v82
	s_nop 1
	v_addc_co_u32_e32 v5, vcc, 0, v83, vcc
	global_store_dword v[4:5], v3, off offset:64 sc1
; __device__ __forceinline__ int crow(int r, int hi) { return (r & 3) + 8 * (r >> 2) + 4 * hi; }
; __device__ __forceinline__ unsigned cvtpk(float lo, float hi) { unsigned r; asm volatile("v_cvt_pk_bf16_f32 %0, %1, %2" : "=v"(r) : "v"(lo), "v"(hi)); return r; }
; __device__ __forceinline__ void moba_block(const BlockRef& cur, const BlockRef& nxt, char* lds, Seam& S) {
;     ...
;     for (int r = 0; r < 16; ++r) rli[r] = __builtin_amdgcn_rcpf(li_l[crow(r, hi)]);
;     bf16* Ow = cur.O + (size_t)(wid * QBLK) * OSTR;
; #pragma unroll
;     for (int r = 0; r < 16; ++r) { const int orow = crow(r, hi);
; #pragma unroll
;         for (int d0 = 0; d0 < 4; ++d0) { const float v = o[d0][r] * rli[r];
;             const float vn = __shfl_xor(v, 1);
;             if ((r32 & 1) == 0) *(unsigned*)(Ow + (size_t)orow * OSTR + d0 * 32 + r32) = cvtpk(v, vn); } }
.LBB0_199:
	s_or_b64 exec, exec, s[0:1]
	v_mul_f32_e32 v3, v28, v2
	s_waitcnt lgkmcnt(0)
	ds_bpermute_b32 v4, v78, v3
	s_and_saveexec_b64 s[0:1], s[38:39]
	s_cbranch_execz .LBB0_201
	s_waitcnt lgkmcnt(0)
	v_cvt_pk_bf16_f32 v3, v3, v4
	v_add_co_u32_e32 v4, vcc, 0x9000, v82
	s_nop 1
	v_addc_co_u32_e32 v5, vcc, 0, v83, vcc
	global_store_dword v[4:5], v3, off offset:128 sc1
.LBB0_201:
	s_or_b64 exec, exec, s[0:1]
	v_mul_f32_e32 v2, v12, v2
	ds_bpermute_b32 v3, v78, v2
	s_and_saveexec_b64 s[0:1], s[38:39]
	s_cbranch_execz .LBB0_203
	s_waitcnt lgkmcnt(0)
	v_cvt_pk_bf16_f32 v4, v2, v3
	v_add_co_u32_e32 v2, vcc, 0x9000, v82
	s_nop 1
	v_addc_co_u32_e32 v3, vcc, 0, v83, vcc
	global_store_dword v[2:3], v4, off offset:192 sc1
.LBB0_203:
	s_or_b64 exec, exec, s[0:1]
	v_rcp_f32_e32 v2, v73
	s_waitcnt lgkmcnt(0)
	v_mul_f32_e32 v3, v61, v2
	ds_bpermute_b32 v4, v78, v3
	s_and_saveexec_b64 s[0:1], s[38:39]
	s_cbranch_execz .LBB0_205
	s_waitcnt lgkmcnt(0)
	v_cvt_pk_bf16_f32 v3, v3, v4
	v_add_co_u32_e32 v4, vcc, 0x9000, v82
	s_nop 1
	v_addc_co_u32_e32 v5, vcc, 0, v83, vcc
	global_store_dword v[4:5], v3, off offset:2048 sc1
.LBB0_205:
	s_or_b64 exec, exec, s[0:1]
	v_mul_f32_e32 v3, v45, v2
	s_waitcnt lgkmcnt(0)
	ds_bpermute_b32 v4, v78, v3
	s_and_saveexec_b64 s[0:1], s[38:39]
	s_cbranch_execz .LBB0_207
	s_waitcnt lgkmcnt(0)
	v_cvt_pk_bf16_f32 v3, v3, v4
	v_add_co_u32_e32 v4, vcc, 0x9000, v82
	s_nop 1
	v_addc_co_u32_e32 v5, vcc, 0, v83, vcc
	global_store_dword v[4:5], v3, off offset:2112 sc1
.LBB0_207:
	s_or_b64 exec, exec, s[0:1]
	v_mul_f32_e32 v3, v29, v2
	s_waitcnt lgkmcnt(0)
	ds_bpermute_b32 v4, v78, v3
	s_and_saveexec_b64 s[0:1], s[38:39]
	s_cbranch_execz .LBB0_209
	s_waitcnt lgkmcnt(0)
	v_cvt_pk_bf16_f32 v3, v3, v4
	v_add_co_u32_e32 v4, vcc, 0x9000, v82
	s_nop 1
	v_addc_co_u32_e32 v5, vcc, 0, v83, vcc
	global_store_dword v[4:5], v3, off offset:2176 sc1
.LBB0_209:
	s_or_b64 exec, exec, s[0:1]
	v_mul_f32_e32 v2, v13, v2
	ds_bpermute_b32 v3, v78, v2
	s_and_saveexec_b64 s[0:1], s[38:39]
	s_cbranch_execz .LBB0_211
	s_waitcnt lgkmcnt(0)
	v_cvt_pk_bf16_f32 v4, v2, v3
	v_add_co_u32_e32 v2, vcc, 0x9000, v82
	s_nop 1
	v_addc_co_u32_e32 v3, vcc, 0, v83, vcc
	global_store_dword v[2:3], v4, off offset:2240 sc1
.LBB0_211:
	s_or_b64 exec, exec, s[0:1]
	v_rcp_f32_e32 v2, v66
	s_waitcnt lgkmcnt(0)
	v_mul_f32_e32 v3, v62, v2
	ds_bpermute_b32 v4, v78, v3
	s_and_saveexec_b64 s[0:1], s[38:39]
	s_cbranch_execz .LBB0_213
	s_waitcnt lgkmcnt(0)
	v_cvt_pk_bf16_f32 v3, v3, v4
	v_add_co_u32_e32 v4, vcc, 0xc000, v82
	s_nop 1
	v_addc_co_u32_e32 v5, vcc, 0, v83, vcc
	global_store_dword v[4:5], v3, off sc1
.LBB0_213:
	s_or_b64 exec, exec, s[0:1]
	v_mul_f32_e32 v3, v46, v2
	s_waitcnt lgkmcnt(0)
	ds_bpermute_b32 v4, v78, v3
	s_and_saveexec_b64 s[0:1], s[38:39]
	s_cbranch_execz .LBB0_215
	s_waitcnt lgkmcnt(0)
	v_cvt_pk_bf16_f32 v3, v3, v4
	v_add_co_u32_e32 v4, vcc, 0xc000, v82
	s_nop 1
	v_addc_co_u32_e32 v5, vcc, 0, v83, vcc
	global_store_dword v[4:5], v3, off offset:64 sc1
.LBB0_215:
	s_or_b64 exec, exec, s[0:1]
	v_mul_f32_e32 v3, v30, v2
	s_waitcnt lgkmcnt(0)
	ds_bpermute_b32 v4, v78, v3
	s_and_saveexec_b64 s[0:1], s[38:39]
	s_cbranch_execz .LBB0_217
	s_waitcnt lgkmcnt(0)
	v_cvt_pk_bf16_f32 v3, v3, v4
	v_add_co_u32_e32 v4, vcc, 0xc000, v82
	s_nop 1
	v_addc_co_u32_e32 v5, vcc, 0, v83, vcc
	global_store_dword v[4:5], v3, off offset:128 sc1
.LBB0_217:
	s_or_b64 exec, exec, s[0:1]
	v_mul_f32_e32 v2, v14, v2
	ds_bpermute_b32 v3, v78, v2
	s_and_saveexec_b64 s[0:1], s[38:39]
	s_cbranch_execz .LBB0_219
	s_waitcnt lgkmcnt(0)
	v_cvt_pk_bf16_f32 v4, v2, v3
	v_add_co_u32_e32 v2, vcc, 0xc000, v82
	s_nop 1
	v_addc_co_u32_e32 v3, vcc, 0, v83, vcc
	global_store_dword v[2:3], v4, off offset:192 sc1
.LBB0_219:
	s_or_b64 exec, exec, s[0:1]
	v_rcp_f32_e32 v2, v67
	s_waitcnt lgkmcnt(0)
	v_mul_f32_e32 v3, v63, v2
	ds_bpermute_b32 v4, v78, v3
	s_and_saveexec_b64 s[0:1], s[38:39]
	s_cbranch_execz .LBB0_221
	s_waitcnt lgkmcnt(0)
	v_cvt_pk_bf16_f32 v3, v3, v4
	v_add_co_u32_e32 v4, vcc, 0xc000, v82
	s_nop 1
	v_addc_co_u32_e32 v5, vcc, 0, v83, vcc
	global_store_dword v[4:5], v3, off offset:2048 sc1
; __device__ __forceinline__ int crow(int r, int hi) { return (r & 3) + 8 * (r >> 2) + 4 * hi; }
; __device__ __forceinline__ unsigned cvtpk(float lo, float hi) { unsigned r; asm volatile("v_cvt_pk_bf16_f32 %0, %1, %2" : "=v"(r) : "v"(lo), "v"(hi)); return r; }
; __device__ __forceinline__ void moba_block(const BlockRef& cur, const BlockRef& nxt, char* lds, Seam& S) {
;     ...
;     for (int r = 0; r < 16; ++r) rli[r] = __builtin_amdgcn_rcpf(li_l[crow(r, hi)]);
;     bf16* Ow = cur.O + (size_t)(wid * QBLK) * OSTR;
; #pragma unroll
;     for (int r = 0; r < 16; ++r) { const int orow = crow(r, hi);
; #pragma unroll
;         for (int d0 = 0; d0 < 4; ++d0) { const float v = o[d0][r] * rli[r];
;             const float vn = __shfl_xor(v, 1);
;             if ((r32 & 1) == 0) *(unsigned*)(Ow + (size_t)orow * OSTR + d0 * 32 + r32) = cvtpk(v, vn); } }
.LBB0_221:
	s_or_b64 exec, exec, s[0:1]
	v_mul_f32_e32 v3, v47, v2
	s_waitcnt lgkmcnt(0)
	ds_bpermute_b32 v4, v78, v3
	s_and_saveexec_b64 s[0:1], s[38:39]
	s_cbranch_execz .LBB0_223
	s_waitcnt lgkmcnt(0)
	v_cvt_pk_bf16_f32 v3, v3, v4
	v_add_co_u32_e32 v4, vcc, 0xc000, v82
	s_nop 1
	v_addc_co_u32_e32 v5, vcc, 0, v83, vcc
	global_store_dword v[4:5], v3, off offset:2112 sc1
.LBB0_223:
	s_or_b64 exec, exec, s[0:1]
	v_mul_f32_e32 v3, v31, v2
	s_waitcnt lgkmcnt(0)
	ds_bpermute_b32 v4, v78, v3
	s_and_saveexec_b64 s[0:1], s[38:39]
	s_cbranch_execz .LBB0_225
	s_waitcnt lgkmcnt(0)
	v_cvt_pk_bf16_f32 v3, v3, v4
	v_add_co_u32_e32 v4, vcc, 0xc000, v82
	s_nop 1
	v_addc_co_u32_e32 v5, vcc, 0, v83, vcc
	global_store_dword v[4:5], v3, off offset:2176 sc1
.LBB0_225:
	s_or_b64 exec, exec, s[0:1]
	v_mul_f32_e32 v2, v15, v2
	ds_bpermute_b32 v3, v78, v2
	s_and_saveexec_b64 s[0:1], s[38:39]
	s_cbranch_execz .LBB0_227
	s_waitcnt lgkmcnt(0)
	v_cvt_pk_bf16_f32 v4, v2, v3
	v_add_co_u32_e32 v2, vcc, 0xc000, v82
	s_nop 1
	v_addc_co_u32_e32 v3, vcc, 0, v83, vcc
	global_store_dword v[2:3], v4, off offset:2240 sc1
.LBB0_227:
	s_or_b64 exec, exec, s[0:1]
	v_rcp_f32_e32 v2, v68
	s_waitcnt lgkmcnt(0)
	v_mul_f32_e32 v3, v64, v2
	ds_bpermute_b32 v4, v78, v3
	s_and_saveexec_b64 s[0:1], s[38:39]
	s_cbranch_execz .LBB0_229
	s_waitcnt lgkmcnt(0)
	v_cvt_pk_bf16_f32 v3, v3, v4
	v_add_co_u32_e32 v4, vcc, 0xd000, v82
	s_nop 1
	v_addc_co_u32_e32 v5, vcc, 0, v83, vcc
	global_store_dword v[4:5], v3, off sc1
.LBB0_229:
	s_or_b64 exec, exec, s[0:1]
	v_mul_f32_e32 v3, v48, v2
	s_waitcnt lgkmcnt(0)
	ds_bpermute_b32 v4, v78, v3
	s_and_saveexec_b64 s[0:1], s[38:39]
	s_cbranch_execz .LBB0_231
	s_waitcnt lgkmcnt(0)
	v_cvt_pk_bf16_f32 v3, v3, v4
	v_add_co_u32_e32 v4, vcc, 0xd000, v82
	s_nop 1
	v_addc_co_u32_e32 v5, vcc, 0, v83, vcc
	global_store_dword v[4:5], v3, off offset:64 sc1
.LBB0_231:
	s_or_b64 exec, exec, s[0:1]
	v_mul_f32_e32 v3, v32, v2
	s_waitcnt lgkmcnt(0)
	ds_bpermute_b32 v4, v78, v3
	s_and_saveexec_b64 s[0:1], s[38:39]
	s_cbranch_execz .LBB0_233
	s_waitcnt lgkmcnt(0)
	v_cvt_pk_bf16_f32 v3, v3, v4
	v_add_co_u32_e32 v4, vcc, 0xd000, v82
	s_nop 1
	v_addc_co_u32_e32 v5, vcc, 0, v83, vcc
	global_store_dword v[4:5], v3, off offset:128 sc1
.LBB0_233:
	s_or_b64 exec, exec, s[0:1]
	v_mul_f32_e32 v2, v16, v2
	ds_bpermute_b32 v3, v78, v2
	s_and_saveexec_b64 s[0:1], s[38:39]
	s_cbranch_execz .LBB0_235
	s_waitcnt lgkmcnt(0)
	v_cvt_pk_bf16_f32 v4, v2, v3
	v_add_co_u32_e32 v2, vcc, 0xd000, v82
	s_nop 1
	v_addc_co_u32_e32 v3, vcc, 0, v83, vcc
	global_store_dword v[2:3], v4, off offset:192 sc1
.LBB0_235:
	s_or_b64 exec, exec, s[0:1]
	v_rcp_f32_e32 v2, v69
	s_waitcnt lgkmcnt(0)
	v_mul_f32_e32 v3, v65, v2
	ds_bpermute_b32 v4, v78, v3
	s_and_saveexec_b64 s[0:1], s[38:39]
	s_cbranch_execz .LBB0_237
	s_waitcnt lgkmcnt(0)
	v_cvt_pk_bf16_f32 v3, v3, v4
	v_add_co_u32_e32 v4, vcc, 0xd000, v82
	s_nop 1
	v_addc_co_u32_e32 v5, vcc, 0, v83, vcc
	global_store_dword v[4:5], v3, off offset:2048 sc1
.LBB0_237:
	s_or_b64 exec, exec, s[0:1]
	v_mul_f32_e32 v3, v49, v2
	s_waitcnt lgkmcnt(0)
	ds_bpermute_b32 v4, v78, v3
	s_and_saveexec_b64 s[0:1], s[38:39]
	s_cbranch_execz .LBB0_239
	s_waitcnt lgkmcnt(0)
	v_cvt_pk_bf16_f32 v3, v3, v4
	v_add_co_u32_e32 v4, vcc, 0xd000, v82
	s_nop 1
	v_addc_co_u32_e32 v5, vcc, 0, v83, vcc
	global_store_dword v[4:5], v3, off offset:2112 sc1
.LBB0_239:
	s_or_b64 exec, exec, s[0:1]
	v_mul_f32_e32 v3, v33, v2
	s_waitcnt lgkmcnt(0)
	ds_bpermute_b32 v4, v78, v3
	s_and_saveexec_b64 s[0:1], s[38:39]
	s_cbranch_execz .LBB0_241
	s_waitcnt lgkmcnt(0)
	v_cvt_pk_bf16_f32 v3, v3, v4
	v_add_co_u32_e32 v4, vcc, 0xd000, v82
	s_nop 1
	v_addc_co_u32_e32 v5, vcc, 0, v83, vcc
	global_store_dword v[4:5], v3, off offset:2176 sc1
.LBB0_241:
	s_or_b64 exec, exec, s[0:1]
	v_mul_f32_e32 v2, v17, v2
	ds_bpermute_b32 v3, v78, v2
	s_and_saveexec_b64 s[0:1], s[38:39]
	s_cbranch_execz .LBB0_243
	s_waitcnt lgkmcnt(0)
	v_cvt_pk_bf16_f32 v4, v2, v3
	v_add_co_u32_e32 v2, vcc, 0xd000, v82
	s_nop 1
	v_addc_co_u32_e32 v3, vcc, 0, v83, vcc
	global_store_dword v[2:3], v4, off offset:2240 sc1

; __device__ __forceinline__ u32x4 pack8(f32x4 a, f32x4 b) { u32x4 w; w.x = cvt_pk_bf16(a[0], a[1]); w.y = cvt_pk_bf16(a[2], a[3]); w.z = cvt_pk_bf16(b[0], b[1]); w.w = cvt_pk_bf16(b[2], b[3]); return w; }
; __device__ __forceinline__ bf16x8 pack8(f32x4 a, f32x4 b) { u32x4 w = {cvtpk(a[0], a[1]), cvtpk(a[2], a[3]), cvtpk(b[0], b[1]), cvtpk(b[2], b[3])}; return *reinterpret_cast<bf16x8*>(&w); }
;     PG8_RSTD_HOOKS
;     __device__ __forceinline__ void operator()(const f32x4 (&acc)[2][2][4][2], const Unit& u, int wr, int wc, int fr, int fq, int par) const {
;         const int row0 = u.pm * BM + wr * 64 + fr;
;         float rsv[2][4]; rstd_read(tab, par, wr, fr, rsv);
; #pragma unroll
;         for (int ai = 0; ai < 2; ++ai)
; #pragma unroll
;             for (int m = 0; m < 4; ++m) { const int row = row0 + ai * HALF + m * 16; const float rs = rsv[ai][m];
;                 if (u.pn < 8) { const float rs2 = rs * rs;
;                     const f32x4 z0 = acc[ai][0][m][0] * acc[ai][1][m][0] * rs2, z1 = acc[ai][0][m][1] * acc[ai][1][m][1] * rs2;
;                     *(u32x4*)(Z + (size_t)row * 1024 + u.pn * 128 + wc * 32 + 8 * fq) = pack8(z0, z1);
;                 } else {
; #pragma unroll
;                     for (int bj = 0; bj < 2; ++bj)
;                         *(u32x4*)(GB + (size_t)row * 1024 + (u.pn - 8) * 256 + bj * HALF + wc * 32 + 8 * fq) = pack8(acc[ai][bj][m][0] * rs, acc[ai][bj][m][1] * rs);
;                 } }
.LBB0_266:
	s_lshl_b32 s0, s42, 10
	s_and_b32 s0, s0, 0x400
	v_add_u32_e32 v140, s0, v171
	ds_read2_b32 v[164:165], v140 offset1:16
	ds_read2_b32 v[162:163], v140 offset0:32 offset1:48
	ds_read2_b32 v[160:161], v140 offset0:128 offset1:144
	ds_read2_b32 v[156:157], v140 offset0:160 offset1:176
	v_lshl_add_u32 v158, s41, 8, v169
	s_cmp_gt_i32 s40, 7
	s_mov_b64 s[6:7], -1
	s_cselect_b64 s[0:1], -1, 0
	s_cmp_lt_i32 s40, 8
	v_ashrrev_i32_e32 v159, 31, v158
	s_cbranch_scc1 .LBB0_268
	v_readlane_b32 s6, v253, 51
	v_lshlrev_b64 v[166:167], 11, v[158:159]
	v_readlane_b32 s7, v253, 52
	s_lshl_b32 s86, s40, 9
	s_waitcnt lgkmcnt(0)
	v_pk_mul_f32 v[142:143], v[138:139], v[164:165] op_sel_hi:[1,0]
	v_lshl_add_u64 v[166:167], s[6:7], 0, v[166:167]
	v_pk_mul_f32 v[140:141], v[136:137], v[164:165] op_sel_hi:[1,0]
	v_pk_mul_f32 v[172:173], v[134:135], v[164:165] op_sel_hi:[1,0]
	v_lshl_add_u64 v[166:167], v[166:167], 0, s[86:87]
	s_lshl_b32 s86, s27, 1
	v_pk_mul_f32 v[174:175], v[132:133], v[164:165] op_sel_hi:[1,0]
	v_cvt_pk_bf16_f32 v140, v140, v141
	v_cvt_pk_bf16_f32 v141, v142, v143
	s_movk_i32 s6, 0xf100
	v_cvt_pk_bf16_f32 v142, v174, v175
	v_cvt_pk_bf16_f32 v143, v172, v173
	v_lshl_add_u64 v[172:173], v[166:167], 0, s[86:87]
	v_lshl_add_u64 v[172:173], v[172:173], 0, v[98:99]
	s_mov_b32 s7, -1
	global_store_dwordx4 v[172:173], v[140:143], off offset:-4096 sc1
	v_lshl_add_u64 v[166:167], v[166:167], 0, s[6:7]
	s_mov_b64 s[6:7], 0
	v_pk_mul_f32 v[142:143], v[130:131], v[164:165] op_sel_hi:[1,0]
	v_pk_mul_f32 v[140:141], v[128:129], v[164:165] op_sel_hi:[1,0]
	v_pk_mul_f32 v[172:173], v[126:127], v[164:165] op_sel_hi:[1,0]
	v_pk_mul_f32 v[174:175], v[124:125], v[164:165] op_sel_hi:[1,0]
	v_cvt_pk_bf16_f32 v140, v140, v141
	v_cvt_pk_bf16_f32 v141, v142, v143
	s_nop 0
	v_cvt_pk_bf16_f32 v142, v174, v175
	v_cvt_pk_bf16_f32 v143, v172, v173

; __device__ __forceinline__ u32x4 pack8(f32x4 a, f32x4 b) { u32x4 w; w.x = cvt_pk_bf16(a[0], a[1]); w.y = cvt_pk_bf16(a[2], a[3]); w.z = cvt_pk_bf16(b[0], b[1]); w.w = cvt_pk_bf16(b[2], b[3]); return w; }
; __device__ __forceinline__ bf16x8 pack8(f32x4 a, f32x4 b) { u32x4 w = {cvtpk(a[0], a[1]), cvtpk(a[2], a[3]), cvtpk(b[0], b[1]), cvtpk(b[2], b[3])}; return *reinterpret_cast<bf16x8*>(&w); }
;     PG8_RSTD_HOOKS
;     __device__ __forceinline__ void operator()(const f32x4 (&acc)[2][2][4][2], const Unit& u, int wr, int wc, int fr, int fq, int par) const {
;     ...
;             for (int m = 0; m < 4; ++m) { const int row = row0 + ai * HALF + m * 16; const float rs = rsv[ai][m];
;                 if (u.pn < 8) { const float rs2 = rs * rs;
;                     const f32x4 z0 = acc[ai][0][m][0] * acc[ai][1][m][0] * rs2, z1 = acc[ai][0][m][1] * acc[ai][1][m][1] * rs2;
;                     *(u32x4*)(Z + (size_t)row * 1024 + u.pn * 128 + wc * 32 + 8 * fq) = pack8(z0, z1);
;                 } else {
; #pragma unroll
;                     for (int bj = 0; bj < 2; ++bj)
;                         *(u32x4*)(GB + (size_t)row * 1024 + (u.pn - 8) * 256 + bj * HALF + wc * 32 + 8 * fq) = pack8(acc[ai][bj][m][0] * rs, acc[ai][bj][m][1] * rs);
;                 } }
.LBB0_270:
	s_lshl_b32 s86, s27, 1
	v_lshl_add_u64 v[124:125], v[166:167], 0, s[86:87]
	v_lshl_add_u64 v[124:125], v[124:125], 0, v[98:99]
	global_store_dwordx4 v[124:125], v[140:143], off sc1
	v_or_b32_e32 v128, 16, v158
	v_cndmask_b32_e64 v124, 0, 1, s[0:1]
	s_mov_b64 s[6:7], -1
	v_cmp_ne_u32_e64 s[38:39], 1, v124
	s_andn2_b64 vcc, exec, s[0:1]
	v_ashrrev_i32_e32 v129, 31, v128
	s_cbranch_vccnz .LBB0_272
	v_readlane_b32 s0, v253, 51
	v_lshlrev_b64 v[130:131], 11, v[128:129]
	v_readlane_b32 s1, v253, 52
	s_waitcnt lgkmcnt(0)
	v_mov_b32_e32 v132, v165
	v_pk_mul_f32 v[126:127], v[122:123], v[132:133] op_sel_hi:[1,0]
	v_lshl_add_u64 v[130:131], s[0:1], 0, v[130:131]
	s_lshl_b32 s0, s40, 9
	s_mov_b32 s1, s87
	v_pk_mul_f32 v[124:125], v[120:121], v[132:133] op_sel_hi:[1,0]
	v_pk_mul_f32 v[134:135], v[118:119], v[132:133] op_sel_hi:[1,0]
	v_lshl_add_u64 v[130:131], v[130:131], 0, s[0:1]
	v_pk_mul_f32 v[136:137], v[116:117], v[132:133] op_sel_hi:[1,0]
	v_cvt_pk_bf16_f32 v124, v124, v125
	v_cvt_pk_bf16_f32 v125, v126, v127
	s_movk_i32 s0, 0xf100
	v_cvt_pk_bf16_f32 v126, v136, v137
	v_cvt_pk_bf16_f32 v127, v134, v135
	v_lshl_add_u64 v[134:135], v[130:131], 0, s[86:87]
	v_lshl_add_u64 v[134:135], v[134:135], 0, v[98:99]
	s_mov_b32 s1, -1
	global_store_dwordx4 v[134:135], v[124:127], off offset:-4096 sc1
	v_lshl_add_u64 v[130:131], v[130:131], 0, s[0:1]
	s_mov_b64 s[6:7], 0
	v_pk_mul_f32 v[126:127], v[114:115], v[132:133] op_sel_hi:[1,0]
	v_pk_mul_f32 v[124:125], v[112:113], v[132:133] op_sel_hi:[1,0]
	v_pk_mul_f32 v[134:135], v[110:111], v[132:133] op_sel_hi:[1,0]
	v_pk_mul_f32 v[132:133], v[108:109], v[132:133] op_sel_hi:[1,0]
	v_cvt_pk_bf16_f32 v124, v124, v125
	v_cvt_pk_bf16_f32 v125, v126, v127
	s_nop 0
	v_cvt_pk_bf16_f32 v126, v132, v133
	v_cvt_pk_bf16_f32 v127, v134, v135

; __device__ __forceinline__ u32x4 pack8(f32x4 a, f32x4 b) { u32x4 w; w.x = cvt_pk_bf16(a[0], a[1]); w.y = cvt_pk_bf16(a[2], a[3]); w.z = cvt_pk_bf16(b[0], b[1]); w.w = cvt_pk_bf16(b[2], b[3]); return w; }
; __device__ __forceinline__ bf16x8 pack8(f32x4 a, f32x4 b) { u32x4 w = {cvtpk(a[0], a[1]), cvtpk(a[2], a[3]), cvtpk(b[0], b[1]), cvtpk(b[2], b[3])}; return *reinterpret_cast<bf16x8*>(&w); }
;     PG8_RSTD_HOOKS
;     __device__ __forceinline__ void operator()(const f32x4 (&acc)[2][2][4][2], const Unit& u, int wr, int wc, int fr, int fq, int par) const {
;     ...
;             for (int m = 0; m < 4; ++m) { const int row = row0 + ai * HALF + m * 16; const float rs = rsv[ai][m];
;                 if (u.pn < 8) { const float rs2 = rs * rs;
;                     const f32x4 z0 = acc[ai][0][m][0] * acc[ai][1][m][0] * rs2, z1 = acc[ai][0][m][1] * acc[ai][1][m][1] * rs2;
;                     *(u32x4*)(Z + (size_t)row * 1024 + u.pn * 128 + wc * 32 + 8 * fq) = pack8(z0, z1);
;                 } else {
; #pragma unroll
;                     for (int bj = 0; bj < 2; ++bj)
;                         *(u32x4*)(GB + (size_t)row * 1024 + (u.pn - 8) * 256 + bj * HALF + wc * 32 + 8 * fq) = pack8(acc[ai][bj][m][0] * rs, acc[ai][bj][m][1] * rs);
;                 } }
.LBB0_274:
	v_lshl_add_u64 v[108:109], v[130:131], 0, s[86:87]
	v_or_b32_e32 v112, 32, v158
	v_lshl_add_u64 v[108:109], v[108:109], 0, v[98:99]
	s_mov_b64 s[0:1], -1
	s_and_b64 vcc, exec, s[38:39]
	v_ashrrev_i32_e32 v113, 31, v112
	global_store_dwordx4 v[108:109], v[124:127], off sc1
	s_cbranch_vccnz .LBB0_276
	v_readlane_b32 s0, v253, 51
	v_lshlrev_b64 v[114:115], 11, v[112:113]
	v_readlane_b32 s1, v253, 52
	s_waitcnt lgkmcnt(0)
	v_pk_mul_f32 v[110:111], v[106:107], v[162:163] op_sel_hi:[1,0]
	v_pk_mul_f32 v[108:109], v[104:105], v[162:163] op_sel_hi:[1,0]
	v_lshl_add_u64 v[114:115], s[0:1], 0, v[114:115]
	s_lshl_b32 s0, s40, 9
	s_mov_b32 s1, s87
	v_pk_mul_f32 v[116:117], v[102:103], v[162:163] op_sel_hi:[1,0]
	v_lshl_add_u64 v[114:115], v[114:115], 0, s[0:1]
	v_pk_mul_f32 v[118:119], v[100:101], v[162:163] op_sel_hi:[1,0]
	v_cvt_pk_bf16_f32 v108, v108, v109
	v_cvt_pk_bf16_f32 v109, v110, v111
	s_movk_i32 s0, 0xf100
	v_cvt_pk_bf16_f32 v110, v118, v119
	v_cvt_pk_bf16_f32 v111, v116, v117
	v_lshl_add_u64 v[116:117], v[114:115], 0, s[86:87]
	v_lshl_add_u64 v[116:117], v[116:117], 0, v[98:99]
	s_mov_b32 s1, -1
	global_store_dwordx4 v[116:117], v[108:111], off offset:-4096 sc1
	v_lshl_add_u64 v[114:115], v[114:115], 0, s[0:1]
	s_mov_b64 s[0:1], 0
	v_pk_mul_f32 v[110:111], v[96:97], v[162:163] op_sel_hi:[1,0]
	v_pk_mul_f32 v[108:109], v[94:95], v[162:163] op_sel_hi:[1,0]
	v_pk_mul_f32 v[116:117], v[92:93], v[162:163] op_sel_hi:[1,0]
	v_pk_mul_f32 v[118:119], v[90:91], v[162:163] op_sel_hi:[1,0]
	v_cvt_pk_bf16_f32 v108, v108, v109
	v_cvt_pk_bf16_f32 v109, v110, v111
	s_nop 0
	v_cvt_pk_bf16_f32 v110, v118, v119
	v_cvt_pk_bf16_f32 v111, v116, v117

; __device__ __forceinline__ u32x4 pack8(f32x4 a, f32x4 b) { u32x4 w; w.x = cvt_pk_bf16(a[0], a[1]); w.y = cvt_pk_bf16(a[2], a[3]); w.z = cvt_pk_bf16(b[0], b[1]); w.w = cvt_pk_bf16(b[2], b[3]); return w; }
; __device__ __forceinline__ bf16x8 pack8(f32x4 a, f32x4 b) { u32x4 w = {cvtpk(a[0], a[1]), cvtpk(a[2], a[3]), cvtpk(b[0], b[1]), cvtpk(b[2], b[3])}; return *reinterpret_cast<bf16x8*>(&w); }
;     PG8_RSTD_HOOKS
;     __device__ __forceinline__ void operator()(const f32x4 (&acc)[2][2][4][2], const Unit& u, int wr, int wc, int fr, int fq, int par) const {
;     ...
;             for (int m = 0; m < 4; ++m) { const int row = row0 + ai * HALF + m * 16; const float rs = rsv[ai][m];
;                 if (u.pn < 8) { const float rs2 = rs * rs;
;                     const f32x4 z0 = acc[ai][0][m][0] * acc[ai][1][m][0] * rs2, z1 = acc[ai][0][m][1] * acc[ai][1][m][1] * rs2;
;                     *(u32x4*)(Z + (size_t)row * 1024 + u.pn * 128 + wc * 32 + 8 * fq) = pack8(z0, z1);
;                 } else {
; #pragma unroll
;                     for (int bj = 0; bj < 2; ++bj)
;                         *(u32x4*)(GB + (size_t)row * 1024 + (u.pn - 8) * 256 + bj * HALF + wc * 32 + 8 * fq) = pack8(acc[ai][bj][m][0] * rs, acc[ai][bj][m][1] * rs);
;                 } }
.LBB0_278:
	v_lshl_add_u64 v[90:91], v[114:115], 0, s[86:87]
	v_or_b32_e32 v94, 48, v158
	v_lshl_add_u64 v[90:91], v[90:91], 0, v[98:99]
	s_mov_b64 s[0:1], -1
	s_and_b64 vcc, exec, s[38:39]
	v_ashrrev_i32_e32 v95, 31, v94
	global_store_dwordx4 v[90:91], v[108:111], off sc1
	s_cbranch_vccnz .LBB0_280
	v_readlane_b32 s0, v253, 51
	v_lshlrev_b64 v[96:97], 11, v[94:95]
	v_readlane_b32 s1, v253, 52
	s_waitcnt lgkmcnt(0)
	v_mov_b32_e32 v100, v163
	v_pk_mul_f32 v[92:93], v[88:89], v[100:101] op_sel_hi:[1,0]
	v_lshl_add_u64 v[96:97], s[0:1], 0, v[96:97]
	s_lshl_b32 s0, s40, 9
	s_mov_b32 s1, s87
	v_pk_mul_f32 v[90:91], v[86:87], v[100:101] op_sel_hi:[1,0]
	v_pk_mul_f32 v[102:103], v[84:85], v[100:101] op_sel_hi:[1,0]
	v_lshl_add_u64 v[96:97], v[96:97], 0, s[0:1]
	v_pk_mul_f32 v[104:105], v[82:83], v[100:101] op_sel_hi:[1,0]
	v_cvt_pk_bf16_f32 v90, v90, v91
	v_cvt_pk_bf16_f32 v91, v92, v93
	s_movk_i32 s0, 0xf100
	v_cvt_pk_bf16_f32 v92, v104, v105
	v_cvt_pk_bf16_f32 v93, v102, v103
	v_lshl_add_u64 v[102:103], v[96:97], 0, s[86:87]
	v_lshl_add_u64 v[102:103], v[102:103], 0, v[98:99]
	s_mov_b32 s1, -1
	global_store_dwordx4 v[102:103], v[90:93], off offset:-4096 sc1
	v_lshl_add_u64 v[96:97], v[96:97], 0, s[0:1]
	s_mov_b64 s[0:1], 0
	v_pk_mul_f32 v[92:93], v[80:81], v[100:101] op_sel_hi:[1,0]
	v_pk_mul_f32 v[90:91], v[78:79], v[100:101] op_sel_hi:[1,0]
	v_pk_mul_f32 v[102:103], v[76:77], v[100:101] op_sel_hi:[1,0]
	v_pk_mul_f32 v[100:101], v[74:75], v[100:101] op_sel_hi:[1,0]
	v_cvt_pk_bf16_f32 v90, v90, v91
	v_cvt_pk_bf16_f32 v91, v92, v93
	s_nop 0
	v_cvt_pk_bf16_f32 v92, v100, v101
	v_cvt_pk_bf16_f32 v93, v102, v103

; __device__ __forceinline__ u32x4 pack8(f32x4 a, f32x4 b) { u32x4 w; w.x = cvt_pk_bf16(a[0], a[1]); w.y = cvt_pk_bf16(a[2], a[3]); w.z = cvt_pk_bf16(b[0], b[1]); w.w = cvt_pk_bf16(b[2], b[3]); return w; }
; __device__ __forceinline__ bf16x8 pack8(f32x4 a, f32x4 b) { u32x4 w = {cvtpk(a[0], a[1]), cvtpk(a[2], a[3]), cvtpk(b[0], b[1]), cvtpk(b[2], b[3])}; return *reinterpret_cast<bf16x8*>(&w); }
;     PG8_RSTD_HOOKS
;     __device__ __forceinline__ void operator()(const f32x4 (&acc)[2][2][4][2], const Unit& u, int wr, int wc, int fr, int fq, int par) const {
;     ...
;             for (int m = 0; m < 4; ++m) { const int row = row0 + ai * HALF + m * 16; const float rs = rsv[ai][m];
;                 if (u.pn < 8) { const float rs2 = rs * rs;
;                     const f32x4 z0 = acc[ai][0][m][0] * acc[ai][1][m][0] * rs2, z1 = acc[ai][0][m][1] * acc[ai][1][m][1] * rs2;
;                     *(u32x4*)(Z + (size_t)row * 1024 + u.pn * 128 + wc * 32 + 8 * fq) = pack8(z0, z1);
;                 } else {
; #pragma unroll
;                     for (int bj = 0; bj < 2; ++bj)
;                         *(u32x4*)(GB + (size_t)row * 1024 + (u.pn - 8) * 256 + bj * HALF + wc * 32 + 8 * fq) = pack8(acc[ai][bj][m][0] * rs, acc[ai][bj][m][1] * rs);
;                 } }
.LBB0_282:
	v_lshl_add_u64 v[74:75], v[96:97], 0, s[86:87]
	v_add_u32_e32 v78, 0x80, v158
	v_lshl_add_u64 v[74:75], v[74:75], 0, v[98:99]
	s_mov_b64 s[0:1], -1
	s_and_b64 vcc, exec, s[38:39]
	v_ashrrev_i32_e32 v79, 31, v78
	global_store_dwordx4 v[74:75], v[90:93], off sc1
	s_cbranch_vccnz .LBB0_284
	v_readlane_b32 s0, v253, 51
	v_lshlrev_b64 v[80:81], 11, v[78:79]
	v_readlane_b32 s1, v253, 52
	s_waitcnt lgkmcnt(0)
	v_pk_mul_f32 v[76:77], v[72:73], v[160:161] op_sel_hi:[1,0]
	v_pk_mul_f32 v[74:75], v[70:71], v[160:161] op_sel_hi:[1,0]
	v_lshl_add_u64 v[80:81], s[0:1], 0, v[80:81]
	s_lshl_b32 s0, s40, 9
	s_mov_b32 s1, s87
	v_pk_mul_f32 v[82:83], v[68:69], v[160:161] op_sel_hi:[1,0]
	v_lshl_add_u64 v[80:81], v[80:81], 0, s[0:1]
	v_pk_mul_f32 v[84:85], v[66:67], v[160:161] op_sel_hi:[1,0]
	v_cvt_pk_bf16_f32 v74, v74, v75
	v_cvt_pk_bf16_f32 v75, v76, v77
	s_movk_i32 s0, 0xf100
	v_cvt_pk_bf16_f32 v76, v84, v85
	v_cvt_pk_bf16_f32 v77, v82, v83
	v_lshl_add_u64 v[82:83], v[80:81], 0, s[86:87]
	v_lshl_add_u64 v[82:83], v[82:83], 0, v[98:99]
	s_mov_b32 s1, -1
	global_store_dwordx4 v[82:83], v[74:77], off offset:-4096 sc1
	v_lshl_add_u64 v[80:81], v[80:81], 0, s[0:1]
	s_mov_b64 s[0:1], 0
	v_pk_mul_f32 v[76:77], v[64:65], v[160:161] op_sel_hi:[1,0]
	v_pk_mul_f32 v[74:75], v[62:63], v[160:161] op_sel_hi:[1,0]
	v_pk_mul_f32 v[82:83], v[60:61], v[160:161] op_sel_hi:[1,0]
	v_pk_mul_f32 v[84:85], v[58:59], v[160:161] op_sel_hi:[1,0]
	v_cvt_pk_bf16_f32 v74, v74, v75
	v_cvt_pk_bf16_f32 v75, v76, v77
	s_nop 0
	v_cvt_pk_bf16_f32 v76, v84, v85
	v_cvt_pk_bf16_f32 v77, v82, v83

; __device__ __forceinline__ u32x4 pack8(f32x4 a, f32x4 b) { u32x4 w; w.x = cvt_pk_bf16(a[0], a[1]); w.y = cvt_pk_bf16(a[2], a[3]); w.z = cvt_pk_bf16(b[0], b[1]); w.w = cvt_pk_bf16(b[2], b[3]); return w; }
; __device__ __forceinline__ bf16x8 pack8(f32x4 a, f32x4 b) { u32x4 w = {cvtpk(a[0], a[1]), cvtpk(a[2], a[3]), cvtpk(b[0], b[1]), cvtpk(b[2], b[3])}; return *reinterpret_cast<bf16x8*>(&w); }
;     PG8_RSTD_HOOKS
;     __device__ __forceinline__ void operator()(const f32x4 (&acc)[2][2][4][2], const Unit& u, int wr, int wc, int fr, int fq, int par) const {
;     ...
;             for (int m = 0; m < 4; ++m) { const int row = row0 + ai * HALF + m * 16; const float rs = rsv[ai][m];
;                 if (u.pn < 8) { const float rs2 = rs * rs;
;                     const f32x4 z0 = acc[ai][0][m][0] * acc[ai][1][m][0] * rs2, z1 = acc[ai][0][m][1] * acc[ai][1][m][1] * rs2;
;                     *(u32x4*)(Z + (size_t)row * 1024 + u.pn * 128 + wc * 32 + 8 * fq) = pack8(z0, z1);
;                 } else {
; #pragma unroll
;                     for (int bj = 0; bj < 2; ++bj)
;                         *(u32x4*)(GB + (size_t)row * 1024 + (u.pn - 8) * 256 + bj * HALF + wc * 32 + 8 * fq) = pack8(acc[ai][bj][m][0] * rs, acc[ai][bj][m][1] * rs);
;                 } }
.LBB0_286:
	v_lshl_add_u64 v[58:59], v[80:81], 0, s[86:87]
	v_add_u32_e32 v62, 0x90, v158
	v_lshl_add_u64 v[58:59], v[58:59], 0, v[98:99]
	s_mov_b64 s[0:1], -1
	s_and_b64 vcc, exec, s[38:39]
	v_ashrrev_i32_e32 v63, 31, v62
	global_store_dwordx4 v[58:59], v[74:77], off sc1
	s_cbranch_vccnz .LBB0_288
	v_readlane_b32 s0, v253, 51
	v_lshlrev_b64 v[64:65], 11, v[62:63]
	v_readlane_b32 s1, v253, 52
	s_waitcnt lgkmcnt(0)
	v_mov_b32_e32 v66, v161
	v_pk_mul_f32 v[60:61], v[56:57], v[66:67] op_sel_hi:[1,0]
	v_lshl_add_u64 v[64:65], s[0:1], 0, v[64:65]
	s_lshl_b32 s0, s40, 9
	s_mov_b32 s1, s87
	v_pk_mul_f32 v[58:59], v[54:55], v[66:67] op_sel_hi:[1,0]
	v_pk_mul_f32 v[68:69], v[52:53], v[66:67] op_sel_hi:[1,0]
	v_lshl_add_u64 v[64:65], v[64:65], 0, s[0:1]
	v_pk_mul_f32 v[70:71], v[50:51], v[66:67] op_sel_hi:[1,0]
	v_cvt_pk_bf16_f32 v58, v58, v59
	v_cvt_pk_bf16_f32 v59, v60, v61
	s_movk_i32 s0, 0xf100
	v_cvt_pk_bf16_f32 v60, v70, v71
	v_cvt_pk_bf16_f32 v61, v68, v69
	v_lshl_add_u64 v[68:69], v[64:65], 0, s[86:87]
	v_lshl_add_u64 v[68:69], v[68:69], 0, v[98:99]
	s_mov_b32 s1, -1
	global_store_dwordx4 v[68:69], v[58:61], off offset:-4096 sc1
	v_lshl_add_u64 v[64:65], v[64:65], 0, s[0:1]
	s_mov_b64 s[0:1], 0
	v_pk_mul_f32 v[60:61], v[48:49], v[66:67] op_sel_hi:[1,0]
	v_pk_mul_f32 v[58:59], v[46:47], v[66:67] op_sel_hi:[1,0]
	v_pk_mul_f32 v[68:69], v[44:45], v[66:67] op_sel_hi:[1,0]
	v_pk_mul_f32 v[66:67], v[42:43], v[66:67] op_sel_hi:[1,0]
	v_cvt_pk_bf16_f32 v58, v58, v59
	v_cvt_pk_bf16_f32 v59, v60, v61
	s_nop 0
	v_cvt_pk_bf16_f32 v60, v66, v67
	v_cvt_pk_bf16_f32 v61, v68, v69

; __device__ __forceinline__ u32x4 pack8(f32x4 a, f32x4 b) { u32x4 w; w.x = cvt_pk_bf16(a[0], a[1]); w.y = cvt_pk_bf16(a[2], a[3]); w.z = cvt_pk_bf16(b[0], b[1]); w.w = cvt_pk_bf16(b[2], b[3]); return w; }
; __device__ __forceinline__ bf16x8 pack8(f32x4 a, f32x4 b) { u32x4 w = {cvtpk(a[0], a[1]), cvtpk(a[2], a[3]), cvtpk(b[0], b[1]), cvtpk(b[2], b[3])}; return *reinterpret_cast<bf16x8*>(&w); }
;     PG8_RSTD_HOOKS
;     __device__ __forceinline__ void operator()(const f32x4 (&acc)[2][2][4][2], const Unit& u, int wr, int wc, int fr, int fq, int par) const {
;     ...
;             for (int m = 0; m < 4; ++m) { const int row = row0 + ai * HALF + m * 16; const float rs = rsv[ai][m];
;                 if (u.pn < 8) { const float rs2 = rs * rs;
;                     const f32x4 z0 = acc[ai][0][m][0] * acc[ai][1][m][0] * rs2, z1 = acc[ai][0][m][1] * acc[ai][1][m][1] * rs2;
;                     *(u32x4*)(Z + (size_t)row * 1024 + u.pn * 128 + wc * 32 + 8 * fq) = pack8(z0, z1);
;                 } else {
; #pragma unroll
;                     for (int bj = 0; bj < 2; ++bj)
;                         *(u32x4*)(GB + (size_t)row * 1024 + (u.pn - 8) * 256 + bj * HALF + wc * 32 + 8 * fq) = pack8(acc[ai][bj][m][0] * rs, acc[ai][bj][m][1] * rs);
;                 } }
.LBB0_290:
	v_lshl_add_u64 v[42:43], v[64:65], 0, s[86:87]
	v_add_u32_e32 v46, 0xa0, v158
	v_lshl_add_u64 v[42:43], v[42:43], 0, v[98:99]
	s_mov_b64 s[0:1], -1
	s_and_b64 vcc, exec, s[38:39]
	v_ashrrev_i32_e32 v47, 31, v46
	global_store_dwordx4 v[42:43], v[58:61], off sc1
	s_cbranch_vccnz .LBB0_292
	v_readlane_b32 s0, v253, 51
	v_lshlrev_b64 v[48:49], 11, v[46:47]
	v_readlane_b32 s1, v253, 52
	s_waitcnt lgkmcnt(0)
	v_pk_mul_f32 v[44:45], v[40:41], v[156:157] op_sel_hi:[1,0]
	v_pk_mul_f32 v[42:43], v[38:39], v[156:157] op_sel_hi:[1,0]
	v_lshl_add_u64 v[48:49], s[0:1], 0, v[48:49]
	s_lshl_b32 s0, s40, 9
	s_mov_b32 s1, s87
	v_pk_mul_f32 v[50:51], v[36:37], v[156:157] op_sel_hi:[1,0]
	v_lshl_add_u64 v[48:49], v[48:49], 0, s[0:1]
	v_pk_mul_f32 v[52:53], v[34:35], v[156:157] op_sel_hi:[1,0]
	v_cvt_pk_bf16_f32 v42, v42, v43
	v_cvt_pk_bf16_f32 v43, v44, v45
	s_movk_i32 s0, 0xf100
	v_cvt_pk_bf16_f32 v44, v52, v53
	v_cvt_pk_bf16_f32 v45, v50, v51
	v_lshl_add_u64 v[50:51], v[48:49], 0, s[86:87]
	v_lshl_add_u64 v[50:51], v[50:51], 0, v[98:99]
	s_mov_b32 s1, -1
	global_store_dwordx4 v[50:51], v[42:45], off offset:-4096 sc1
	v_lshl_add_u64 v[48:49], v[48:49], 0, s[0:1]
	s_mov_b64 s[0:1], 0
	v_pk_mul_f32 v[44:45], v[32:33], v[156:157] op_sel_hi:[1,0]
	v_pk_mul_f32 v[42:43], v[30:31], v[156:157] op_sel_hi:[1,0]
	v_pk_mul_f32 v[50:51], v[28:29], v[156:157] op_sel_hi:[1,0]
	v_pk_mul_f32 v[52:53], v[26:27], v[156:157] op_sel_hi:[1,0]
	v_cvt_pk_bf16_f32 v42, v42, v43
	v_cvt_pk_bf16_f32 v43, v44, v45
	s_nop 0
	v_cvt_pk_bf16_f32 v44, v52, v53
	v_cvt_pk_bf16_f32 v45, v50, v51

; __device__ __forceinline__ u32x4 pack8(f32x4 a, f32x4 b) { u32x4 w; w.x = cvt_pk_bf16(a[0], a[1]); w.y = cvt_pk_bf16(a[2], a[3]); w.z = cvt_pk_bf16(b[0], b[1]); w.w = cvt_pk_bf16(b[2], b[3]); return w; }
; __device__ __forceinline__ bf16x8 pack8(f32x4 a, f32x4 b) { u32x4 w = {cvtpk(a[0], a[1]), cvtpk(a[2], a[3]), cvtpk(b[0], b[1]), cvtpk(b[2], b[3])}; return *reinterpret_cast<bf16x8*>(&w); }
;     PG8_RSTD_HOOKS
;     __device__ __forceinline__ void operator()(const f32x4 (&acc)[2][2][4][2], const Unit& u, int wr, int wc, int fr, int fq, int par) const {
;     ...
;             for (int m = 0; m < 4; ++m) { const int row = row0 + ai * HALF + m * 16; const float rs = rsv[ai][m];
;                 if (u.pn < 8) { const float rs2 = rs * rs;
;                     const f32x4 z0 = acc[ai][0][m][0] * acc[ai][1][m][0] * rs2, z1 = acc[ai][0][m][1] * acc[ai][1][m][1] * rs2;
;                     *(u32x4*)(Z + (size_t)row * 1024 + u.pn * 128 + wc * 32 + 8 * fq) = pack8(z0, z1);
;                 } else {
; #pragma unroll
;                     for (int bj = 0; bj < 2; ++bj)
;                         *(u32x4*)(GB + (size_t)row * 1024 + (u.pn - 8) * 256 + bj * HALF + wc * 32 + 8 * fq) = pack8(acc[ai][bj][m][0] * rs, acc[ai][bj][m][1] * rs);
;                 } }
.LBB0_294:
	v_lshl_add_u64 v[26:27], v[48:49], 0, s[86:87]
	v_add_u32_e32 v30, 0xb0, v158
	v_lshl_add_u64 v[26:27], v[26:27], 0, v[98:99]
	s_mov_b64 s[0:1], -1
	s_and_b64 vcc, exec, s[38:39]
	v_ashrrev_i32_e32 v31, 31, v30
	global_store_dwordx4 v[26:27], v[42:45], off sc1
	s_cbranch_vccnz .LBB0_296
	v_readlane_b32 s0, v253, 51
	v_lshlrev_b64 v[32:33], 11, v[30:31]
	v_readlane_b32 s1, v253, 52
	s_waitcnt lgkmcnt(0)
	v_mov_b32_e32 v34, v157
	v_pk_mul_f32 v[28:29], v[24:25], v[34:35] op_sel_hi:[1,0]
	v_lshl_add_u64 v[32:33], s[0:1], 0, v[32:33]
	s_lshl_b32 s0, s40, 9
	s_mov_b32 s1, s87
	v_pk_mul_f32 v[26:27], v[22:23], v[34:35] op_sel_hi:[1,0]
	v_pk_mul_f32 v[36:37], v[20:21], v[34:35] op_sel_hi:[1,0]
	v_lshl_add_u64 v[32:33], v[32:33], 0, s[0:1]
	v_pk_mul_f32 v[38:39], v[18:19], v[34:35] op_sel_hi:[1,0]
	v_cvt_pk_bf16_f32 v26, v26, v27
	v_cvt_pk_bf16_f32 v27, v28, v29
	s_movk_i32 s0, 0xf100
	v_cvt_pk_bf16_f32 v28, v38, v39
	v_cvt_pk_bf16_f32 v29, v36, v37
	v_lshl_add_u64 v[36:37], v[32:33], 0, s[86:87]
	v_lshl_add_u64 v[36:37], v[36:37], 0, v[98:99]
	s_mov_b32 s1, -1
	global_store_dwordx4 v[36:37], v[26:29], off offset:-4096 sc1
	v_lshl_add_u64 v[32:33], v[32:33], 0, s[0:1]
	s_mov_b64 s[0:1], 0
	v_pk_mul_f32 v[28:29], v[16:17], v[34:35] op_sel_hi:[1,0]
	v_pk_mul_f32 v[26:27], v[14:15], v[34:35] op_sel_hi:[1,0]
	v_pk_mul_f32 v[36:37], v[12:13], v[34:35] op_sel_hi:[1,0]
	v_pk_mul_f32 v[34:35], v[10:11], v[34:35] op_sel_hi:[1,0]
	v_cvt_pk_bf16_f32 v26, v26, v27
	v_cvt_pk_bf16_f32 v27, v28, v29
	s_nop 0
	v_cvt_pk_bf16_f32 v28, v34, v35
	v_cvt_pk_bf16_f32 v29, v36, v37

; __device__ __forceinline__ int opaque_tid() { int t = threadIdx.x; asm volatile("" : "+v"(t)); return t; }
; #define PG8_LAS __attribute__((address_space(3)))
; __device__ __forceinline__ u32x4 pack8(f32x4 a, f32x4 b) { u32x4 w; w.x = cvt_pk_bf16(a[0], a[1]); w.y = cvt_pk_bf16(a[2], a[3]); w.z = cvt_pk_bf16(b[0], b[1]); w.w = cvt_pk_bf16(b[2], b[3]); return w; }
; __device__ __forceinline__ bf16x8 pack8(f32x4 a, f32x4 b) { u32x4 w = {cvtpk(a[0], a[1]), cvtpk(a[2], a[3]), cvtpk(b[0], b[1]), cvtpk(b[2], b[3])}; return *reinterpret_cast<bf16x8*>(&w); }
; __device__ __forceinline__ void rstd_store(PG8_LAS float* tab, const RstdIni& ini, int par) {
;     const int tid = opaque_tid();
;     float s = ((ini.a[0] + ini.a[1]) + (ini.a[2] + ini.a[3])) + ((ini.b[0] + ini.b[1]) + (ini.b[2] + ini.b[3]));
;     s += __shfl_xor(s, 1);
;     if (!(tid & 1)) tab[par * BM + (tid >> 1)] = __builtin_amdgcn_rsqf(s * (1.0f / 1024.0f) + 1e-6f);
; }
;     PG8_RSTD_HOOKS
;     __device__ __forceinline__ void operator()(const f32x4 (&acc)[2][2][4][2], const Unit& u, int wr, int wc, int fr, int fq, int par) const {
;     ...
;             for (int m = 0; m < 4; ++m) { const int row = row0 + ai * HALF + m * 16; const float rs = rsv[ai][m];
;                 if (u.pn < 8) { const float rs2 = rs * rs;
;                     const f32x4 z0 = acc[ai][0][m][0] * acc[ai][1][m][0] * rs2, z1 = acc[ai][0][m][1] * acc[ai][1][m][1] * rs2;
;                     *(u32x4*)(Z + (size_t)row * 1024 + u.pn * 128 + wc * 32 + 8 * fq) = pack8(z0, z1);
;                 } else {
; #pragma unroll
;                     for (int bj = 0; bj < 2; ++bj)
;                         *(u32x4*)(GB + (size_t)row * 1024 + (u.pn - 8) * 256 + bj * HALF + wc * 32 + 8 * fq) = pack8(acc[ai][bj][m][0] * rs, acc[ai][bj][m][1] * rs);
;                 } }
.LBB0_298:
	v_lshl_add_u64 v[10:11], v[32:33], 0, s[86:87]
	v_lshl_add_u64 v[10:11], v[10:11], 0, v[98:99]
	s_and_b64 vcc, exec, s[36:37]
	s_mov_b64 s[0:1], -1
	global_store_dwordx4 v[10:11], v[26:29], off sc1
	s_cbranch_vccnz .LBB0_257
	s_waitcnt vmcnt(0)
	v_add_f32_e32 v10, v6, v7
	v_add_f32_e32 v11, v8, v9
	v_add_f32_e32 v10, v10, v11
	v_add_f32_e32 v11, v2, v3
	v_add_f32_e32 v12, v4, v5
	v_add_f32_e32 v11, v11, v12
	v_add_f32_e32 v11, v11, v10
	ds_bpermute_b32 v12, v168, v11
	v_mov_b32_e32 v10, v0
	s_nop 0
	v_and_b32_e32 v13, 1, v10
	v_cmp_eq_u32_e32 vcc, 0, v13
	s_and_saveexec_b64 s[0:1], vcc
	s_cbranch_execz .LBB0_301
	s_waitcnt lgkmcnt(0)
	v_add_f32_e32 v11, v11, v12
	s_lshl_b32 s6, s31, 10
	v_fmamk_f32 v11, v11, 0x3a800000, v1
	s_and_b32 s6, s6, 0x400
	v_rsq_f32_e32 v11, v11
	s_add_i32 s6, s6, 0
	v_lshl_add_u32 v10, v10, 1, s6
	v_add_u32_e32 v10, 0x21000, v10
	ds_write_b32 v10, v11

; __device__ __forceinline__ unsigned pk2(float lo, float hi) { return pg8::cvt_pk_bf16(lo, hi); }
; __device__ __forceinline__ f32x4 ld4bf(const bf16* p) { const v2u w = *(const v2u*)p; return (f32x4){bf_lo(w.x), bf_hi(w.x), bf_lo(w.y), bf_hi(w.y)}; }
; __device__ __forceinline__ void pool_prep(const bf16* X, const float* ss, const float* gain, bf16* PB, LAS unsigned char* lds, int vcu, int G, int tid) {
;     ...
;         for (int i = 0; i < 32; ++i) { const int row = ra + i, t = row - bstart;
;             const f32x4 xn = ld4bf(xp + (size_t)row * DM) * rsl[row - r0 + 16];
;             f32x4 old = {0.f, 0.f, 0.f, 0.f};
;             if (t >= w) old = ld4bf(xp + (size_t)(row - w) * DM) * rsl[row - w - r0 + 16];
;             S = S + xn - old;
;             const int cnt = (t + 1 < w) ? t + 1 : w;
;             const f32x4 p = (S * (1.0f / (float)cnt) - xn) * gn;
;             v2u o; o.x = pk2(p[0], p[1]); o.y = pk2(p[2], p[3]); *(v2u*)(PB + (size_t)row * DM + 4 * q) = o; }
.LBB0_346:
	s_or_b64 exec, exec, s[0:1]
	s_waitcnt vmcnt(0)
	v_lshlrev_b32_e32 v26, 16, v22
	v_and_b32_e32 v27, 0xffff0000, v22
	v_lshlrev_b32_e32 v22, 16, v23
	v_and_b32_e32 v23, 0xffff0000, v23
	s_waitcnt lgkmcnt(0)
	v_pk_mul_f32 v[28:29], v[16:17], v[22:23] op_sel_hi:[0,1]
	v_pk_mul_f32 v[42:43], v[16:17], v[26:27] op_sel_hi:[0,1]
	v_pk_fma_f32 v[18:19], v[16:17], v[26:27], v[18:19] op_sel_hi:[0,1,1]
	v_add_u32_e32 v17, 8, v41
	v_min_i32_e32 v17, v17, v32
	v_cvt_f32_i32_e32 v17, v17
	v_sub_f32_e32 v6, v18, v6
	v_sub_f32_e32 v7, v19, v7
	v_lshlrev_b64 v[20:21], 10, v[20:21]
	v_pk_fma_f32 v[8:9], v[16:17], v[22:23], v[8:9] op_sel_hi:[0,1,1]
	v_div_scale_f32 v16, s[0:1], v17, v17, 1.0
	v_rcp_f32_e32 v22, v16
	v_sub_f32_e32 v9, v9, v25
	v_sub_f32_e32 v8, v8, v24
	s_add_i32 s6, s6, 8
	v_fma_f32 v18, -v16, v22, 1.0
	v_fmac_f32_e32 v22, v18, v22
	v_div_scale_f32 v18, vcc, 1.0, v17, 1.0
	v_mul_f32_e32 v19, v18, v22
	v_fma_f32 v23, -v16, v19, v18
	v_fmac_f32_e32 v19, v23, v22
	v_fma_f32 v16, -v16, v19, v18
	v_div_fmas_f32 v16, v16, v22, v19
	v_div_fixup_f32 v16, v16, v17, 1.0
	v_pk_fma_f32 v[18:19], v[16:17], v[6:7], v[42:43] op_sel_hi:[0,1,1] neg_lo:[0,0,1] neg_hi:[0,0,1]
	v_pk_fma_f32 v[16:17], v[16:17], v[8:9], v[28:29] op_sel_hi:[0,1,1] neg_lo:[0,0,1] neg_hi:[0,0,1]
	v_pk_mul_f32 v[16:17], v[4:5], v[16:17]
	v_pk_mul_f32 v[18:19], v[2:3], v[18:19]
	s_cmp_eq_u32 s6, 32
	v_cvt_pk_bf16_f32 v18, v18, v19
	v_cvt_pk_bf16_f32 v19, v16, v17
	v_lshl_add_u64 v[16:17], v[20:21], 1, v[14:15]
	v_add_u32_e32 v40, 32, v40
	global_store_dwordx2 v[16:17], v[18:19], off sc1
	s_cbranch_scc1 .LBB0_308

; __device__ __forceinline__ unsigned pk2(float lo, float hi) { return pg8::cvt_pk_bf16(lo, hi); }
; __device__ __forceinline__ f32x4 ld4bf(const bf16* p) { const v2u w = *(const v2u*)p; return (f32x4){bf_lo(w.x), bf_hi(w.x), bf_lo(w.y), bf_hi(w.y)}; }
; __device__ __forceinline__ void pool_prep(const bf16* X, const float* ss, const float* gain, bf16* PB, LAS unsigned char* lds, int vcu, int G, int tid) {
;     ...
;         for (int i = 0; i < 32; ++i) { const int row = ra + i, t = row - bstart;
;             const f32x4 xn = ld4bf(xp + (size_t)row * DM) * rsl[row - r0 + 16];
;             f32x4 old = {0.f, 0.f, 0.f, 0.f};
;             if (t >= w) old = ld4bf(xp + (size_t)(row - w) * DM) * rsl[row - w - r0 + 16];
;             S = S + xn - old;
;             const int cnt = (t + 1 < w) ? t + 1 : w;
;             const f32x4 p = (S * (1.0f / (float)cnt) - xn) * gn;
;             v2u o; o.x = pk2(p[0], p[1]); o.y = pk2(p[2], p[3]); *(v2u*)(PB + (size_t)row * DM + 4 * q) = o; }
.LBB0_349:
	s_or_b64 exec, exec, s[0:1]
	v_lshlrev_b64 v[28:29], 10, v[16:17]
	s_waitcnt vmcnt(0)
	v_lshlrev_b32_e32 v44, 16, v22
	v_and_b32_e32 v45, 0xffff0000, v22
	v_add_u32_e32 v17, 1, v41
	s_waitcnt lgkmcnt(0)
	v_pk_mul_f32 v[48:49], v[20:21], v[44:45] op_sel_hi:[0,1]
	v_pk_fma_f32 v[44:45], v[20:21], v[44:45], v[6:7] op_sel_hi:[0,1,1]
	v_min_i32_e32 v6, v17, v32
	v_cvt_f32_i32_e32 v19, v6
	v_lshlrev_b32_e32 v22, 16, v23
	v_and_b32_e32 v23, 0xffff0000, v23
	v_pk_mul_f32 v[46:47], v[20:21], v[22:23] op_sel_hi:[0,1]
	v_pk_fma_f32 v[6:7], v[20:21], v[22:23], v[8:9] op_sel_hi:[0,1,1]
	v_div_scale_f32 v20, s[0:1], v19, v19, 1.0
	v_rcp_f32_e32 v21, v20
	v_sub_f32_e32 v8, v44, v24
	v_sub_f32_e32 v7, v7, v27
	v_sub_f32_e32 v6, v6, v26
	v_fma_f32 v22, -v20, v21, 1.0
	v_fmac_f32_e32 v21, v22, v21
	v_div_scale_f32 v22, vcc, 1.0, v19, 1.0
	v_mul_f32_e32 v23, v22, v21
	v_fma_f32 v24, -v20, v23, v22
	v_fmac_f32_e32 v23, v24, v21
	v_fma_f32 v20, -v20, v23, v22
	v_div_fmas_f32 v20, v20, v21, v23
	v_sub_f32_e32 v9, v45, v25
	v_div_fixup_f32 v20, v20, v19, 1.0
	v_pk_fma_f32 v[22:23], v[20:21], v[8:9], v[48:49] op_sel_hi:[0,1,1] neg_lo:[0,0,1] neg_hi:[0,0,1]
	v_pk_fma_f32 v[20:21], v[20:21], v[6:7], v[46:47] op_sel_hi:[0,1,1] neg_lo:[0,0,1] neg_hi:[0,0,1]
	v_pk_mul_f32 v[20:21], v[4:5], v[20:21]
	v_pk_mul_f32 v[22:23], v[2:3], v[22:23]
	v_cmp_ge_i32_e32 vcc, v17, v32
	v_cvt_pk_bf16_f32 v22, v22, v23
	v_cvt_pk_bf16_f32 v23, v20, v21
	v_lshl_add_u64 v[20:21], v[28:29], 1, v[14:15]
	global_store_dwordx2 v[20:21], v[22:23], off sc1
	v_add_u32_e32 v22, 1, v16
	v_ashrrev_i32_e32 v23, 31, v22
	v_lshlrev_b64 v[20:21], 11, v[22:23]
	v_lshl_add_u64 v[20:21], v[12:13], 0, v[20:21]
	global_load_dwordx2 v[24:25], v[20:21], off
	ds_read_b32 v20, v40 offset:4
	v_mov_b32_e32 v19, 0
	v_mov_b32_e32 v26, 0
	v_mov_b32_e32 v27, 0
	s_and_saveexec_b64 s[0:1], vcc
	s_cbranch_execz .LBB0_351
	v_add3_u32 v18, v38, s6, 1
	v_ashrrev_i32_e32 v19, 31, v18
	v_lshlrev_b64 v[18:19], 11, v[18:19]
	v_lshl_add_u64 v[18:19], v[12:13], 0, v[18:19]
	global_load_dwordx2 v[18:19], v[18:19], off
	ds_read_b32 v28, v42 offset:4
	s_waitcnt vmcnt(0)
	v_lshlrev_b32_e32 v44, 16, v18
	v_and_b32_e32 v45, 0xffff0000, v18
	v_lshlrev_b32_e32 v18, 16, v19
	v_and_b32_e32 v19, 0xffff0000, v19
	s_waitcnt lgkmcnt(0)
	v_pk_mul_f32 v[26:27], v[28:29], v[18:19] op_sel_hi:[0,1]
	v_pk_mul_f32 v[18:19], v[28:29], v[44:45] op_sel_hi:[0,1]
.LBB0_351:
	s_or_b64 exec, exec, s[0:1]
	s_waitcnt vmcnt(0)
	v_lshlrev_b32_e32 v28, 16, v24
	v_and_b32_e32 v29, 0xffff0000, v24
	v_add_u32_e32 v17, 2, v41
	v_lshlrev_b32_e32 v24, 16, v25
	v_and_b32_e32 v25, 0xffff0000, v25
	s_waitcnt lgkmcnt(0)
	v_pk_mul_f32 v[46:47], v[20:21], v[28:29] op_sel_hi:[0,1]
	v_pk_fma_f32 v[28:29], v[20:21], v[28:29], v[8:9] op_sel_hi:[0,1,1]
	v_min_i32_e32 v8, v17, v32
	v_pk_mul_f32 v[44:45], v[20:21], v[24:25] op_sel_hi:[0,1]
	v_cvt_f32_i32_e32 v21, v8
	v_sub_f32_e32 v19, v29, v19
	v_sub_f32_e32 v18, v28, v18
	v_lshlrev_b64 v[22:23], 10, v[22:23]
	v_pk_fma_f32 v[6:7], v[20:21], v[24:25], v[6:7] op_sel_hi:[0,1,1]
	v_sub_f32_e32 v9, v7, v27
	v_div_scale_f32 v7, s[0:1], v21, v21, 1.0
	v_rcp_f32_e32 v20, v7
	v_sub_f32_e32 v8, v6, v26
	v_mov_b32_e32 v26, 0
	v_mov_b32_e32 v27, 0
	v_fma_f32 v6, -v7, v20, 1.0
	v_fmac_f32_e32 v20, v6, v20
	v_div_scale_f32 v6, vcc, 1.0, v21, 1.0
	v_mul_f32_e32 v24, v6, v20
	v_fma_f32 v25, -v7, v24, v6
	v_fmac_f32_e32 v24, v25, v20
	v_fma_f32 v6, -v7, v24, v6
	v_div_fmas_f32 v6, v6, v20, v24
	v_div_fixup_f32 v6, v6, v21, 1.0
	v_pk_fma_f32 v[20:21], v[6:7], v[18:19], v[46:47] op_sel_hi:[0,1,1] neg_lo:[0,0,1] neg_hi:[0,0,1]
	v_pk_fma_f32 v[6:7], v[6:7], v[8:9], v[44:45] op_sel_hi:[0,1,1] neg_lo:[0,0,1] neg_hi:[0,0,1]
	v_pk_mul_f32 v[6:7], v[4:5], v[6:7]
	v_pk_mul_f32 v[20:21], v[2:3], v[20:21]
	v_cmp_ge_i32_e32 vcc, v17, v32
	v_cvt_pk_bf16_f32 v20, v20, v21
	v_cvt_pk_bf16_f32 v21, v6, v7
	v_lshl_add_u64 v[6:7], v[22:23], 1, v[14:15]
	v_add_u32_e32 v22, 2, v16
	v_ashrrev_i32_e32 v23, 31, v22
	global_store_dwordx2 v[6:7], v[20:21], off sc1
	v_lshlrev_b64 v[6:7], 11, v[22:23]
	v_lshl_add_u64 v[6:7], v[12:13], 0, v[6:7]
	global_load_dwordx2 v[24:25], v[6:7], off
	ds_read_b32 v20, v40 offset:8
	v_mov_b32_e32 v6, 0
	v_mov_b32_e32 v28, 0
	v_mov_b32_e32 v29, 0
	s_and_saveexec_b64 s[0:1], vcc
	s_cbranch_execz .LBB0_353
	v_add3_u32 v26, v38, s6, 2
	v_ashrrev_i32_e32 v27, 31, v26
	v_lshlrev_b64 v[26:27], 11, v[26:27]
	v_lshl_add_u64 v[26:27], v[12:13], 0, v[26:27]
	global_load_dwordx2 v[26:27], v[26:27], off
	ds_read_b32 v44, v42 offset:8
	s_waitcnt vmcnt(0)
	v_lshlrev_b32_e32 v46, 16, v26
	v_and_b32_e32 v47, 0xffff0000, v26
	v_lshlrev_b32_e32 v26, 16, v27
	v_and_b32_e32 v27, 0xffff0000, v27
	s_waitcnt lgkmcnt(0)
	v_pk_mul_f32 v[28:29], v[44:45], v[26:27] op_sel_hi:[0,1]
	v_pk_mul_f32 v[26:27], v[44:45], v[46:47] op_sel_hi:[0,1]
; __device__ __forceinline__ unsigned pk2(float lo, float hi) { return pg8::cvt_pk_bf16(lo, hi); }
; __device__ __forceinline__ f32x4 ld4bf(const bf16* p) { const v2u w = *(const v2u*)p; return (f32x4){bf_lo(w.x), bf_hi(w.x), bf_lo(w.y), bf_hi(w.y)}; }
; __device__ __forceinline__ void pool_prep(const bf16* X, const float* ss, const float* gain, bf16* PB, LAS unsigned char* lds, int vcu, int G, int tid) {
;     ...
;         for (int i = 0; i < 32; ++i) { const int row = ra + i, t = row - bstart;
;             const f32x4 xn = ld4bf(xp + (size_t)row * DM) * rsl[row - r0 + 16];
;             f32x4 old = {0.f, 0.f, 0.f, 0.f};
;             if (t >= w) old = ld4bf(xp + (size_t)(row - w) * DM) * rsl[row - w - r0 + 16];
;             S = S + xn - old;
;             const int cnt = (t + 1 < w) ? t + 1 : w;
;             const f32x4 p = (S * (1.0f / (float)cnt) - xn) * gn;
;             v2u o; o.x = pk2(p[0], p[1]); o.y = pk2(p[2], p[3]); *(v2u*)(PB + (size_t)row * DM + 4 * q) = o; }
.LBB0_353:
	s_or_b64 exec, exec, s[0:1]
	v_add_u32_e32 v7, 3, v41
	v_min_i32_e32 v17, v7, v32
	v_cvt_f32_i32_e32 v17, v17
	s_waitcnt vmcnt(0)
	v_lshlrev_b32_e32 v44, 16, v24
	v_and_b32_e32 v45, 0xffff0000, v24
	v_lshlrev_b32_e32 v24, 16, v25
	v_and_b32_e32 v25, 0xffff0000, v25
	s_waitcnt lgkmcnt(0)
	v_pk_mul_f32 v[46:47], v[20:21], v[24:25] op_sel_hi:[0,1]
	v_pk_mul_f32 v[48:49], v[20:21], v[44:45] op_sel_hi:[0,1]
	v_pk_fma_f32 v[18:19], v[20:21], v[44:45], v[18:19] op_sel_hi:[0,1,1]
	v_pk_fma_f32 v[8:9], v[20:21], v[24:25], v[8:9] op_sel_hi:[0,1,1]
	v_div_scale_f32 v20, s[0:1], v17, v17, 1.0
	v_rcp_f32_e32 v21, v20
	v_sub_f32_e32 v18, v18, v26
	v_sub_f32_e32 v9, v9, v29
	v_sub_f32_e32 v8, v8, v28
	v_fma_f32 v24, -v20, v21, 1.0
	v_fmac_f32_e32 v21, v24, v21
	v_div_scale_f32 v24, vcc, 1.0, v17, 1.0
	v_mul_f32_e32 v25, v24, v21
	v_fma_f32 v26, -v20, v25, v24
	v_fmac_f32_e32 v25, v26, v21
	v_fma_f32 v20, -v20, v25, v24
	v_div_fmas_f32 v20, v20, v21, v25
	v_sub_f32_e32 v19, v19, v27
	v_div_fixup_f32 v20, v20, v17, 1.0
	v_pk_fma_f32 v[24:25], v[20:21], v[18:19], v[48:49] op_sel_hi:[0,1,1] neg_lo:[0,0,1] neg_hi:[0,0,1]
	v_pk_fma_f32 v[20:21], v[20:21], v[8:9], v[46:47] op_sel_hi:[0,1,1] neg_lo:[0,0,1] neg_hi:[0,0,1]
	v_lshlrev_b64 v[22:23], 10, v[22:23]
	v_pk_mul_f32 v[20:21], v[4:5], v[20:21]
	v_pk_mul_f32 v[24:25], v[2:3], v[24:25]
	v_cmp_ge_i32_e32 vcc, v7, v32
	v_cvt_pk_bf16_f32 v24, v24, v25
	v_cvt_pk_bf16_f32 v25, v20, v21
	v_lshl_add_u64 v[20:21], v[22:23], 1, v[14:15]
	v_add_u32_e32 v22, 3, v16
	v_ashrrev_i32_e32 v23, 31, v22
	global_store_dwordx2 v[20:21], v[24:25], off sc1
	v_lshlrev_b64 v[20:21], 11, v[22:23]
	v_lshl_add_u64 v[20:21], v[12:13], 0, v[20:21]
	global_load_dwordx2 v[24:25], v[20:21], off
	ds_read_b32 v20, v40 offset:12
	v_mov_b32_e32 v7, 0
	v_mov_b32_e32 v26, 0
	v_mov_b32_e32 v27, 0
	s_and_saveexec_b64 s[0:1], vcc
	s_cbranch_execz .LBB0_355
	v_add3_u32 v6, v38, s6, 3
	v_ashrrev_i32_e32 v7, 31, v6
	v_lshlrev_b64 v[6:7], 11, v[6:7]
	v_lshl_add_u64 v[6:7], v[12:13], 0, v[6:7]
	global_load_dwordx2 v[6:7], v[6:7], off
	ds_read_b32 v28, v42 offset:12
	s_waitcnt vmcnt(0)
	v_lshlrev_b32_e32 v44, 16, v6
	v_and_b32_e32 v45, 0xffff0000, v6
	v_lshlrev_b32_e32 v6, 16, v7
	v_and_b32_e32 v7, 0xffff0000, v7
	s_waitcnt lgkmcnt(0)
	v_pk_mul_f32 v[26:27], v[28:29], v[6:7] op_sel_hi:[0,1]
	v_pk_mul_f32 v[6:7], v[28:29], v[44:45] op_sel_hi:[0,1]
.LBB0_355:
	s_or_b64 exec, exec, s[0:1]
	s_waitcnt vmcnt(0)
	v_lshlrev_b32_e32 v28, 16, v24
	v_and_b32_e32 v29, 0xffff0000, v24
	v_lshlrev_b32_e32 v24, 16, v25
	v_and_b32_e32 v25, 0xffff0000, v25
	v_add_u32_e32 v17, 4, v41
	s_waitcnt lgkmcnt(0)
	v_pk_mul_f32 v[44:45], v[20:21], v[24:25] op_sel_hi:[0,1]
	v_pk_mul_f32 v[46:47], v[20:21], v[28:29] op_sel_hi:[0,1]
	v_pk_fma_f32 v[18:19], v[20:21], v[28:29], v[18:19] op_sel_hi:[0,1,1]
	v_min_i32_e32 v21, v17, v32
	v_cvt_f32_i32_e32 v21, v21
	v_sub_f32_e32 v18, v18, v6
	v_sub_f32_e32 v19, v19, v7
	v_lshlrev_b64 v[22:23], 10, v[22:23]
	v_pk_fma_f32 v[8:9], v[20:21], v[24:25], v[8:9] op_sel_hi:[0,1,1]
	v_div_scale_f32 v20, s[0:1], v21, v21, 1.0
	v_rcp_f32_e32 v24, v20
	v_sub_f32_e32 v9, v9, v27
	v_sub_f32_e32 v8, v8, v26
	v_mov_b32_e32 v26, 0
	v_fma_f32 v6, -v20, v24, 1.0
	v_fmac_f32_e32 v24, v6, v24
	v_div_scale_f32 v6, vcc, 1.0, v21, 1.0
	v_mul_f32_e32 v7, v6, v24
	v_fma_f32 v25, -v20, v7, v6
	v_fmac_f32_e32 v7, v25, v24
	v_fma_f32 v6, -v20, v7, v6
	v_div_fmas_f32 v6, v6, v24, v7
	v_div_fixup_f32 v6, v6, v21, 1.0
	v_pk_fma_f32 v[20:21], v[6:7], v[18:19], v[46:47] op_sel_hi:[0,1,1] neg_lo:[0,0,1] neg_hi:[0,0,1]
	v_pk_fma_f32 v[6:7], v[6:7], v[8:9], v[44:45] op_sel_hi:[0,1,1] neg_lo:[0,0,1] neg_hi:[0,0,1]
	v_pk_mul_f32 v[6:7], v[4:5], v[6:7]
	v_pk_mul_f32 v[20:21], v[2:3], v[20:21]
	v_cmp_ge_i32_e32 vcc, v17, v32
	v_cvt_pk_bf16_f32 v20, v20, v21
	v_cvt_pk_bf16_f32 v21, v6, v7
	v_lshl_add_u64 v[6:7], v[22:23], 1, v[14:15]
	v_add_u32_e32 v22, 4, v16
	v_ashrrev_i32_e32 v23, 31, v22
	global_store_dwordx2 v[6:7], v[20:21], off sc1
	v_lshlrev_b64 v[6:7], 11, v[22:23]
	v_lshl_add_u64 v[6:7], v[12:13], 0, v[6:7]
	global_load_dwordx2 v[24:25], v[6:7], off
	ds_read_b32 v20, v40 offset:16
	v_mov_b32_e32 v6, 0
	v_mov_b32_e32 v27, 0
	v_mov_b32_e32 v28, 0
	v_mov_b32_e32 v29, 0
	s_and_saveexec_b64 s[0:1], vcc
	s_cbranch_execz .LBB0_357
	v_add3_u32 v26, v38, s6, 4
	v_ashrrev_i32_e32 v27, 31, v26
	v_lshlrev_b64 v[26:27], 11, v[26:27]
	v_lshl_add_u64 v[26:27], v[12:13], 0, v[26:27]
	global_load_dwordx2 v[26:27], v[26:27], off
	ds_read_b32 v44, v42 offset:16
	s_waitcnt vmcnt(0)
	v_lshlrev_b32_e32 v46, 16, v26
	v_and_b32_e32 v47, 0xffff0000, v26
	v_lshlrev_b32_e32 v26, 16, v27
	v_and_b32_e32 v27, 0xffff0000, v27
	s_waitcnt lgkmcnt(0)
	v_pk_mul_f32 v[28:29], v[44:45], v[26:27] op_sel_hi:[0,1]
	v_pk_mul_f32 v[26:27], v[44:45], v[46:47] op_sel_hi:[0,1]
; __device__ __forceinline__ unsigned pk2(float lo, float hi) { return pg8::cvt_pk_bf16(lo, hi); }
; __device__ __forceinline__ f32x4 ld4bf(const bf16* p) { const v2u w = *(const v2u*)p; return (f32x4){bf_lo(w.x), bf_hi(w.x), bf_lo(w.y), bf_hi(w.y)}; }
; __device__ __forceinline__ void pool_prep(const bf16* X, const float* ss, const float* gain, bf16* PB, LAS unsigned char* lds, int vcu, int G, int tid) {
;     ...
;         for (int i = 0; i < 32; ++i) { const int row = ra + i, t = row - bstart;
;             const f32x4 xn = ld4bf(xp + (size_t)row * DM) * rsl[row - r0 + 16];
;             f32x4 old = {0.f, 0.f, 0.f, 0.f};
;             if (t >= w) old = ld4bf(xp + (size_t)(row - w) * DM) * rsl[row - w - r0 + 16];
;             S = S + xn - old;
;             const int cnt = (t + 1 < w) ? t + 1 : w;
;             const f32x4 p = (S * (1.0f / (float)cnt) - xn) * gn;
;             v2u o; o.x = pk2(p[0], p[1]); o.y = pk2(p[2], p[3]); *(v2u*)(PB + (size_t)row * DM + 4 * q) = o; }
.LBB0_357:
	s_or_b64 exec, exec, s[0:1]
	v_add_u32_e32 v7, 5, v41
	v_min_i32_e32 v17, v7, v32
	v_cvt_f32_i32_e32 v17, v17
	s_waitcnt vmcnt(0)
	v_lshlrev_b32_e32 v44, 16, v24
	v_and_b32_e32 v45, 0xffff0000, v24
	v_lshlrev_b32_e32 v24, 16, v25
	v_and_b32_e32 v25, 0xffff0000, v25
	s_waitcnt lgkmcnt(0)
	v_pk_mul_f32 v[46:47], v[20:21], v[24:25] op_sel_hi:[0,1]
	v_pk_mul_f32 v[48:49], v[20:21], v[44:45] op_sel_hi:[0,1]
	v_pk_fma_f32 v[18:19], v[20:21], v[44:45], v[18:19] op_sel_hi:[0,1,1]
	v_pk_fma_f32 v[8:9], v[20:21], v[24:25], v[8:9] op_sel_hi:[0,1,1]
	v_div_scale_f32 v20, s[0:1], v17, v17, 1.0
	v_rcp_f32_e32 v21, v20
	v_sub_f32_e32 v18, v18, v26
	v_sub_f32_e32 v9, v9, v29
	v_sub_f32_e32 v8, v8, v28
	v_fma_f32 v24, -v20, v21, 1.0
	v_fmac_f32_e32 v21, v24, v21
	v_div_scale_f32 v24, vcc, 1.0, v17, 1.0
	v_mul_f32_e32 v25, v24, v21
	v_fma_f32 v26, -v20, v25, v24
	v_fmac_f32_e32 v25, v26, v21
	v_fma_f32 v20, -v20, v25, v24
	v_div_fmas_f32 v20, v20, v21, v25
	v_sub_f32_e32 v19, v19, v27
	v_div_fixup_f32 v20, v20, v17, 1.0
	v_pk_fma_f32 v[24:25], v[20:21], v[18:19], v[48:49] op_sel_hi:[0,1,1] neg_lo:[0,0,1] neg_hi:[0,0,1]
	v_pk_fma_f32 v[20:21], v[20:21], v[8:9], v[46:47] op_sel_hi:[0,1,1] neg_lo:[0,0,1] neg_hi:[0,0,1]
	v_lshlrev_b64 v[22:23], 10, v[22:23]
	v_pk_mul_f32 v[20:21], v[4:5], v[20:21]
	v_pk_mul_f32 v[24:25], v[2:3], v[24:25]
	v_cmp_ge_i32_e32 vcc, v7, v32
	v_cvt_pk_bf16_f32 v24, v24, v25
	v_cvt_pk_bf16_f32 v25, v20, v21
	v_lshl_add_u64 v[20:21], v[22:23], 1, v[14:15]
	v_add_u32_e32 v22, 5, v16
	v_ashrrev_i32_e32 v23, 31, v22
	global_store_dwordx2 v[20:21], v[24:25], off sc1
	v_lshlrev_b64 v[20:21], 11, v[22:23]
	v_lshl_add_u64 v[20:21], v[12:13], 0, v[20:21]
	global_load_dwordx2 v[24:25], v[20:21], off
	ds_read_b32 v20, v40 offset:20
	v_mov_b32_e32 v7, 0
	v_mov_b32_e32 v26, 0
	v_mov_b32_e32 v27, 0
	s_and_saveexec_b64 s[0:1], vcc
	s_cbranch_execz .LBB0_359
	v_add3_u32 v6, v38, s6, 5
	v_ashrrev_i32_e32 v7, 31, v6
	v_lshlrev_b64 v[6:7], 11, v[6:7]
	v_lshl_add_u64 v[6:7], v[12:13], 0, v[6:7]
	global_load_dwordx2 v[6:7], v[6:7], off
	ds_read_b32 v28, v42 offset:20
	s_waitcnt vmcnt(0)
	v_lshlrev_b32_e32 v44, 16, v6
	v_and_b32_e32 v45, 0xffff0000, v6
	v_lshlrev_b32_e32 v6, 16, v7
	v_and_b32_e32 v7, 0xffff0000, v7
	s_waitcnt lgkmcnt(0)
	v_pk_mul_f32 v[26:27], v[28:29], v[6:7] op_sel_hi:[0,1]
	v_pk_mul_f32 v[6:7], v[28:29], v[44:45] op_sel_hi:[0,1]
.LBB0_359:
	s_or_b64 exec, exec, s[0:1]
	s_waitcnt vmcnt(0)
	v_lshlrev_b32_e32 v28, 16, v24
	v_and_b32_e32 v29, 0xffff0000, v24
	v_lshlrev_b32_e32 v24, 16, v25
	v_and_b32_e32 v25, 0xffff0000, v25
	v_add_u32_e32 v17, 6, v41
	s_waitcnt lgkmcnt(0)
	v_pk_mul_f32 v[44:45], v[20:21], v[24:25] op_sel_hi:[0,1]
	v_pk_mul_f32 v[46:47], v[20:21], v[28:29] op_sel_hi:[0,1]
	v_pk_fma_f32 v[18:19], v[20:21], v[28:29], v[18:19] op_sel_hi:[0,1,1]
	v_min_i32_e32 v21, v17, v32
	v_cvt_f32_i32_e32 v21, v21
	v_sub_f32_e32 v18, v18, v6
	v_sub_f32_e32 v19, v19, v7
	v_lshlrev_b64 v[22:23], 10, v[22:23]
	v_pk_fma_f32 v[8:9], v[20:21], v[24:25], v[8:9] op_sel_hi:[0,1,1]
	v_div_scale_f32 v20, s[0:1], v21, v21, 1.0
	v_rcp_f32_e32 v24, v20
	v_sub_f32_e32 v9, v9, v27
	v_sub_f32_e32 v8, v8, v26
	v_mov_b32_e32 v26, 0
	v_fma_f32 v6, -v20, v24, 1.0
	v_fmac_f32_e32 v24, v6, v24
	v_div_scale_f32 v6, vcc, 1.0, v21, 1.0
	v_mul_f32_e32 v7, v6, v24
	v_fma_f32 v25, -v20, v7, v6
	v_fmac_f32_e32 v7, v25, v24
	v_fma_f32 v6, -v20, v7, v6
	v_div_fmas_f32 v6, v6, v24, v7
	v_div_fixup_f32 v6, v6, v21, 1.0
	v_pk_fma_f32 v[20:21], v[6:7], v[18:19], v[46:47] op_sel_hi:[0,1,1] neg_lo:[0,0,1] neg_hi:[0,0,1]
	v_pk_fma_f32 v[6:7], v[6:7], v[8:9], v[44:45] op_sel_hi:[0,1,1] neg_lo:[0,0,1] neg_hi:[0,0,1]
	v_pk_mul_f32 v[6:7], v[4:5], v[6:7]
	v_pk_mul_f32 v[20:21], v[2:3], v[20:21]
	v_cmp_ge_i32_e32 vcc, v17, v32
	v_cvt_pk_bf16_f32 v20, v20, v21
	v_cvt_pk_bf16_f32 v21, v6, v7
	v_lshl_add_u64 v[6:7], v[22:23], 1, v[14:15]
	v_add_u32_e32 v22, 6, v16
	v_ashrrev_i32_e32 v23, 31, v22
	global_store_dwordx2 v[6:7], v[20:21], off sc1
	v_lshlrev_b64 v[6:7], 11, v[22:23]
	v_lshl_add_u64 v[6:7], v[12:13], 0, v[6:7]
	global_load_dwordx2 v[24:25], v[6:7], off
	ds_read_b32 v20, v40 offset:24
	v_mov_b32_e32 v6, 0
	v_mov_b32_e32 v27, 0
	v_mov_b32_e32 v28, 0
	v_mov_b32_e32 v29, 0
	s_and_saveexec_b64 s[0:1], vcc
	s_cbranch_execz .LBB0_361
	v_add3_u32 v26, v38, s6, 6
	v_ashrrev_i32_e32 v27, 31, v26
	v_lshlrev_b64 v[26:27], 11, v[26:27]
	v_lshl_add_u64 v[26:27], v[12:13], 0, v[26:27]
	global_load_dwordx2 v[26:27], v[26:27], off
	ds_read_b32 v44, v42 offset:24
	s_waitcnt vmcnt(0)
	v_lshlrev_b32_e32 v46, 16, v26
	v_and_b32_e32 v47, 0xffff0000, v26
	v_lshlrev_b32_e32 v26, 16, v27
	v_and_b32_e32 v27, 0xffff0000, v27
	s_waitcnt lgkmcnt(0)
	v_pk_mul_f32 v[28:29], v[44:45], v[26:27] op_sel_hi:[0,1]
	v_pk_mul_f32 v[26:27], v[44:45], v[46:47] op_sel_hi:[0,1]
; __device__ __forceinline__ unsigned pk2(float lo, float hi) { return pg8::cvt_pk_bf16(lo, hi); }
; __device__ __forceinline__ f32x4 ld4bf(const bf16* p) { const v2u w = *(const v2u*)p; return (f32x4){bf_lo(w.x), bf_hi(w.x), bf_lo(w.y), bf_hi(w.y)}; }
; __device__ __forceinline__ void pool_prep(const bf16* X, const float* ss, const float* gain, bf16* PB, LAS unsigned char* lds, int vcu, int G, int tid) {
;     ...
;         for (int i = 0; i < 32; ++i) { const int row = ra + i, t = row - bstart;
;             const f32x4 xn = ld4bf(xp + (size_t)row * DM) * rsl[row - r0 + 16];
;             f32x4 old = {0.f, 0.f, 0.f, 0.f};
;             if (t >= w) old = ld4bf(xp + (size_t)(row - w) * DM) * rsl[row - w - r0 + 16];
;             S = S + xn - old;
;             const int cnt = (t + 1 < w) ? t + 1 : w;
;             const f32x4 p = (S * (1.0f / (float)cnt) - xn) * gn;
;             v2u o; o.x = pk2(p[0], p[1]); o.y = pk2(p[2], p[3]); *(v2u*)(PB + (size_t)row * DM + 4 * q) = o; }
.LBB0_361:
	s_or_b64 exec, exec, s[0:1]
	v_add_u32_e32 v7, 7, v41
	v_min_i32_e32 v17, v7, v32
	v_cvt_f32_i32_e32 v17, v17
	s_waitcnt vmcnt(0)
	v_lshlrev_b32_e32 v44, 16, v24
	v_and_b32_e32 v45, 0xffff0000, v24
	v_lshlrev_b32_e32 v24, 16, v25
	v_and_b32_e32 v25, 0xffff0000, v25
	s_waitcnt lgkmcnt(0)
	v_pk_mul_f32 v[46:47], v[20:21], v[24:25] op_sel_hi:[0,1]
	v_pk_mul_f32 v[48:49], v[20:21], v[44:45] op_sel_hi:[0,1]
	v_pk_fma_f32 v[18:19], v[20:21], v[44:45], v[18:19] op_sel_hi:[0,1,1]
	v_pk_fma_f32 v[8:9], v[20:21], v[24:25], v[8:9] op_sel_hi:[0,1,1]
	v_div_scale_f32 v20, s[0:1], v17, v17, 1.0
	v_rcp_f32_e32 v21, v20
	v_sub_f32_e32 v18, v18, v26
	v_sub_f32_e32 v9, v9, v29
	v_sub_f32_e32 v8, v8, v28
	v_fma_f32 v24, -v20, v21, 1.0
	v_fmac_f32_e32 v21, v24, v21
	v_div_scale_f32 v24, vcc, 1.0, v17, 1.0
	v_mul_f32_e32 v25, v24, v21
	v_fma_f32 v26, -v20, v25, v24
	v_fmac_f32_e32 v25, v26, v21
	v_fma_f32 v20, -v20, v25, v24
	v_div_fmas_f32 v20, v20, v21, v25
	v_sub_f32_e32 v19, v19, v27
	v_div_fixup_f32 v20, v20, v17, 1.0
	v_pk_fma_f32 v[24:25], v[20:21], v[18:19], v[48:49] op_sel_hi:[0,1,1] neg_lo:[0,0,1] neg_hi:[0,0,1]
	v_pk_fma_f32 v[20:21], v[20:21], v[8:9], v[46:47] op_sel_hi:[0,1,1] neg_lo:[0,0,1] neg_hi:[0,0,1]
	v_lshlrev_b64 v[22:23], 10, v[22:23]
	v_pk_mul_f32 v[20:21], v[4:5], v[20:21]
	v_pk_mul_f32 v[24:25], v[2:3], v[24:25]
	v_cmp_ge_i32_e32 vcc, v7, v32
	v_cvt_pk_bf16_f32 v24, v24, v25
	v_cvt_pk_bf16_f32 v25, v20, v21
	v_lshl_add_u64 v[20:21], v[22:23], 1, v[14:15]
	global_store_dwordx2 v[20:21], v[24:25], off sc1
	v_add_u32_e32 v20, 7, v16
	v_ashrrev_i32_e32 v21, 31, v20
	v_lshlrev_b64 v[16:17], 11, v[20:21]
	v_lshl_add_u64 v[16:17], v[12:13], 0, v[16:17]
	global_load_dwordx2 v[22:23], v[16:17], off
	ds_read_b32 v16, v40 offset:28
	v_mov_b32_e32 v7, 0
	v_mov_b32_e32 v24, 0
	v_mov_b32_e32 v25, 0
	s_and_saveexec_b64 s[0:1], vcc
	s_cbranch_execz .LBB0_346
	v_add3_u32 v6, v38, s6, 7
	v_ashrrev_i32_e32 v7, 31, v6
	v_lshlrev_b64 v[6:7], 11, v[6:7]
	v_lshl_add_u64 v[6:7], v[12:13], 0, v[6:7]
	global_load_dwordx2 v[6:7], v[6:7], off
	ds_read_b32 v26, v42 offset:28
	s_waitcnt vmcnt(0)
	v_lshlrev_b32_e32 v28, 16, v6
	v_and_b32_e32 v29, 0xffff0000, v6
	v_lshlrev_b32_e32 v6, 16, v7
	v_and_b32_e32 v7, 0xffff0000, v7
	s_waitcnt lgkmcnt(0)
	v_pk_mul_f32 v[24:25], v[26:27], v[6:7] op_sel_hi:[0,1]
	v_pk_mul_f32 v[6:7], v[26:27], v[28:29] op_sel_hi:[0,1]
	s_branch .LBB0_346

; __device__ __forceinline__ u32x4 pack8(f32x4 a, f32x4 b) { u32x4 w; w.x = cvt_pk_bf16(a[0], a[1]); w.y = cvt_pk_bf16(a[2], a[3]); w.z = cvt_pk_bf16(b[0], b[1]); w.w = cvt_pk_bf16(b[2], b[3]); return w; }
; __device__ __forceinline__ bf16x8 pack8(f32x4 a, f32x4 b) { u32x4 w = {cvtpk(a[0], a[1]), cvtpk(a[2], a[3]), cvtpk(b[0], b[1]), cvtpk(b[2], b[3])}; return *reinterpret_cast<bf16x8*>(&w); }
;     PG8_RSTD_HOOKS
;     __device__ __forceinline__ void operator()(const f32x4 (&acc)[2][2][4][2], const Unit& u, int wr, int wc, int fr, int fq, int par) const {
;     ...
;                 for (int mm = 0; mm < 2; ++mm) { const float* cp = rope + (size_t)(row0 + ai * HALF + (2 * mp + mm) * 16) * 32 + 8 * (fq & 1);
;                     c[mm][0] = *(const f32x4*)(cp); c[mm][1] = *(const f32x4*)(cp + 4); sn[mm][0] = *(const f32x4*)(cp + 16); sn[mm][1] = *(const f32x4*)(cp + 20); }
;             }
; #pragma unroll
;             for (int mm = 0; mm < 2; ++mm) { const int m = 2 * mp + mm;
;                 const int row = row0 + ai * HALF + m * 16; const int s = row & 4095; const float rs = rsv[ai][m];
;                 f32x4 v[2][2];
; #pragma unroll
;                 for (int bj = 0; bj < 2; ++bj)
; #pragma unroll
;                     for (int n = 0; n < 2; ++n) v[bj][n] = acc[ai][bj][m][n] * rs;
;                 if (rot) {
;                     const float sgn = (fq < 2) ? -1.f : 1.f;
; #pragma unroll
;                     for (int n = 0; n < 2; ++n)
; #pragma unroll
;                         for (int j = 0; j < 4; ++j) { const float mine = v[0][n][j]; const float other = __shfl_xor(mine, 32); v[0][n][j] = mine * c[mm][n][j] + sgn * other * sn[mm][n][j]; }
;                 }
; #pragma unroll
;                 for (int bj = 0; bj < 2; ++bj) {
;                     bf16_t* dst = base + ((size_t)((b * 8 + hh) * 4096 + s)) * 128 + cih0 + 32 * bj;
;                     *(u32x4*)dst = pack8(v[bj][0], v[bj][1]);
;                     cs[bj][0] += v[bj][0]; cs[bj][1] += v[bj][1];
;                 }
.LBB0_385:
	s_lshl_b32 s1, s3, 1
	s_and_b32 s1, s1, 6
	s_ashr_i32 s0, s2, 4
	s_or_b32 s1, s1, s89
	s_lshl_b32 s3, s0, 15
	s_lshl_b32 s6, s1, 12
	s_or_b32 s3, s6, s3
	v_and_b32_e32 v98, 0xfcf, v198
	v_or_b32_e32 v204, s3, v98
	s_ashr_i32 s91, s90, 31
	v_mov_b32_e32 v172, v206
	v_mov_b32_e32 v173, v206
	s_lshl_b64 s[6:7], s[90:91], 25
	v_ashrrev_i32_e32 v205, 31, v204
	v_mov_b32_e32 v174, v206
	v_mov_b32_e32 v175, v206
	v_pk_mul_f32 v[160:161], v[160:161], v[172:173]
	v_pk_mul_f32 v[156:157], v[156:157], v[172:173]
	v_lshl_add_u64 v[196:197], v[184:185], 0, s[6:7]
	v_lshlrev_b64 v[172:173], 8, v[204:205]
	v_mov_b32_e32 v98, v207
	v_pk_mul_f32 v[162:163], v[162:163], v[174:175]
	v_pk_mul_f32 v[158:159], v[158:159], v[174:175]
	v_lshl_add_u64 v[214:215], v[196:197], 0, v[172:173]
	v_cvt_pk_bf16_f32 v172, v168, v169
	v_cvt_pk_bf16_f32 v173, v170, v171
	v_cvt_pk_bf16_f32 v174, v164, v165
	v_cvt_pk_bf16_f32 v175, v166, v167
	v_pk_mul_f32 v[154:155], v[154:155], v[98:99] op_sel_hi:[1,0]
	v_pk_mul_f32 v[152:153], v[152:153], v[98:99] op_sel_hi:[1,0]
	v_pk_mul_f32 v[150:151], v[150:151], v[98:99] op_sel_hi:[1,0]
	s_and_b64 vcc, exec, s[42:43]
	v_pk_mul_f32 v[148:149], v[148:149], v[98:99] op_sel_hi:[1,0]
	global_store_dwordx4 v[214:215], v[172:175], off sc1
	s_nop 1
	v_cvt_pk_bf16_f32 v172, v160, v161
	v_cvt_pk_bf16_f32 v173, v162, v163
	v_cvt_pk_bf16_f32 v174, v156, v157
	v_cvt_pk_bf16_f32 v175, v158, v159
	global_store_dwordx4 v[214:215], v[172:175], off offset:64 sc1
	s_cbranch_vccnz .LBB0_387
	ds_bpermute_b32 v98, v224, v153
	ds_bpermute_b32 v174, v224, v154
	ds_bpermute_b32 v175, v224, v155
	ds_bpermute_b32 v172, v224, v152
	v_mov_b32_e32 v216, v155
	s_waitcnt lgkmcnt(0)
	v_cndmask_b32_e64 v173, v98, -v98, s[36:37]
	v_cndmask_b32_e64 v98, v174, -v174, s[36:37]
	s_waitcnt vmcnt(0)
	v_mul_f32_e32 v174, v122, v98
	ds_bpermute_b32 v98, v224, v149
	v_cndmask_b32_e64 v215, v175, -v175, s[36:37]
	v_mov_b32_e32 v217, v123
	v_mov_b32_e32 v214, v93
	v_pk_mul_f32 v[152:153], v[152:153], v[90:91]
	v_cndmask_b32_e64 v172, v172, -v172, s[36:37]
	v_pk_mul_f32 v[214:215], v[216:217], v[214:215]
	v_mul_f32_e32 v154, v154, v92
	v_mov_b32_e32 v155, v214
	v_mov_b32_e32 v175, v215
	v_pk_fma_f32 v[152:153], v[120:121], v[172:173], v[152:153]
	s_waitcnt lgkmcnt(0)
	v_cndmask_b32_e64 v173, v98, -v98, s[36:37]
	ds_bpermute_b32 v98, v224, v151
	v_pk_add_f32 v[154:155], v[154:155], v[174:175]
	ds_bpermute_b32 v174, v224, v150
	ds_bpermute_b32 v172, v224, v148
	v_mov_b32_e32 v216, v151
	s_waitcnt lgkmcnt(2)
	v_cndmask_b32_e64 v215, v98, -v98, s[36:37]
	v_mov_b32_e32 v217, v97
	v_mov_b32_e32 v214, v85
	s_waitcnt lgkmcnt(1)
	v_cndmask_b32_e64 v174, v174, -v174, s[36:37]
	v_pk_mul_f32 v[214:215], v[216:217], v[214:215]
	v_pk_mul_f32 v[148:149], v[148:149], v[82:83]
	s_waitcnt lgkmcnt(0)
	v_cndmask_b32_e64 v172, v172, -v172, s[36:37]
	v_mul_f32_e32 v150, v150, v84
	v_mul_f32_e32 v174, v96, v174
	v_mov_b32_e32 v151, v214
	v_mov_b32_e32 v175, v215
	v_pk_fma_f32 v[148:149], v[94:95], v[172:173], v[148:149]
	v_pk_add_f32 v[150:151], v[150:151], v[174:175]
.LBB0_387:
	s_nop 0
	v_mov_b32_e32 v172, v207
	v_mov_b32_e32 v173, v207
	v_pk_mul_f32 v[146:147], v[146:147], v[172:173]
	v_pk_mul_f32 v[142:143], v[142:143], v[172:173]
	v_or_b32_e32 v172, 16, v204
	v_ashrrev_i32_e32 v173, 31, v172
	v_mov_b32_e32 v206, v207
	v_lshlrev_b64 v[172:173], 8, v[172:173]
	v_pk_mul_f32 v[144:145], v[144:145], v[206:207]
	v_pk_mul_f32 v[140:141], v[140:141], v[206:207]
	v_lshl_add_u64 v[206:207], v[196:197], 0, v[172:173]
	v_cvt_pk_bf16_f32 v172, v152, v153
	v_cvt_pk_bf16_f32 v173, v154, v155
	v_cvt_pk_bf16_f32 v174, v148, v149
	v_cvt_pk_bf16_f32 v175, v150, v151
	s_and_b64 vcc, exec, s[42:43]
	global_store_dwordx4 v[206:207], v[172:175], off sc1
	s_nop 1
	v_cvt_pk_bf16_f32 v172, v144, v145
	v_cvt_pk_bf16_f32 v173, v146, v147
	v_cvt_pk_bf16_f32 v174, v140, v141
	v_cvt_pk_bf16_f32 v175, v142, v143
	global_store_dwordx4 v[206:207], v[172:175], off offset:64 sc1
	s_cbranch_vccnz .LBB0_389
	s_waitcnt vmcnt(0)
	v_or_b32_e32 v82, 32, v198
	v_ashrrev_i32_e32 v83, 31, v82
	v_lshlrev_b64 v[82:83], 7, v[82:83]
	v_lshl_add_u64 v[82:83], v[188:189], 0, v[82:83]
	global_load_dwordx4 v[100:103], v[82:83], off offset:16
	global_load_dwordx4 v[116:119], v[82:83], off
	global_load_dwordx4 v[124:127], v[82:83], off offset:80
	global_load_dwordx4 v[128:131], v[82:83], off offset:64
	v_or_b32_e32 v82, 48, v198
	v_ashrrev_i32_e32 v83, 31, v82
	v_lshlrev_b64 v[82:83], 7, v[82:83]
	v_lshl_add_u64 v[120:121], v[188:189], 0, v[82:83]
	global_load_dwordx4 v[82:85], v[120:121], off offset:16
	global_load_dwordx4 v[90:93], v[120:121], off
	global_load_dwordx4 v[94:97], v[120:121], off offset:80
	s_nop 0
	global_load_dwordx4 v[120:123], v[120:121], off offset:64

; __device__ __forceinline__ u32x4 pack8(f32x4 a, f32x4 b) { u32x4 w; w.x = cvt_pk_bf16(a[0], a[1]); w.y = cvt_pk_bf16(a[2], a[3]); w.z = cvt_pk_bf16(b[0], b[1]); w.w = cvt_pk_bf16(b[2], b[3]); return w; }
; __device__ __forceinline__ bf16x8 pack8(f32x4 a, f32x4 b) { u32x4 w = {cvtpk(a[0], a[1]), cvtpk(a[2], a[3]), cvtpk(b[0], b[1]), cvtpk(b[2], b[3])}; return *reinterpret_cast<bf16x8*>(&w); }
;     PG8_RSTD_HOOKS
;     __device__ __forceinline__ void operator()(const f32x4 (&acc)[2][2][4][2], const Unit& u, int wr, int wc, int fr, int fq, int par) const {
;     ...
;             for (int mm = 0; mm < 2; ++mm) { const int m = 2 * mp + mm;
;                 const int row = row0 + ai * HALF + m * 16; const int s = row & 4095; const float rs = rsv[ai][m];
;                 f32x4 v[2][2];
; #pragma unroll
;                 for (int bj = 0; bj < 2; ++bj)
; #pragma unroll
;                     for (int n = 0; n < 2; ++n) v[bj][n] = acc[ai][bj][m][n] * rs;
;                 if (rot) {
;                     const float sgn = (fq < 2) ? -1.f : 1.f;
; #pragma unroll
;                     for (int n = 0; n < 2; ++n)
; #pragma unroll
;                         for (int j = 0; j < 4; ++j) { const float mine = v[0][n][j]; const float other = __shfl_xor(mine, 32); v[0][n][j] = mine * c[mm][n][j] + sgn * other * sn[mm][n][j]; }
;                 }
; #pragma unroll
;                 for (int bj = 0; bj < 2; ++bj) {
;                     bf16_t* dst = base + ((size_t)((b * 8 + hh) * 4096 + s)) * 128 + cih0 + 32 * bj;
;                     *(u32x4*)dst = pack8(v[bj][0], v[bj][1]);
;                     cs[bj][0] += v[bj][0]; cs[bj][1] += v[bj][1];
;                 }
.LBB0_391:
	v_mov_b32_e32 v172, v202
	v_mov_b32_e32 v173, v202
	v_pk_mul_f32 v[112:113], v[112:113], v[172:173]
	v_pk_mul_f32 v[108:109], v[108:109], v[172:173]
	v_or_b32_e32 v172, 32, v204
	v_ashrrev_i32_e32 v173, 31, v172
	v_mov_b32_e32 v174, v202
	v_mov_b32_e32 v175, v202
	v_lshlrev_b64 v[172:173], 8, v[172:173]
	v_mov_b32_e32 v98, v203
	v_pk_mul_f32 v[114:115], v[114:115], v[174:175]
	v_pk_mul_f32 v[110:111], v[110:111], v[174:175]
	v_lshl_add_u64 v[206:207], v[196:197], 0, v[172:173]
	v_cvt_pk_bf16_f32 v172, v136, v137
	v_cvt_pk_bf16_f32 v173, v138, v139
	v_cvt_pk_bf16_f32 v174, v132, v133
	v_cvt_pk_bf16_f32 v175, v134, v135
	v_pk_mul_f32 v[106:107], v[106:107], v[98:99] op_sel_hi:[1,0]
	v_pk_mul_f32 v[104:105], v[104:105], v[98:99] op_sel_hi:[1,0]
	v_pk_mul_f32 v[88:89], v[88:89], v[98:99] op_sel_hi:[1,0]
	s_and_b64 vcc, exec, s[42:43]
	v_pk_mul_f32 v[86:87], v[86:87], v[98:99] op_sel_hi:[1,0]
	global_store_dwordx4 v[206:207], v[172:175], off sc1
	s_nop 1
	v_cvt_pk_bf16_f32 v172, v112, v113
	v_cvt_pk_bf16_f32 v173, v114, v115
	v_cvt_pk_bf16_f32 v174, v108, v109
	v_cvt_pk_bf16_f32 v175, v110, v111
	global_store_dwordx4 v[206:207], v[172:175], off offset:64 sc1
	s_cbranch_vccnz .LBB0_393
	ds_bpermute_b32 v98, v224, v105
	ds_bpermute_b32 v174, v224, v106
	ds_bpermute_b32 v175, v224, v107
	ds_bpermute_b32 v172, v224, v104
	v_mov_b32_e32 v214, v107
	s_waitcnt lgkmcnt(0)
	v_cndmask_b32_e64 v173, v98, -v98, s[36:37]
	v_cndmask_b32_e64 v98, v174, -v174, s[36:37]
	s_waitcnt vmcnt(0)
	v_mul_f32_e32 v174, v122, v98
	ds_bpermute_b32 v98, v224, v87
	v_cndmask_b32_e64 v207, v175, -v175, s[36:37]
	v_mov_b32_e32 v215, v123
	v_mov_b32_e32 v206, v93
	v_pk_mul_f32 v[104:105], v[104:105], v[90:91]
	v_cndmask_b32_e64 v172, v172, -v172, s[36:37]
	v_pk_mul_f32 v[206:207], v[214:215], v[206:207]
	v_mul_f32_e32 v106, v106, v92
	v_mov_b32_e32 v107, v206
	v_mov_b32_e32 v175, v207
	v_pk_fma_f32 v[104:105], v[120:121], v[172:173], v[104:105]
	s_waitcnt lgkmcnt(0)
	v_cndmask_b32_e64 v173, v98, -v98, s[36:37]
	ds_bpermute_b32 v98, v224, v89
	v_pk_add_f32 v[106:107], v[106:107], v[174:175]
	ds_bpermute_b32 v174, v224, v88
	ds_bpermute_b32 v172, v224, v86
	v_mov_b32_e32 v214, v89
	s_waitcnt lgkmcnt(2)
	v_cndmask_b32_e64 v207, v98, -v98, s[36:37]
	v_mov_b32_e32 v215, v97
	v_mov_b32_e32 v206, v85
	s_waitcnt lgkmcnt(1)
	v_cndmask_b32_e64 v174, v174, -v174, s[36:37]
	v_pk_mul_f32 v[206:207], v[214:215], v[206:207]
	v_pk_mul_f32 v[86:87], v[86:87], v[82:83]
	s_waitcnt lgkmcnt(0)
	v_cndmask_b32_e64 v172, v172, -v172, s[36:37]
	v_mul_f32_e32 v88, v88, v84
	v_mul_f32_e32 v174, v96, v174
	v_mov_b32_e32 v89, v206
	v_mov_b32_e32 v175, v207
	v_pk_fma_f32 v[86:87], v[94:95], v[172:173], v[86:87]
	v_pk_add_f32 v[88:89], v[88:89], v[174:175]
.LBB0_393:
	s_nop 0
	v_mov_b32_e32 v172, v203
	v_mov_b32_e32 v173, v203
	v_pk_mul_f32 v[80:81], v[80:81], v[172:173]
	v_pk_mul_f32 v[76:77], v[76:77], v[172:173]
	v_or_b32_e32 v172, 48, v204
	v_ashrrev_i32_e32 v173, 31, v172
	v_mov_b32_e32 v202, v203
	v_lshlrev_b64 v[172:173], 8, v[172:173]
	v_pk_mul_f32 v[78:79], v[78:79], v[202:203]
	v_pk_mul_f32 v[74:75], v[74:75], v[202:203]
	v_lshl_add_u64 v[202:203], v[196:197], 0, v[172:173]
	v_cvt_pk_bf16_f32 v172, v104, v105
	v_cvt_pk_bf16_f32 v173, v106, v107
	v_cvt_pk_bf16_f32 v174, v86, v87
	v_cvt_pk_bf16_f32 v175, v88, v89
	s_and_b64 vcc, exec, s[42:43]
	v_add_u32_e32 v204, 0x80, v198
	global_store_dwordx4 v[202:203], v[172:175], off sc1
	s_nop 1
	v_cvt_pk_bf16_f32 v172, v78, v79
	v_cvt_pk_bf16_f32 v173, v80, v81
	v_cvt_pk_bf16_f32 v174, v74, v75
	v_cvt_pk_bf16_f32 v175, v76, v77
	global_store_dwordx4 v[202:203], v[172:175], off offset:64 sc1
	s_cbranch_vccnz .LBB0_395
	v_ashrrev_i32_e32 v205, 31, v204
	s_waitcnt vmcnt(0)
	v_lshlrev_b64 v[82:83], 7, v[204:205]
	v_lshl_add_u64 v[82:83], v[188:189], 0, v[82:83]
	global_load_dwordx4 v[100:103], v[82:83], off offset:16
	global_load_dwordx4 v[116:119], v[82:83], off
	global_load_dwordx4 v[124:127], v[82:83], off offset:80
	global_load_dwordx4 v[128:131], v[82:83], off offset:64
	v_lshlrev_b64 v[82:83], 7, v[198:199]
	v_lshl_add_u64 v[82:83], v[188:189], 0, v[82:83]
	s_mov_b64 s[6:7], 0x4800
	v_lshl_add_u64 v[120:121], v[82:83], 0, s[6:7]
	s_movk_i32 s6, 0x4000
	v_add_co_u32_e32 v82, vcc, s6, v82
	s_nop 1
	v_addc_co_u32_e32 v83, vcc, 0, v83, vcc
	global_load_dwordx4 v[90:93], v[82:83], off offset:2048
	global_load_dwordx4 v[94:97], v[120:121], off offset:80
	s_nop 0
	global_load_dwordx4 v[82:85], v[120:121], off offset:16
	s_nop 0
	global_load_dwordx4 v[120:123], v[120:121], off offset:64

; __device__ __forceinline__ u32x4 pack8(f32x4 a, f32x4 b) { u32x4 w; w.x = cvt_pk_bf16(a[0], a[1]); w.y = cvt_pk_bf16(a[2], a[3]); w.z = cvt_pk_bf16(b[0], b[1]); w.w = cvt_pk_bf16(b[2], b[3]); return w; }
; __device__ __forceinline__ bf16x8 pack8(f32x4 a, f32x4 b) { u32x4 w = {cvtpk(a[0], a[1]), cvtpk(a[2], a[3]), cvtpk(b[0], b[1]), cvtpk(b[2], b[3])}; return *reinterpret_cast<bf16x8*>(&w); }
;     PG8_RSTD_HOOKS
;     __device__ __forceinline__ void operator()(const f32x4 (&acc)[2][2][4][2], const Unit& u, int wr, int wc, int fr, int fq, int par) const {
;     ...
;             for (int mm = 0; mm < 2; ++mm) { const int m = 2 * mp + mm;
;                 const int row = row0 + ai * HALF + m * 16; const int s = row & 4095; const float rs = rsv[ai][m];
;                 f32x4 v[2][2];
; #pragma unroll
;                 for (int bj = 0; bj < 2; ++bj)
; #pragma unroll
;                     for (int n = 0; n < 2; ++n) v[bj][n] = acc[ai][bj][m][n] * rs;
;                 if (rot) {
;                     const float sgn = (fq < 2) ? -1.f : 1.f;
; #pragma unroll
;                     for (int n = 0; n < 2; ++n)
; #pragma unroll
;                         for (int j = 0; j < 4; ++j) { const float mine = v[0][n][j]; const float other = __shfl_xor(mine, 32); v[0][n][j] = mine * c[mm][n][j] + sgn * other * sn[mm][n][j]; }
;                 }
; #pragma unroll
;                 for (int bj = 0; bj < 2; ++bj) {
;                     bf16_t* dst = base + ((size_t)((b * 8 + hh) * 4096 + s)) * 128 + cih0 + 32 * bj;
;                     *(u32x4*)dst = pack8(v[bj][0], v[bj][1]);
;                     cs[bj][0] += v[bj][0]; cs[bj][1] += v[bj][1];
;                 }
.LBB0_397:
	v_and_b32_e32 v98, 0xfcf, v204
	v_or_b32_e32 v202, s3, v98
	v_mov_b32_e32 v172, v200
	v_mov_b32_e32 v173, v200
	v_ashrrev_i32_e32 v203, 31, v202
	v_mov_b32_e32 v174, v200
	v_mov_b32_e32 v175, v200
	v_pk_mul_f32 v[62:63], v[62:63], v[172:173]
	v_pk_mul_f32 v[58:59], v[58:59], v[172:173]
	v_lshlrev_b64 v[172:173], 8, v[202:203]
	v_mov_b32_e32 v98, v201
	v_pk_mul_f32 v[64:65], v[64:65], v[174:175]
	v_pk_mul_f32 v[60:61], v[60:61], v[174:175]
	v_lshl_add_u64 v[206:207], v[196:197], 0, v[172:173]
	v_cvt_pk_bf16_f32 v172, v70, v71
	v_cvt_pk_bf16_f32 v173, v72, v73
	v_cvt_pk_bf16_f32 v174, v66, v67
	v_cvt_pk_bf16_f32 v175, v68, v69
	v_pk_mul_f32 v[56:57], v[56:57], v[98:99] op_sel_hi:[1,0]
	v_pk_mul_f32 v[54:55], v[54:55], v[98:99] op_sel_hi:[1,0]
	v_pk_mul_f32 v[52:53], v[52:53], v[98:99] op_sel_hi:[1,0]
	s_and_b64 vcc, exec, s[42:43]
	v_pk_mul_f32 v[50:51], v[50:51], v[98:99] op_sel_hi:[1,0]
	global_store_dwordx4 v[206:207], v[172:175], off sc1
	s_nop 1
	v_cvt_pk_bf16_f32 v172, v62, v63
	v_cvt_pk_bf16_f32 v173, v64, v65
	v_cvt_pk_bf16_f32 v174, v58, v59
	v_cvt_pk_bf16_f32 v175, v60, v61
	global_store_dwordx4 v[206:207], v[172:175], off offset:64 sc1
	s_cbranch_vccnz .LBB0_399
	ds_bpermute_b32 v98, v224, v55
	ds_bpermute_b32 v174, v224, v56
	ds_bpermute_b32 v175, v224, v57
	ds_bpermute_b32 v172, v224, v54
	v_mov_b32_e32 v214, v57
	s_waitcnt lgkmcnt(0)
	v_cndmask_b32_e64 v173, v98, -v98, s[36:37]
	v_cndmask_b32_e64 v98, v174, -v174, s[36:37]
	s_waitcnt vmcnt(0)
	v_mul_f32_e32 v174, v122, v98
	ds_bpermute_b32 v98, v224, v51
	v_cndmask_b32_e64 v207, v175, -v175, s[36:37]
	v_mov_b32_e32 v215, v123
	v_mov_b32_e32 v206, v93
	v_pk_mul_f32 v[54:55], v[54:55], v[90:91]
	v_cndmask_b32_e64 v172, v172, -v172, s[36:37]
	v_pk_mul_f32 v[206:207], v[214:215], v[206:207]
	v_mul_f32_e32 v56, v56, v92
	v_mov_b32_e32 v57, v206
	v_mov_b32_e32 v175, v207
	v_pk_fma_f32 v[54:55], v[120:121], v[172:173], v[54:55]
	s_waitcnt lgkmcnt(0)
	v_cndmask_b32_e64 v173, v98, -v98, s[36:37]
	ds_bpermute_b32 v98, v224, v53
	v_pk_add_f32 v[56:57], v[56:57], v[174:175]
	ds_bpermute_b32 v174, v224, v52
	ds_bpermute_b32 v172, v224, v50
	v_mov_b32_e32 v214, v53
	s_waitcnt lgkmcnt(2)
	v_cndmask_b32_e64 v207, v98, -v98, s[36:37]
	v_mov_b32_e32 v215, v97
	v_mov_b32_e32 v206, v85
	s_waitcnt lgkmcnt(1)
	v_cndmask_b32_e64 v174, v174, -v174, s[36:37]
	v_pk_mul_f32 v[206:207], v[214:215], v[206:207]
	v_pk_mul_f32 v[50:51], v[50:51], v[82:83]
	s_waitcnt lgkmcnt(0)
	v_cndmask_b32_e64 v172, v172, -v172, s[36:37]
	v_mul_f32_e32 v52, v52, v84
	v_mul_f32_e32 v174, v96, v174
	v_mov_b32_e32 v53, v206
	v_mov_b32_e32 v175, v207
	v_pk_fma_f32 v[50:51], v[94:95], v[172:173], v[50:51]
	v_pk_add_f32 v[52:53], v[52:53], v[174:175]
.LBB0_399:
	s_nop 0
	v_mov_b32_e32 v172, v201
	v_mov_b32_e32 v173, v201
	v_pk_mul_f32 v[48:49], v[48:49], v[172:173]
	v_pk_mul_f32 v[44:45], v[44:45], v[172:173]
	v_or_b32_e32 v172, 16, v202
	v_ashrrev_i32_e32 v173, 31, v172
	v_mov_b32_e32 v200, v201
	v_lshlrev_b64 v[172:173], 8, v[172:173]
	v_pk_mul_f32 v[46:47], v[46:47], v[200:201]
	v_pk_mul_f32 v[42:43], v[42:43], v[200:201]
	v_lshl_add_u64 v[200:201], v[196:197], 0, v[172:173]
	v_cvt_pk_bf16_f32 v172, v54, v55
	v_cvt_pk_bf16_f32 v173, v56, v57
	v_cvt_pk_bf16_f32 v174, v50, v51
	v_cvt_pk_bf16_f32 v175, v52, v53
	s_and_b64 vcc, exec, s[42:43]
	global_store_dwordx4 v[200:201], v[172:175], off sc1
	s_nop 1
	v_cvt_pk_bf16_f32 v172, v46, v47
	v_cvt_pk_bf16_f32 v173, v48, v49
	v_cvt_pk_bf16_f32 v174, v42, v43
	v_cvt_pk_bf16_f32 v175, v44, v45
	global_store_dwordx4 v[200:201], v[172:175], off offset:64 sc1
	s_cbranch_vccnz .LBB0_401
	s_waitcnt vmcnt(0)
	v_or_b32_e32 v82, 32, v204
	v_ashrrev_i32_e32 v83, 31, v82
	v_lshlrev_b64 v[82:83], 7, v[82:83]
	v_lshl_add_u64 v[82:83], v[188:189], 0, v[82:83]
	global_load_dwordx4 v[100:103], v[82:83], off offset:16
	global_load_dwordx4 v[116:119], v[82:83], off
	global_load_dwordx4 v[124:127], v[82:83], off offset:80
	global_load_dwordx4 v[128:131], v[82:83], off offset:64
	v_lshlrev_b64 v[82:83], 7, v[198:199]
	v_lshl_add_u64 v[82:83], v[188:189], 0, v[82:83]
	s_mov_b64 s[6:7], 0x5800
	s_movk_i32 s3, 0x5000
	v_lshl_add_u64 v[120:121], v[82:83], 0, s[6:7]
	v_add_co_u32_e32 v82, vcc, s3, v82
	s_nop 1
	v_addc_co_u32_e32 v83, vcc, 0, v83, vcc
	global_load_dwordx4 v[90:93], v[82:83], off offset:2048
	global_load_dwordx4 v[94:97], v[120:121], off offset:80
	s_nop 0
	global_load_dwordx4 v[82:85], v[120:121], off offset:16
	s_nop 0
	global_load_dwordx4 v[120:123], v[120:121], off offset:64

; __device__ __forceinline__ u32x4 pack8(f32x4 a, f32x4 b) { u32x4 w; w.x = cvt_pk_bf16(a[0], a[1]); w.y = cvt_pk_bf16(a[2], a[3]); w.z = cvt_pk_bf16(b[0], b[1]); w.w = cvt_pk_bf16(b[2], b[3]); return w; }
; __device__ __forceinline__ bf16x8 pack8(f32x4 a, f32x4 b) { u32x4 w = {cvtpk(a[0], a[1]), cvtpk(a[2], a[3]), cvtpk(b[0], b[1]), cvtpk(b[2], b[3])}; return *reinterpret_cast<bf16x8*>(&w); }
;     PG8_RSTD_HOOKS
;     __device__ __forceinline__ void operator()(const f32x4 (&acc)[2][2][4][2], const Unit& u, int wr, int wc, int fr, int fq, int par) const {
;     ...
;             for (int mm = 0; mm < 2; ++mm) { const int m = 2 * mp + mm;
;                 const int row = row0 + ai * HALF + m * 16; const int s = row & 4095; const float rs = rsv[ai][m];
;                 f32x4 v[2][2];
; #pragma unroll
;                 for (int bj = 0; bj < 2; ++bj)
; #pragma unroll
;                     for (int n = 0; n < 2; ++n) v[bj][n] = acc[ai][bj][m][n] * rs;
;                 if (rot) {
;                     const float sgn = (fq < 2) ? -1.f : 1.f;
; #pragma unroll
;                     for (int n = 0; n < 2; ++n)
; #pragma unroll
;                         for (int j = 0; j < 4; ++j) { const float mine = v[0][n][j]; const float other = __shfl_xor(mine, 32); v[0][n][j] = mine * c[mm][n][j] + sgn * other * sn[mm][n][j]; }
;                 }
; #pragma unroll
;                 for (int bj = 0; bj < 2; ++bj) {
;                     bf16_t* dst = base + ((size_t)((b * 8 + hh) * 4096 + s)) * 128 + cih0 + 32 * bj;
;                     *(u32x4*)dst = pack8(v[bj][0], v[bj][1]);
;                     cs[bj][0] += v[bj][0]; cs[bj][1] += v[bj][1];
;                 }
;             }
;         }
;         if (t == 1) {
; #pragma unroll
;             for (int bj = 0; bj < 2; ++bj)
; #pragma unroll
;                 for (int n = 0; n < 2; ++n)
; #pragma unroll
;                     for (int j = 0; j < 4; ++j) { float x = cs[bj][n][j]; x += __shfl_xor(x, 1); x += __shfl_xor(x, 2); x += __shfl_xor(x, 4); x += __shfl_xor(x, 8);
;                         if (fr == 0) atomicAdd(kmean + ((size_t)((b * 8 + hh) * 16 + blk)) * 128 + cih0 + 32 * bj + 4 * n + j, x); }
.LBB0_403:
	s_waitcnt vmcnt(0)
	v_mov_b32_e32 v100, v194
	v_mov_b32_e32 v101, v194
	v_pk_mul_f32 v[30:31], v[30:31], v[100:101]
	v_pk_mul_f32 v[26:27], v[26:27], v[100:101]
	v_or_b32_e32 v100, 32, v202
	v_ashrrev_i32_e32 v101, 31, v100
	v_lshlrev_b64 v[100:101], 8, v[100:101]
	v_mov_b32_e32 v102, v194
	v_mov_b32_e32 v103, v194
	v_lshl_add_u64 v[116:117], v[196:197], 0, v[100:101]
	v_cvt_pk_bf16_f32 v100, v38, v39
	v_cvt_pk_bf16_f32 v101, v40, v41
	v_pk_mul_f32 v[32:33], v[32:33], v[102:103]
	v_pk_mul_f32 v[28:29], v[28:29], v[102:103]
	v_cvt_pk_bf16_f32 v102, v34, v35
	v_cvt_pk_bf16_f32 v103, v36, v37
	global_store_dwordx4 v[116:117], v[100:103], off sc1
	v_mov_b32_e32 v98, v195
	v_pk_mul_f32 v[24:25], v[24:25], v[98:99] op_sel_hi:[1,0]
	v_cvt_pk_bf16_f32 v100, v30, v31
	v_cvt_pk_bf16_f32 v101, v32, v33
	v_cvt_pk_bf16_f32 v102, v26, v27
	v_cvt_pk_bf16_f32 v103, v28, v29
	global_store_dwordx4 v[116:117], v[100:103], off offset:64 sc1
	v_pk_mul_f32 v[20:21], v[20:21], v[98:99] op_sel_hi:[1,0]
	s_and_b64 vcc, exec, s[42:43]
	v_pk_mul_f32 v[100:101], v[22:23], v[98:99] op_sel_hi:[1,0]
	v_pk_mul_f32 v[22:23], v[18:19], v[98:99] op_sel_hi:[1,0]
	s_cbranch_vccnz .LBB0_405
	ds_bpermute_b32 v102, v224, v100
	v_pk_mul_f32 v[18:19], v[100:101], v[90:91]
	ds_bpermute_b32 v100, v224, v24
	ds_bpermute_b32 v98, v224, v101
	ds_bpermute_b32 v101, v224, v25
	v_mul_f32_e32 v24, v24, v92
	s_waitcnt lgkmcnt(3)
	v_cndmask_b32_e64 v90, v102, -v102, s[36:37]
	s_waitcnt lgkmcnt(2)
	v_cndmask_b32_e64 v92, v100, -v100, s[36:37]
	v_mul_f32_e32 v92, v122, v92
	s_waitcnt lgkmcnt(0)
	v_cndmask_b32_e64 v101, v101, -v101, s[36:37]
	v_mov_b32_e32 v122, v25
	v_mov_b32_e32 v100, v93
	v_cndmask_b32_e64 v91, v98, -v98, s[36:37]
	v_pk_mul_f32 v[100:101], v[122:123], v[100:101]
	s_nop 0
	v_mov_b32_e32 v25, v100
	v_mov_b32_e32 v93, v101
	v_pk_fma_f32 v[100:101], v[120:121], v[90:91], v[18:19]
	v_pk_mul_f32 v[18:19], v[22:23], v[82:83]
	ds_bpermute_b32 v82, v224, v20
	ds_bpermute_b32 v90, v224, v23
	ds_bpermute_b32 v91, v224, v22
	ds_bpermute_b32 v83, v224, v21
	v_mul_f32_e32 v20, v20, v84
	s_waitcnt lgkmcnt(3)
	v_cndmask_b32_e64 v82, v82, -v82, s[36:37]
	s_waitcnt lgkmcnt(2)
	v_cndmask_b32_e64 v23, v90, -v90, s[36:37]
	s_waitcnt lgkmcnt(1)
	v_cndmask_b32_e64 v22, v91, -v91, s[36:37]
	v_mul_f32_e32 v82, v96, v82
	s_waitcnt lgkmcnt(0)
	v_cndmask_b32_e64 v91, v83, -v83, s[36:37]
	v_mov_b32_e32 v96, v21
	v_mov_b32_e32 v90, v85
	v_pk_mul_f32 v[84:85], v[96:97], v[90:91]
	v_pk_add_f32 v[24:25], v[24:25], v[92:93]
	v_mov_b32_e32 v21, v84
	v_mov_b32_e32 v83, v85
	v_pk_fma_f32 v[22:23], v[94:95], v[22:23], v[18:19]
	v_pk_add_f32 v[20:21], v[20:21], v[82:83]
.LBB0_405:
	v_mov_b32_e32 v194, v195
	v_pk_mul_f32 v[18:19], v[14:15], v[194:195]
	v_pk_mul_f32 v[14:15], v[10:11], v[194:195]
	v_or_b32_e32 v10, 48, v202
	v_ashrrev_i32_e32 v11, 31, v10
	v_mov_b32_e32 v82, v195
	v_mov_b32_e32 v83, v195
	v_lshlrev_b64 v[10:11], 8, v[10:11]
	v_pk_mul_f32 v[16:17], v[16:17], v[82:83]
	v_pk_mul_f32 v[12:13], v[12:13], v[82:83]
	v_lshl_add_u64 v[10:11], v[196:197], 0, v[10:11]
	v_cvt_pk_bf16_f32 v82, v100, v101
	v_cvt_pk_bf16_f32 v83, v24, v25
	v_cvt_pk_bf16_f32 v84, v22, v23
	v_cvt_pk_bf16_f32 v85, v20, v21
	s_cmp_eq_u32 s90, 1
	global_store_dwordx4 v[10:11], v[82:85], off sc1
	s_nop 1
	v_cvt_pk_bf16_f32 v82, v18, v19
	v_cvt_pk_bf16_f32 v83, v16, v17
	v_cvt_pk_bf16_f32 v84, v14, v15
	v_cvt_pk_bf16_f32 v85, v12, v13
	global_store_dwordx4 v[10:11], v[82:85], off offset:64 sc1
	s_cbranch_scc0 .LBB0_439
	v_pk_add_f32 v[10:11], v[168:169], 0 op_sel_hi:[1,0]
	s_lshl_b32 s0, s0, 7
	v_pk_add_f32 v[10:11], v[10:11], v[152:153]
	s_lshl_b32 s1, s1, 4
	v_pk_add_f32 v[10:11], v[10:11], v[136:137]
	s_and_b32 s2, s2, 15
	v_pk_add_f32 v[10:11], v[10:11], v[104:105]
	s_or_b32 s0, s1, s0
	v_pk_add_f32 v[10:11], v[10:11], v[70:71]
	s_or_b32 s0, s0, s2
	v_pk_add_f32 v[10:11], v[10:11], v[54:55]
	s_ashr_i32 s1, s0, 31
	v_pk_add_f32 v[10:11], v[10:11], v[38:39]
	s_lshl_b64 s[0:1], s[0:1], 9
	v_pk_add_f32 v[38:39], v[10:11], v[100:101]
	ds_bpermute_b32 v10, v208, v38
	s_waitcnt lgkmcnt(0)
	v_add_f32_e32 v10, v38, v10
	ds_bpermute_b32 v11, v225, v10
	s_waitcnt lgkmcnt(0)
	v_add_f32_e32 v10, v10, v11
	ds_bpermute_b32 v11, v226, v10
	s_waitcnt lgkmcnt(0)
	v_add_f32_e32 v38, v10, v11
	ds_bpermute_b32 v54, v227, v38
	v_lshl_add_u64 v[10:11], v[186:187], 0, s[0:1]
	s_and_saveexec_b64 s[0:1], s[38:39]
	s_cbranch_execz .LBB0_408
	s_waitcnt lgkmcnt(0)
	v_add_f32_e32 v38, v38, v54
	global_atomic_add_f32 v[10:11], v38, off

; __device__ __forceinline__ u32x4 pack8(f32x4 a, f32x4 b) { u32x4 w; w.x = cvt_pk_bf16(a[0], a[1]); w.y = cvt_pk_bf16(a[2], a[3]); w.z = cvt_pk_bf16(b[0], b[1]); w.w = cvt_pk_bf16(b[2], b[3]); return w; }
; __device__ __forceinline__ bf16x8 pack8(f32x4 a, f32x4 b) { u32x4 w = {cvtpk(a[0], a[1]), cvtpk(a[2], a[3]), cvtpk(b[0], b[1]), cvtpk(b[2], b[3])}; return *reinterpret_cast<bf16x8*>(&w); }
;     __device__ __forceinline__ void operator()(const f32x4 (&acc)[2][2][4][2], const Unit& u, int wr, int wc, int fr, int fq, int par) const {
;     ...
;             for (int m = 0; m < 4; ++m) { const size_t off = (size_t)(row0 + ai * HALF + m * 16) * 1024 + col0; float qq = 0.f;
; #pragma unroll
;                 for (int bj = 0; bj < 2; ++bj) { const f32x4 o0 = acc[ai][bj][m][0] * sc[bj][0], o1 = acc[ai][bj][m][1] * sc[bj][1];
;                     *(u32x4*)(xb + off + bj * 32) = pack8(o0, o1);
;                     qq += ((o0[0] * o0[0] + o0[1] * o0[1]) + (o0[2] * o0[2] + o0[3] * o0[3])) + ((o1[0] * o1[0] + o1[1] * o1[1]) + (o1[2] * o1[2] + o1[3] * o1[3])); }
;                 qq += __shfl_xor(qq, 16); qq += __shfl_xor(qq, 32);
;                 if (fq == 0) ssout[(size_t)(row0 + ai * HALF + m * 16) * 16 + u.pn * 4 + wc] = qq; }
.LBB0_496:
	s_waitcnt vmcnt(0)
	v_pk_mul_f32 v[34:35], v[34:35], v[140:141]
	v_pk_mul_f32 v[36:37], v[36:37], v[142:143]
	v_pk_mul_f32 v[166:167], v[100:101], v[132:133]
	v_cvt_pk_bf16_f32 v100, v34, v35
	v_mul_f32_e32 v35, v35, v35
	v_fmac_f32_e32 v35, v34, v34
	v_mul_f32_e32 v34, v37, v37
	v_pk_mul_f32 v[164:165], v[102:103], v[134:135]
	v_fmac_f32_e32 v34, v36, v36
	v_cvt_pk_bf16_f32 v101, v36, v37
	v_add_f32_e32 v34, v35, v34
	v_mul_f32_e32 v35, v167, v167
	v_mul_f32_e32 v36, v165, v165
	v_fmac_f32_e32 v35, v166, v166
	v_fmac_f32_e32 v36, v164, v164
	v_add_f32_e32 v35, v35, v36
	v_add_f32_e32 v36, v34, v35
	v_pk_mul_f32 v[106:107], v[106:107], v[146:147]
	v_pk_mul_f32 v[34:35], v[104:105], v[144:145]
	v_pk_mul_f32 v[104:105], v[130:131], v[138:139]
	v_mul_f32_e32 v37, v35, v35
	v_mul_f32_e32 v130, v107, v107
	v_pk_mul_f32 v[128:129], v[128:129], v[136:137]
	v_fmac_f32_e32 v37, v34, v34
	v_fmac_f32_e32 v130, v106, v106
	v_add_f32_e32 v37, v37, v130
	v_mul_f32_e32 v130, v129, v129
	v_mul_f32_e32 v131, v105, v105
	v_fmac_f32_e32 v130, v128, v128
	v_fmac_f32_e32 v131, v104, v104
	v_add_f32_e32 v130, v130, v131
	v_add_f32_e32 v37, v37, v130
	v_cmp_lt_i32_e32 vcc, v252, v213
	v_add_f32_e32 v37, v36, v37
	v_lshl_add_u32 v156, s86, 8, v158
	v_cndmask_b32_e32 v36, v212, v252, vcc
	v_lshlrev_b32_e32 v36, 2, v36
	v_ashrrev_i32_e32 v157, 31, v156
	v_cvt_pk_bf16_f32 v102, v166, v167
	v_cvt_pk_bf16_f32 v103, v164, v165
	ds_bpermute_b32 v164, v36, v37
	v_lshlrev_b64 v[162:163], 11, v[156:157]
	v_lshl_add_u64 v[130:131], s[96:97], 0, v[162:163]
	v_lshl_add_u64 v[130:131], v[154:155], 1, v[130:131]
	v_cmp_lt_i32_e32 vcc, v211, v213
	global_store_dwordx4 v[130:131], v[100:103], off sc1
	s_nop 1
	v_cvt_pk_bf16_f32 v100, v34, v35
	v_cndmask_b32_e32 v35, v212, v211, vcc
	s_waitcnt lgkmcnt(0)
	v_add_f32_e32 v34, v37, v164
	v_lshlrev_b32_e32 v37, 2, v35
	ds_bpermute_b32 v35, v37, v34
	v_cvt_pk_bf16_f32 v101, v106, v107
	v_cvt_pk_bf16_f32 v102, v128, v129
	v_cvt_pk_bf16_f32 v103, v104, v105
	global_store_dwordx4 v[130:131], v[100:103], off offset:64 sc1
	s_and_saveexec_b64 s[6:7], s[38:39]
	s_cbranch_execz .LBB0_498
	s_waitcnt lgkmcnt(0)
	v_add_f32_e32 v100, v34, v35
	s_lshl_b32 s12, s89, 2
	v_lshlrev_b64 v[34:35], 6, v[156:157]
	s_ashr_i32 s13, s12, 31
	v_lshl_add_u64 v[34:35], s[16:17], 0, v[34:35]
	v_lshl_add_u64 v[34:35], s[12:13], 2, v[34:35]
	s_lshl_b32 s86, s27, 2
	v_lshl_add_u64 v[34:35], v[34:35], 0, s[86:87]
	global_store_dword v[34:35], v100, off sc1
.LBB0_498:
	s_or_b64 exec, exec, s[6:7]
	v_pk_mul_f32 v[90:91], v[90:91], v[132:133]
	v_pk_mul_f32 v[102:103], v[32:33], v[142:143]
	v_pk_mul_f32 v[104:105], v[30:31], v[140:141]
	v_pk_mul_f32 v[92:93], v[92:93], v[134:135]
	v_cvt_pk_bf16_f32 v30, v104, v105
	v_cvt_pk_bf16_f32 v31, v102, v103
	v_cvt_pk_bf16_f32 v32, v90, v91
	v_mul_f32_e32 v91, v91, v91
	v_mul_f32_e32 v105, v105, v105
	v_mul_f32_e32 v103, v103, v103
	v_fmac_f32_e32 v91, v90, v90
	v_mul_f32_e32 v90, v93, v93
	v_fmac_f32_e32 v105, v104, v104
	v_fmac_f32_e32 v103, v102, v102
	v_fmac_f32_e32 v90, v92, v92
	v_pk_mul_f32 v[84:85], v[84:85], v[146:147]
	v_pk_mul_f32 v[82:83], v[82:83], v[144:145]
	v_add_f32_e32 v102, v105, v103
	v_add_f32_e32 v90, v91, v90
	v_mul_f32_e32 v103, v83, v83
	v_mul_f32_e32 v104, v85, v85
	v_cvt_pk_bf16_f32 v33, v92, v93
	v_add_f32_e32 v102, v102, v90
	v_pk_mul_f32 v[90:91], v[126:127], v[138:139]
	v_pk_mul_f32 v[92:93], v[124:125], v[136:137]
	v_fmac_f32_e32 v103, v82, v82
	v_fmac_f32_e32 v104, v84, v84
	v_add_f32_e32 v103, v103, v104
	v_mul_f32_e32 v104, v93, v93
	v_mul_f32_e32 v105, v91, v91
	v_fmac_f32_e32 v104, v92, v92
	v_fmac_f32_e32 v105, v90, v90
	v_add_f32_e32 v104, v104, v105
	v_add_f32_e32 v103, v103, v104
	v_add_f32_e32 v102, v102, v103
	v_or_b32_e32 v34, 16, v156
	ds_bpermute_b32 v103, v36, v102
	s_waitcnt lgkmcnt(1)
	v_ashrrev_i32_e32 v35, 31, v34
	v_lshlrev_b64 v[100:101], 11, v[34:35]
	v_lshl_add_u64 v[100:101], s[96:97], 0, v[100:101]
	v_lshl_add_u64 v[100:101], v[154:155], 1, v[100:101]
	global_store_dwordx4 v[100:101], v[30:33], off sc1
	v_cvt_pk_bf16_f32 v82, v82, v83
	v_cvt_pk_bf16_f32 v83, v84, v85
	v_cvt_pk_bf16_f32 v84, v92, v93
	v_cvt_pk_bf16_f32 v85, v90, v91
	global_store_dwordx4 v[100:101], v[82:85], off offset:64 sc1
	s_waitcnt lgkmcnt(0)
	v_add_f32_e32 v30, v102, v103
	ds_bpermute_b32 v31, v37, v30
	s_and_saveexec_b64 s[6:7], s[38:39]
	s_cbranch_execz .LBB0_500
	s_waitcnt lgkmcnt(0)
	v_add_f32_e32 v32, v30, v31
	s_lshl_b32 s12, s89, 2
	v_lshlrev_b64 v[30:31], 6, v[34:35]
	s_ashr_i32 s13, s12, 31
	v_lshl_add_u64 v[30:31], s[16:17], 0, v[30:31]
	v_lshl_add_u64 v[30:31], s[12:13], 2, v[30:31]
	s_lshl_b32 s86, s27, 2
	v_lshl_add_u64 v[30:31], v[30:31], 0, s[86:87]
	global_store_dword v[30:31], v32, off sc1
; __device__ __forceinline__ u32x4 pack8(f32x4 a, f32x4 b) { u32x4 w; w.x = cvt_pk_bf16(a[0], a[1]); w.y = cvt_pk_bf16(a[2], a[3]); w.z = cvt_pk_bf16(b[0], b[1]); w.w = cvt_pk_bf16(b[2], b[3]); return w; }
; __device__ __forceinline__ bf16x8 pack8(f32x4 a, f32x4 b) { u32x4 w = {cvtpk(a[0], a[1]), cvtpk(a[2], a[3]), cvtpk(b[0], b[1]), cvtpk(b[2], b[3])}; return *reinterpret_cast<bf16x8*>(&w); }
;     __device__ __forceinline__ void operator()(const f32x4 (&acc)[2][2][4][2], const Unit& u, int wr, int wc, int fr, int fq, int par) const {
;     ...
;             for (int m = 0; m < 4; ++m) { const size_t off = (size_t)(row0 + ai * HALF + m * 16) * 1024 + col0; float qq = 0.f;
; #pragma unroll
;                 for (int bj = 0; bj < 2; ++bj) { const f32x4 o0 = acc[ai][bj][m][0] * sc[bj][0], o1 = acc[ai][bj][m][1] * sc[bj][1];
;                     *(u32x4*)(xb + off + bj * 32) = pack8(o0, o1);
;                     qq += ((o0[0] * o0[0] + o0[1] * o0[1]) + (o0[2] * o0[2] + o0[3] * o0[3])) + ((o1[0] * o1[0] + o1[1] * o1[1]) + (o1[2] * o1[2] + o1[3] * o1[3])); }
;                 qq += __shfl_xor(qq, 16); qq += __shfl_xor(qq, 32);
;                 if (fq == 0) ssout[(size_t)(row0 + ai * HALF + m * 16) * 16 + u.pn * 4 + wc] = qq; }
.LBB0_500:
	s_or_b64 exec, exec, s[6:7]
	v_pk_mul_f32 v[34:35], v[24:25], v[142:143]
	v_pk_mul_f32 v[82:83], v[22:23], v[140:141]
	v_pk_mul_f32 v[78:79], v[78:79], v[132:133]
	v_cvt_pk_bf16_f32 v22, v82, v83
	v_cvt_pk_bf16_f32 v23, v34, v35
	v_mul_f32_e32 v83, v83, v83
	v_mul_f32_e32 v35, v35, v35
	v_fmac_f32_e32 v83, v82, v82
	v_fmac_f32_e32 v35, v34, v34
	v_pk_mul_f32 v[80:81], v[80:81], v[134:135]
	v_add_f32_e32 v34, v83, v35
	v_mul_f32_e32 v35, v79, v79
	v_cvt_pk_bf16_f32 v24, v78, v79
	v_fmac_f32_e32 v35, v78, v78
	v_mul_f32_e32 v78, v81, v81
	v_fmac_f32_e32 v78, v80, v80
	v_add_f32_e32 v35, v35, v78
	v_cvt_pk_bf16_f32 v25, v80, v81
	v_add_f32_e32 v80, v34, v35
	v_pk_mul_f32 v[34:35], v[72:73], v[146:147]
	v_pk_mul_f32 v[70:71], v[70:71], v[144:145]
	v_mul_f32_e32 v82, v35, v35
	v_mul_f32_e32 v81, v71, v71
	v_pk_mul_f32 v[72:73], v[122:123], v[138:139]
	v_pk_mul_f32 v[78:79], v[120:121], v[136:137]
	v_fmac_f32_e32 v81, v70, v70
	v_fmac_f32_e32 v82, v34, v34
	v_add_f32_e32 v81, v81, v82
	v_mul_f32_e32 v82, v79, v79
	v_mul_f32_e32 v83, v73, v73
	v_fmac_f32_e32 v82, v78, v78
	v_fmac_f32_e32 v83, v72, v72
	v_add_f32_e32 v82, v82, v83
	v_add_f32_e32 v81, v81, v82
	v_add_f32_e32 v82, v80, v81
	v_or_b32_e32 v30, 32, v156
	ds_bpermute_b32 v83, v36, v82
	s_waitcnt lgkmcnt(1)
	v_ashrrev_i32_e32 v31, 31, v30
	v_lshlrev_b64 v[32:33], 11, v[30:31]
	v_lshl_add_u64 v[32:33], s[96:97], 0, v[32:33]
	v_lshl_add_u64 v[80:81], v[154:155], 1, v[32:33]
	global_store_dwordx4 v[80:81], v[22:25], off sc1
	v_cvt_pk_bf16_f32 v32, v70, v71
	v_cvt_pk_bf16_f32 v33, v34, v35
	v_cvt_pk_bf16_f32 v34, v78, v79
	v_cvt_pk_bf16_f32 v35, v72, v73
	global_store_dwordx4 v[80:81], v[32:35], off offset:64 sc1
	s_waitcnt lgkmcnt(0)
	v_add_f32_e32 v22, v82, v83
	ds_bpermute_b32 v23, v37, v22
	s_and_saveexec_b64 s[6:7], s[38:39]
	s_cbranch_execz .LBB0_502
	s_waitcnt lgkmcnt(0)
	v_add_f32_e32 v24, v22, v23
	s_lshl_b32 s12, s89, 2
	v_lshlrev_b64 v[22:23], 6, v[30:31]
	s_ashr_i32 s13, s12, 31
	v_lshl_add_u64 v[22:23], s[16:17], 0, v[22:23]
	v_lshl_add_u64 v[22:23], s[12:13], 2, v[22:23]
	s_lshl_b32 s86, s27, 2
	v_lshl_add_u64 v[22:23], v[22:23], 0, s[86:87]
	global_store_dword v[22:23], v24, off sc1
.LBB0_502:
	s_or_b64 exec, exec, s[6:7]
	v_pk_mul_f32 v[30:31], v[16:17], v[142:143]
	v_pk_mul_f32 v[32:33], v[14:15], v[140:141]
	v_pk_mul_f32 v[34:35], v[64:65], v[134:135]
	v_cvt_pk_bf16_f32 v14, v32, v33
	v_cvt_pk_bf16_f32 v15, v30, v31
	v_mul_f32_e32 v33, v33, v33
	v_mul_f32_e32 v31, v31, v31
	v_pk_mul_f32 v[62:63], v[62:63], v[132:133]
	v_fmac_f32_e32 v33, v32, v32
	v_fmac_f32_e32 v31, v30, v30
	v_add_f32_e32 v30, v33, v31
	v_mul_f32_e32 v31, v63, v63
	v_mul_f32_e32 v32, v35, v35
	v_fmac_f32_e32 v31, v62, v62
	v_fmac_f32_e32 v32, v34, v34
	v_add_f32_e32 v31, v31, v32
	v_cvt_pk_bf16_f32 v16, v62, v63
	v_add_f32_e32 v62, v30, v31
	v_pk_mul_f32 v[32:33], v[56:57], v[146:147]
	v_pk_mul_f32 v[30:31], v[54:55], v[144:145]
	v_mul_f32_e32 v57, v33, v33
	v_mul_f32_e32 v56, v31, v31
	v_cvt_pk_bf16_f32 v17, v34, v35
	v_pk_mul_f32 v[34:35], v[114:115], v[138:139]
	v_pk_mul_f32 v[54:55], v[112:113], v[136:137]
	v_fmac_f32_e32 v56, v30, v30
	v_fmac_f32_e32 v57, v32, v32
	v_add_f32_e32 v56, v56, v57
	v_mul_f32_e32 v57, v55, v55
	v_mul_f32_e32 v63, v35, v35
	v_fmac_f32_e32 v57, v54, v54
	v_fmac_f32_e32 v63, v34, v34
	v_add_f32_e32 v57, v57, v63
	v_add_f32_e32 v56, v56, v57
	v_add_f32_e32 v56, v62, v56
	v_or_b32_e32 v22, 48, v156
	ds_bpermute_b32 v57, v36, v56
	s_waitcnt lgkmcnt(1)
	v_ashrrev_i32_e32 v23, 31, v22
	v_lshlrev_b64 v[24:25], 11, v[22:23]
	v_lshl_add_u64 v[24:25], s[96:97], 0, v[24:25]
	v_lshl_add_u64 v[24:25], v[154:155], 1, v[24:25]
	global_store_dwordx4 v[24:25], v[14:17], off sc1
	v_cvt_pk_bf16_f32 v30, v30, v31
	v_cvt_pk_bf16_f32 v31, v32, v33
	v_cvt_pk_bf16_f32 v32, v54, v55
	v_cvt_pk_bf16_f32 v33, v34, v35
	global_store_dwordx4 v[24:25], v[30:33], off offset:64 sc1
	s_waitcnt lgkmcnt(0)
	v_add_f32_e32 v14, v56, v57
	ds_bpermute_b32 v15, v37, v14
	s_and_saveexec_b64 s[6:7], s[38:39]
	s_cbranch_execz .LBB0_504
	s_waitcnt lgkmcnt(0)
	v_add_f32_e32 v16, v14, v15
	s_lshl_b32 s12, s89, 2
	v_lshlrev_b64 v[14:15], 6, v[22:23]
	s_ashr_i32 s13, s12, 31
	v_lshl_add_u64 v[14:15], s[16:17], 0, v[14:15]
	v_lshl_add_u64 v[14:15], s[12:13], 2, v[14:15]
	s_lshl_b32 s86, s27, 2
	v_lshl_add_u64 v[14:15], v[14:15], 0, s[86:87]
	global_store_dword v[14:15], v16, off sc1
.LBB0_504:
	s_or_b64 exec, exec, s[6:7]
	v_pk_mul_f32 v[20:21], v[20:21], v[142:143]
	v_pk_mul_f32 v[24:25], v[18:19], v[140:141]
	v_pk_mul_f32 v[30:31], v[76:77], v[134:135]
	v_cvt_pk_bf16_f32 v16, v24, v25
	v_cvt_pk_bf16_f32 v17, v20, v21
	v_mul_f32_e32 v25, v25, v25
	v_mul_f32_e32 v21, v21, v21
	v_pk_mul_f32 v[32:33], v[74:75], v[132:133]
	v_fmac_f32_e32 v25, v24, v24
	v_fmac_f32_e32 v21, v20, v20
	v_add_f32_e32 v20, v25, v21
	v_mul_f32_e32 v21, v33, v33
	v_mul_f32_e32 v24, v31, v31
	v_fmac_f32_e32 v21, v32, v32
	v_fmac_f32_e32 v24, v30, v30
	v_add_f32_e32 v21, v21, v24
	v_add_f32_e32 v34, v20, v21
	v_pk_mul_f32 v[20:21], v[68:69], v[146:147]
	v_pk_mul_f32 v[24:25], v[66:67], v[144:145]
	v_mul_f32_e32 v54, v21, v21
	v_mul_f32_e32 v35, v25, v25
	v_cvt_pk_bf16_f32 v18, v32, v33
	v_cvt_pk_bf16_f32 v19, v30, v31
	v_pk_mul_f32 v[30:31], v[118:119], v[138:139]
	v_pk_mul_f32 v[32:33], v[116:117], v[136:137]
	v_fmac_f32_e32 v35, v24, v24
	v_fmac_f32_e32 v54, v20, v20
	v_add_f32_e32 v35, v35, v54
	v_mul_f32_e32 v54, v33, v33
	v_mul_f32_e32 v55, v31, v31
	v_fmac_f32_e32 v54, v32, v32
	v_fmac_f32_e32 v55, v30, v30
	v_add_f32_e32 v54, v54, v55
	v_add_f32_e32 v35, v35, v54
	v_add_f32_e32 v34, v34, v35
	v_add_u32_e32 v14, 0x80, v156
	ds_bpermute_b32 v35, v36, v34
	s_waitcnt lgkmcnt(1)
	v_ashrrev_i32_e32 v15, 31, v14
	v_lshlrev_b64 v[22:23], 11, v[14:15]
	v_lshl_add_u64 v[22:23], s[96:97], 0, v[22:23]
	v_lshl_add_u64 v[22:23], v[154:155], 1, v[22:23]
	global_store_dwordx4 v[22:23], v[16:19], off sc1
	s_waitcnt lgkmcnt(0)
	s_nop 0
	v_add_f32_e32 v16, v34, v35
	ds_bpermute_b32 v17, v37, v16
	v_cvt_pk_bf16_f32 v18, v24, v25
	v_cvt_pk_bf16_f32 v19, v20, v21
	v_cvt_pk_bf16_f32 v20, v32, v33
	v_cvt_pk_bf16_f32 v21, v30, v31
	global_store_dwordx4 v[22:23], v[18:21], off offset:64 sc1
	s_and_saveexec_b64 s[6:7], s[38:39]
	s_cbranch_execz .LBB0_506
	s_lshl_b32 s12, s89, 2
	v_lshlrev_b64 v[14:15], 6, v[14:15]
	s_ashr_i32 s13, s12, 31
	v_lshl_add_u64 v[14:15], s[16:17], 0, v[14:15]
	v_lshl_add_u64 v[14:15], s[12:13], 2, v[14:15]
	s_lshl_b32 s86, s27, 2
	s_waitcnt lgkmcnt(0)
	v_add_f32_e32 v16, v16, v17
	v_lshl_add_u64 v[14:15], v[14:15], 0, s[86:87]
	global_store_dword v[14:15], v16, off sc1
; __device__ __forceinline__ u32x4 pack8(f32x4 a, f32x4 b) { u32x4 w; w.x = cvt_pk_bf16(a[0], a[1]); w.y = cvt_pk_bf16(a[2], a[3]); w.z = cvt_pk_bf16(b[0], b[1]); w.w = cvt_pk_bf16(b[2], b[3]); return w; }
; __device__ __forceinline__ bf16x8 pack8(f32x4 a, f32x4 b) { u32x4 w = {cvtpk(a[0], a[1]), cvtpk(a[2], a[3]), cvtpk(b[0], b[1]), cvtpk(b[2], b[3])}; return *reinterpret_cast<bf16x8*>(&w); }
;     __device__ __forceinline__ void operator()(const f32x4 (&acc)[2][2][4][2], const Unit& u, int wr, int wc, int fr, int fq, int par) const {
;     ...
;             for (int m = 0; m < 4; ++m) { const size_t off = (size_t)(row0 + ai * HALF + m * 16) * 1024 + col0; float qq = 0.f;
; #pragma unroll
;                 for (int bj = 0; bj < 2; ++bj) { const f32x4 o0 = acc[ai][bj][m][0] * sc[bj][0], o1 = acc[ai][bj][m][1] * sc[bj][1];
;                     *(u32x4*)(xb + off + bj * 32) = pack8(o0, o1);
;                     qq += ((o0[0] * o0[0] + o0[1] * o0[1]) + (o0[2] * o0[2] + o0[3] * o0[3])) + ((o1[0] * o1[0] + o1[1] * o1[1]) + (o1[2] * o1[2] + o1[3] * o1[3])); }
;                 qq += __shfl_xor(qq, 16); qq += __shfl_xor(qq, 32);
;                 if (fq == 0) ssout[(size_t)(row0 + ai * HALF + m * 16) * 16 + u.pn * 4 + wc] = qq; }
.LBB0_506:
	s_or_b64 exec, exec, s[6:7]
	v_pk_mul_f32 v[18:19], v[12:13], v[142:143]
	v_pk_mul_f32 v[20:21], v[10:11], v[140:141]
	v_pk_mul_f32 v[22:23], v[60:61], v[134:135]
	v_cvt_pk_bf16_f32 v10, v20, v21
	v_cvt_pk_bf16_f32 v11, v18, v19
	v_mul_f32_e32 v21, v21, v21
	v_mul_f32_e32 v19, v19, v19
	v_pk_mul_f32 v[24:25], v[58:59], v[132:133]
	v_fmac_f32_e32 v21, v20, v20
	v_fmac_f32_e32 v19, v18, v18
	v_add_f32_e32 v18, v21, v19
	v_mul_f32_e32 v19, v25, v25
	v_mul_f32_e32 v20, v23, v23
	v_fmac_f32_e32 v19, v24, v24
	v_fmac_f32_e32 v20, v22, v22
	v_add_f32_e32 v19, v19, v20
	v_add_f32_e32 v30, v18, v19
	v_pk_mul_f32 v[18:19], v[52:53], v[146:147]
	v_pk_mul_f32 v[20:21], v[50:51], v[144:145]
	v_mul_f32_e32 v32, v19, v19
	v_mul_f32_e32 v31, v21, v21
	v_cvt_pk_bf16_f32 v12, v24, v25
	v_cvt_pk_bf16_f32 v13, v22, v23
	v_pk_mul_f32 v[22:23], v[110:111], v[138:139]
	v_pk_mul_f32 v[24:25], v[108:109], v[136:137]
	v_fmac_f32_e32 v31, v20, v20
	v_fmac_f32_e32 v32, v18, v18
	v_add_f32_e32 v31, v31, v32
	v_mul_f32_e32 v32, v25, v25
	v_mul_f32_e32 v33, v23, v23
	v_fmac_f32_e32 v32, v24, v24
	v_fmac_f32_e32 v33, v22, v22
	v_add_f32_e32 v32, v32, v33
	v_add_f32_e32 v31, v31, v32
	v_add_f32_e32 v32, v30, v31
	v_add_u32_e32 v14, 0x90, v156
	ds_bpermute_b32 v33, v36, v32
	v_ashrrev_i32_e32 v15, 31, v14
	s_waitcnt lgkmcnt(1)
	v_lshlrev_b64 v[16:17], 11, v[14:15]
	v_lshl_add_u64 v[16:17], s[96:97], 0, v[16:17]
	v_lshl_add_u64 v[30:31], v[154:155], 1, v[16:17]
	global_store_dwordx4 v[30:31], v[10:13], off sc1
	v_cvt_pk_bf16_f32 v16, v20, v21
	v_cvt_pk_bf16_f32 v17, v18, v19
	v_cvt_pk_bf16_f32 v18, v24, v25
	v_cvt_pk_bf16_f32 v19, v22, v23
	global_store_dwordx4 v[30:31], v[16:19], off offset:64 sc1
	s_waitcnt lgkmcnt(0)
	v_add_f32_e32 v10, v32, v33
	ds_bpermute_b32 v11, v37, v10
	s_and_saveexec_b64 s[6:7], s[38:39]
	s_cbranch_execz .LBB0_508
	s_waitcnt lgkmcnt(0)
	v_add_f32_e32 v12, v10, v11
	s_lshl_b32 s12, s89, 2
	v_lshlrev_b64 v[10:11], 6, v[14:15]
	s_ashr_i32 s13, s12, 31
	v_lshl_add_u64 v[10:11], s[16:17], 0, v[10:11]
	v_lshl_add_u64 v[10:11], s[12:13], 2, v[10:11]
	s_lshl_b32 s86, s27, 2
	v_lshl_add_u64 v[10:11], v[10:11], 0, s[86:87]
	global_store_dword v[10:11], v12, off sc1
.LBB0_508:
	s_or_b64 exec, exec, s[6:7]
	v_pk_mul_f32 v[14:15], v[8:9], v[142:143]
	v_pk_mul_f32 v[16:17], v[6:7], v[140:141]
	v_pk_mul_f32 v[18:19], v[48:49], v[134:135]
	v_cvt_pk_bf16_f32 v6, v16, v17
	v_cvt_pk_bf16_f32 v7, v14, v15
	v_mul_f32_e32 v17, v17, v17
	v_mul_f32_e32 v15, v15, v15
	v_pk_mul_f32 v[20:21], v[46:47], v[132:133]
	v_fmac_f32_e32 v17, v16, v16
	v_fmac_f32_e32 v15, v14, v14
	v_add_f32_e32 v14, v17, v15
	v_mul_f32_e32 v15, v21, v21
	v_mul_f32_e32 v16, v19, v19
	v_fmac_f32_e32 v15, v20, v20
	v_fmac_f32_e32 v16, v18, v18
	v_add_f32_e32 v15, v15, v16
	v_add_f32_e32 v22, v14, v15
	v_pk_mul_f32 v[14:15], v[44:45], v[146:147]
	v_pk_mul_f32 v[16:17], v[42:43], v[144:145]
	v_mul_f32_e32 v24, v15, v15
	v_mul_f32_e32 v23, v17, v17
	v_cvt_pk_bf16_f32 v8, v20, v21
	v_cvt_pk_bf16_f32 v9, v18, v19
	v_pk_mul_f32 v[18:19], v[96:97], v[138:139]
	v_pk_mul_f32 v[20:21], v[94:95], v[136:137]
	v_fmac_f32_e32 v23, v16, v16
	v_fmac_f32_e32 v24, v14, v14
	v_add_f32_e32 v23, v23, v24
	v_mul_f32_e32 v24, v21, v21
	v_mul_f32_e32 v25, v19, v19
	v_fmac_f32_e32 v24, v20, v20
	v_fmac_f32_e32 v25, v18, v18
	v_add_f32_e32 v24, v24, v25
	v_add_f32_e32 v23, v23, v24
	v_add_f32_e32 v24, v22, v23
	v_add_u32_e32 v10, 0xa0, v156
	ds_bpermute_b32 v25, v36, v24
	s_waitcnt lgkmcnt(1)
	v_ashrrev_i32_e32 v11, 31, v10
	v_lshlrev_b64 v[12:13], 11, v[10:11]
	v_lshl_add_u64 v[12:13], s[96:97], 0, v[12:13]
	v_lshl_add_u64 v[22:23], v[154:155], 1, v[12:13]
	global_store_dwordx4 v[22:23], v[6:9], off sc1
	v_cvt_pk_bf16_f32 v12, v16, v17
	v_cvt_pk_bf16_f32 v13, v14, v15
	v_cvt_pk_bf16_f32 v14, v20, v21
	v_cvt_pk_bf16_f32 v15, v18, v19
	global_store_dwordx4 v[22:23], v[12:15], off offset:64 sc1
	s_waitcnt lgkmcnt(0)
	v_add_f32_e32 v6, v24, v25
	ds_bpermute_b32 v7, v37, v6
	s_and_saveexec_b64 s[6:7], s[38:39]
	s_cbranch_execz .LBB0_510
	s_waitcnt lgkmcnt(0)
	v_add_f32_e32 v8, v6, v7
	s_lshl_b32 s12, s89, 2
	v_lshlrev_b64 v[6:7], 6, v[10:11]
	s_ashr_i32 s13, s12, 31
	v_lshl_add_u64 v[6:7], s[16:17], 0, v[6:7]
	v_lshl_add_u64 v[6:7], s[12:13], 2, v[6:7]
	s_lshl_b32 s86, s27, 2
	v_lshl_add_u64 v[6:7], v[6:7], 0, s[86:87]
	global_store_dword v[6:7], v8, off sc1
.LBB0_510:
	s_or_b64 exec, exec, s[6:7]
	v_pk_mul_f32 v[10:11], v[4:5], v[142:143]
	v_pk_mul_f32 v[12:13], v[2:3], v[140:141]
	v_pk_mul_f32 v[14:15], v[40:41], v[134:135]
	v_cvt_pk_bf16_f32 v2, v12, v13
	v_cvt_pk_bf16_f32 v3, v10, v11
	v_mul_f32_e32 v13, v13, v13
	v_mul_f32_e32 v11, v11, v11
	v_pk_mul_f32 v[16:17], v[38:39], v[132:133]
	v_fmac_f32_e32 v13, v12, v12
	v_fmac_f32_e32 v11, v10, v10
	v_add_f32_e32 v10, v13, v11
	v_mul_f32_e32 v11, v17, v17
	v_mul_f32_e32 v12, v15, v15
	v_fmac_f32_e32 v11, v16, v16
	v_fmac_f32_e32 v12, v14, v14
	v_add_f32_e32 v11, v11, v12
	v_add_f32_e32 v18, v10, v11
	v_pk_mul_f32 v[10:11], v[28:29], v[146:147]
	v_pk_mul_f32 v[12:13], v[26:27], v[144:145]
	v_mul_f32_e32 v20, v11, v11
	v_mul_f32_e32 v19, v13, v13
	v_cvt_pk_bf16_f32 v4, v16, v17
	v_cvt_pk_bf16_f32 v5, v14, v15
	v_pk_mul_f32 v[14:15], v[88:89], v[138:139]
	v_pk_mul_f32 v[16:17], v[86:87], v[136:137]
	v_fmac_f32_e32 v19, v12, v12
	v_fmac_f32_e32 v20, v10, v10
	v_add_f32_e32 v19, v19, v20
	v_mul_f32_e32 v20, v17, v17
	v_mul_f32_e32 v21, v15, v15
	v_fmac_f32_e32 v20, v16, v16
	v_fmac_f32_e32 v21, v14, v14
	v_add_f32_e32 v20, v20, v21
	v_add_f32_e32 v19, v19, v20
	v_add_f32_e32 v20, v18, v19
	v_add_u32_e32 v6, 0xb0, v156
	ds_bpermute_b32 v21, v36, v20
	s_waitcnt lgkmcnt(1)
	v_ashrrev_i32_e32 v7, 31, v6
	v_lshlrev_b64 v[8:9], 11, v[6:7]
	v_lshl_add_u64 v[8:9], s[96:97], 0, v[8:9]
	v_lshl_add_u64 v[18:19], v[154:155], 1, v[8:9]
	global_store_dwordx4 v[18:19], v[2:5], off sc1
	v_cvt_pk_bf16_f32 v8, v12, v13
	v_cvt_pk_bf16_f32 v9, v10, v11
	v_cvt_pk_bf16_f32 v10, v16, v17
	v_cvt_pk_bf16_f32 v11, v14, v15
	global_store_dwordx4 v[18:19], v[8:11], off offset:64 sc1
	s_waitcnt lgkmcnt(0)
	v_add_f32_e32 v2, v20, v21
	ds_bpermute_b32 v3, v37, v2
	s_and_saveexec_b64 s[6:7], s[38:39]
	s_cbranch_execz .LBB0_512
	s_waitcnt lgkmcnt(0)
	v_add_f32_e32 v4, v2, v3
	s_lshl_b32 s12, s89, 2
	v_lshlrev_b64 v[2:3], 6, v[6:7]
	s_ashr_i32 s13, s12, 31
	v_lshl_add_u64 v[2:3], s[16:17], 0, v[2:3]
	v_lshl_add_u64 v[2:3], s[12:13], 2, v[2:3]
	s_lshl_b32 s86, s27, 2
	v_lshl_add_u64 v[2:3], v[2:3], 0, s[86:87]
	global_store_dword v[2:3], v4, off sc1

; #define LAS __attribute__((address_space(3)))
; #define LDS_WAIT() asm volatile("s_waitcnt lgkmcnt(0)" ::: "memory")
; __device__ __forceinline__ unsigned pk2(float lo, float hi) { return pg8::cvt_pk_bf16(lo, hi); }
; __device__ __forceinline__ void xpose_item(const float* W, int K, int N, bf16* WT, const float* gain, int cmap, LAS float* scr, int item, int lane) {
;     ...
;     for (int i = 0; i < 16; ++i) { LAS float* d = scr + (4 * i + ks) * XP_STRIDE + n4; d[0] = w[i][0]; d[1] = w[i][1]; d[2] = w[i][2]; d[3] = w[i][3]; }
;     LDS_WAIT(); asm volatile("" ::: "memory");
;     int r0 = n0;
;     if (cmap == 1) { if (n0 < 1024) r0 = 2048 + n0; else if (n0 < 2048) { const int c = n0 - 1024; r0 = (c >> 7) * 256 + (c & 127); } else { const int c = n0 - 2048; r0 = (c >> 7) * 256 + 128 + (c & 127); } }
;     const int c = lane & 7;
; #pragma unroll
;     for (int j = 0; j < 8; ++j) { const int n = (lane >> 3) + 8 * j; const LAS float* sp = scr + (8 * c) * XP_STRIDE + n;
;         v4u o; o.x = pk2(sp[0 * XP_STRIDE], sp[1 * XP_STRIDE]); o.y = pk2(sp[2 * XP_STRIDE], sp[3 * XP_STRIDE]); o.z = pk2(sp[4 * XP_STRIDE], sp[5 * XP_STRIDE]); o.w = pk2(sp[6 * XP_STRIDE], sp[7 * XP_STRIDE]);
;         int rr = r0 + n;
;         if (cmap == 4) { const int cc = rr & 255; rr = (rr & ~255) + 128 * ((cc >> 5) & 1) + 32 * (cc >> 6) + (cc & 31); }
;         *(v4u*)(WT + (size_t)rr * K + k0 + 8 * c) = o; }
.LBB0_527:
	s_waitcnt vmcnt(15)
	ds_write2_b32 v69, v62, v63 offset1:1
	ds_write2_b32 v69, v64, v65 offset0:2 offset1:3
	v_add_u32_e32 v62, 0x410, v69
	s_waitcnt vmcnt(14)
	ds_write2_b32 v62, v50, v51 offset1:1
	v_add_u32_e32 v50, 0x418, v69
	ds_write2_b32 v50, v52, v53 offset1:1
	v_add_u32_e32 v50, 0x820, v69
	s_waitcnt vmcnt(13)
	ds_write2_b32 v50, v58, v59 offset1:1
	v_add_u32_e32 v50, 0x828, v69
	ds_write2_b32 v50, v60, v61 offset1:1
	v_add_u32_e32 v50, 0xc30, v69
	s_waitcnt vmcnt(12)
	ds_write2_b32 v50, v42, v43 offset1:1
	v_add_u32_e32 v42, 0xc38, v69
	ds_write2_b32 v42, v44, v45 offset1:1
	v_add_u32_e32 v42, 0x1040, v69
	s_waitcnt vmcnt(11)
	ds_write2_b32 v42, v54, v55 offset1:1
	v_add_u32_e32 v42, 0x1048, v69
	ds_write2_b32 v42, v56, v57 offset1:1
	v_add_u32_e32 v42, 0x1450, v69
	s_waitcnt vmcnt(10)
	ds_write2_b32 v42, v34, v35 offset1:1
	v_add_u32_e32 v34, 0x1458, v69
	ds_write2_b32 v34, v36, v37 offset1:1
	v_add_u32_e32 v34, 0x1860, v69
	s_waitcnt vmcnt(9)
	ds_write2_b32 v34, v46, v47 offset1:1
	v_add_u32_e32 v34, 0x1868, v69
	ds_write2_b32 v34, v48, v49 offset1:1
	v_add_u32_e32 v34, 0x1c70, v69
	s_waitcnt vmcnt(8)
	ds_write2_b32 v34, v26, v27 offset1:1
	v_add_u32_e32 v26, 0x1c78, v69
	ds_write2_b32 v26, v28, v29 offset1:1
	v_add_u32_e32 v26, 0x2080, v69
	s_waitcnt vmcnt(7)
	ds_write2_b32 v26, v38, v39 offset1:1
	v_add_u32_e32 v26, 0x2088, v69
	ds_write2_b32 v26, v40, v41 offset1:1
	v_add_u32_e32 v26, 0x2490, v69
	s_waitcnt vmcnt(6)
	ds_write2_b32 v26, v18, v19 offset1:1
	v_add_u32_e32 v18, 0x2498, v69
	ds_write2_b32 v18, v20, v21 offset1:1
	v_add_u32_e32 v18, 0x28a0, v69
	s_waitcnt vmcnt(5)
	ds_write2_b32 v18, v30, v31 offset1:1
	v_add_u32_e32 v18, 0x28a8, v69
	ds_write2_b32 v18, v32, v33 offset1:1
	v_add_u32_e32 v18, 0x2cb0, v69
	s_waitcnt vmcnt(4)
	ds_write2_b32 v18, v10, v11 offset1:1
	v_add_u32_e32 v10, 0x2cb8, v69
	ds_write2_b32 v10, v12, v13 offset1:1
	v_add_u32_e32 v10, 0x30c0, v69
	s_waitcnt vmcnt(3)
	ds_write2_b32 v10, v22, v23 offset1:1
	v_add_u32_e32 v10, 0x30c8, v69
	ds_write2_b32 v10, v24, v25 offset1:1
	v_add_u32_e32 v10, 0x34d0, v69
	s_waitcnt vmcnt(2)
	ds_write2_b32 v10, v6, v7 offset1:1
	v_add_u32_e32 v6, 0x34d8, v69
	ds_write2_b32 v6, v8, v9 offset1:1
	v_add_u32_e32 v6, 0x38e0, v69
	s_waitcnt vmcnt(1)
	ds_write2_b32 v6, v14, v15 offset1:1
	v_add_u32_e32 v6, 0x38e8, v69
	ds_write2_b32 v6, v16, v17 offset1:1
	v_add_u32_e32 v6, 0x3cf0, v69
	s_mul_hi_i32 s3, s2, 0x600000
	s_mul_i32 s2, s2, 0x600000
	v_readlane_b32 s5, v253, 16
	s_waitcnt vmcnt(0)
	ds_write2_b32 v6, v2, v3 offset1:1
	v_add_u32_e32 v2, 0x3cf8, v69
	s_add_u32 s5, s5, s2
	v_readlane_b32 s2, v253, 17
	ds_write2_b32 v2, v4, v5 offset1:1
	s_addc_u32 s8, s2, s3
	s_ashr_i32 s11, s10, 31
	s_waitcnt lgkmcnt(0)
	s_lshl_b64 s[2:3], s[10:11], 1
	s_add_u32 s2, s5, s2
	ds_read2_b32 v[2:3], v73 offset1:65
	s_addc_u32 s3, s8, s3
	v_lshlrev_b32_e32 v98, 1, v72
	s_waitcnt lgkmcnt(0)
	v_cvt_pk_bf16_f32 v2, v2, v3
	ds_read2_b32 v[4:5], v73 offset0:130 offset1:195
	v_add_u32_e32 v14, 0x400, v73
	v_lshl_add_u64 v[8:9], s[2:3], 0, v[98:99]
	s_lshr_b32 s2, s4, 1
	s_waitcnt lgkmcnt(0)
	v_cvt_pk_bf16_f32 v3, v4, v5
	ds_read2_b32 v[4:5], v14 offset0:4 offset1:69
	s_and_b32 s2, s2, 0x60
	s_and_b32 s3, s4, 0xffffff00
	s_waitcnt lgkmcnt(0)
	v_cvt_pk_bf16_f32 v4, v4, v5
	ds_read2_b32 v[6:7], v14 offset0:134 offset1:199
	s_or_b32 s3, s2, s3
	s_waitcnt lgkmcnt(0)
	v_cvt_pk_bf16_f32 v5, v6, v7
	v_or_b32_e32 v6, s3, v71
	v_ashrrev_i32_e32 v7, 31, v6
	v_lshlrev_b64 v[12:13], 11, v[6:7]
	v_lshl_add_u64 v[12:13], v[8:9], 0, v[12:13]
	ds_read2_b32 v[10:11], v73 offset0:8 offset1:73
	global_store_dwordx4 v[12:13], v[2:5], off sc1
	v_or_b32_e32 v6, 0x80, v6
	v_ashrrev_i32_e32 v7, 31, v6
	s_waitcnt lgkmcnt(0)
	v_cvt_pk_bf16_f32 v2, v10, v11
	ds_read2_b32 v[4:5], v73 offset0:138 offset1:203
	s_waitcnt lgkmcnt(0)
	v_cvt_pk_bf16_f32 v3, v4, v5
	ds_read2_b32 v[4:5], v14 offset0:12 offset1:77
	s_waitcnt lgkmcnt(0)
	v_cvt_pk_bf16_f32 v4, v4, v5
	ds_read2_b32 v[10:11], v14 offset0:142 offset1:207
	s_waitcnt lgkmcnt(0)
; #define LAS __attribute__((address_space(3)))
; __device__ __forceinline__ unsigned pk2(float lo, float hi) { return pg8::cvt_pk_bf16(lo, hi); }
; __device__ __forceinline__ void xpose_item(const float* W, int K, int N, bf16* WT, const float* gain, int cmap, LAS float* scr, int item, int lane) {
;     ...
;     for (int j = 0; j < 8; ++j) { const int n = (lane >> 3) + 8 * j; const LAS float* sp = scr + (8 * c) * XP_STRIDE + n;
;         v4u o; o.x = pk2(sp[0 * XP_STRIDE], sp[1 * XP_STRIDE]); o.y = pk2(sp[2 * XP_STRIDE], sp[3 * XP_STRIDE]); o.z = pk2(sp[4 * XP_STRIDE], sp[5 * XP_STRIDE]); o.w = pk2(sp[6 * XP_STRIDE], sp[7 * XP_STRIDE]);
;         int rr = r0 + n;
;         if (cmap == 4) { const int cc = rr & 255; rr = (rr & ~255) + 128 * ((cc >> 5) & 1) + 32 * (cc >> 6) + (cc & 31); }
;         *(v4u*)(WT + (size_t)rr * K + k0 + 8 * c) = o; }
	v_cvt_pk_bf16_f32 v5, v10, v11
	v_or_b32_e32 v10, s3, v84
	v_ashrrev_i32_e32 v11, 31, v10
	v_lshlrev_b64 v[10:11], 11, v[10:11]
	v_lshl_add_u64 v[10:11], v[8:9], 0, v[10:11]
	ds_read2_b32 v[12:13], v73 offset0:16 offset1:81
	global_store_dwordx4 v[10:11], v[2:5], off sc1
	v_lshlrev_b64 v[6:7], 11, v[6:7]
	v_lshl_add_u64 v[6:7], v[8:9], 0, v[6:7]
	s_waitcnt lgkmcnt(0)
	v_cvt_pk_bf16_f32 v2, v12, v13
	ds_read2_b32 v[4:5], v73 offset0:146 offset1:211
	s_waitcnt lgkmcnt(0)
	v_cvt_pk_bf16_f32 v3, v4, v5
	ds_read2_b32 v[4:5], v14 offset0:20 offset1:85
	s_waitcnt lgkmcnt(0)
	v_cvt_pk_bf16_f32 v4, v4, v5
	ds_read2_b32 v[10:11], v14 offset0:150 offset1:215
	s_waitcnt lgkmcnt(0)
	v_cvt_pk_bf16_f32 v5, v10, v11
	v_or_b32_e32 v10, s3, v85
	v_ashrrev_i32_e32 v11, 31, v10
	v_lshlrev_b64 v[10:11], 11, v[10:11]
	v_lshl_add_u64 v[10:11], v[8:9], 0, v[10:11]
	ds_read2_b32 v[12:13], v73 offset0:24 offset1:89
	global_store_dwordx4 v[10:11], v[2:5], off sc1
	s_waitcnt lgkmcnt(0)
	s_nop 0
	v_cvt_pk_bf16_f32 v2, v12, v13
	ds_read2_b32 v[4:5], v73 offset0:154 offset1:219
	s_waitcnt lgkmcnt(0)
	v_cvt_pk_bf16_f32 v3, v4, v5
	ds_read2_b32 v[4:5], v14 offset0:28 offset1:93
	s_waitcnt lgkmcnt(0)
	v_cvt_pk_bf16_f32 v4, v4, v5
	ds_read2_b32 v[10:11], v14 offset0:158 offset1:223
	s_waitcnt lgkmcnt(0)
	v_cvt_pk_bf16_f32 v5, v10, v11
	v_or_b32_e32 v10, s3, v86
	v_ashrrev_i32_e32 v11, 31, v10
	v_lshlrev_b64 v[10:11], 11, v[10:11]
	v_lshl_add_u64 v[10:11], v[8:9], 0, v[10:11]
	ds_read2_b32 v[12:13], v73 offset0:32 offset1:97
	global_store_dwordx4 v[10:11], v[2:5], off sc1
	s_waitcnt lgkmcnt(0)
	s_nop 0
	v_cvt_pk_bf16_f32 v2, v12, v13
	ds_read2_b32 v[4:5], v73 offset0:162 offset1:227
	s_waitcnt lgkmcnt(0)
	v_cvt_pk_bf16_f32 v3, v4, v5
	ds_read2_b32 v[4:5], v14 offset0:36 offset1:101
	s_waitcnt lgkmcnt(0)
	v_cvt_pk_bf16_f32 v4, v4, v5
	ds_read2_b32 v[10:11], v14 offset0:166 offset1:231
	s_waitcnt lgkmcnt(0)
	v_cvt_pk_bf16_f32 v5, v10, v11
	ds_read2_b32 v[10:11], v73 offset0:40 offset1:105
	global_store_dwordx4 v[6:7], v[2:5], off sc1
	s_waitcnt lgkmcnt(0)
	s_nop 0
	v_cvt_pk_bf16_f32 v2, v10, v11
	ds_read2_b32 v[4:5], v73 offset0:170 offset1:235
	s_waitcnt lgkmcnt(0)
	v_cvt_pk_bf16_f32 v3, v4, v5
	ds_read2_b32 v[4:5], v14 offset0:44 offset1:109
	s_waitcnt lgkmcnt(0)
	v_cvt_pk_bf16_f32 v4, v4, v5
	ds_read2_b32 v[6:7], v14 offset0:174 offset1:239
	s_waitcnt lgkmcnt(0)
	v_cvt_pk_bf16_f32 v5, v6, v7
	v_mov_b32_e32 v6, 0xffffff0f
	v_bitop3_b32 v6, s4, v6, v87 bitop3:0xc8
	v_or_b32_e32 v6, s2, v6
	v_or_b32_e32 v6, 0x80, v6
	v_ashrrev_i32_e32 v7, 31, v6
	v_lshlrev_b64 v[6:7], 11, v[6:7]
	v_lshl_add_u64 v[6:7], v[8:9], 0, v[6:7]
	ds_read2_b32 v[10:11], v73 offset0:48 offset1:113
	global_store_dwordx4 v[6:7], v[2:5], off sc1
	s_waitcnt lgkmcnt(0)
	s_nop 0
	v_cvt_pk_bf16_f32 v2, v10, v11
	ds_read2_b32 v[4:5], v73 offset0:178 offset1:243
	s_waitcnt lgkmcnt(0)
	v_cvt_pk_bf16_f32 v3, v4, v5
	ds_read2_b32 v[4:5], v14 offset0:52 offset1:117
	s_waitcnt lgkmcnt(0)
	v_cvt_pk_bf16_f32 v4, v4, v5
	ds_read2_b32 v[6:7], v14 offset0:182 offset1:247
	s_waitcnt lgkmcnt(0)
	v_cvt_pk_bf16_f32 v5, v6, v7
	v_mov_b32_e32 v6, 0xffffff17
	v_bitop3_b32 v6, s4, v6, v88 bitop3:0xc8
	v_or_b32_e32 v6, s2, v6
	v_or_b32_e32 v6, 0x80, v6
	v_ashrrev_i32_e32 v7, 31, v6
	v_lshlrev_b64 v[6:7], 11, v[6:7]
	v_lshl_add_u64 v[6:7], v[8:9], 0, v[6:7]
	ds_read2_b32 v[10:11], v73 offset0:56 offset1:121
	global_store_dwordx4 v[6:7], v[2:5], off sc1
	s_waitcnt lgkmcnt(0)
	s_nop 0
	v_cvt_pk_bf16_f32 v2, v10, v11
	ds_read2_b32 v[4:5], v73 offset0:186 offset1:251
	s_waitcnt lgkmcnt(0)
	v_cvt_pk_bf16_f32 v3, v4, v5
	ds_read2_b32 v[4:5], v14 offset0:60 offset1:125
	s_waitcnt lgkmcnt(0)
	v_cvt_pk_bf16_f32 v4, v4, v5
	ds_read2_b32 v[6:7], v14 offset0:190 offset1:255
	s_waitcnt lgkmcnt(0)
	v_cvt_pk_bf16_f32 v5, v6, v7
	v_mov_b32_e32 v6, 0xffffff1f
	v_bitop3_b32 v6, s4, v6, v89 bitop3:0xc8
	v_or_b32_e32 v6, s2, v6
	v_or_b32_e32 v6, 0x80, v6
	v_ashrrev_i32_e32 v7, 31, v6
	v_lshlrev_b64 v[6:7], 11, v[6:7]
	v_lshl_add_u64 v[6:7], v[8:9], 0, v[6:7]
	global_store_dwordx4 v[6:7], v[2:5], off sc1
	s_waitcnt lgkmcnt(0)

; #define LAS __attribute__((address_space(3)))
; __device__ __forceinline__ void xpose_item(const float* W, int K, int N, bf16* WT, const float* gain, int cmap, LAS float* scr, int item, int lane) {
;     ...
;     for (int i = 0; i < 16; ++i) w[i] = __builtin_nontemporal_load((const f32x4*)(W + (size_t)(k0 + 4 * i + ks) * N + n0 + n4));
;     if (gain) {
; #pragma unroll
;         for (int i = 0; i < 16; ++i) w[i] = w[i] * gain[k0 + 4 * i + ks];
;     }
; #pragma unroll
;     for (int i = 0; i < 16; ++i) { LAS float* d = scr + (4 * i + ks) * XP_STRIDE + n4; d[0] = w[i][0]; d[1] = w[i][1]; d[2] = w[i][2]; d[3] = w[i][3]; }
; __device__ __forceinline__ void prologue(const Args& a, LAS unsigned char* lds, int vcu, int G, int wave, int lane, int tid) {
;     ...
;     for (int it = gw; it < NITEMS; it += NGW) {
;         int r = it;
;         if (r < 2 * I_QKV) { const int l = r / I_QKV; r -= l * I_QKV; xpose_item(a.in[4] + (size_t)l * 1024 * 3072, 1024, 3072, (bf16*)(ws + WS_WQKV) + (size_t)l * 3072 * 1024, nmix + (l ? 3 : 0) * 1024, 4, scr, r, lane); continue; } r -= 2 * I_QKV;
;         if (r < 2 * I_SQ) { const int l = r / I_SQ; r -= l * I_SQ; xpose_item(a.in[5] + (size_t)l * 1024 * 1024, 1024, 1024, (bf16*)(ws + WS_WO) + (size_t)l * 1024 * 1024, nullptr, 4, scr, r, lane); continue; } r -= 2 * I_SQ;
;         if (r < 4 * I_POOL) { const int g = r / I_POOL; r -= g * I_POOL; xpose_item(a.in[6] + (size_t)g * 65536, 256, 256, (bf16*)(ws + WS_WPOOL) + (size_t)g * 65536, nullptr, 4, scr, r, lane); continue; } r -= 4 * I_POOL;
;         if (r < I_QKV) { xpose_item(a.in[8], 1024, 3072, (bf16*)(ws + WS_WCI), nmix + 2 * 1024, 1, scr, r, lane); continue; } r -= I_QKV;
;         if (r < I_SQ) { xpose_item(a.in[10], 1024, 1024, (bf16*)(ws + WS_WCO), nullptr, 4, scr, r, lane); continue; } r -= I_SQ;
;         if (r < 4 * I_UP) { const int l = r / I_UP; r -= l * I_UP; xpose_item(a.in[11] + (size_t)l * 1024 * 4096, 1024, 4096, (bf16*)(ws + WS_WUP) + (size_t)l * 4096 * 1024, nmlp + l * 1024, 4, scr, r, lane); continue; } r -= 4 * I_UP;
;         { const int l = r / I_DN; r -= l * I_DN; xpose_item(a.in[12] + (size_t)l * 4096 * 1024, 4096, 1024, (bf16*)(ws + WS_WDN) + (size_t)l * 1024 * 4096, nullptr, 4, scr, r, lane); }
.LBB0_529:
	s_add_i32 s2, s7, 0x1c40
	s_cmpk_gt_i32 s2, 0x5ff
	s_mov_b64 s[4:5], -1
	s_cbranch_scc0 .LBB0_561
	s_cmpk_gt_u32 s2, 0x7ff
	s_cbranch_scc0 .LBB0_558
	s_cmpk_gt_u32 s2, 0x83f
	s_cbranch_scc0 .LBB0_555
	s_cmpk_gt_u32 s2, 0xb3f
	s_cbranch_scc0 .LBB0_544
	s_cmpk_gt_u32 s2, 0xc3f
	s_cbranch_scc0 .LBB0_541
	s_cmpk_gt_u32 s2, 0x1c3f
	s_cbranch_scc0 .LBB0_536
	s_lshr_b32 s86, s7, 10
	s_lshl_b64 s[4:5], s[86:87], 24
	s_add_u32 s3, s56, s4
	s_addc_u32 s8, s57, s5
	s_lshl_b64 s[4:5], s[86:87], 23
	v_readlane_b32 s9, v253, 3
	s_add_u32 s9, s9, s4
	v_readlane_b32 s4, v253, 4
	s_addc_u32 s10, s4, s5
	s_add_i32 s4, s1, 0xffff8f00
	s_and_b32 s11, s4, 0xfc0
	s_and_b32 s4, s13, 0x3c0
	s_lshl_b32 s4, s4, 2
	s_add_u32 s4, s3, s4
	v_or_b32_e32 v4, s11, v67
	s_addc_u32 s5, s8, 0
	v_lshlrev_b32_e32 v98, 2, v70
	v_lshl_add_u64 v[2:3], s[4:5], 0, v[98:99]
	v_lshlrev_b32_e32 v98, 12, v4
	v_lshl_add_u64 v[62:63], v[2:3], 0, v[98:99]
	s_movk_i32 s3, 0x4000
	v_add_co_u32_e32 v6, vcc, s3, v62
	s_mov_b32 s3, 0x8000
	s_nop 0
	v_addc_co_u32_e32 v7, vcc, 0, v63, vcc
	v_add_co_u32_e32 v10, vcc, s3, v62
	global_load_dwordx4 v[2:5], v[62:63], off nt
	s_nop 0
	global_load_dwordx4 v[6:9], v[6:7], off nt
	v_addc_co_u32_e32 v11, vcc, 0, v63, vcc
	s_mov_b32 s3, 0xc000
	v_add_co_u32_e32 v14, vcc, s3, v62
	s_mov_b32 s3, 0x10000
	s_nop 0
	v_addc_co_u32_e32 v15, vcc, 0, v63, vcc
	global_load_dwordx4 v[10:13], v[10:11], off nt
	s_nop 0
	global_load_dwordx4 v[14:17], v[14:15], off nt
	v_add_co_u32_e32 v18, vcc, s3, v62
	s_mov_b32 s3, 0x14000
	s_nop 0
	v_addc_co_u32_e32 v19, vcc, 0, v63, vcc
	v_add_co_u32_e32 v22, vcc, s3, v62
	s_mov_b32 s3, 0x18000
	s_nop 0
	v_addc_co_u32_e32 v23, vcc, 0, v63, vcc
	global_load_dwordx4 v[18:21], v[18:19], off nt
	s_nop 0
	global_load_dwordx4 v[22:25], v[22:23], off nt
	v_add_co_u32_e32 v26, vcc, s3, v62
	s_mov_b32 s3, 0x1c000
	s_nop 0
	v_addc_co_u32_e32 v27, vcc, 0, v63, vcc
	v_add_co_u32_e32 v30, vcc, s3, v62
	s_mov_b32 s3, 0x20000
	s_nop 0
	v_addc_co_u32_e32 v31, vcc, 0, v63, vcc
	global_load_dwordx4 v[26:29], v[26:27], off nt
	s_nop 0
	global_load_dwordx4 v[30:33], v[30:31], off nt
	v_add_co_u32_e32 v34, vcc, s3, v62
	s_mov_b32 s3, 0x24000
	s_nop 0
	v_addc_co_u32_e32 v35, vcc, 0, v63, vcc
	v_add_co_u32_e32 v38, vcc, s3, v62
	s_mov_b32 s3, 0x28000
	s_nop 0
	v_addc_co_u32_e32 v39, vcc, 0, v63, vcc
	global_load_dwordx4 v[34:37], v[34:35], off nt
	s_nop 0
	global_load_dwordx4 v[38:41], v[38:39], off nt
	v_add_co_u32_e32 v42, vcc, s3, v62
	s_mov_b32 s3, 0x2c000
	s_nop 0
	v_addc_co_u32_e32 v43, vcc, 0, v63, vcc
	v_add_co_u32_e32 v46, vcc, s3, v62
	s_mov_b32 s3, 0x30000
	s_nop 0
	v_addc_co_u32_e32 v47, vcc, 0, v63, vcc
	global_load_dwordx4 v[42:45], v[42:43], off nt
	s_nop 0
	global_load_dwordx4 v[46:49], v[46:47], off nt
	v_add_co_u32_e32 v50, vcc, s3, v62
	s_mov_b32 s3, 0x34000
	s_nop 0
	v_addc_co_u32_e32 v51, vcc, 0, v63, vcc
	global_load_dwordx4 v[50:53], v[50:51], off nt
	v_add_co_u32_e32 v54, vcc, s3, v62
	s_mov_b32 s3, 0x38000
	s_nop 0
	v_addc_co_u32_e32 v55, vcc, 0, v63, vcc
	global_load_dwordx4 v[54:57], v[54:55], off nt
	v_add_co_u32_e32 v58, vcc, s3, v62
	s_mov_b32 s3, 0x3c000
	s_nop 0
	v_addc_co_u32_e32 v59, vcc, 0, v63, vcc
	global_load_dwordx4 v[58:61], v[58:59], off nt
	v_add_co_u32_e32 v62, vcc, s3, v62
	s_lshl_b32 s3, s11, 1
	s_nop 0
	v_addc_co_u32_e32 v63, vcc, 0, v63, vcc
	global_load_dwordx4 v[62:65], v[62:63], off nt
	s_waitcnt vmcnt(15)
	ds_write2_b32 v69, v2, v3 offset1:1
	ds_write2_b32 v69, v4, v5 offset0:2 offset1:3
	v_add_u32_e32 v2, 0x410, v69
	s_waitcnt vmcnt(14)
	ds_write2_b32 v2, v6, v7 offset1:1
	v_add_u32_e32 v2, 0x418, v69
	ds_write2_b32 v2, v8, v9 offset1:1
	v_add_u32_e32 v2, 0x820, v69
	s_add_u32 s4, s9, s3
	s_addc_u32 s5, s10, 0
	v_lshlrev_b32_e32 v98, 1, v72
	s_waitcnt vmcnt(13)
	ds_write2_b32 v2, v10, v11 offset1:1
	v_add_u32_e32 v2, 0x828, v69
	ds_write2_b32 v2, v12, v13 offset1:1
	v_add_u32_e32 v2, 0xc30, v69
	s_waitcnt vmcnt(12)
	ds_write2_b32 v2, v14, v15 offset1:1
	v_add_u32_e32 v2, 0xc38, v69
	ds_write2_b32 v2, v16, v17 offset1:1
	v_add_u32_e32 v2, 0x1040, v69
	v_lshl_add_u64 v[8:9], s[4:5], 0, v[98:99]
	s_and_b32 s3, s15, 0x60
	s_and_b32 s4, s13, 0x300
	s_waitcnt vmcnt(11)
	ds_write2_b32 v2, v18, v19 offset1:1
	v_add_u32_e32 v2, 0x1048, v69
	ds_write2_b32 v2, v20, v21 offset1:1
	v_add_u32_e32 v2, 0x1450, v69
	s_waitcnt vmcnt(10)
	ds_write2_b32 v2, v22, v23 offset1:1
	v_add_u32_e32 v2, 0x1458, v69
	ds_write2_b32 v2, v24, v25 offset1:1
	v_add_u32_e32 v2, 0x1860, v69
	s_or_b32 s4, s4, s3
	v_add_u32_e32 v14, 0x400, v73
	v_or_b32_e32 v10, s4, v71
	s_waitcnt vmcnt(9)
	ds_write2_b32 v2, v26, v27 offset1:1
	v_add_u32_e32 v2, 0x1868, v69
	ds_write2_b32 v2, v28, v29 offset1:1
	v_add_u32_e32 v2, 0x1c70, v69
	s_waitcnt vmcnt(8)
	ds_write2_b32 v2, v30, v31 offset1:1
	v_add_u32_e32 v2, 0x1c78, v69
	ds_write2_b32 v2, v32, v33 offset1:1
	v_add_u32_e32 v2, 0x2080, v69
	v_lshlrev_b32_e32 v98, 13, v10
	v_lshl_add_u64 v[10:11], v[8:9], 0, v[98:99]
	v_or_b32_e32 v12, s4, v84
	s_waitcnt vmcnt(7)
	ds_write2_b32 v2, v34, v35 offset1:1
	v_add_u32_e32 v2, 0x2088, v69
	ds_write2_b32 v2, v36, v37 offset1:1
	v_add_u32_e32 v2, 0x2490, v69
	s_waitcnt vmcnt(6)
	ds_write2_b32 v2, v38, v39 offset1:1
	v_add_u32_e32 v2, 0x2498, v69
	ds_write2_b32 v2, v40, v41 offset1:1
	v_add_u32_e32 v2, 0x28a0, v69
	v_lshlrev_b32_e32 v98, 13, v12
	v_lshl_add_u64 v[12:13], v[8:9], 0, v[98:99]
	s_waitcnt vmcnt(5)
	ds_write2_b32 v2, v42, v43 offset1:1
	v_add_u32_e32 v2, 0x28a8, v69
	ds_write2_b32 v2, v44, v45 offset1:1
	v_add_u32_e32 v2, 0x2cb0, v69
	s_waitcnt vmcnt(4)
; #define LAS __attribute__((address_space(3)))
; #define LDS_WAIT() asm volatile("s_waitcnt lgkmcnt(0)" ::: "memory")
; __device__ __forceinline__ unsigned pk2(float lo, float hi) { return pg8::cvt_pk_bf16(lo, hi); }
; __device__ __forceinline__ void xpose_item(const float* W, int K, int N, bf16* WT, const float* gain, int cmap, LAS float* scr, int item, int lane) {
;     ...
;     for (int i = 0; i < 16; ++i) { LAS float* d = scr + (4 * i + ks) * XP_STRIDE + n4; d[0] = w[i][0]; d[1] = w[i][1]; d[2] = w[i][2]; d[3] = w[i][3]; }
;     LDS_WAIT(); asm volatile("" ::: "memory");
;     int r0 = n0;
;     if (cmap == 1) { if (n0 < 1024) r0 = 2048 + n0; else if (n0 < 2048) { const int c = n0 - 1024; r0 = (c >> 7) * 256 + (c & 127); } else { const int c = n0 - 2048; r0 = (c >> 7) * 256 + 128 + (c & 127); } }
;     const int c = lane & 7;
; #pragma unroll
;     for (int j = 0; j < 8; ++j) { const int n = (lane >> 3) + 8 * j; const LAS float* sp = scr + (8 * c) * XP_STRIDE + n;
;         v4u o; o.x = pk2(sp[0 * XP_STRIDE], sp[1 * XP_STRIDE]); o.y = pk2(sp[2 * XP_STRIDE], sp[3 * XP_STRIDE]); o.z = pk2(sp[4 * XP_STRIDE], sp[5 * XP_STRIDE]); o.w = pk2(sp[6 * XP_STRIDE], sp[7 * XP_STRIDE]);
;         int rr = r0 + n;
;         if (cmap == 4) { const int cc = rr & 255; rr = (rr & ~255) + 128 * ((cc >> 5) & 1) + 32 * (cc >> 6) + (cc & 31); }
;         *(v4u*)(WT + (size_t)rr * K + k0 + 8 * c) = o; }
	ds_write2_b32 v2, v46, v47 offset1:1
	v_add_u32_e32 v2, 0x2cb8, v69
	ds_write2_b32 v2, v48, v49 offset1:1
	v_add_u32_e32 v2, 0x30c0, v69
	s_waitcnt vmcnt(3)
	ds_write2_b32 v2, v50, v51 offset1:1
	v_add_u32_e32 v2, 0x30c8, v69
	ds_write2_b32 v2, v52, v53 offset1:1
	v_add_u32_e32 v2, 0x34d0, v69
	s_waitcnt vmcnt(2)
	ds_write2_b32 v2, v54, v55 offset1:1
	v_add_u32_e32 v2, 0x34d8, v69
	ds_write2_b32 v2, v56, v57 offset1:1
	v_add_u32_e32 v2, 0x38e0, v69
	s_waitcnt vmcnt(1)
	ds_write2_b32 v2, v58, v59 offset1:1
	v_add_u32_e32 v2, 0x38e8, v69
	ds_write2_b32 v2, v60, v61 offset1:1
	v_add_u32_e32 v2, 0x3cf0, v69
	s_waitcnt vmcnt(0)
	ds_write2_b32 v2, v62, v63 offset1:1
	v_add_u32_e32 v2, 0x3cf8, v69
	ds_write2_b32 v2, v64, v65 offset1:1
	s_waitcnt lgkmcnt(0)
	ds_read2_b32 v[2:3], v73 offset1:65
	s_waitcnt lgkmcnt(0)
	v_cvt_pk_bf16_f32 v2, v2, v3
	ds_read2_b32 v[4:5], v73 offset0:130 offset1:195
	s_waitcnt lgkmcnt(0)
	v_cvt_pk_bf16_f32 v3, v4, v5
	ds_read2_b32 v[4:5], v14 offset0:4 offset1:69
	s_waitcnt lgkmcnt(0)
	v_cvt_pk_bf16_f32 v4, v4, v5
	ds_read2_b32 v[6:7], v14 offset0:134 offset1:199
	s_waitcnt lgkmcnt(0)
	v_cvt_pk_bf16_f32 v5, v6, v7
	ds_read2_b32 v[6:7], v73 offset0:8 offset1:73
	global_store_dwordx4 v[10:11], v[2:5], off sc1
	s_waitcnt lgkmcnt(0)
	s_nop 0
	v_cvt_pk_bf16_f32 v2, v6, v7
	ds_read2_b32 v[4:5], v73 offset0:138 offset1:203
	s_waitcnt lgkmcnt(0)
	v_cvt_pk_bf16_f32 v3, v4, v5
	ds_read2_b32 v[4:5], v14 offset0:12 offset1:77
	s_waitcnt lgkmcnt(0)
	v_cvt_pk_bf16_f32 v4, v4, v5
	ds_read2_b32 v[6:7], v14 offset0:142 offset1:207
	s_waitcnt lgkmcnt(0)
	v_cvt_pk_bf16_f32 v5, v6, v7
	ds_read2_b32 v[6:7], v73 offset0:16 offset1:81
	global_store_dwordx4 v[12:13], v[2:5], off sc1
	v_or_b32_e32 v12, s4, v85
	v_lshlrev_b32_e32 v98, 13, v12
	s_waitcnt lgkmcnt(0)
	v_cvt_pk_bf16_f32 v2, v6, v7
	ds_read2_b32 v[4:5], v73 offset0:146 offset1:211
	s_waitcnt lgkmcnt(0)
	v_cvt_pk_bf16_f32 v3, v4, v5
	ds_read2_b32 v[4:5], v14 offset0:20 offset1:85
	s_waitcnt lgkmcnt(0)
	v_cvt_pk_bf16_f32 v4, v4, v5
	ds_read2_b32 v[6:7], v14 offset0:150 offset1:215
	s_waitcnt lgkmcnt(0)
	v_cvt_pk_bf16_f32 v5, v6, v7
	v_lshl_add_u64 v[12:13], v[8:9], 0, v[98:99]
	ds_read2_b32 v[6:7], v73 offset0:24 offset1:89
	global_store_dwordx4 v[12:13], v[2:5], off sc1
	v_or_b32_e32 v12, s4, v86
	v_lshlrev_b32_e32 v98, 13, v12
	s_waitcnt lgkmcnt(0)
	v_cvt_pk_bf16_f32 v2, v6, v7
	ds_read2_b32 v[4:5], v73 offset0:154 offset1:219
	s_waitcnt lgkmcnt(0)
	v_cvt_pk_bf16_f32 v3, v4, v5
	ds_read2_b32 v[4:5], v14 offset0:28 offset1:93
	s_waitcnt lgkmcnt(0)
	v_cvt_pk_bf16_f32 v4, v4, v5
	ds_read2_b32 v[6:7], v14 offset0:158 offset1:223
	s_waitcnt lgkmcnt(0)
	v_cvt_pk_bf16_f32 v5, v6, v7
	v_lshl_add_u64 v[12:13], v[8:9], 0, v[98:99]
	ds_read2_b32 v[6:7], v73 offset0:32 offset1:97
	global_store_dwordx4 v[12:13], v[2:5], off sc1
	s_mov_b32 s4, 0x100000
	v_add_co_u32_e32 v10, vcc, s4, v10
	s_waitcnt lgkmcnt(0)
	v_cvt_pk_bf16_f32 v2, v6, v7
	ds_read2_b32 v[4:5], v73 offset0:162 offset1:227
	s_waitcnt lgkmcnt(0)
	v_cvt_pk_bf16_f32 v3, v4, v5
	ds_read2_b32 v[4:5], v14 offset0:36 offset1:101
	s_waitcnt lgkmcnt(0)
	v_cvt_pk_bf16_f32 v4, v4, v5
	ds_read2_b32 v[6:7], v14 offset0:166 offset1:231
	s_waitcnt lgkmcnt(0)
	v_cvt_pk_bf16_f32 v5, v6, v7
	v_addc_co_u32_e32 v11, vcc, 0, v11, vcc
	ds_read2_b32 v[6:7], v73 offset0:40 offset1:105
	global_store_dwordx4 v[10:11], v[2:5], off sc1
	v_add_u32_e32 v12, s13, v71
	s_waitcnt lgkmcnt(0)
	v_cvt_pk_bf16_f32 v2, v6, v7
	ds_read2_b32 v[4:5], v73 offset0:170 offset1:235
	s_waitcnt lgkmcnt(0)
	v_cvt_pk_bf16_f32 v3, v4, v5
	ds_read2_b32 v[4:5], v14 offset0:44 offset1:109
	s_waitcnt lgkmcnt(0)
	v_cvt_pk_bf16_f32 v4, v4, v5
	ds_read2_b32 v[6:7], v14 offset0:174 offset1:239
	s_waitcnt lgkmcnt(0)
	v_cvt_pk_bf16_f32 v5, v6, v7
	v_add_u32_e32 v6, 40, v12
	v_and_b32_e32 v6, 0x30f, v6
	v_or_b32_e32 v6, s3, v6
	v_lshlrev_b32_e32 v98, 13, v6
	v_lshl_add_u64 v[6:7], v[8:9], 0, v[98:99]
	v_add_co_u32_e32 v6, vcc, s4, v6
	ds_read2_b32 v[10:11], v73 offset0:48 offset1:113
	s_nop 0
	v_addc_co_u32_e32 v7, vcc, 0, v7, vcc
	global_store_dwordx4 v[6:7], v[2:5], off sc1
	s_waitcnt lgkmcnt(0)
	s_nop 0
	v_cvt_pk_bf16_f32 v2, v10, v11
	ds_read2_b32 v[4:5], v73 offset0:178 offset1:243
	s_waitcnt lgkmcnt(0)
	v_cvt_pk_bf16_f32 v3, v4, v5
	ds_read2_b32 v[4:5], v14 offset0:52 offset1:117
	s_waitcnt lgkmcnt(0)
	v_cvt_pk_bf16_f32 v4, v4, v5
	ds_read2_b32 v[6:7], v14 offset0:182 offset1:247
	s_waitcnt lgkmcnt(0)
	v_cvt_pk_bf16_f32 v5, v6, v7
	v_add_u32_e32 v6, 48, v12
	v_and_b32_e32 v6, 0x317, v6
	v_or_b32_e32 v6, s3, v6
	v_lshlrev_b32_e32 v98, 13, v6
	v_lshl_add_u64 v[6:7], v[8:9], 0, v[98:99]
	v_add_co_u32_e32 v6, vcc, s4, v6
	ds_read2_b32 v[10:11], v73 offset0:56 offset1:121
	s_nop 0
	v_addc_co_u32_e32 v7, vcc, 0, v7, vcc
	global_store_dwordx4 v[6:7], v[2:5], off sc1
	s_mov_b64 s[4:5], 0
	s_waitcnt lgkmcnt(0)
	v_cvt_pk_bf16_f32 v2, v10, v11
	ds_read2_b32 v[4:5], v73 offset0:186 offset1:251
	s_waitcnt lgkmcnt(0)
	v_cvt_pk_bf16_f32 v3, v4, v5
	ds_read2_b32 v[4:5], v14 offset0:60 offset1:125
	s_waitcnt lgkmcnt(0)
	v_cvt_pk_bf16_f32 v4, v4, v5
	ds_read2_b32 v[6:7], v14 offset0:190 offset1:255
	s_waitcnt lgkmcnt(0)
	v_cvt_pk_bf16_f32 v5, v6, v7
	v_add_u32_e32 v6, 56, v12
	v_and_b32_e32 v6, 0x31f, v6
	v_or_b32_e32 v6, s3, v6
	v_lshlrev_b32_e32 v98, 13, v6
	v_lshl_add_u64 v[6:7], v[8:9], 0, v[98:99]
	v_add_co_u32_e32 v6, vcc, 0x100000, v6
	s_nop 1
	v_addc_co_u32_e32 v7, vcc, 0, v7, vcc
	global_store_dwordx4 v[6:7], v[2:5], off sc1
	s_waitcnt lgkmcnt(0)

; #define LAS __attribute__((address_space(3)))
; #define LDS_WAIT() asm volatile("s_waitcnt lgkmcnt(0)" ::: "memory")
; __device__ __forceinline__ unsigned pk2(float lo, float hi) { return pg8::cvt_pk_bf16(lo, hi); }
; __device__ __forceinline__ void xpose_item(const float* W, int K, int N, bf16* WT, const float* gain, int cmap, LAS float* scr, int item, int lane) {
;     ...
;     for (int i = 0; i < 16; ++i) { LAS float* d = scr + (4 * i + ks) * XP_STRIDE + n4; d[0] = w[i][0]; d[1] = w[i][1]; d[2] = w[i][2]; d[3] = w[i][3]; }
;     LDS_WAIT(); asm volatile("" ::: "memory");
;     int r0 = n0;
;     if (cmap == 1) { if (n0 < 1024) r0 = 2048 + n0; else if (n0 < 2048) { const int c = n0 - 1024; r0 = (c >> 7) * 256 + (c & 127); } else { const int c = n0 - 2048; r0 = (c >> 7) * 256 + 128 + (c & 127); } }
;     const int c = lane & 7;
; #pragma unroll
;     for (int j = 0; j < 8; ++j) { const int n = (lane >> 3) + 8 * j; const LAS float* sp = scr + (8 * c) * XP_STRIDE + n;
;         v4u o; o.x = pk2(sp[0 * XP_STRIDE], sp[1 * XP_STRIDE]); o.y = pk2(sp[2 * XP_STRIDE], sp[3 * XP_STRIDE]); o.z = pk2(sp[4 * XP_STRIDE], sp[5 * XP_STRIDE]); o.w = pk2(sp[6 * XP_STRIDE], sp[7 * XP_STRIDE]);
;         int rr = r0 + n;
;         if (cmap == 4) { const int cc = rr & 255; rr = (rr & ~255) + 128 * ((cc >> 5) & 1) + 32 * (cc >> 6) + (cc & 31); }
;         *(v4u*)(WT + (size_t)rr * K + k0 + 8 * c) = o; }
.LBB0_539:
	s_waitcnt vmcnt(15)
	ds_write2_b32 v69, v10, v11 offset1:1
	ds_write2_b32 v69, v12, v13 offset0:2 offset1:3
	v_add_u32_e32 v10, 0x410, v69
	s_waitcnt vmcnt(14)
	ds_write2_b32 v10, v2, v3 offset1:1
	v_add_u32_e32 v2, 0x418, v69
	ds_write2_b32 v2, v4, v5 offset1:1
	v_add_u32_e32 v2, 0x820, v69
	s_waitcnt vmcnt(13)
	ds_write2_b32 v2, v18, v19 offset1:1
	v_add_u32_e32 v2, 0x828, v69
	ds_write2_b32 v2, v20, v21 offset1:1
	v_add_u32_e32 v2, 0xc30, v69
	s_waitcnt vmcnt(12)
	ds_write2_b32 v2, v6, v7 offset1:1
	v_add_u32_e32 v2, 0xc38, v69
	ds_write2_b32 v2, v8, v9 offset1:1
	v_add_u32_e32 v2, 0x1040, v69
	s_waitcnt vmcnt(11)
	ds_write2_b32 v2, v26, v27 offset1:1
	v_add_u32_e32 v2, 0x1048, v69
	ds_write2_b32 v2, v28, v29 offset1:1
	v_add_u32_e32 v2, 0x1450, v69
	s_waitcnt vmcnt(10)
	ds_write2_b32 v2, v14, v15 offset1:1
	v_add_u32_e32 v2, 0x1458, v69
	ds_write2_b32 v2, v16, v17 offset1:1
	v_add_u32_e32 v2, 0x1860, v69
	s_waitcnt vmcnt(9)
	ds_write2_b32 v2, v34, v35 offset1:1
	v_add_u32_e32 v2, 0x1868, v69
	ds_write2_b32 v2, v36, v37 offset1:1
	v_add_u32_e32 v2, 0x1c70, v69
	s_waitcnt vmcnt(8)
	ds_write2_b32 v2, v22, v23 offset1:1
	v_add_u32_e32 v2, 0x1c78, v69
	ds_write2_b32 v2, v24, v25 offset1:1
	v_add_u32_e32 v2, 0x2080, v69
	s_waitcnt vmcnt(7)
	ds_write2_b32 v2, v42, v43 offset1:1
	v_add_u32_e32 v2, 0x2088, v69
	ds_write2_b32 v2, v44, v45 offset1:1
	v_add_u32_e32 v2, 0x2490, v69
	s_waitcnt vmcnt(6)
	ds_write2_b32 v2, v30, v31 offset1:1
	v_add_u32_e32 v2, 0x2498, v69
	ds_write2_b32 v2, v32, v33 offset1:1
	v_add_u32_e32 v2, 0x28a0, v69
	s_waitcnt vmcnt(5)
	ds_write2_b32 v2, v50, v51 offset1:1
	v_add_u32_e32 v2, 0x28a8, v69
	ds_write2_b32 v2, v52, v53 offset1:1
	v_add_u32_e32 v2, 0x2cb0, v69
	s_waitcnt vmcnt(4)
	ds_write2_b32 v2, v38, v39 offset1:1
	v_add_u32_e32 v2, 0x2cb8, v69
	ds_write2_b32 v2, v40, v41 offset1:1
	v_add_u32_e32 v2, 0x30c0, v69
	s_waitcnt vmcnt(3)
	ds_write2_b32 v2, v58, v59 offset1:1
	v_add_u32_e32 v2, 0x30c8, v69
	ds_write2_b32 v2, v60, v61 offset1:1
	v_add_u32_e32 v2, 0x34d0, v69
	s_waitcnt vmcnt(2)
	ds_write2_b32 v2, v46, v47 offset1:1
	v_add_u32_e32 v2, 0x34d8, v69
	ds_write2_b32 v2, v48, v49 offset1:1
	v_add_u32_e32 v2, 0x38e0, v69
	s_waitcnt vmcnt(1)
	ds_write2_b32 v2, v62, v63 offset1:1
	v_add_u32_e32 v2, 0x38e8, v69
	s_lshl_b64 s[4:5], s[86:87], 23
	v_readlane_b32 s8, v253, 5
	ds_write2_b32 v2, v64, v65 offset1:1
	v_add_u32_e32 v2, 0x3cf0, v69
	s_add_u32 s4, s8, s4
	v_readlane_b32 s8, v253, 6
	s_waitcnt vmcnt(0)
	ds_write2_b32 v2, v54, v55 offset1:1
	v_add_u32_e32 v2, 0x3cf8, v69
	s_addc_u32 s5, s8, s5
	s_lshl_b32 s3, s3, 1
	ds_write2_b32 v2, v56, v57 offset1:1
	s_add_u32 s4, s4, s3
	s_waitcnt lgkmcnt(0)
	s_addc_u32 s5, s5, 0
	v_lshlrev_b32_e32 v98, 1, v72
	v_lshl_add_u64 v[8:9], s[4:5], 0, v[98:99]
	s_and_b32 s3, s15, 0x60
	s_and_b32 s4, s13, 0xf00
	ds_read2_b32 v[2:3], v73 offset1:65
	s_or_b32 s4, s4, s3
	s_waitcnt lgkmcnt(0)
	v_cvt_pk_bf16_f32 v2, v2, v3
	ds_read2_b32 v[4:5], v73 offset0:130 offset1:195
	v_add_u32_e32 v14, 0x400, v73
	v_or_b32_e32 v10, s4, v71
	s_waitcnt lgkmcnt(0)
	v_cvt_pk_bf16_f32 v3, v4, v5
	ds_read2_b32 v[4:5], v14 offset0:4 offset1:69
	v_lshlrev_b32_e32 v98, 11, v10
	s_waitcnt lgkmcnt(0)
	v_cvt_pk_bf16_f32 v4, v4, v5
	ds_read2_b32 v[6:7], v14 offset0:134 offset1:199
	s_waitcnt lgkmcnt(0)
	v_cvt_pk_bf16_f32 v5, v6, v7
	v_lshl_add_u64 v[10:11], v[8:9], 0, v[98:99]
	ds_read2_b32 v[6:7], v73 offset0:8 offset1:73
	global_store_dwordx4 v[10:11], v[2:5], off sc1
	v_or_b32_e32 v12, s4, v84
	v_lshlrev_b32_e32 v98, 11, v12
	s_waitcnt lgkmcnt(0)
	v_cvt_pk_bf16_f32 v2, v6, v7
	ds_read2_b32 v[4:5], v73 offset0:138 offset1:203
	s_waitcnt lgkmcnt(0)
	v_cvt_pk_bf16_f32 v3, v4, v5
	ds_read2_b32 v[4:5], v14 offset0:12 offset1:77
	s_waitcnt lgkmcnt(0)
	v_cvt_pk_bf16_f32 v4, v4, v5
	ds_read2_b32 v[6:7], v14 offset0:142 offset1:207
	s_waitcnt lgkmcnt(0)
; #define LAS __attribute__((address_space(3)))
; __device__ __forceinline__ unsigned pk2(float lo, float hi) { return pg8::cvt_pk_bf16(lo, hi); }
; __device__ __forceinline__ void xpose_item(const float* W, int K, int N, bf16* WT, const float* gain, int cmap, LAS float* scr, int item, int lane) {
;     ...
;     for (int j = 0; j < 8; ++j) { const int n = (lane >> 3) + 8 * j; const LAS float* sp = scr + (8 * c) * XP_STRIDE + n;
;         v4u o; o.x = pk2(sp[0 * XP_STRIDE], sp[1 * XP_STRIDE]); o.y = pk2(sp[2 * XP_STRIDE], sp[3 * XP_STRIDE]); o.z = pk2(sp[4 * XP_STRIDE], sp[5 * XP_STRIDE]); o.w = pk2(sp[6 * XP_STRIDE], sp[7 * XP_STRIDE]);
;         int rr = r0 + n;
;         if (cmap == 4) { const int cc = rr & 255; rr = (rr & ~255) + 128 * ((cc >> 5) & 1) + 32 * (cc >> 6) + (cc & 31); }
;         *(v4u*)(WT + (size_t)rr * K + k0 + 8 * c) = o; }
	v_cvt_pk_bf16_f32 v5, v6, v7
	v_lshl_add_u64 v[12:13], v[8:9], 0, v[98:99]
	ds_read2_b32 v[6:7], v73 offset0:16 offset1:81
	global_store_dwordx4 v[12:13], v[2:5], off sc1
	v_or_b32_e32 v12, s4, v85
	v_lshlrev_b32_e32 v98, 11, v12
	s_waitcnt lgkmcnt(0)
	v_cvt_pk_bf16_f32 v2, v6, v7
	ds_read2_b32 v[4:5], v73 offset0:146 offset1:211
	s_waitcnt lgkmcnt(0)
	v_cvt_pk_bf16_f32 v3, v4, v5
	ds_read2_b32 v[4:5], v14 offset0:20 offset1:85
	s_waitcnt lgkmcnt(0)
	v_cvt_pk_bf16_f32 v4, v4, v5
	ds_read2_b32 v[6:7], v14 offset0:150 offset1:215
	s_waitcnt lgkmcnt(0)
	v_cvt_pk_bf16_f32 v5, v6, v7
	v_lshl_add_u64 v[12:13], v[8:9], 0, v[98:99]
	ds_read2_b32 v[6:7], v73 offset0:24 offset1:89
	global_store_dwordx4 v[12:13], v[2:5], off sc1
	v_or_b32_e32 v12, s4, v86
	v_lshlrev_b32_e32 v98, 11, v12
	s_waitcnt lgkmcnt(0)
	v_cvt_pk_bf16_f32 v2, v6, v7
	ds_read2_b32 v[4:5], v73 offset0:154 offset1:219
	s_waitcnt lgkmcnt(0)
	v_cvt_pk_bf16_f32 v3, v4, v5
	ds_read2_b32 v[4:5], v14 offset0:28 offset1:93
	s_waitcnt lgkmcnt(0)
	v_cvt_pk_bf16_f32 v4, v4, v5
	ds_read2_b32 v[6:7], v14 offset0:158 offset1:223
	s_waitcnt lgkmcnt(0)
	v_cvt_pk_bf16_f32 v5, v6, v7
	v_lshl_add_u64 v[12:13], v[8:9], 0, v[98:99]
	ds_read2_b32 v[6:7], v73 offset0:32 offset1:97
	global_store_dwordx4 v[12:13], v[2:5], off sc1
	s_mov_b32 s4, 0x40000
	v_add_co_u32_e32 v10, vcc, s4, v10
	s_waitcnt lgkmcnt(0)
	v_cvt_pk_bf16_f32 v2, v6, v7
	ds_read2_b32 v[4:5], v73 offset0:162 offset1:227
	s_waitcnt lgkmcnt(0)
	v_cvt_pk_bf16_f32 v3, v4, v5
	ds_read2_b32 v[4:5], v14 offset0:36 offset1:101
	s_waitcnt lgkmcnt(0)
	v_cvt_pk_bf16_f32 v4, v4, v5
	ds_read2_b32 v[6:7], v14 offset0:166 offset1:231
	s_waitcnt lgkmcnt(0)
	v_cvt_pk_bf16_f32 v5, v6, v7
	v_addc_co_u32_e32 v11, vcc, 0, v11, vcc
	ds_read2_b32 v[6:7], v73 offset0:40 offset1:105
	global_store_dwordx4 v[10:11], v[2:5], off sc1
	v_add_u32_e32 v12, s13, v71
	s_waitcnt lgkmcnt(0)
	v_cvt_pk_bf16_f32 v2, v6, v7
	ds_read2_b32 v[4:5], v73 offset0:170 offset1:235
	s_waitcnt lgkmcnt(0)
	v_cvt_pk_bf16_f32 v3, v4, v5
	ds_read2_b32 v[4:5], v14 offset0:44 offset1:109
	s_waitcnt lgkmcnt(0)
	v_cvt_pk_bf16_f32 v4, v4, v5
	ds_read2_b32 v[6:7], v14 offset0:174 offset1:239
	s_waitcnt lgkmcnt(0)
	v_cvt_pk_bf16_f32 v5, v6, v7
	v_add_u32_e32 v6, 40, v12
	v_and_b32_e32 v6, 0xf0f, v6
	v_or_b32_e32 v6, s3, v6
	v_lshlrev_b32_e32 v98, 11, v6
	v_lshl_add_u64 v[6:7], v[8:9], 0, v[98:99]
	v_add_co_u32_e32 v6, vcc, s4, v6
	ds_read2_b32 v[10:11], v73 offset0:48 offset1:113
	s_nop 0
	v_addc_co_u32_e32 v7, vcc, 0, v7, vcc
	global_store_dwordx4 v[6:7], v[2:5], off sc1
	s_waitcnt lgkmcnt(0)
	s_nop 0
	v_cvt_pk_bf16_f32 v2, v10, v11
	ds_read2_b32 v[4:5], v73 offset0:178 offset1:243
	s_waitcnt lgkmcnt(0)
	v_cvt_pk_bf16_f32 v3, v4, v5
	ds_read2_b32 v[4:5], v14 offset0:52 offset1:117
	s_waitcnt lgkmcnt(0)
	v_cvt_pk_bf16_f32 v4, v4, v5
	ds_read2_b32 v[6:7], v14 offset0:182 offset1:247
	s_waitcnt lgkmcnt(0)
	v_cvt_pk_bf16_f32 v5, v6, v7
	v_add_u32_e32 v6, 48, v12
	v_and_b32_e32 v6, 0xf17, v6
	v_or_b32_e32 v6, s3, v6
	v_lshlrev_b32_e32 v98, 11, v6
	v_lshl_add_u64 v[6:7], v[8:9], 0, v[98:99]
	v_add_co_u32_e32 v6, vcc, s4, v6
	ds_read2_b32 v[10:11], v73 offset0:56 offset1:121
	s_nop 0
	v_addc_co_u32_e32 v7, vcc, 0, v7, vcc
	global_store_dwordx4 v[6:7], v[2:5], off sc1
	s_waitcnt lgkmcnt(0)
	s_nop 0
	v_cvt_pk_bf16_f32 v2, v10, v11
	ds_read2_b32 v[4:5], v73 offset0:186 offset1:251
	s_waitcnt lgkmcnt(0)
	v_cvt_pk_bf16_f32 v3, v4, v5
	ds_read2_b32 v[4:5], v14 offset0:60 offset1:125
	s_waitcnt lgkmcnt(0)
	v_cvt_pk_bf16_f32 v4, v4, v5
	ds_read2_b32 v[6:7], v14 offset0:190 offset1:255
	s_waitcnt lgkmcnt(0)
	v_cvt_pk_bf16_f32 v5, v6, v7
	v_add_u32_e32 v6, 56, v12
	v_and_b32_e32 v6, 0xf1f, v6
	v_or_b32_e32 v6, s3, v6
	v_lshlrev_b32_e32 v98, 11, v6
	v_lshl_add_u64 v[6:7], v[8:9], 0, v[98:99]
	v_add_co_u32_e32 v6, vcc, 0x40000, v6
	s_nop 1
	v_addc_co_u32_e32 v7, vcc, 0, v7, vcc
	global_store_dwordx4 v[6:7], v[2:5], off sc1
	s_waitcnt lgkmcnt(0)

; #define LAS __attribute__((address_space(3)))
; __device__ __forceinline__ void xpose_item(const float* W, int K, int N, bf16* WT, const float* gain, int cmap, LAS float* scr, int item, int lane) {
;     ...
;     for (int i = 0; i < 16; ++i) w[i] = __builtin_nontemporal_load((const f32x4*)(W + (size_t)(k0 + 4 * i + ks) * N + n0 + n4));
;     if (gain) {
; #pragma unroll
;         for (int i = 0; i < 16; ++i) w[i] = w[i] * gain[k0 + 4 * i + ks];
;     }
; #pragma unroll
;     for (int i = 0; i < 16; ++i) { LAS float* d = scr + (4 * i + ks) * XP_STRIDE + n4; d[0] = w[i][0]; d[1] = w[i][1]; d[2] = w[i][2]; d[3] = w[i][3]; }
.LBB0_541:
	s_andn2_b64 vcc, exec, s[4:5]
	s_cbranch_vccnz .LBB0_543
	s_add_i32 s3, s1, 0x300
	s_and_b32 s3, s3, 0x3c0
	s_and_b32 s4, s13, 0x3c0
	v_or_b32_e32 v4, s3, v67
	s_lshl_b32 s86, s4, 2
	v_lshl_add_u64 v[2:3], v[78:79], 0, s[86:87]
	v_lshlrev_b32_e32 v98, 12, v4
	v_lshl_add_u64 v[62:63], v[2:3], 0, v[98:99]
	v_add_co_u32_e32 v6, vcc, 0x4000, v62
	s_lshl_b32 s86, s3, 1
	s_nop 0
	v_addc_co_u32_e32 v7, vcc, 0, v63, vcc
	v_add_co_u32_e32 v10, vcc, 0x8000, v62
	global_load_dwordx4 v[2:5], v[62:63], off nt
	s_nop 0
	global_load_dwordx4 v[6:9], v[6:7], off nt
	v_addc_co_u32_e32 v11, vcc, 0, v63, vcc
	v_add_co_u32_e32 v14, vcc, 0xc000, v62
	s_and_b32 s3, s15, 0x60
	s_nop 0
	v_addc_co_u32_e32 v15, vcc, 0, v63, vcc
	global_load_dwordx4 v[10:13], v[10:11], off nt
	s_nop 0
	global_load_dwordx4 v[14:17], v[14:15], off nt
	v_add_co_u32_e32 v18, vcc, 0x10000, v62
	s_and_b32 s4, s13, 0x300
	s_nop 0
	v_addc_co_u32_e32 v19, vcc, 0, v63, vcc
	v_add_co_u32_e32 v22, vcc, 0x14000, v62
	s_or_b32 s4, s4, s3
	s_nop 0
	v_addc_co_u32_e32 v23, vcc, 0, v63, vcc
	global_load_dwordx4 v[18:21], v[18:19], off nt
	s_nop 0
	global_load_dwordx4 v[22:25], v[22:23], off nt
	v_add_co_u32_e32 v26, vcc, 0x18000, v62
	s_nop 1
	v_addc_co_u32_e32 v27, vcc, 0, v63, vcc
	v_add_co_u32_e32 v30, vcc, 0x1c000, v62
	s_nop 1
	v_addc_co_u32_e32 v31, vcc, 0, v63, vcc
	global_load_dwordx4 v[26:29], v[26:27], off nt
	s_nop 0
	global_load_dwordx4 v[30:33], v[30:31], off nt
	v_add_co_u32_e32 v34, vcc, 0x20000, v62
	s_nop 1
	v_addc_co_u32_e32 v35, vcc, 0, v63, vcc
	v_add_co_u32_e32 v38, vcc, 0x24000, v62
	s_nop 1
	v_addc_co_u32_e32 v39, vcc, 0, v63, vcc
	global_load_dwordx4 v[34:37], v[34:35], off nt
	s_nop 0
	global_load_dwordx4 v[38:41], v[38:39], off nt
	v_add_co_u32_e32 v42, vcc, 0x28000, v62
	s_nop 1
	v_addc_co_u32_e32 v43, vcc, 0, v63, vcc
	v_add_co_u32_e32 v46, vcc, 0x2c000, v62
	s_nop 1
	v_addc_co_u32_e32 v47, vcc, 0, v63, vcc
	global_load_dwordx4 v[42:45], v[42:43], off nt
	s_nop 0
	global_load_dwordx4 v[46:49], v[46:47], off nt
	v_add_co_u32_e32 v50, vcc, 0x30000, v62
	s_nop 1
	v_addc_co_u32_e32 v51, vcc, 0, v63, vcc
	v_add_co_u32_e32 v54, vcc, 0x34000, v62
	s_nop 1
	v_addc_co_u32_e32 v55, vcc, 0, v63, vcc
	global_load_dwordx4 v[50:53], v[50:51], off nt
	s_nop 0
	global_load_dwordx4 v[54:57], v[54:55], off nt
	v_add_co_u32_e32 v58, vcc, 0x38000, v62
	s_nop 1
	v_addc_co_u32_e32 v59, vcc, 0, v63, vcc
	global_load_dwordx4 v[58:61], v[58:59], off nt
	v_add_co_u32_e32 v62, vcc, 0x3c000, v62
	s_nop 1
	v_addc_co_u32_e32 v63, vcc, 0, v63, vcc
	global_load_dwordx4 v[62:65], v[62:63], off nt
	s_waitcnt vmcnt(15)
	ds_write2_b32 v69, v2, v3 offset1:1
	ds_write2_b32 v69, v4, v5 offset0:2 offset1:3
	v_add_u32_e32 v2, 0x410, v69
	s_waitcnt vmcnt(14)
	ds_write2_b32 v2, v6, v7 offset1:1
	v_add_u32_e32 v2, 0x418, v69
	ds_write2_b32 v2, v8, v9 offset1:1
	v_add_u32_e32 v2, 0x820, v69
	v_lshl_add_u64 v[8:9], v[74:75], 0, s[86:87]
	s_waitcnt vmcnt(13)
	ds_write2_b32 v2, v10, v11 offset1:1
	v_add_u32_e32 v2, 0x828, v69
	ds_write2_b32 v2, v12, v13 offset1:1
	v_add_u32_e32 v2, 0xc30, v69
	s_waitcnt vmcnt(12)
	ds_write2_b32 v2, v14, v15 offset1:1
	v_add_u32_e32 v2, 0xc38, v69
	ds_write2_b32 v2, v16, v17 offset1:1
	v_add_u32_e32 v2, 0x1040, v69
	v_add_u32_e32 v14, 0x400, v73
	v_or_b32_e32 v10, s4, v71
	v_lshlrev_b32_e32 v98, 11, v10
	s_waitcnt vmcnt(11)
	ds_write2_b32 v2, v18, v19 offset1:1
	v_add_u32_e32 v2, 0x1048, v69
	ds_write2_b32 v2, v20, v21 offset1:1
	v_add_u32_e32 v2, 0x1450, v69
	s_waitcnt vmcnt(10)
	ds_write2_b32 v2, v22, v23 offset1:1
	v_add_u32_e32 v2, 0x1458, v69
	ds_write2_b32 v2, v24, v25 offset1:1
	v_add_u32_e32 v2, 0x1860, v69
	v_lshl_add_u64 v[10:11], v[8:9], 0, v[98:99]
	v_or_b32_e32 v12, s4, v84
	v_lshlrev_b32_e32 v98, 11, v12
	s_waitcnt vmcnt(9)
	ds_write2_b32 v2, v26, v27 offset1:1
	v_add_u32_e32 v2, 0x1868, v69
	ds_write2_b32 v2, v28, v29 offset1:1
	v_add_u32_e32 v2, 0x1c70, v69
	s_waitcnt vmcnt(8)
	ds_write2_b32 v2, v30, v31 offset1:1
	v_add_u32_e32 v2, 0x1c78, v69
	ds_write2_b32 v2, v32, v33 offset1:1
	v_add_u32_e32 v2, 0x2080, v69
	v_lshl_add_u64 v[12:13], v[8:9], 0, v[98:99]
	s_waitcnt vmcnt(7)
	ds_write2_b32 v2, v34, v35 offset1:1
	v_add_u32_e32 v2, 0x2088, v69
	ds_write2_b32 v2, v36, v37 offset1:1
	v_add_u32_e32 v2, 0x2490, v69
	s_waitcnt vmcnt(6)
	ds_write2_b32 v2, v38, v39 offset1:1
	v_add_u32_e32 v2, 0x2498, v69
	ds_write2_b32 v2, v40, v41 offset1:1
	v_add_u32_e32 v2, 0x28a0, v69
	s_waitcnt vmcnt(5)
	ds_write2_b32 v2, v42, v43 offset1:1
	v_add_u32_e32 v2, 0x28a8, v69
	ds_write2_b32 v2, v44, v45 offset1:1
	v_add_u32_e32 v2, 0x2cb0, v69
	s_waitcnt vmcnt(4)
	ds_write2_b32 v2, v46, v47 offset1:1
	v_add_u32_e32 v2, 0x2cb8, v69
	ds_write2_b32 v2, v48, v49 offset1:1
	v_add_u32_e32 v2, 0x30c0, v69
	s_waitcnt vmcnt(3)
	ds_write2_b32 v2, v50, v51 offset1:1
	v_add_u32_e32 v2, 0x30c8, v69
	ds_write2_b32 v2, v52, v53 offset1:1
	v_add_u32_e32 v2, 0x34d0, v69
	s_waitcnt vmcnt(2)
	ds_write2_b32 v2, v54, v55 offset1:1
	v_add_u32_e32 v2, 0x34d8, v69
	ds_write2_b32 v2, v56, v57 offset1:1
	v_add_u32_e32 v2, 0x38e0, v69
	s_waitcnt vmcnt(1)
; #define LAS __attribute__((address_space(3)))
; __device__ __forceinline__ unsigned pk2(float lo, float hi) { return pg8::cvt_pk_bf16(lo, hi); }
; __device__ __forceinline__ void xpose_item(const float* W, int K, int N, bf16* WT, const float* gain, int cmap, LAS float* scr, int item, int lane) {
;     ...
;     for (int j = 0; j < 8; ++j) { const int n = (lane >> 3) + 8 * j; const LAS float* sp = scr + (8 * c) * XP_STRIDE + n;
;         v4u o; o.x = pk2(sp[0 * XP_STRIDE], sp[1 * XP_STRIDE]); o.y = pk2(sp[2 * XP_STRIDE], sp[3 * XP_STRIDE]); o.z = pk2(sp[4 * XP_STRIDE], sp[5 * XP_STRIDE]); o.w = pk2(sp[6 * XP_STRIDE], sp[7 * XP_STRIDE]);
;         int rr = r0 + n;
;         if (cmap == 4) { const int cc = rr & 255; rr = (rr & ~255) + 128 * ((cc >> 5) & 1) + 32 * (cc >> 6) + (cc & 31); }
;         *(v4u*)(WT + (size_t)rr * K + k0 + 8 * c) = o; }
	ds_write2_b32 v2, v58, v59 offset1:1
	v_add_u32_e32 v2, 0x38e8, v69
	ds_write2_b32 v2, v60, v61 offset1:1
	v_add_u32_e32 v2, 0x3cf0, v69
	s_waitcnt vmcnt(0)
	ds_write2_b32 v2, v62, v63 offset1:1
	v_add_u32_e32 v2, 0x3cf8, v69
	ds_write2_b32 v2, v64, v65 offset1:1
	s_waitcnt lgkmcnt(0)
	ds_read2_b32 v[2:3], v73 offset1:65
	s_waitcnt lgkmcnt(0)
	v_cvt_pk_bf16_f32 v2, v2, v3
	ds_read2_b32 v[4:5], v73 offset0:130 offset1:195
	s_waitcnt lgkmcnt(0)
	v_cvt_pk_bf16_f32 v3, v4, v5
	ds_read2_b32 v[4:5], v14 offset0:4 offset1:69
	s_waitcnt lgkmcnt(0)
	v_cvt_pk_bf16_f32 v4, v4, v5
	ds_read2_b32 v[6:7], v14 offset0:134 offset1:199
	s_waitcnt lgkmcnt(0)
	v_cvt_pk_bf16_f32 v5, v6, v7
	ds_read2_b32 v[6:7], v73 offset0:8 offset1:73
	global_store_dwordx4 v[10:11], v[2:5], off sc1
	s_waitcnt lgkmcnt(0)
	s_nop 0
	v_cvt_pk_bf16_f32 v2, v6, v7
	ds_read2_b32 v[4:5], v73 offset0:138 offset1:203
	s_waitcnt lgkmcnt(0)
	v_cvt_pk_bf16_f32 v3, v4, v5
	ds_read2_b32 v[4:5], v14 offset0:12 offset1:77
	s_waitcnt lgkmcnt(0)
	v_cvt_pk_bf16_f32 v4, v4, v5
	ds_read2_b32 v[6:7], v14 offset0:142 offset1:207
	s_waitcnt lgkmcnt(0)
	v_cvt_pk_bf16_f32 v5, v6, v7
	ds_read2_b32 v[6:7], v73 offset0:16 offset1:81
	global_store_dwordx4 v[12:13], v[2:5], off sc1
	v_or_b32_e32 v12, s4, v85
	v_lshlrev_b32_e32 v98, 11, v12
	s_waitcnt lgkmcnt(0)
	v_cvt_pk_bf16_f32 v2, v6, v7
	ds_read2_b32 v[4:5], v73 offset0:146 offset1:211
	s_waitcnt lgkmcnt(0)
	v_cvt_pk_bf16_f32 v3, v4, v5
	ds_read2_b32 v[4:5], v14 offset0:20 offset1:85
	s_waitcnt lgkmcnt(0)
	v_cvt_pk_bf16_f32 v4, v4, v5
	ds_read2_b32 v[6:7], v14 offset0:150 offset1:215
	s_waitcnt lgkmcnt(0)
	v_cvt_pk_bf16_f32 v5, v6, v7
	v_lshl_add_u64 v[12:13], v[8:9], 0, v[98:99]
	ds_read2_b32 v[6:7], v73 offset0:24 offset1:89
	global_store_dwordx4 v[12:13], v[2:5], off sc1
	v_or_b32_e32 v12, s4, v86
	v_lshlrev_b32_e32 v98, 11, v12
	s_waitcnt lgkmcnt(0)
	v_cvt_pk_bf16_f32 v2, v6, v7
	ds_read2_b32 v[4:5], v73 offset0:154 offset1:219
	s_waitcnt lgkmcnt(0)
	v_cvt_pk_bf16_f32 v3, v4, v5
	ds_read2_b32 v[4:5], v14 offset0:28 offset1:93
	s_waitcnt lgkmcnt(0)
	v_cvt_pk_bf16_f32 v4, v4, v5
	ds_read2_b32 v[6:7], v14 offset0:158 offset1:223
	s_waitcnt lgkmcnt(0)
	v_cvt_pk_bf16_f32 v5, v6, v7
	v_lshl_add_u64 v[12:13], v[8:9], 0, v[98:99]
	ds_read2_b32 v[6:7], v73 offset0:32 offset1:97
	global_store_dwordx4 v[12:13], v[2:5], off sc1
	s_mov_b32 s4, 0x40000
	v_add_co_u32_e32 v10, vcc, s4, v10
	s_waitcnt lgkmcnt(0)
	v_cvt_pk_bf16_f32 v2, v6, v7
	ds_read2_b32 v[4:5], v73 offset0:162 offset1:227
	s_waitcnt lgkmcnt(0)
	v_cvt_pk_bf16_f32 v3, v4, v5
	ds_read2_b32 v[4:5], v14 offset0:36 offset1:101
	s_waitcnt lgkmcnt(0)
	v_cvt_pk_bf16_f32 v4, v4, v5
	ds_read2_b32 v[6:7], v14 offset0:166 offset1:231
	s_waitcnt lgkmcnt(0)
	v_cvt_pk_bf16_f32 v5, v6, v7
	v_addc_co_u32_e32 v11, vcc, 0, v11, vcc
	ds_read2_b32 v[6:7], v73 offset0:40 offset1:105
	global_store_dwordx4 v[10:11], v[2:5], off sc1
	v_add_u32_e32 v12, s13, v71
	s_waitcnt lgkmcnt(0)
	v_cvt_pk_bf16_f32 v2, v6, v7
	ds_read2_b32 v[4:5], v73 offset0:170 offset1:235
	s_waitcnt lgkmcnt(0)
	v_cvt_pk_bf16_f32 v3, v4, v5
	ds_read2_b32 v[4:5], v14 offset0:44 offset1:109
	s_waitcnt lgkmcnt(0)
	v_cvt_pk_bf16_f32 v4, v4, v5
	ds_read2_b32 v[6:7], v14 offset0:174 offset1:239
	s_waitcnt lgkmcnt(0)
	v_cvt_pk_bf16_f32 v5, v6, v7
	v_add_u32_e32 v6, 40, v12
	v_and_b32_e32 v6, 0x30f, v6
	v_or_b32_e32 v6, s3, v6
	v_lshlrev_b32_e32 v98, 11, v6
	v_lshl_add_u64 v[6:7], v[8:9], 0, v[98:99]
	v_add_co_u32_e32 v6, vcc, s4, v6
	ds_read2_b32 v[10:11], v73 offset0:48 offset1:113
	s_nop 0
	v_addc_co_u32_e32 v7, vcc, 0, v7, vcc
	global_store_dwordx4 v[6:7], v[2:5], off sc1
	s_waitcnt lgkmcnt(0)
	s_nop 0
	v_cvt_pk_bf16_f32 v2, v10, v11
	ds_read2_b32 v[4:5], v73 offset0:178 offset1:243
	s_waitcnt lgkmcnt(0)
	v_cvt_pk_bf16_f32 v3, v4, v5
	ds_read2_b32 v[4:5], v14 offset0:52 offset1:117
	s_waitcnt lgkmcnt(0)
	v_cvt_pk_bf16_f32 v4, v4, v5
	ds_read2_b32 v[6:7], v14 offset0:182 offset1:247
	s_waitcnt lgkmcnt(0)
	v_cvt_pk_bf16_f32 v5, v6, v7
	v_add_u32_e32 v6, 48, v12
	v_and_b32_e32 v6, 0x317, v6
	v_or_b32_e32 v6, s3, v6
	v_lshlrev_b32_e32 v98, 11, v6
	v_lshl_add_u64 v[6:7], v[8:9], 0, v[98:99]
	v_add_co_u32_e32 v6, vcc, s4, v6
	ds_read2_b32 v[10:11], v73 offset0:56 offset1:121
	s_nop 0
	v_addc_co_u32_e32 v7, vcc, 0, v7, vcc
	global_store_dwordx4 v[6:7], v[2:5], off sc1
	s_waitcnt lgkmcnt(0)
	s_nop 0
	v_cvt_pk_bf16_f32 v2, v10, v11
	ds_read2_b32 v[4:5], v73 offset0:186 offset1:251
	s_waitcnt lgkmcnt(0)
	v_cvt_pk_bf16_f32 v3, v4, v5
	ds_read2_b32 v[4:5], v14 offset0:60 offset1:125
	s_waitcnt lgkmcnt(0)
	v_cvt_pk_bf16_f32 v4, v4, v5
	ds_read2_b32 v[6:7], v14 offset0:190 offset1:255
	s_waitcnt lgkmcnt(0)
	v_cvt_pk_bf16_f32 v5, v6, v7
	v_add_u32_e32 v6, 56, v12
	v_and_b32_e32 v6, 0x31f, v6
	v_or_b32_e32 v6, s3, v6
	v_lshlrev_b32_e32 v98, 11, v6
	v_lshl_add_u64 v[6:7], v[8:9], 0, v[98:99]
	v_add_co_u32_e32 v6, vcc, 0x40000, v6
	s_nop 1
	v_addc_co_u32_e32 v7, vcc, 0, v7, vcc
	global_store_dwordx4 v[6:7], v[2:5], off sc1
	s_waitcnt lgkmcnt(0)

; #define LAS __attribute__((address_space(3)))
; __device__ __forceinline__ unsigned pk2(float lo, float hi) { return pg8::cvt_pk_bf16(lo, hi); }
; __device__ __forceinline__ void xpose_item(const float* W, int K, int N, bf16* WT, const float* gain, int cmap, LAS float* scr, int item, int lane) {
;     ...
;     for (int j = 0; j < 8; ++j) { const int n = (lane >> 3) + 8 * j; const LAS float* sp = scr + (8 * c) * XP_STRIDE + n;
;         v4u o; o.x = pk2(sp[0 * XP_STRIDE], sp[1 * XP_STRIDE]); o.y = pk2(sp[2 * XP_STRIDE], sp[3 * XP_STRIDE]); o.z = pk2(sp[4 * XP_STRIDE], sp[5 * XP_STRIDE]); o.w = pk2(sp[6 * XP_STRIDE], sp[7 * XP_STRIDE]);
;         int rr = r0 + n;
;         if (cmap == 4) { const int cc = rr & 255; rr = (rr & ~255) + 128 * ((cc >> 5) & 1) + 32 * (cc >> 6) + (cc & 31); }
;         *(v4u*)(WT + (size_t)rr * K + k0 + 8 * c) = o; }
.LBB0_553:
	v_add_u32_e32 v8, s8, v71
	ds_read2_b32 v[2:3], v73 offset1:65
	s_lshl_b32 s86, s3, 1
	v_ashrrev_i32_e32 v9, 31, v8
	s_waitcnt lgkmcnt(0)
	v_cvt_pk_bf16_f32 v2, v2, v3
	ds_read2_b32 v[4:5], v73 offset0:130 offset1:195
	v_add_u32_e32 v12, 0x400, v73
	v_lshl_add_u64 v[10:11], v[76:77], 0, s[86:87]
	v_lshlrev_b64 v[8:9], 11, v[8:9]
	s_waitcnt lgkmcnt(0)
	v_cvt_pk_bf16_f32 v3, v4, v5
	ds_read2_b32 v[4:5], v12 offset0:4 offset1:69
	v_lshl_add_u64 v[8:9], v[10:11], 0, v[8:9]
	s_waitcnt lgkmcnt(0)
	v_cvt_pk_bf16_f32 v4, v4, v5
	ds_read2_b32 v[6:7], v12 offset0:134 offset1:199
	s_waitcnt lgkmcnt(0)
	v_cvt_pk_bf16_f32 v5, v6, v7
	global_store_dwordx4 v[8:9], v[2:5], off sc1
	v_add_u32_e32 v8, s8, v84
	v_ashrrev_i32_e32 v9, 31, v8
	ds_read2_b32 v[6:7], v73 offset0:8 offset1:73
	s_waitcnt lgkmcnt(0)
	v_cvt_pk_bf16_f32 v2, v6, v7
	ds_read2_b32 v[4:5], v73 offset0:138 offset1:203
	v_lshlrev_b64 v[8:9], 11, v[8:9]
	s_waitcnt lgkmcnt(0)
	v_cvt_pk_bf16_f32 v3, v4, v5
	ds_read2_b32 v[4:5], v12 offset0:12 offset1:77
	v_lshl_add_u64 v[8:9], v[10:11], 0, v[8:9]
	s_waitcnt lgkmcnt(0)
	v_cvt_pk_bf16_f32 v4, v4, v5
	ds_read2_b32 v[6:7], v12 offset0:142 offset1:207
	s_waitcnt lgkmcnt(0)
	v_cvt_pk_bf16_f32 v5, v6, v7
	global_store_dwordx4 v[8:9], v[2:5], off sc1
	v_add_u32_e32 v8, s8, v85
	v_ashrrev_i32_e32 v9, 31, v8
	ds_read2_b32 v[6:7], v73 offset0:16 offset1:81
	s_waitcnt lgkmcnt(0)
	v_cvt_pk_bf16_f32 v2, v6, v7
	ds_read2_b32 v[4:5], v73 offset0:146 offset1:211
	v_lshlrev_b64 v[8:9], 11, v[8:9]
	s_waitcnt lgkmcnt(0)
	v_cvt_pk_bf16_f32 v3, v4, v5
	ds_read2_b32 v[4:5], v12 offset0:20 offset1:85
	v_lshl_add_u64 v[8:9], v[10:11], 0, v[8:9]
	s_waitcnt lgkmcnt(0)
	v_cvt_pk_bf16_f32 v4, v4, v5
	ds_read2_b32 v[6:7], v12 offset0:150 offset1:215
	s_waitcnt lgkmcnt(0)
	v_cvt_pk_bf16_f32 v5, v6, v7
	global_store_dwordx4 v[8:9], v[2:5], off sc1
	v_add_u32_e32 v8, s8, v86
	v_ashrrev_i32_e32 v9, 31, v8
	ds_read2_b32 v[6:7], v73 offset0:24 offset1:89
	s_waitcnt lgkmcnt(0)
	v_cvt_pk_bf16_f32 v2, v6, v7
	ds_read2_b32 v[4:5], v73 offset0:154 offset1:219
	v_lshlrev_b64 v[8:9], 11, v[8:9]
	s_waitcnt lgkmcnt(0)
	v_cvt_pk_bf16_f32 v3, v4, v5
	ds_read2_b32 v[4:5], v12 offset0:28 offset1:93
	v_lshl_add_u64 v[8:9], v[10:11], 0, v[8:9]
	s_waitcnt lgkmcnt(0)
	v_cvt_pk_bf16_f32 v4, v4, v5
	ds_read2_b32 v[6:7], v12 offset0:158 offset1:223
	s_waitcnt lgkmcnt(0)
	v_cvt_pk_bf16_f32 v5, v6, v7
	global_store_dwordx4 v[8:9], v[2:5], off sc1
	v_add_u32_e32 v8, s8, v90
	v_ashrrev_i32_e32 v9, 31, v8
	ds_read2_b32 v[6:7], v73 offset0:32 offset1:97
	s_waitcnt lgkmcnt(0)
	v_cvt_pk_bf16_f32 v2, v6, v7
	ds_read2_b32 v[4:5], v73 offset0:162 offset1:227
	v_lshlrev_b64 v[8:9], 11, v[8:9]
	s_waitcnt lgkmcnt(0)
	v_cvt_pk_bf16_f32 v3, v4, v5
	ds_read2_b32 v[4:5], v12 offset0:36 offset1:101
	v_lshl_add_u64 v[8:9], v[10:11], 0, v[8:9]
	s_waitcnt lgkmcnt(0)
	v_cvt_pk_bf16_f32 v4, v4, v5
	ds_read2_b32 v[6:7], v12 offset0:166 offset1:231
	s_waitcnt lgkmcnt(0)
	v_cvt_pk_bf16_f32 v5, v6, v7
	global_store_dwordx4 v[8:9], v[2:5], off sc1
	v_add_u32_e32 v8, s8, v87
	v_ashrrev_i32_e32 v9, 31, v8
	ds_read2_b32 v[6:7], v73 offset0:40 offset1:105
	s_waitcnt lgkmcnt(0)
	v_cvt_pk_bf16_f32 v2, v6, v7
	ds_read2_b32 v[4:5], v73 offset0:170 offset1:235
	v_lshlrev_b64 v[8:9], 11, v[8:9]
	s_waitcnt lgkmcnt(0)
	v_cvt_pk_bf16_f32 v3, v4, v5
	ds_read2_b32 v[4:5], v12 offset0:44 offset1:109
	v_lshl_add_u64 v[8:9], v[10:11], 0, v[8:9]
	s_waitcnt lgkmcnt(0)
	v_cvt_pk_bf16_f32 v4, v4, v5
	ds_read2_b32 v[6:7], v12 offset0:174 offset1:239
	s_waitcnt lgkmcnt(0)
	v_cvt_pk_bf16_f32 v5, v6, v7
	global_store_dwordx4 v[8:9], v[2:5], off sc1
	v_add_u32_e32 v8, s8, v88
	ds_read2_b32 v[6:7], v73 offset0:48 offset1:113
	s_waitcnt lgkmcnt(0)
	v_cvt_pk_bf16_f32 v2, v6, v7
	ds_read2_b32 v[4:5], v73 offset0:178 offset1:243
	v_ashrrev_i32_e32 v9, 31, v8
	s_waitcnt lgkmcnt(0)
	v_cvt_pk_bf16_f32 v3, v4, v5
	ds_read2_b32 v[4:5], v12 offset0:52 offset1:117
	v_lshlrev_b64 v[8:9], 11, v[8:9]
	s_waitcnt lgkmcnt(0)
	v_cvt_pk_bf16_f32 v4, v4, v5
	ds_read2_b32 v[6:7], v12 offset0:182 offset1:247
	s_waitcnt lgkmcnt(0)
	v_cvt_pk_bf16_f32 v5, v6, v7
	v_lshl_add_u64 v[8:9], v[10:11], 0, v[8:9]
	ds_read2_b32 v[6:7], v73 offset0:56 offset1:121
	global_store_dwordx4 v[8:9], v[2:5], off sc1
	v_add_u32_e32 v8, s8, v89
	v_ashrrev_i32_e32 v9, 31, v8
	s_waitcnt lgkmcnt(0)
	v_cvt_pk_bf16_f32 v2, v6, v7
	ds_read2_b32 v[4:5], v73 offset0:186 offset1:251
	s_waitcnt lgkmcnt(0)
	v_cvt_pk_bf16_f32 v3, v4, v5
	ds_read2_b32 v[4:5], v12 offset0:60 offset1:125
	s_waitcnt lgkmcnt(0)
	v_cvt_pk_bf16_f32 v4, v4, v5
	ds_read2_b32 v[6:7], v12 offset0:190 offset1:255
	v_lshlrev_b64 v[8:9], 11, v[8:9]
	s_waitcnt lgkmcnt(0)
	v_cvt_pk_bf16_f32 v5, v6, v7
	v_lshl_add_u64 v[6:7], v[10:11], 0, v[8:9]
	global_store_dwordx4 v[6:7], v[2:5], off sc1
	s_waitcnt lgkmcnt(0)

; #define LAS __attribute__((address_space(3)))
; __device__ __forceinline__ void xpose_item(const float* W, int K, int N, bf16* WT, const float* gain, int cmap, LAS float* scr, int item, int lane) {
;     ...
;     for (int i = 0; i < 16; ++i) w[i] = __builtin_nontemporal_load((const f32x4*)(W + (size_t)(k0 + 4 * i + ks) * N + n0 + n4));
;     if (gain) {
; #pragma unroll
;         for (int i = 0; i < 16; ++i) w[i] = w[i] * gain[k0 + 4 * i + ks];
;     }
; #pragma unroll
;     for (int i = 0; i < 16; ++i) { LAS float* d = scr + (4 * i + ks) * XP_STRIDE + n4; d[0] = w[i][0]; d[1] = w[i][1]; d[2] = w[i][2]; d[3] = w[i][3]; }
; __device__ __forceinline__ void prologue(const Args& a, LAS unsigned char* lds, int vcu, int G, int wave, int lane, int tid) {
;     ...
;         if (r < 4 * I_POOL) { const int g = r / I_POOL; r -= g * I_POOL; xpose_item(a.in[6] + (size_t)g * 65536, 256, 256, (bf16*)(ws + WS_WPOOL) + (size_t)g * 65536, nullptr, 4, scr, r, lane); continue; } r -= 4 * I_POOL;
.LBB0_555:
	s_andn2_b64 vcc, exec, s[4:5]
	s_cbranch_vccnz .LBB0_557
	s_add_i32 s3, s7, 0x1440
	s_lshr_b32 s86, s3, 4
	v_readlane_b32 s68, v253, 18
	s_lshl_b64 s[4:5], s[86:87], 18
	v_readlane_b32 s80, v253, 30
	v_readlane_b32 s81, v253, 31
	s_add_u32 s3, s80, s4
	s_addc_u32 s8, s81, s5
	s_lshl_b64 s[4:5], s[86:87], 17
	v_readlane_b32 s10, v253, 13
	v_readlane_b32 s11, v253, 14
	s_add_u32 s9, s10, s4
	s_addc_u32 s10, s11, s5
	s_and_b32 s4, s13, 0xc0
	s_and_b32 s11, s17, 0xc0
	s_lshl_b32 s4, s4, 2
	s_add_u32 s4, s3, s4
	v_or_b32_e32 v4, s11, v67
	s_addc_u32 s5, s8, 0
	v_lshlrev_b32_e32 v98, 2, v70
	v_lshl_add_u64 v[2:3], s[4:5], 0, v[98:99]
	v_lshlrev_b32_e32 v98, 10, v4
	v_lshl_add_u64 v[62:63], v[2:3], 0, v[98:99]
	s_movk_i32 s3, 0x2000
	v_add_co_u32_e32 v10, vcc, s3, v62
	s_movk_i32 s3, 0x4000
	s_nop 0
	v_addc_co_u32_e32 v11, vcc, 0, v63, vcc
	v_add_co_u32_e32 v18, vcc, s3, v62
	s_movk_i32 s3, 0x6000
	s_nop 0
	v_addc_co_u32_e32 v19, vcc, 0, v63, vcc
	v_add_co_u32_e32 v26, vcc, s3, v62
	s_mov_b32 s3, 0x8000
	s_nop 0
	v_addc_co_u32_e32 v27, vcc, 0, v63, vcc
	v_add_co_u32_e32 v34, vcc, s3, v62
	global_load_dwordx4 v[2:5], v[62:63], off nt
	global_load_dwordx4 v[6:9], v[10:11], off offset:-4096 nt
	s_nop 0
	global_load_dwordx4 v[10:13], v[10:11], off nt
	s_nop 0
	global_load_dwordx4 v[14:17], v[18:19], off offset:-4096 nt
	s_nop 0
	global_load_dwordx4 v[18:21], v[18:19], off nt
	s_nop 0
	global_load_dwordx4 v[22:25], v[26:27], off offset:-4096 nt
	s_nop 0
	global_load_dwordx4 v[26:29], v[26:27], off nt
	v_addc_co_u32_e32 v35, vcc, 0, v63, vcc
	global_load_dwordx4 v[30:33], v[34:35], off offset:-4096 nt
	s_nop 0
	global_load_dwordx4 v[34:37], v[34:35], off nt
	s_mov_b32 s3, 0xa000
	v_add_co_u32_e32 v42, vcc, s3, v62
	s_mov_b32 s3, 0xc000
	s_nop 0
	v_addc_co_u32_e32 v43, vcc, 0, v63, vcc
	global_load_dwordx4 v[38:41], v[42:43], off offset:-4096 nt
	s_nop 0
	global_load_dwordx4 v[42:45], v[42:43], off nt
	v_add_co_u32_e32 v50, vcc, s3, v62
	s_mov_b32 s3, 0xe000
	s_nop 0
	v_addc_co_u32_e32 v51, vcc, 0, v63, vcc
	global_load_dwordx4 v[46:49], v[50:51], off offset:-4096 nt
	s_nop 0
	global_load_dwordx4 v[50:53], v[50:51], off nt
	v_add_co_u32_e32 v58, vcc, s3, v62
	s_mov_b32 s3, 0xf000
	s_nop 0
	v_addc_co_u32_e32 v59, vcc, 0, v63, vcc
	global_load_dwordx4 v[54:57], v[58:59], off offset:-4096 nt
	s_nop 0
	global_load_dwordx4 v[58:61], v[58:59], off nt
	v_add_co_u32_e32 v62, vcc, s3, v62
	v_add_u32_e32 v82, 0x410, v69
	s_nop 0
	v_addc_co_u32_e32 v63, vcc, 0, v63, vcc
	global_load_dwordx4 v[62:65], v[62:63], off nt
	v_add_u32_e32 v83, 0x418, v69
	v_add_u32_e32 v94, 0x820, v69
	v_add_u32_e32 v95, 0x828, v69
	v_add_u32_e32 v96, 0xc30, v69
	v_add_u32_e32 v97, 0xc38, v69
	v_add_u32_e32 v98, 0x1040, v69
	v_add_u32_e32 v100, 0x1048, v69
	v_add_u32_e32 v101, 0x1450, v69
	v_add_u32_e32 v102, 0x1458, v69
	v_add_u32_e32 v103, 0x1860, v69
	v_add_u32_e32 v104, 0x1868, v69
	v_add_u32_e32 v105, 0x1c70, v69
	s_lshl_b32 s3, s11, 1
	s_add_u32 s4, s9, s3
	s_addc_u32 s5, s10, 0
	s_and_b32 s3, s15, 0x60
	v_readlane_b32 s69, v253, 19
	v_readlane_b32 s70, v253, 20
	v_readlane_b32 s71, v253, 21
	v_readlane_b32 s72, v253, 22
	v_readlane_b32 s73, v253, 23
	v_readlane_b32 s74, v253, 24
	v_readlane_b32 s75, v253, 25
	v_readlane_b32 s76, v253, 26
	v_readlane_b32 s77, v253, 27
	v_readlane_b32 s78, v253, 28
	s_waitcnt vmcnt(15)
	ds_write2_b32 v69, v2, v3 offset1:1
	ds_write2_b32 v69, v4, v5 offset0:2 offset1:3
	s_waitcnt vmcnt(14)
	ds_write2_b32 v82, v6, v7 offset1:1
	ds_write2_b32 v83, v8, v9 offset1:1
	s_waitcnt vmcnt(13)
	ds_write2_b32 v94, v10, v11 offset1:1
	ds_write2_b32 v95, v12, v13 offset1:1
	s_waitcnt vmcnt(12)
	ds_write2_b32 v96, v14, v15 offset1:1
	ds_write2_b32 v97, v16, v17 offset1:1
	s_waitcnt vmcnt(11)
	ds_write2_b32 v98, v18, v19 offset1:1
	ds_write2_b32 v100, v20, v21 offset1:1
	s_waitcnt vmcnt(10)
	ds_write2_b32 v101, v22, v23 offset1:1
	ds_write2_b32 v102, v24, v25 offset1:1
	s_waitcnt vmcnt(9)
	ds_write2_b32 v103, v26, v27 offset1:1
	ds_write2_b32 v104, v28, v29 offset1:1
	s_waitcnt vmcnt(8)
	ds_write2_b32 v105, v30, v31 offset1:1
	v_add_u32_e32 v2, 0x1c78, v69
	ds_write2_b32 v2, v32, v33 offset1:1
	v_add_u32_e32 v2, 0x2080, v69
	s_waitcnt vmcnt(7)
	ds_write2_b32 v2, v34, v35 offset1:1
	v_add_u32_e32 v2, 0x2088, v69
	ds_write2_b32 v2, v36, v37 offset1:1
	v_add_u32_e32 v2, 0x2490, v69
	s_waitcnt vmcnt(6)
	ds_write2_b32 v2, v38, v39 offset1:1
	v_add_u32_e32 v2, 0x2498, v69
	ds_write2_b32 v2, v40, v41 offset1:1
	v_add_u32_e32 v2, 0x28a0, v69
	s_waitcnt vmcnt(5)
	ds_write2_b32 v2, v42, v43 offset1:1
	v_add_u32_e32 v2, 0x28a8, v69
	ds_write2_b32 v2, v44, v45 offset1:1
	v_add_u32_e32 v2, 0x2cb0, v69
	s_waitcnt vmcnt(4)
	ds_write2_b32 v2, v46, v47 offset1:1
	v_add_u32_e32 v2, 0x2cb8, v69
	ds_write2_b32 v2, v48, v49 offset1:1
	v_add_u32_e32 v2, 0x30c0, v69
	s_waitcnt vmcnt(3)
	ds_write2_b32 v2, v50, v51 offset1:1
	v_add_u32_e32 v2, 0x30c8, v69
	ds_write2_b32 v2, v52, v53 offset1:1
	v_add_u32_e32 v2, 0x34d0, v69
	s_waitcnt vmcnt(2)
	ds_write2_b32 v2, v54, v55 offset1:1
	v_add_u32_e32 v2, 0x34d8, v69
	ds_write2_b32 v2, v56, v57 offset1:1
	v_add_u32_e32 v2, 0x38e0, v69
	s_waitcnt vmcnt(1)
; #define LAS __attribute__((address_space(3)))
; #define LDS_WAIT() asm volatile("s_waitcnt lgkmcnt(0)" ::: "memory")
; __device__ __forceinline__ unsigned pk2(float lo, float hi) { return pg8::cvt_pk_bf16(lo, hi); }
; __device__ __forceinline__ void xpose_item(const float* W, int K, int N, bf16* WT, const float* gain, int cmap, LAS float* scr, int item, int lane) {
;     ...
;     for (int i = 0; i < 16; ++i) { LAS float* d = scr + (4 * i + ks) * XP_STRIDE + n4; d[0] = w[i][0]; d[1] = w[i][1]; d[2] = w[i][2]; d[3] = w[i][3]; }
;     LDS_WAIT(); asm volatile("" ::: "memory");
;     int r0 = n0;
;     if (cmap == 1) { if (n0 < 1024) r0 = 2048 + n0; else if (n0 < 2048) { const int c = n0 - 1024; r0 = (c >> 7) * 256 + (c & 127); } else { const int c = n0 - 2048; r0 = (c >> 7) * 256 + 128 + (c & 127); } }
;     const int c = lane & 7;
; #pragma unroll
;     for (int j = 0; j < 8; ++j) { const int n = (lane >> 3) + 8 * j; const LAS float* sp = scr + (8 * c) * XP_STRIDE + n;
;         v4u o; o.x = pk2(sp[0 * XP_STRIDE], sp[1 * XP_STRIDE]); o.y = pk2(sp[2 * XP_STRIDE], sp[3 * XP_STRIDE]); o.z = pk2(sp[4 * XP_STRIDE], sp[5 * XP_STRIDE]); o.w = pk2(sp[6 * XP_STRIDE], sp[7 * XP_STRIDE]);
;         int rr = r0 + n;
;         if (cmap == 4) { const int cc = rr & 255; rr = (rr & ~255) + 128 * ((cc >> 5) & 1) + 32 * (cc >> 6) + (cc & 31); }
;         *(v4u*)(WT + (size_t)rr * K + k0 + 8 * c) = o; }
	ds_write2_b32 v2, v58, v59 offset1:1
	v_add_u32_e32 v2, 0x38e8, v69
	ds_write2_b32 v2, v60, v61 offset1:1
	v_add_u32_e32 v2, 0x3cf0, v69
	s_waitcnt vmcnt(0)
	ds_write2_b32 v2, v62, v63 offset1:1
	v_add_u32_e32 v2, 0x3cf8, v69
	ds_write2_b32 v2, v64, v65 offset1:1
	s_waitcnt lgkmcnt(0)
	ds_read2_b32 v[2:3], v73 offset1:65
	s_waitcnt lgkmcnt(0)
	v_cvt_pk_bf16_f32 v2, v2, v3
	ds_read2_b32 v[4:5], v73 offset0:130 offset1:195
	v_add_u32_e32 v14, 0x400, v73
	v_lshlrev_b32_e32 v98, 1, v72
	v_or_b32_e32 v10, s3, v71
	s_waitcnt lgkmcnt(0)
	v_cvt_pk_bf16_f32 v3, v4, v5
	ds_read2_b32 v[4:5], v14 offset0:4 offset1:69
	v_lshl_add_u64 v[8:9], s[4:5], 0, v[98:99]
	v_lshlrev_b32_e32 v98, 9, v10
	s_waitcnt lgkmcnt(0)
	v_cvt_pk_bf16_f32 v4, v4, v5
	ds_read2_b32 v[6:7], v14 offset0:134 offset1:199
	s_waitcnt lgkmcnt(0)
	v_cvt_pk_bf16_f32 v5, v6, v7
	v_lshl_add_u64 v[10:11], v[8:9], 0, v[98:99]
	ds_read2_b32 v[6:7], v73 offset0:8 offset1:73
	global_store_dwordx4 v[10:11], v[2:5], off sc1
	v_or_b32_e32 v12, s3, v84
	v_lshlrev_b32_e32 v98, 9, v12
	s_waitcnt lgkmcnt(0)
	v_cvt_pk_bf16_f32 v2, v6, v7
	ds_read2_b32 v[4:5], v73 offset0:138 offset1:203
	s_waitcnt lgkmcnt(0)
	v_cvt_pk_bf16_f32 v3, v4, v5
	ds_read2_b32 v[4:5], v14 offset0:12 offset1:77
	s_waitcnt lgkmcnt(0)
	v_cvt_pk_bf16_f32 v4, v4, v5
	ds_read2_b32 v[6:7], v14 offset0:142 offset1:207
	s_waitcnt lgkmcnt(0)
	v_cvt_pk_bf16_f32 v5, v6, v7
	v_lshl_add_u64 v[12:13], v[8:9], 0, v[98:99]
	ds_read2_b32 v[6:7], v73 offset0:16 offset1:81
	global_store_dwordx4 v[12:13], v[2:5], off sc1
	v_or_b32_e32 v12, s3, v85
	v_lshlrev_b32_e32 v98, 9, v12
	s_waitcnt lgkmcnt(0)
	v_cvt_pk_bf16_f32 v2, v6, v7
	ds_read2_b32 v[4:5], v73 offset0:146 offset1:211
	s_waitcnt lgkmcnt(0)
	v_cvt_pk_bf16_f32 v3, v4, v5
	ds_read2_b32 v[4:5], v14 offset0:20 offset1:85
	s_waitcnt lgkmcnt(0)
	v_cvt_pk_bf16_f32 v4, v4, v5
	ds_read2_b32 v[6:7], v14 offset0:150 offset1:215
	s_waitcnt lgkmcnt(0)
	v_cvt_pk_bf16_f32 v5, v6, v7
	v_lshl_add_u64 v[12:13], v[8:9], 0, v[98:99]
	ds_read2_b32 v[6:7], v73 offset0:24 offset1:89
	global_store_dwordx4 v[12:13], v[2:5], off sc1
	v_or_b32_e32 v12, s3, v86
	v_lshlrev_b32_e32 v98, 9, v12
	s_waitcnt lgkmcnt(0)
	v_cvt_pk_bf16_f32 v2, v6, v7
	ds_read2_b32 v[4:5], v73 offset0:154 offset1:219
	s_waitcnt lgkmcnt(0)
	v_cvt_pk_bf16_f32 v3, v4, v5
	ds_read2_b32 v[4:5], v14 offset0:28 offset1:93
	s_waitcnt lgkmcnt(0)
	v_cvt_pk_bf16_f32 v4, v4, v5
	ds_read2_b32 v[6:7], v14 offset0:158 offset1:223
	s_waitcnt lgkmcnt(0)
	v_cvt_pk_bf16_f32 v5, v6, v7
	v_lshl_add_u64 v[12:13], v[8:9], 0, v[98:99]
	ds_read2_b32 v[6:7], v73 offset0:32 offset1:97
	global_store_dwordx4 v[12:13], v[2:5], off sc1
	s_mov_b32 s4, 0x10000
	v_add_co_u32_e32 v10, vcc, s4, v10
	s_waitcnt lgkmcnt(0)
	v_cvt_pk_bf16_f32 v2, v6, v7
	ds_read2_b32 v[4:5], v73 offset0:162 offset1:227
	s_waitcnt lgkmcnt(0)
	v_cvt_pk_bf16_f32 v3, v4, v5
	ds_read2_b32 v[4:5], v14 offset0:36 offset1:101
	s_waitcnt lgkmcnt(0)
	v_cvt_pk_bf16_f32 v4, v4, v5
	ds_read2_b32 v[6:7], v14 offset0:166 offset1:231
	s_waitcnt lgkmcnt(0)
	v_cvt_pk_bf16_f32 v5, v6, v7
	v_addc_co_u32_e32 v11, vcc, 0, v11, vcc
	ds_read2_b32 v[6:7], v73 offset0:40 offset1:105
	global_store_dwordx4 v[10:11], v[2:5], off sc1
	v_readlane_b32 s79, v253, 29
	v_readlane_b32 s82, v253, 32
	s_waitcnt lgkmcnt(0)
	v_cvt_pk_bf16_f32 v2, v6, v7
	ds_read2_b32 v[4:5], v73 offset0:170 offset1:235
	s_waitcnt lgkmcnt(0)
	v_cvt_pk_bf16_f32 v3, v4, v5
	ds_read2_b32 v[4:5], v14 offset0:44 offset1:109
	s_waitcnt lgkmcnt(0)
	v_cvt_pk_bf16_f32 v4, v4, v5
	v_or_b32_e32 v5, s3, v91
	v_lshlrev_b32_e32 v98, 9, v5
	v_lshl_add_u64 v[10:11], v[8:9], 0, v[98:99]
	v_add_co_u32_e32 v10, vcc, s4, v10
	ds_read2_b32 v[6:7], v14 offset0:174 offset1:239
	s_waitcnt lgkmcnt(0)
	v_cvt_pk_bf16_f32 v5, v6, v7
	v_addc_co_u32_e32 v11, vcc, 0, v11, vcc
	ds_read2_b32 v[6:7], v73 offset0:48 offset1:113
	global_store_dwordx4 v[10:11], v[2:5], off sc1
	v_readlane_b32 s83, v253, 33
	s_waitcnt lgkmcnt(0)
	v_cvt_pk_bf16_f32 v2, v6, v7
	ds_read2_b32 v[4:5], v73 offset0:178 offset1:243
	s_waitcnt lgkmcnt(0)
	v_cvt_pk_bf16_f32 v3, v4, v5
	ds_read2_b32 v[4:5], v14 offset0:52 offset1:117
	s_waitcnt lgkmcnt(0)
	v_cvt_pk_bf16_f32 v4, v4, v5
	v_or_b32_e32 v5, s3, v92
	v_lshlrev_b32_e32 v98, 9, v5
	v_lshl_add_u64 v[10:11], v[8:9], 0, v[98:99]
	v_add_co_u32_e32 v10, vcc, s4, v10
	ds_read2_b32 v[6:7], v14 offset0:182 offset1:247
	s_nop 0
	v_addc_co_u32_e32 v11, vcc, 0, v11, vcc
	s_waitcnt lgkmcnt(0)
	v_cvt_pk_bf16_f32 v5, v6, v7
	global_store_dwordx4 v[10:11], v[2:5], off sc1
	v_or_b32_e32 v10, s3, v93
	v_lshlrev_b32_e32 v98, 9, v10
	v_lshl_add_u64 v[8:9], v[8:9], 0, v[98:99]
	ds_read2_b32 v[6:7], v73 offset0:56 offset1:121
	s_waitcnt lgkmcnt(0)
	v_cvt_pk_bf16_f32 v2, v6, v7
	ds_read2_b32 v[4:5], v73 offset0:186 offset1:251
	v_add_co_u32_e32 v8, vcc, 0x10000, v8
	s_waitcnt lgkmcnt(0)
	v_cvt_pk_bf16_f32 v3, v4, v5
	ds_read2_b32 v[4:5], v14 offset0:60 offset1:125
	v_addc_co_u32_e32 v9, vcc, 0, v9, vcc
	s_waitcnt lgkmcnt(0)
	v_cvt_pk_bf16_f32 v4, v4, v5
	ds_read2_b32 v[6:7], v14 offset0:190 offset1:255
	s_waitcnt lgkmcnt(0)
	v_cvt_pk_bf16_f32 v5, v6, v7
	global_store_dwordx4 v[8:9], v[2:5], off sc1
	s_waitcnt lgkmcnt(0)

; #define LAS __attribute__((address_space(3)))
; __device__ __forceinline__ void xpose_item(const float* W, int K, int N, bf16* WT, const float* gain, int cmap, LAS float* scr, int item, int lane) {
;     ...
;     for (int i = 0; i < 16; ++i) w[i] = __builtin_nontemporal_load((const f32x4*)(W + (size_t)(k0 + 4 * i + ks) * N + n0 + n4));
;     if (gain) {
; #pragma unroll
;         for (int i = 0; i < 16; ++i) w[i] = w[i] * gain[k0 + 4 * i + ks];
;     }
; #pragma unroll
;     for (int i = 0; i < 16; ++i) { LAS float* d = scr + (4 * i + ks) * XP_STRIDE + n4; d[0] = w[i][0]; d[1] = w[i][1]; d[2] = w[i][2]; d[3] = w[i][3]; }
.LBB0_558:
	s_andn2_b64 vcc, exec, s[4:5]
	s_cbranch_vccnz .LBB0_560
	s_add_i32 s3, s7, 0x1640
	s_lshr_b32 s86, s3, 8
	v_readlane_b32 s68, v253, 18
	s_lshl_b64 s[4:5], s[86:87], 22
	v_readlane_b32 s78, v253, 28
	v_readlane_b32 s79, v253, 29
	s_add_u32 s3, s78, s4
	s_addc_u32 s8, s79, s5
	s_lshl_b64 s[4:5], s[86:87], 21
	s_add_u32 s9, s28, s4
	v_readlane_b32 s4, v253, 15
	s_addc_u32 s10, s4, s5
	s_and_b32 s4, s13, 0x3c0
	s_and_b32 s11, s1, 0x3c0
	s_lshl_b32 s4, s4, 2
	s_add_u32 s4, s3, s4
	v_or_b32_e32 v4, s11, v67
	s_addc_u32 s5, s8, 0
	v_lshlrev_b32_e32 v98, 2, v70
	v_lshl_add_u64 v[2:3], s[4:5], 0, v[98:99]
	v_lshlrev_b32_e32 v98, 12, v4
	v_lshl_add_u64 v[62:63], v[2:3], 0, v[98:99]
	s_movk_i32 s3, 0x4000
	v_add_co_u32_e32 v6, vcc, s3, v62
	s_mov_b32 s3, 0x8000
	s_nop 0
	v_addc_co_u32_e32 v7, vcc, 0, v63, vcc
	v_add_co_u32_e32 v10, vcc, s3, v62
	global_load_dwordx4 v[2:5], v[62:63], off nt
	s_nop 0
	global_load_dwordx4 v[6:9], v[6:7], off nt
	v_addc_co_u32_e32 v11, vcc, 0, v63, vcc
	s_mov_b32 s3, 0xc000
	v_add_co_u32_e32 v14, vcc, s3, v62
	s_mov_b32 s3, 0x10000
	s_nop 0
	v_addc_co_u32_e32 v15, vcc, 0, v63, vcc
	global_load_dwordx4 v[10:13], v[10:11], off nt
	s_nop 0
	global_load_dwordx4 v[14:17], v[14:15], off nt
	v_add_co_u32_e32 v18, vcc, s3, v62
	s_mov_b32 s3, 0x14000
	s_nop 0
	v_addc_co_u32_e32 v19, vcc, 0, v63, vcc
	v_add_co_u32_e32 v22, vcc, s3, v62
	s_mov_b32 s3, 0x18000
	s_nop 0
	v_addc_co_u32_e32 v23, vcc, 0, v63, vcc
	global_load_dwordx4 v[18:21], v[18:19], off nt
	s_nop 0
	global_load_dwordx4 v[22:25], v[22:23], off nt
	v_add_co_u32_e32 v26, vcc, s3, v62
	s_mov_b32 s3, 0x1c000
	s_nop 0
	v_addc_co_u32_e32 v27, vcc, 0, v63, vcc
	v_add_co_u32_e32 v30, vcc, s3, v62
	s_mov_b32 s3, 0x20000
	s_nop 0
	v_addc_co_u32_e32 v31, vcc, 0, v63, vcc
	global_load_dwordx4 v[26:29], v[26:27], off nt
	s_nop 0
	global_load_dwordx4 v[30:33], v[30:31], off nt
	v_add_co_u32_e32 v34, vcc, s3, v62
	s_mov_b32 s3, 0x24000
	s_nop 0
	v_addc_co_u32_e32 v35, vcc, 0, v63, vcc
	v_add_co_u32_e32 v38, vcc, s3, v62
	s_mov_b32 s3, 0x28000
	s_nop 0
	v_addc_co_u32_e32 v39, vcc, 0, v63, vcc
	global_load_dwordx4 v[34:37], v[34:35], off nt
	s_nop 0
	global_load_dwordx4 v[38:41], v[38:39], off nt
	v_add_co_u32_e32 v42, vcc, s3, v62
	s_mov_b32 s3, 0x2c000
	s_nop 0
	v_addc_co_u32_e32 v43, vcc, 0, v63, vcc
	v_add_co_u32_e32 v46, vcc, s3, v62
	s_mov_b32 s3, 0x30000
	s_nop 0
	v_addc_co_u32_e32 v47, vcc, 0, v63, vcc
	global_load_dwordx4 v[42:45], v[42:43], off nt
	s_nop 0
	global_load_dwordx4 v[46:49], v[46:47], off nt
	v_add_co_u32_e32 v50, vcc, s3, v62
	s_mov_b32 s3, 0x34000
	s_nop 0
	v_addc_co_u32_e32 v51, vcc, 0, v63, vcc
	global_load_dwordx4 v[50:53], v[50:51], off nt
	v_add_co_u32_e32 v54, vcc, s3, v62
	s_mov_b32 s3, 0x38000
	s_nop 0
	v_addc_co_u32_e32 v55, vcc, 0, v63, vcc
	global_load_dwordx4 v[54:57], v[54:55], off nt
	v_add_co_u32_e32 v58, vcc, s3, v62
	s_mov_b32 s3, 0x3c000
	s_nop 0
	v_addc_co_u32_e32 v59, vcc, 0, v63, vcc
	global_load_dwordx4 v[58:61], v[58:59], off nt
	v_add_co_u32_e32 v62, vcc, s3, v62
	s_lshl_b32 s3, s11, 1
	s_nop 0
	v_addc_co_u32_e32 v63, vcc, 0, v63, vcc
	global_load_dwordx4 v[62:65], v[62:63], off nt
	s_waitcnt vmcnt(15)
	ds_write2_b32 v69, v2, v3 offset1:1
	ds_write2_b32 v69, v4, v5 offset0:2 offset1:3
	v_add_u32_e32 v2, 0x410, v69
	s_waitcnt vmcnt(14)
	ds_write2_b32 v2, v6, v7 offset1:1
	v_add_u32_e32 v2, 0x418, v69
	ds_write2_b32 v2, v8, v9 offset1:1
	v_add_u32_e32 v2, 0x820, v69
	s_add_u32 s4, s9, s3
	s_addc_u32 s5, s10, 0
	v_lshlrev_b32_e32 v98, 1, v72
	s_waitcnt vmcnt(13)
	ds_write2_b32 v2, v10, v11 offset1:1
	v_add_u32_e32 v2, 0x828, v69
	ds_write2_b32 v2, v12, v13 offset1:1
	v_add_u32_e32 v2, 0xc30, v69
	s_waitcnt vmcnt(12)
	ds_write2_b32 v2, v14, v15 offset1:1
	v_add_u32_e32 v2, 0xc38, v69
	ds_write2_b32 v2, v16, v17 offset1:1
	v_add_u32_e32 v2, 0x1040, v69
	v_lshl_add_u64 v[8:9], s[4:5], 0, v[98:99]
	s_and_b32 s3, s15, 0x60
	s_and_b32 s4, s13, 0x300
	s_waitcnt vmcnt(11)
	ds_write2_b32 v2, v18, v19 offset1:1
	v_add_u32_e32 v2, 0x1048, v69
	ds_write2_b32 v2, v20, v21 offset1:1
	v_add_u32_e32 v2, 0x1450, v69
	s_waitcnt vmcnt(10)
	ds_write2_b32 v2, v22, v23 offset1:1
	v_add_u32_e32 v2, 0x1458, v69
	ds_write2_b32 v2, v24, v25 offset1:1
	v_add_u32_e32 v2, 0x1860, v69
	s_or_b32 s4, s4, s3
	v_add_u32_e32 v14, 0x400, v73
	v_or_b32_e32 v10, s4, v71
	s_waitcnt vmcnt(9)
	ds_write2_b32 v2, v26, v27 offset1:1
	v_add_u32_e32 v2, 0x1868, v69
	ds_write2_b32 v2, v28, v29 offset1:1
	v_add_u32_e32 v2, 0x1c70, v69
	s_waitcnt vmcnt(8)
	ds_write2_b32 v2, v30, v31 offset1:1
	v_add_u32_e32 v2, 0x1c78, v69
	ds_write2_b32 v2, v32, v33 offset1:1
	v_add_u32_e32 v2, 0x2080, v69
	v_lshlrev_b32_e32 v98, 11, v10
	v_lshl_add_u64 v[10:11], v[8:9], 0, v[98:99]
	v_or_b32_e32 v12, s4, v84
	s_waitcnt vmcnt(7)
	ds_write2_b32 v2, v34, v35 offset1:1
	v_add_u32_e32 v2, 0x2088, v69
	ds_write2_b32 v2, v36, v37 offset1:1
	v_add_u32_e32 v2, 0x2490, v69
	s_waitcnt vmcnt(6)
	ds_write2_b32 v2, v38, v39 offset1:1
	v_add_u32_e32 v2, 0x2498, v69
	ds_write2_b32 v2, v40, v41 offset1:1
	v_add_u32_e32 v2, 0x28a0, v69
	v_lshlrev_b32_e32 v98, 11, v12
	v_lshl_add_u64 v[12:13], v[8:9], 0, v[98:99]
	v_readlane_b32 s69, v253, 19
	s_waitcnt vmcnt(5)
	ds_write2_b32 v2, v42, v43 offset1:1
	v_add_u32_e32 v2, 0x28a8, v69
	ds_write2_b32 v2, v44, v45 offset1:1
	v_add_u32_e32 v2, 0x2cb0, v69
	s_waitcnt vmcnt(4)
	ds_write2_b32 v2, v46, v47 offset1:1
	v_add_u32_e32 v2, 0x2cb8, v69
	ds_write2_b32 v2, v48, v49 offset1:1
	v_add_u32_e32 v2, 0x30c0, v69
	s_waitcnt vmcnt(3)
; #define LAS __attribute__((address_space(3)))
; #define LDS_WAIT() asm volatile("s_waitcnt lgkmcnt(0)" ::: "memory")
; __device__ __forceinline__ unsigned pk2(float lo, float hi) { return pg8::cvt_pk_bf16(lo, hi); }
; __device__ __forceinline__ void xpose_item(const float* W, int K, int N, bf16* WT, const float* gain, int cmap, LAS float* scr, int item, int lane) {
;     ...
;     for (int i = 0; i < 16; ++i) { LAS float* d = scr + (4 * i + ks) * XP_STRIDE + n4; d[0] = w[i][0]; d[1] = w[i][1]; d[2] = w[i][2]; d[3] = w[i][3]; }
;     LDS_WAIT(); asm volatile("" ::: "memory");
;     int r0 = n0;
;     if (cmap == 1) { if (n0 < 1024) r0 = 2048 + n0; else if (n0 < 2048) { const int c = n0 - 1024; r0 = (c >> 7) * 256 + (c & 127); } else { const int c = n0 - 2048; r0 = (c >> 7) * 256 + 128 + (c & 127); } }
;     const int c = lane & 7;
; #pragma unroll
;     for (int j = 0; j < 8; ++j) { const int n = (lane >> 3) + 8 * j; const LAS float* sp = scr + (8 * c) * XP_STRIDE + n;
;         v4u o; o.x = pk2(sp[0 * XP_STRIDE], sp[1 * XP_STRIDE]); o.y = pk2(sp[2 * XP_STRIDE], sp[3 * XP_STRIDE]); o.z = pk2(sp[4 * XP_STRIDE], sp[5 * XP_STRIDE]); o.w = pk2(sp[6 * XP_STRIDE], sp[7 * XP_STRIDE]);
;         int rr = r0 + n;
;         if (cmap == 4) { const int cc = rr & 255; rr = (rr & ~255) + 128 * ((cc >> 5) & 1) + 32 * (cc >> 6) + (cc & 31); }
;         *(v4u*)(WT + (size_t)rr * K + k0 + 8 * c) = o; }
	ds_write2_b32 v2, v50, v51 offset1:1
	v_add_u32_e32 v2, 0x30c8, v69
	ds_write2_b32 v2, v52, v53 offset1:1
	v_add_u32_e32 v2, 0x34d0, v69
	v_readlane_b32 s70, v253, 20
	s_waitcnt vmcnt(2)
	ds_write2_b32 v2, v54, v55 offset1:1
	v_add_u32_e32 v2, 0x34d8, v69
	ds_write2_b32 v2, v56, v57 offset1:1
	v_add_u32_e32 v2, 0x38e0, v69
	v_readlane_b32 s71, v253, 21
	v_readlane_b32 s72, v253, 22
	s_waitcnt vmcnt(1)
	ds_write2_b32 v2, v58, v59 offset1:1
	v_add_u32_e32 v2, 0x38e8, v69
	ds_write2_b32 v2, v60, v61 offset1:1
	v_add_u32_e32 v2, 0x3cf0, v69
	v_readlane_b32 s73, v253, 23
	v_readlane_b32 s74, v253, 24
	s_waitcnt vmcnt(0)
	ds_write2_b32 v2, v62, v63 offset1:1
	v_add_u32_e32 v2, 0x3cf8, v69
	ds_write2_b32 v2, v64, v65 offset1:1
	s_waitcnt lgkmcnt(0)
	ds_read2_b32 v[2:3], v73 offset1:65
	s_waitcnt lgkmcnt(0)
	v_cvt_pk_bf16_f32 v2, v2, v3
	ds_read2_b32 v[4:5], v73 offset0:130 offset1:195
	s_waitcnt lgkmcnt(0)
	v_cvt_pk_bf16_f32 v3, v4, v5
	ds_read2_b32 v[4:5], v14 offset0:4 offset1:69
	s_waitcnt lgkmcnt(0)
	v_cvt_pk_bf16_f32 v4, v4, v5
	ds_read2_b32 v[6:7], v14 offset0:134 offset1:199
	s_waitcnt lgkmcnt(0)
	v_cvt_pk_bf16_f32 v5, v6, v7
	ds_read2_b32 v[6:7], v73 offset0:8 offset1:73
	global_store_dwordx4 v[10:11], v[2:5], off sc1
	v_readlane_b32 s75, v253, 25
	v_readlane_b32 s76, v253, 26
	s_waitcnt lgkmcnt(0)
	v_cvt_pk_bf16_f32 v2, v6, v7
	ds_read2_b32 v[4:5], v73 offset0:138 offset1:203
	s_waitcnt lgkmcnt(0)
	v_cvt_pk_bf16_f32 v3, v4, v5
	ds_read2_b32 v[4:5], v14 offset0:12 offset1:77
	s_waitcnt lgkmcnt(0)
	v_cvt_pk_bf16_f32 v4, v4, v5
	ds_read2_b32 v[6:7], v14 offset0:142 offset1:207
	s_waitcnt lgkmcnt(0)
	v_cvt_pk_bf16_f32 v5, v6, v7
	ds_read2_b32 v[6:7], v73 offset0:16 offset1:81
	global_store_dwordx4 v[12:13], v[2:5], off sc1
	v_or_b32_e32 v12, s4, v85
	v_lshlrev_b32_e32 v98, 11, v12
	s_waitcnt lgkmcnt(0)
	v_cvt_pk_bf16_f32 v2, v6, v7
	ds_read2_b32 v[4:5], v73 offset0:146 offset1:211
	s_waitcnt lgkmcnt(0)
	v_cvt_pk_bf16_f32 v3, v4, v5
	ds_read2_b32 v[4:5], v14 offset0:20 offset1:85
	s_waitcnt lgkmcnt(0)
	v_cvt_pk_bf16_f32 v4, v4, v5
	ds_read2_b32 v[6:7], v14 offset0:150 offset1:215
	s_waitcnt lgkmcnt(0)
	v_cvt_pk_bf16_f32 v5, v6, v7
	v_lshl_add_u64 v[12:13], v[8:9], 0, v[98:99]
	ds_read2_b32 v[6:7], v73 offset0:24 offset1:89
	global_store_dwordx4 v[12:13], v[2:5], off sc1
	v_or_b32_e32 v12, s4, v86
	v_lshlrev_b32_e32 v98, 11, v12
	s_waitcnt lgkmcnt(0)
	v_cvt_pk_bf16_f32 v2, v6, v7
	ds_read2_b32 v[4:5], v73 offset0:154 offset1:219
	s_waitcnt lgkmcnt(0)
	v_cvt_pk_bf16_f32 v3, v4, v5
	ds_read2_b32 v[4:5], v14 offset0:28 offset1:93
	s_waitcnt lgkmcnt(0)
	v_cvt_pk_bf16_f32 v4, v4, v5
	ds_read2_b32 v[6:7], v14 offset0:158 offset1:223
	s_waitcnt lgkmcnt(0)
	v_cvt_pk_bf16_f32 v5, v6, v7
	v_lshl_add_u64 v[12:13], v[8:9], 0, v[98:99]
	ds_read2_b32 v[6:7], v73 offset0:32 offset1:97
	global_store_dwordx4 v[12:13], v[2:5], off sc1
	s_mov_b32 s4, 0x40000
	v_add_co_u32_e32 v10, vcc, s4, v10
	s_waitcnt lgkmcnt(0)
	v_cvt_pk_bf16_f32 v2, v6, v7
	ds_read2_b32 v[4:5], v73 offset0:162 offset1:227
	s_waitcnt lgkmcnt(0)
	v_cvt_pk_bf16_f32 v3, v4, v5
	ds_read2_b32 v[4:5], v14 offset0:36 offset1:101
	s_waitcnt lgkmcnt(0)
	v_cvt_pk_bf16_f32 v4, v4, v5
	ds_read2_b32 v[6:7], v14 offset0:166 offset1:231
	s_waitcnt lgkmcnt(0)
	v_cvt_pk_bf16_f32 v5, v6, v7
	v_addc_co_u32_e32 v11, vcc, 0, v11, vcc
	ds_read2_b32 v[6:7], v73 offset0:40 offset1:105
	global_store_dwordx4 v[10:11], v[2:5], off sc1
	v_add_u32_e32 v12, s13, v71
	v_readlane_b32 s77, v253, 27
	s_waitcnt lgkmcnt(0)
	v_cvt_pk_bf16_f32 v2, v6, v7
	ds_read2_b32 v[4:5], v73 offset0:170 offset1:235
	s_waitcnt lgkmcnt(0)
	v_cvt_pk_bf16_f32 v3, v4, v5
	ds_read2_b32 v[4:5], v14 offset0:44 offset1:109
	s_waitcnt lgkmcnt(0)
	v_cvt_pk_bf16_f32 v4, v4, v5
	ds_read2_b32 v[6:7], v14 offset0:174 offset1:239
	s_waitcnt lgkmcnt(0)
	v_cvt_pk_bf16_f32 v5, v6, v7
	v_add_u32_e32 v6, 40, v12
	v_and_b32_e32 v6, 0x30f, v6
	v_or_b32_e32 v6, s3, v6
	v_lshlrev_b32_e32 v98, 11, v6
	v_lshl_add_u64 v[6:7], v[8:9], 0, v[98:99]
	v_add_co_u32_e32 v6, vcc, s4, v6
	ds_read2_b32 v[10:11], v73 offset0:48 offset1:113
	s_nop 0
	v_addc_co_u32_e32 v7, vcc, 0, v7, vcc
	global_store_dwordx4 v[6:7], v[2:5], off sc1
	v_readlane_b32 s80, v253, 30
	v_readlane_b32 s81, v253, 31
	s_waitcnt lgkmcnt(0)
	v_cvt_pk_bf16_f32 v2, v10, v11
	ds_read2_b32 v[4:5], v73 offset0:178 offset1:243
	s_waitcnt lgkmcnt(0)
	v_cvt_pk_bf16_f32 v3, v4, v5
	ds_read2_b32 v[4:5], v14 offset0:52 offset1:117
	s_waitcnt lgkmcnt(0)
	v_cvt_pk_bf16_f32 v4, v4, v5
	ds_read2_b32 v[6:7], v14 offset0:182 offset1:247
	s_waitcnt lgkmcnt(0)
	v_cvt_pk_bf16_f32 v5, v6, v7
	v_add_u32_e32 v6, 48, v12
	v_and_b32_e32 v6, 0x317, v6
	v_or_b32_e32 v6, s3, v6
	v_lshlrev_b32_e32 v98, 11, v6
	v_lshl_add_u64 v[6:7], v[8:9], 0, v[98:99]
	v_add_co_u32_e32 v6, vcc, s4, v6
	ds_read2_b32 v[10:11], v73 offset0:56 offset1:121
	s_nop 0
	v_addc_co_u32_e32 v7, vcc, 0, v7, vcc
	global_store_dwordx4 v[6:7], v[2:5], off sc1
	v_readlane_b32 s82, v253, 32
	v_readlane_b32 s83, v253, 33
	s_waitcnt lgkmcnt(0)
	v_cvt_pk_bf16_f32 v2, v10, v11
	ds_read2_b32 v[4:5], v73 offset0:186 offset1:251
	s_waitcnt lgkmcnt(0)
	v_cvt_pk_bf16_f32 v3, v4, v5
	ds_read2_b32 v[4:5], v14 offset0:60 offset1:125
	s_waitcnt lgkmcnt(0)
	v_cvt_pk_bf16_f32 v4, v4, v5
	ds_read2_b32 v[6:7], v14 offset0:190 offset1:255
	s_waitcnt lgkmcnt(0)
	v_cvt_pk_bf16_f32 v5, v6, v7
	v_add_u32_e32 v6, 56, v12
	v_and_b32_e32 v6, 0x31f, v6
	v_or_b32_e32 v6, s3, v6
	v_lshlrev_b32_e32 v98, 11, v6
	v_lshl_add_u64 v[6:7], v[8:9], 0, v[98:99]
	v_add_co_u32_e32 v6, vcc, 0x40000, v6
	s_nop 1
	v_addc_co_u32_e32 v7, vcc, 0, v7, vcc
	global_store_dwordx4 v[6:7], v[2:5], off sc1
	s_waitcnt lgkmcnt(0)

; __device__ __forceinline__ unsigned pk2(float lo, float hi) { return pg8::cvt_pk_bf16(lo, hi); }
; __device__ __forceinline__ void prologue(const Args& a, LAS unsigned char* lds, int vcu, int G, int wave, int lane, int tid) {
;     ...
;         for (int m0 = gw; m0 < M; m0 += 2 * NGW) {
;             f32x4 v[2][4]; float sq[2];
; #pragma unroll
;             for (int u = 0; u < 2; ++u) { const int m = m0 + u * NGW; const f32x4* xr = (const f32x4*)(x + (size_t)(m < M ? m : m0) * DM) + lane;
; #pragma unroll
;                 for (int j = 0; j < 4; ++j) v[u][j] = __builtin_nontemporal_load(xr + 64 * j); }
; #pragma unroll
;             for (int u = 0; u < 2; ++u) { float s = 0.f;
; #pragma unroll
;                 for (int j = 0; j < 4; ++j) s += (v[u][j][0] * v[u][j][0] + v[u][j][1] * v[u][j][1]) + (v[u][j][2] * v[u][j][2] + v[u][j][3] * v[u][j][3]);
;                 sq[u] = wave_sum(s); }
; #pragma unroll
;             for (int u = 0; u < 2; ++u) { const int m = m0 + u * NGW; if (m < M) {
;                 v2u* o8 = (v2u*)(xb + (size_t)m * DM) + lane;
; #pragma unroll
;                 for (int j = 0; j < 4; ++j) { v2u w; w.x = pk2(v[u][j][0], v[u][j][1]); w.y = pk2(v[u][j][2], v[u][j][3]); o8[64 * j] = w; }
;                 if (lane < 16) ss[(size_t)m * 16 + lane] = (lane == 0) ? sq[u] : 0.f; } }
;         }
.LBB0_568:
	s_ashr_i32 s1, s0, 31
	s_lshl_b64 s[2:3], s[0:1], 12
	s_add_i32 s4, s0, s12
	s_cmpk_lt_i32 s4, 0x4000
	v_lshl_add_u64 v[2:3], v[18:19], 0, s[2:3]
	s_cselect_b64 s[6:7], -1, 0
	s_waitcnt lgkmcnt(0)
	global_load_dwordx4 v[30:33], v[2:3], off nt
	global_load_dwordx4 v[34:37], v[2:3], off offset:1024 nt
	global_load_dwordx4 v[38:41], v[2:3], off offset:2048 nt
	global_load_dwordx4 v[42:45], v[2:3], off offset:3072 nt
	s_and_b64 s[2:3], s[6:7], exec
	s_cselect_b32 s2, s4, s0
	s_ashr_i32 s3, s2, 31
	s_lshl_b64 s[2:3], s[2:3], 12
	v_lshl_add_u64 v[2:3], v[18:19], 0, s[2:3]
	global_load_dwordx4 v[14:17], v[2:3], off nt
	global_load_dwordx4 v[10:13], v[2:3], off offset:1024 nt
	global_load_dwordx4 v[6:9], v[2:3], off offset:2048 nt
	s_nop 0
	global_load_dwordx4 v[2:5], v[2:3], off offset:3072 nt
	s_lshl_b64 s[2:3], s[0:1], 11
	s_waitcnt vmcnt(7)
	v_mul_f32_e32 v46, v31, v31
	v_mul_f32_e32 v47, v33, v33
	s_waitcnt vmcnt(6)
	v_mul_f32_e32 v48, v35, v35
	v_mul_f32_e32 v49, v37, v37
	s_waitcnt vmcnt(5)
	v_mul_f32_e32 v50, v39, v39
	v_mul_f32_e32 v51, v41, v41
	v_fmac_f32_e32 v46, v30, v30
	v_fmac_f32_e32 v47, v32, v32
	v_fmac_f32_e32 v48, v34, v34
	v_fmac_f32_e32 v49, v36, v36
	s_waitcnt vmcnt(4)
	v_mul_f32_e32 v52, v43, v43
	v_mul_f32_e32 v53, v45, v45
	v_fmac_f32_e32 v50, v38, v38
	v_fmac_f32_e32 v51, v40, v40
	v_add_f32_e32 v46, v46, v47
	v_add_f32_e32 v47, v48, v49
	v_fmac_f32_e32 v52, v42, v42
	v_fmac_f32_e32 v53, v44, v44
	v_add_f32_e32 v48, v50, v51
	v_add_f32_e32 v46, v46, v47
	v_add_f32_e32 v49, v52, v53
	v_add_f32_e32 v46, v46, v48
	v_add_f32_e32 v46, v46, v49
	s_waitcnt vmcnt(3)
	v_mul_f32_e32 v48, v15, v15
	v_mul_f32_e32 v49, v17, v17
	s_waitcnt vmcnt(2)
	v_mul_f32_e32 v50, v11, v11
	v_mul_f32_e32 v51, v13, v13
	s_waitcnt vmcnt(1)
	v_mul_f32_e32 v52, v7, v7
	v_mul_f32_e32 v53, v9, v9
	v_fmac_f32_e32 v48, v14, v14
	v_fmac_f32_e32 v49, v16, v16
	v_fmac_f32_e32 v50, v10, v10
	v_fmac_f32_e32 v51, v12, v12
	s_waitcnt vmcnt(0)
	v_mul_f32_e32 v54, v3, v3
	v_mul_f32_e32 v55, v5, v5
	v_fmac_f32_e32 v52, v6, v6
	v_fmac_f32_e32 v53, v8, v8
	v_add_f32_e32 v48, v48, v49
	v_add_f32_e32 v49, v50, v51
	v_fmac_f32_e32 v54, v2, v2
	v_fmac_f32_e32 v55, v4, v4
	v_add_f32_e32 v50, v52, v53
	v_add_f32_e32 v48, v48, v49
	v_add_f32_e32 v51, v54, v55
	v_add_f32_e32 v48, v48, v50
	v_add_f32_e32 v48, v48, v51
	ds_bpermute_b32 v47, v24, v46
	ds_bpermute_b32 v49, v24, v48
	v_cvt_pk_bf16_f32 v30, v30, v31
	v_cvt_pk_bf16_f32 v31, v32, v33
	s_waitcnt lgkmcnt(1)
	v_add_f32_e32 v50, v46, v47
	s_waitcnt lgkmcnt(0)
	v_add_f32_e32 v48, v48, v49
	ds_bpermute_b32 v51, v25, v50
	ds_bpermute_b32 v49, v25, v48
	v_lshl_add_u64 v[46:47], v[20:21], 0, s[2:3]
	global_store_dwordx2 v[46:47], v[30:31], off sc1
	v_cvt_pk_bf16_f32 v30, v34, v35
	s_waitcnt lgkmcnt(1)
	v_add_f32_e32 v50, v50, v51
	s_waitcnt lgkmcnt(0)
	v_add_f32_e32 v48, v48, v49
	ds_bpermute_b32 v51, v26, v50
	ds_bpermute_b32 v49, v26, v48
	v_cvt_pk_bf16_f32 v31, v36, v37
	global_store_dwordx2 v[46:47], v[30:31], off offset:512 sc1
	v_cvt_pk_bf16_f32 v34, v38, v39
	s_waitcnt lgkmcnt(1)
	v_add_f32_e32 v32, v50, v51
	s_waitcnt lgkmcnt(0)
	v_add_f32_e32 v48, v48, v49
	ds_bpermute_b32 v33, v27, v32
	ds_bpermute_b32 v49, v27, v48
	s_waitcnt lgkmcnt(1)
	v_add_f32_e32 v32, v32, v33
	s_waitcnt lgkmcnt(0)
	v_add_f32_e32 v35, v48, v49
	ds_bpermute_b32 v33, v28, v32
	ds_bpermute_b32 v36, v28, v35
	s_waitcnt lgkmcnt(1)
	v_add_f32_e32 v32, v32, v33
	s_waitcnt lgkmcnt(0)
	v_add_f32_e32 v30, v35, v36
	ds_bpermute_b32 v33, v29, v32
	ds_bpermute_b32 v31, v29, v30
	v_cvt_pk_bf16_f32 v35, v40, v41
	global_store_dwordx2 v[46:47], v[34:35], off offset:1024 sc1
	v_cvt_pk_bf16_f32 v34, v42, v43
	v_cvt_pk_bf16_f32 v35, v44, v45
	global_store_dwordx2 v[46:47], v[34:35], off offset:1536 sc1
	s_and_saveexec_b64 s[10:11], s[36:37]
	s_cbranch_execnz .LBB0_570
	s_or_b64 exec, exec, s[10:11]
	s_andn2_b64 vcc, exec, s[6:7]
	s_cbranch_vccnz .LBB0_567
	s_branch .LBB0_571
.LBB0_570:
	s_lshl_b64 s[0:1], s[0:1], 6
	s_waitcnt lgkmcnt(1)
	v_add_f32_e32 v32, v32, v33
	v_lshl_add_u64 v[34:35], v[22:23], 0, s[0:1]
	v_cndmask_b32_e64 v32, 0, v32, s[38:39]
	global_store_dword v[34:35], v32, off sc1
	s_or_b64 exec, exec, s[10:11]
	s_andn2_b64 vcc, exec, s[6:7]
	s_cbranch_vccnz .LBB0_567
.LBB0_571:
	s_ashr_i32 s5, s4, 31
	s_lshl_b64 s[0:1], s[4:5], 11
	s_waitcnt lgkmcnt(1)
	v_lshl_add_u64 v[32:33], v[20:21], 0, s[0:1]
	v_cvt_pk_bf16_f32 v14, v14, v15
	v_cvt_pk_bf16_f32 v15, v16, v17
	global_store_dwordx2 v[32:33], v[14:15], off sc1
	v_cvt_pk_bf16_f32 v10, v10, v11
	v_cvt_pk_bf16_f32 v11, v12, v13
	global_store_dwordx2 v[32:33], v[10:11], off offset:512 sc1
	v_cvt_pk_bf16_f32 v6, v6, v7
	v_cvt_pk_bf16_f32 v7, v8, v9
	global_store_dwordx2 v[32:33], v[6:7], off offset:1024 sc1
	v_cvt_pk_bf16_f32 v2, v2, v3
	v_cvt_pk_bf16_f32 v3, v4, v5
	global_store_dwordx2 v[32:33], v[2:3], off offset:1536 sc1
	s_and_saveexec_b64 s[0:1], s[36:37]
	s_cbranch_execz .LBB0_566
	s_waitcnt lgkmcnt(0)
	v_add_f32_e32 v4, v30, v31
	s_lshl_b64 s[2:3], s[4:5], 6
	v_lshl_add_u64 v[2:3], v[22:23], 0, s[2:3]
	v_cndmask_b32_e64 v4, 0, v4, s[38:39]
	global_store_dword v[2:3], v4, off sc1
	s_branch .LBB0_566

; __device__ __forceinline__ void prologue(const Args& a, LAS unsigned char* lds, int vcu, int G, int wave, int lane, int tid) {
;     ...
;         for (int i = gt; i < M * 16; i += NT) { const int row = i >> 4, f = i & 15;
;             float fr = invf[0];
; #pragma unroll
;             for (int q = 1; q < 16; ++q) fr = (f == q) ? invf[q] : fr;
;             const float ang = (float)pos[row] * fr;
;             const double ad = (double)ang; const double k = __builtin_rint(ad * 0.15915494309189535); const float rf = (float)(ad - k * 6.283185307179586);
;             rope[(size_t)row * 32 + f] = __cosf(rf); rope[(size_t)row * 32 + 16 + f] = __sinf(rf); }
.LBB0_575:
	v_ashrrev_i32_e32 v8, 4, v6
	v_ashrrev_i32_e32 v9, 31, v8
	v_lshl_add_u64 v[10:11], v[8:9], 2, s[70:71]
	global_load_dword v7, v[10:11], off
	v_add_u32_e32 v6, s0, v6
	s_mov_b32 s1, 0x3ffff
	v_cmp_lt_i32_e32 vcc, s1, v6
	v_lshlrev_b64 v[8:9], 7, v[8:9]
	s_or_b64 s[6:7], vcc, s[6:7]
	v_lshl_add_u64 v[8:9], v[4:5], 0, v[8:9]
	s_waitcnt vmcnt(0)
	v_cvt_f32_i32_e32 v7, v7
	v_mul_f32_e32 v7, v3, v7
	v_cvt_f64_f32_e32 v[10:11], v7
	v_mul_f64 v[12:13], v[10:11], s[8:9]
	v_rndne_f64_e32 v[12:13], v[12:13]
	v_fmac_f64_e32 v[10:11], s[10:11], v[12:13]
	v_cvt_f32_f64_e32 v7, v[10:11]
	v_mul_f32_e32 v7, 0.15915494, v7
	v_cos_f32_e32 v10, v7
	v_sin_f32_e32 v7, v7
	global_store_dword v[8:9], v10, off sc1
	global_store_dword v[8:9], v7, off offset:64 sc1
	s_andn2_b64 exec, exec, s[6:7]
	s_cbranch_execnz .LBB0_575

; __device__ __forceinline__ void prologue(const Args& a, LAS unsigned char* lds, int vcu, int G, int wave, int lane, int tid) {
;     ...
;         float* km = (float*)(ws + WS_KM);
;         for (int i = gt; i < 2 * 65536; i += NT) km[i] = 0.f;
.LBB0_579:
	v_add_u32_e32 v8, -2, v8
	v_ashrrev_i32_e32 v11, 31, v5
	v_mov_b32_e32 v10, v5
	v_ashrrev_i32_e32 v13, 31, v4
	v_mov_b32_e32 v12, v4
	v_cmp_eq_u32_e32 vcc, 0, v8
	v_add_u32_e32 v5, s2, v5
	v_add_u32_e32 v4, s1, v4
	v_lshl_add_u64 v[12:13], v[12:13], 2, s[8:9]
	v_lshl_add_u64 v[10:11], v[10:11], 2, s[8:9]
	s_or_b64 s[10:11], vcc, s[10:11]
	global_store_dword v[12:13], v99, off sc1
	global_store_dword v[10:11], v99, off sc1
	s_andn2_b64 exec, exec, s[10:11]
	s_cbranch_execnz .LBB0_579
	s_or_b64 exec, exec, s[10:11]
	v_cmp_ne_u32_e32 vcc, v6, v7
	v_mad_u64_u32 v[2:3], s[2:3], v7, s0, v[2:3]
	s_orn2_b64 s[10:11], vcc, exec

; __device__ __forceinline__ void prologue(const Args& a, LAS unsigned char* lds, int vcu, int G, int wave, int lane, int tid) {
;     ...
;         float* km = (float*)(ws + WS_KM);
;         for (int i = gt; i < 2 * 65536; i += NT) km[i] = 0.f;
.LBB0_583:
	v_add_u32_e32 v2, s0, v2
	v_cmp_lt_i32_e32 vcc, s29, v2
	global_store_dword v[4:5], v99, off sc1
	s_or_b64 s[10:11], vcc, s[10:11]
	v_lshl_add_u64 v[4:5], v[4:5], 0, s[6:7]
	s_andn2_b64 exec, exec, s[10:11]
	s_cbranch_execnz .LBB0_583
